# EpiSwiglu rstd batching + placeholder nop runs compressed (all three epilogue patches)
# baseline (speedup 1.0000x reference)
; __device__ __forceinline__ void row_rstd4(const float* ssq, int row0, int fq, float (&rs)[4]) {
;     f32x4 v[4];
; #pragma unroll
;     for (int m = 0; m < 4; ++m) v[m] = *(const f32x4*)(ssq + (size_t)(row0 + m * 16) * 16 + fq * 4);
; #pragma unroll
;     for (int m = 0; m < 4; ++m) { float t = (v[m][0] + v[m][1]) + (v[m][2] + v[m][3]); t += __shfl_xor(t, 16); t += __shfl_xor(t, 32); rs[m] = __builtin_amdgcn_rsqf(t * (1.f / DM) + EPS); }
; }
;     __device__ __forceinline__ void operator()(const f32x4 (&acc)[2][2][4][2], const pg8::Unit& u, int wr, int wc, int fr, int fq) const {
;     ...
;                 f32x4 e0 = acc[ai][0][m][0] * c, e1 = acc[ai][0][m][1] * c;
; #pragma unroll
;                 for (int i = 0; i < 4; ++i) { e0[i] = __builtin_amdgcn_exp2f(e0[i]); e1[i] = __builtin_amdgcn_exp2f(e1[i]); }
;                 e0 = e0 + 1.0f; e1 = e1 + 1.0f;
; #pragma unroll
;                 for (int i = 0; i < 4; ++i) { e0[i] = __builtin_amdgcn_rcpf(e0[i]); e1[i] = __builtin_amdgcn_rcpf(e1[i]); }
;                 const f32x4 h0 = (acc[ai][0][m][0] * acc[ai][1][m][0]) * rs2 * e0, h1 = (acc[ai][0][m][1] * acc[ai][1][m][1]) * rs2 * e1;
.LBB0_159:
	v_lshl_add_u32 v240, s24, 8, v148
	v_mov_b32_e32 v172, v240
	v_ashrrev_i32_e32 v173, 31, v172
	v_lshlrev_b64 v[172:173], 6, v[172:173]
	v_lshl_add_u64 v[172:173], v[134:135], 0, v[172:173]
	global_load_dwordx4 v[172:175], v[172:173], off
	v_add_u32_e32 v176, 16, v240
	v_ashrrev_i32_e32 v177, 31, v176
	v_lshlrev_b64 v[176:177], 6, v[176:177]
	v_lshl_add_u64 v[176:177], v[134:135], 0, v[176:177]
	global_load_dwordx4 v[176:179], v[176:177], off
	v_add_u32_e32 v180, 32, v240
	v_ashrrev_i32_e32 v181, 31, v180
	v_lshlrev_b64 v[180:181], 6, v[180:181]
	v_lshl_add_u64 v[180:181], v[134:135], 0, v[180:181]
	global_load_dwordx4 v[180:183], v[180:181], off
	v_add_u32_e32 v184, 48, v240
	v_ashrrev_i32_e32 v185, 31, v184
	v_lshlrev_b64 v[184:185], 6, v[184:185]
	v_lshl_add_u64 v[184:185], v[134:135], 0, v[184:185]
	global_load_dwordx4 v[184:187], v[184:185], off
	v_add_u32_e32 v188, 0x80, v240
	v_ashrrev_i32_e32 v189, 31, v188
	v_lshlrev_b64 v[188:189], 6, v[188:189]
	v_lshl_add_u64 v[188:189], v[134:135], 0, v[188:189]
	global_load_dwordx4 v[188:191], v[188:189], off
	v_add_u32_e32 v218, 0x90, v240
	v_ashrrev_i32_e32 v219, 31, v218
	v_lshlrev_b64 v[218:219], 6, v[218:219]
	v_lshl_add_u64 v[218:219], v[134:135], 0, v[218:219]
	global_load_dwordx4 v[218:221], v[218:219], off
	v_add_u32_e32 v222, 0xa0, v240
	v_ashrrev_i32_e32 v223, 31, v222
	v_lshlrev_b64 v[222:223], 6, v[222:223]
	v_lshl_add_u64 v[222:223], v[134:135], 0, v[222:223]
	global_load_dwordx4 v[222:225], v[222:223], off
	v_add_u32_e32 v226, 0xb0, v240
	v_ashrrev_i32_e32 v227, 31, v226
	v_lshlrev_b64 v[226:227], 6, v[226:227]
	v_lshl_add_u64 v[226:227], v[134:135], 0, v[226:227]
	global_load_dwordx4 v[226:229], v[226:227], off
	v_xor_b32_e32 v238, 16, v215
	v_xor_b32_e32 v239, 32, v215
	v_lshlrev_b32_e32 v238, 2, v238
	v_lshlrev_b32_e32 v239, 2, v239
	v_lshl_add_u32 v140, s24, 8, v148
	v_or_b32_e32 v146, 16, v140
	v_ashrrev_i32_e32 v141, 31, v140
	v_ashrrev_i32_e32 v147, 31, v146
	v_lshlrev_b64 v[142:143], 6, v[140:141]
	v_lshlrev_b64 v[144:145], 6, v[146:147]
	v_lshl_add_u64 v[142:143], v[134:135], 0, v[142:143]
	v_lshl_add_u64 v[144:145], v[134:135], 0, v[144:145]
	s_nop 1
	v_or_b32_e32 v144, 32, v140
	v_ashrrev_i32_e32 v145, 31, v144
	v_lshlrev_b64 v[142:143], 6, v[144:145]
	v_lshl_add_u64 v[142:143], v[134:135], 0, v[142:143]
	s_nop 0
	v_or_b32_e32 v142, 48, v140
	v_ashrrev_i32_e32 v143, 31, v142
	v_lshlrev_b64 v[164:165], 6, v[142:143]
	v_lshl_add_u64 v[164:165], v[134:135], 0, v[164:165]
	s_nop 0
	v_and_b32_e32 v143, 64, v215
	v_xor_b32_e32 v141, 16, v215
	v_add_u32_e32 v143, 64, v143
	v_xor_b32_e32 v145, 32, v215
	v_cmp_lt_i32_e32 vcc, v141, v143
	v_pk_mul_f32 v[126:127], v[118:119], v[126:127]
	v_pk_mul_f32 v[124:125], v[116:117], v[124:125]
	v_cndmask_b32_e32 v141, v215, v141, vcc
	v_cmp_lt_i32_e32 vcc, v145, v143
	v_lshlrev_b32_e32 v141, 2, v141
	v_pk_mul_f32 v[120:121], v[112:113], v[120:121]
	v_cndmask_b32_e32 v143, v215, v145, vcc
	v_lshlrev_b32_e32 v143, 2, v143
	v_pk_mul_f32 v[122:123], v[114:115], v[122:123]
	v_lshl_or_b32 v168, s70, 7, v150
	v_ashrrev_i32_e32 v169, 31, v168
	v_pk_mul_f32 v[100:101], v[108:109], v[100:101]
	v_pk_mul_f32 v[102:103], v[110:111], v[102:103]
	v_pk_mul_f32 v[98:99], v[106:107], v[98:99]
	v_pk_mul_f32 v[96:97], v[104:105], v[96:97]
	v_pk_mul_f32 v[84:85], v[92:93], v[84:85]
	v_pk_mul_f32 v[86:87], v[94:95], v[86:87]
	v_pk_mul_f32 v[82:83], v[90:91], v[82:83]
	v_pk_mul_f32 v[80:81], v[88:89], v[80:81]
	v_pk_mul_f32 v[68:69], v[76:77], v[68:69]
	v_pk_mul_f32 v[70:71], v[78:79], v[70:71]
	v_pk_mul_f32 v[66:67], v[74:75], v[66:67]
	v_pk_mul_f32 v[64:65], v[72:73], v[64:65]
	v_pk_mul_f32 v[52:53], v[60:61], v[52:53]
	v_pk_mul_f32 v[54:55], v[62:63], v[54:55]
	v_pk_mul_f32 v[50:51], v[58:59], v[50:51]
	v_pk_mul_f32 v[48:49], v[56:57], v[48:49]
	v_pk_mul_f32 v[36:37], v[44:45], v[36:37]
	v_pk_mul_f32 v[38:39], v[46:47], v[38:39]
	v_pk_mul_f32 v[34:35], v[42:43], v[34:35]
	v_pk_mul_f32 v[32:33], v[40:41], v[32:33]
	v_pk_mul_f32 v[20:21], v[28:29], v[20:21]
	v_pk_mul_f32 v[22:23], v[30:31], v[22:23]
	v_pk_mul_f32 v[18:19], v[26:27], v[18:19]
	v_pk_mul_f32 v[16:17], v[24:25], v[16:17]
	v_pk_mul_f32 v[4:5], v[12:13], v[4:5]
	v_pk_mul_f32 v[6:7], v[14:15], v[6:7]
	v_pk_mul_f32 v[2:3], v[10:11], v[2:3]
	v_pk_mul_f32 v[0:1], v[8:9], v[0:1]
	s_andn2_b64 vcc, exec, s[4:5]
	s_mov_b64 s[4:5], -1
	s_waitcnt vmcnt(0)
	v_add_f32_e32 v172, v172, v173
	v_add_f32_e32 v174, v174, v175
	v_add_f32_e32 v176, v176, v177
	v_add_f32_e32 v178, v178, v179
	v_add_f32_e32 v180, v180, v181
	v_add_f32_e32 v182, v182, v183
	v_add_f32_e32 v184, v184, v185
	v_add_f32_e32 v186, v186, v187
	v_add_f32_e32 v188, v188, v189
	v_add_f32_e32 v190, v190, v191
	v_add_f32_e32 v218, v218, v219
	v_add_f32_e32 v220, v220, v221
	v_add_f32_e32 v222, v222, v223
	v_add_f32_e32 v224, v224, v225
	v_add_f32_e32 v226, v226, v227
	v_add_f32_e32 v228, v228, v229
	v_add_f32_e32 v172, v172, v174
	v_add_f32_e32 v176, v176, v178
	v_add_f32_e32 v180, v180, v182
	v_add_f32_e32 v184, v184, v186
	v_add_f32_e32 v188, v188, v190
	v_add_f32_e32 v218, v218, v220
	v_add_f32_e32 v222, v222, v224
	v_add_f32_e32 v226, v226, v228
	ds_bpermute_b32 v173, v238, v172
	ds_bpermute_b32 v177, v238, v176
	ds_bpermute_b32 v181, v238, v180
	ds_bpermute_b32 v185, v238, v184
	ds_bpermute_b32 v189, v238, v188
	ds_bpermute_b32 v219, v238, v218
	ds_bpermute_b32 v223, v238, v222
	ds_bpermute_b32 v227, v238, v226
	s_waitcnt lgkmcnt(0)
; __device__ __forceinline__ v4u pack8(const f32x4 a, const f32x4 b) { v4u w; w.x = cvt_pk_bf16(a[0], a[1]); w.y = cvt_pk_bf16(a[2], a[3]); w.z = cvt_pk_bf16(b[0], b[1]); w.w = cvt_pk_bf16(b[2], b[3]); return w; }
; __device__ __forceinline__ void row_rstd4(const float* ssq, int row0, int fq, float (&rs)[4]) {
;     ...
;     for (int m = 0; m < 4; ++m) v[m] = *(const f32x4*)(ssq + (size_t)(row0 + m * 16) * 16 + fq * 4);
; #pragma unroll
;     for (int m = 0; m < 4; ++m) { float t = (v[m][0] + v[m][1]) + (v[m][2] + v[m][3]); t += __shfl_xor(t, 16); t += __shfl_xor(t, 32); rs[m] = __builtin_amdgcn_rsqf(t * (1.f / DM) + EPS); }
;     __device__ __forceinline__ void operator()(const f32x4 (&acc)[2][2][4][2], const pg8::Unit& u, int wr, int wc, int fr, int fq) const {
;     ...
;                 const int row = row0 + ai * 128 + m * 16; const float rs = rsv[m], c = -rs * LOG2E, rs2 = rs * rs;
;                 f32x4 e0 = acc[ai][0][m][0] * c, e1 = acc[ai][0][m][1] * c;
; #pragma unroll
;                 for (int i = 0; i < 4; ++i) { e0[i] = __builtin_amdgcn_exp2f(e0[i]); e1[i] = __builtin_amdgcn_exp2f(e1[i]); }
;                 e0 = e0 + 1.0f; e1 = e1 + 1.0f;
; #pragma unroll
;                 for (int i = 0; i < 4; ++i) { e0[i] = __builtin_amdgcn_rcpf(e0[i]); e1[i] = __builtin_amdgcn_rcpf(e1[i]); }
;                 const f32x4 h0 = (acc[ai][0][m][0] * acc[ai][1][m][0]) * rs2 * e0, h1 = (acc[ai][0][m][1] * acc[ai][1][m][1]) * rs2 * e1;
;                 *(v4u*)(O + (size_t)row * FFH + col0) = pack8(h0, h1);
	v_add_f32_e32 v172, v172, v173
	v_add_f32_e32 v176, v176, v177
	v_add_f32_e32 v180, v180, v181
	v_add_f32_e32 v184, v184, v185
	v_add_f32_e32 v188, v188, v189
	v_add_f32_e32 v218, v218, v219
	v_add_f32_e32 v222, v222, v223
	v_add_f32_e32 v226, v226, v227
	ds_bpermute_b32 v173, v239, v172
	ds_bpermute_b32 v177, v239, v176
	ds_bpermute_b32 v181, v239, v180
	ds_bpermute_b32 v185, v239, v184
	ds_bpermute_b32 v189, v239, v188
	ds_bpermute_b32 v219, v239, v218
	ds_bpermute_b32 v223, v239, v222
	ds_bpermute_b32 v227, v239, v226
	s_waitcnt lgkmcnt(0)
	v_add_f32_e32 v172, v172, v173
	v_add_f32_e32 v176, v176, v177
	v_add_f32_e32 v180, v180, v181
	v_add_f32_e32 v184, v184, v185
	v_add_f32_e32 v188, v188, v189
	v_add_f32_e32 v218, v218, v219
	v_add_f32_e32 v222, v222, v223
	v_add_f32_e32 v226, v226, v227
	v_fmamk_f32 v172, v172, 0x3a800000, v212
	v_fmamk_f32 v176, v176, 0x3a800000, v212
	v_fmamk_f32 v180, v180, 0x3a800000, v212
	v_fmamk_f32 v184, v184, 0x3a800000, v212
	v_fmamk_f32 v188, v188, 0x3a800000, v212
	v_fmamk_f32 v218, v218, 0x3a800000, v212
	v_fmamk_f32 v222, v222, 0x3a800000, v212
	v_fmamk_f32 v226, v226, 0x3a800000, v212
	v_rsq_f32_e32 v230, v172
	v_rsq_f32_e32 v231, v176
	v_rsq_f32_e32 v232, v180
	v_rsq_f32_e32 v233, v184
	v_rsq_f32_e32 v234, v188
	v_rsq_f32_e32 v235, v218
	v_rsq_f32_e32 v236, v222
	v_rsq_f32_e32 v237, v226
	s_nop 0
	s_waitcnt lgkmcnt(0)
	s_nop 4
	s_waitcnt lgkmcnt(0)
	s_nop 1
	s_waitcnt lgkmcnt(0)
	s_nop 0
	s_waitcnt lgkmcnt(0)
	s_nop 0
	s_waitcnt lgkmcnt(0)
	s_nop 3
	s_waitcnt lgkmcnt(0)
	s_nop 1
	s_waitcnt lgkmcnt(0)
	s_nop 0
	s_waitcnt lgkmcnt(0)
	s_nop 0
	s_waitcnt lgkmcnt(0)
	s_nop 0
	v_mov_b32_e32 v145, v230
	s_nop 0
	v_mov_b32_e32 v153, v233
	s_nop 0
	v_mov_b32_e32 v155, v232
	v_mul_f32_e32 v152, 0xbfb8aa3b, v145
	v_pk_mul_f32 v[118:119], v[118:119], v[152:153] op_sel_hi:[1,0]
	v_pk_mul_f32 v[116:117], v[116:117], v[152:153] op_sel_hi:[1,0]
	v_pk_mul_f32 v[112:113], v[112:113], v[152:153] op_sel_hi:[1,0]
	v_pk_mul_f32 v[114:115], v[114:115], v[152:153] op_sel_hi:[1,0]
	v_exp_f32_e32 v116, v116
	v_exp_f32_e32 v112, v112
	v_exp_f32_e32 v117, v117
	v_exp_f32_e32 v118, v118
	v_exp_f32_e32 v119, v119
	v_exp_f32_e32 v113, v113
	v_exp_f32_e32 v114, v114
	v_exp_f32_e32 v115, v115
	v_pk_add_f32 v[118:119], v[118:119], 1.0 op_sel_hi:[1,0]
	v_pk_add_f32 v[116:117], v[116:117], 1.0 op_sel_hi:[1,0]
	v_pk_add_f32 v[112:113], v[112:113], 1.0 op_sel_hi:[1,0]
	v_pk_add_f32 v[114:115], v[114:115], 1.0 op_sel_hi:[1,0]
	v_rcp_f32_e32 v116, v116
	v_rcp_f32_e32 v112, v112
	v_rcp_f32_e32 v117, v117
	v_rcp_f32_e32 v118, v118
	v_rcp_f32_e32 v119, v119
	v_rcp_f32_e32 v113, v113
	v_rcp_f32_e32 v114, v114
	v_rcp_f32_e32 v115, v115
	v_mul_f32_e32 v154, v145, v145
	s_nop 0
	v_pk_mul_f32 v[124:125], v[124:125], v[154:155] op_sel_hi:[1,0]
	v_pk_mul_f32 v[126:127], v[126:127], v[154:155] op_sel_hi:[1,0]
	v_pk_mul_f32 v[120:121], v[120:121], v[154:155] op_sel_hi:[1,0]
	v_mov_b32_e32 v147, v231
	v_pk_mul_f32 v[122:123], v[122:123], v[154:155] op_sel_hi:[1,0]
	v_pk_mul_f32 v[118:119], v[126:127], v[118:119]
	v_pk_mul_f32 v[116:117], v[124:125], v[116:117]
	v_pk_mul_f32 v[112:113], v[120:121], v[112:113]
	v_pk_mul_f32 v[114:115], v[122:123], v[114:115]
	v_cvt_pk_bf16_f32 v116, v116, v117
	v_cvt_pk_bf16_f32 v117, v118, v119
	v_cvt_pk_bf16_f32 v118, v112, v113
	v_mov_b64_e32 v[112:113], s[12:13]
	v_cvt_pk_bf16_f32 v119, v114, v115
	v_mad_i64_i32 v[120:121], s[8:9], v140, s3, v[112:113]
	v_lshlrev_b64 v[114:115], 1, v[168:169]
	v_lshl_add_u64 v[120:121], v[120:121], 0, v[114:115]
	global_store_dwordx4 v[120:121], v[116:119], off
	v_mul_f32_e32 v124, v147, v147
	v_pk_mul_f32 v[100:101], v[100:101], v[124:125] op_sel_hi:[1,0]
	v_mul_f32_e32 v116, 0xbfb8aa3b, v147
	v_pk_mul_f32 v[120:121], v[108:109], v[116:117] op_sel_hi:[1,0]
	v_pk_mul_f32 v[118:119], v[110:111], v[116:117] op_sel_hi:[1,0]
	v_pk_mul_f32 v[122:123], v[106:107], v[116:117] op_sel_hi:[1,0]
	v_pk_mul_f32 v[116:117], v[104:105], v[116:117] op_sel_hi:[1,0]
	v_exp_f32_e32 v120, v120
	v_exp_f32_e32 v121, v121
	v_exp_f32_e32 v116, v116
	v_exp_f32_e32 v118, v118
	v_exp_f32_e32 v119, v119
	v_exp_f32_e32 v122, v122
	v_exp_f32_e32 v123, v123
	v_exp_f32_e32 v117, v117
	v_pk_add_f32 v[120:121], v[120:121], 1.0 op_sel_hi:[1,0]
	v_pk_add_f32 v[118:119], v[118:119], 1.0 op_sel_hi:[1,0]
	v_pk_add_f32 v[122:123], v[122:123], 1.0 op_sel_hi:[1,0]
	v_pk_add_f32 v[116:117], v[116:117], 1.0 op_sel_hi:[1,0]
	v_rcp_f32_e32 v120, v120
	v_rcp_f32_e32 v121, v121
	v_rcp_f32_e32 v116, v116
	v_rcp_f32_e32 v117, v117
	v_rcp_f32_e32 v118, v118
	v_rcp_f32_e32 v122, v122
	v_rcp_f32_e32 v119, v119
	v_rcp_f32_e32 v123, v123
	v_pk_mul_f32 v[102:103], v[102:103], v[124:125] op_sel_hi:[1,0]
	v_pk_mul_f32 v[100:101], v[100:101], v[120:121]
	v_pk_mul_f32 v[96:97], v[96:97], v[124:125] op_sel_hi:[1,0]
	v_pk_mul_f32 v[98:99], v[98:99], v[124:125] op_sel_hi:[1,0]
	v_pk_mul_f32 v[102:103], v[102:103], v[118:119]
	v_pk_mul_f32 v[104:105], v[98:99], v[122:123]
	v_pk_mul_f32 v[98:99], v[96:97], v[116:117]
	v_cvt_pk_bf16_f32 v96, v100, v101
	v_mad_i64_i32 v[100:101], s[8:9], v146, s3, v[112:113]
	v_cvt_pk_bf16_f32 v97, v102, v103
	v_cvt_pk_bf16_f32 v98, v98, v99
	v_cvt_pk_bf16_f32 v99, v104, v105
	v_lshl_add_u64 v[100:101], v[100:101], 0, v[114:115]
	global_store_dwordx4 v[100:101], v[96:99], off
	v_mul_f32_e32 v104, v155, v155
	v_pk_mul_f32 v[84:85], v[84:85], v[104:105] op_sel_hi:[1,0]
	v_mul_f32_e32 v96, 0xbfb8aa3b, v155
	v_pk_mul_f32 v[100:101], v[92:93], v[96:97] op_sel_hi:[1,0]
	v_pk_mul_f32 v[98:99], v[94:95], v[96:97] op_sel_hi:[1,0]
	v_pk_mul_f32 v[102:103], v[90:91], v[96:97] op_sel_hi:[1,0]
; __device__ __forceinline__ v4u pack8(const f32x4 a, const f32x4 b) { v4u w; w.x = cvt_pk_bf16(a[0], a[1]); w.y = cvt_pk_bf16(a[2], a[3]); w.z = cvt_pk_bf16(b[0], b[1]); w.w = cvt_pk_bf16(b[2], b[3]); return w; }
;     __device__ __forceinline__ void operator()(const f32x4 (&acc)[2][2][4][2], const pg8::Unit& u, int wr, int wc, int fr, int fq) const {
;     ...
;                 const int row = row0 + ai * 128 + m * 16; const float rs = rsv[m], c = -rs * LOG2E, rs2 = rs * rs;
;                 f32x4 e0 = acc[ai][0][m][0] * c, e1 = acc[ai][0][m][1] * c;
; #pragma unroll
;                 for (int i = 0; i < 4; ++i) { e0[i] = __builtin_amdgcn_exp2f(e0[i]); e1[i] = __builtin_amdgcn_exp2f(e1[i]); }
;                 e0 = e0 + 1.0f; e1 = e1 + 1.0f;
; #pragma unroll
;                 for (int i = 0; i < 4; ++i) { e0[i] = __builtin_amdgcn_rcpf(e0[i]); e1[i] = __builtin_amdgcn_rcpf(e1[i]); }
;                 const f32x4 h0 = (acc[ai][0][m][0] * acc[ai][1][m][0]) * rs2 * e0, h1 = (acc[ai][0][m][1] * acc[ai][1][m][1]) * rs2 * e1;
;                 *(v4u*)(O + (size_t)row * FFH + col0) = pack8(h0, h1);
	v_pk_mul_f32 v[96:97], v[88:89], v[96:97] op_sel_hi:[1,0]
	v_exp_f32_e32 v100, v100
	v_exp_f32_e32 v101, v101
	v_exp_f32_e32 v96, v96
	v_exp_f32_e32 v98, v98
	v_exp_f32_e32 v99, v99
	v_exp_f32_e32 v102, v102
	v_exp_f32_e32 v103, v103
	v_exp_f32_e32 v97, v97
	v_pk_add_f32 v[100:101], v[100:101], 1.0 op_sel_hi:[1,0]
	v_pk_add_f32 v[98:99], v[98:99], 1.0 op_sel_hi:[1,0]
	v_pk_add_f32 v[102:103], v[102:103], 1.0 op_sel_hi:[1,0]
	v_pk_add_f32 v[96:97], v[96:97], 1.0 op_sel_hi:[1,0]
	v_rcp_f32_e32 v100, v100
	v_rcp_f32_e32 v101, v101
	v_rcp_f32_e32 v96, v96
	v_rcp_f32_e32 v97, v97
	v_rcp_f32_e32 v98, v98
	v_rcp_f32_e32 v102, v102
	v_rcp_f32_e32 v99, v99
	v_rcp_f32_e32 v103, v103
	v_pk_mul_f32 v[86:87], v[86:87], v[104:105] op_sel_hi:[1,0]
	v_pk_mul_f32 v[84:85], v[84:85], v[100:101]
	v_pk_mul_f32 v[80:81], v[80:81], v[104:105] op_sel_hi:[1,0]
	v_pk_mul_f32 v[82:83], v[82:83], v[104:105] op_sel_hi:[1,0]
	v_pk_mul_f32 v[86:87], v[86:87], v[98:99]
	v_pk_mul_f32 v[88:89], v[82:83], v[102:103]
	v_pk_mul_f32 v[82:83], v[80:81], v[96:97]
	v_cvt_pk_bf16_f32 v80, v84, v85
	v_mad_i64_i32 v[84:85], s[8:9], v144, s3, v[112:113]
	v_cvt_pk_bf16_f32 v81, v86, v87
	v_cvt_pk_bf16_f32 v82, v82, v83
	v_cvt_pk_bf16_f32 v83, v88, v89
	v_lshl_add_u64 v[84:85], v[84:85], 0, v[114:115]
	global_store_dwordx4 v[84:85], v[80:83], off
	v_mul_f32_e32 v88, v153, v153
	v_pk_mul_f32 v[68:69], v[68:69], v[88:89] op_sel_hi:[1,0]
	v_mul_f32_e32 v80, 0xbfb8aa3b, v153
	v_pk_mul_f32 v[84:85], v[76:77], v[80:81] op_sel_hi:[1,0]
	v_pk_mul_f32 v[82:83], v[78:79], v[80:81] op_sel_hi:[1,0]
	v_pk_mul_f32 v[86:87], v[74:75], v[80:81] op_sel_hi:[1,0]
	v_pk_mul_f32 v[80:81], v[72:73], v[80:81] op_sel_hi:[1,0]
	v_exp_f32_e32 v84, v84
	v_exp_f32_e32 v85, v85
	v_exp_f32_e32 v80, v80
	v_exp_f32_e32 v82, v82
	v_exp_f32_e32 v83, v83
	v_exp_f32_e32 v86, v86
	v_exp_f32_e32 v87, v87
	v_exp_f32_e32 v81, v81
	v_pk_add_f32 v[84:85], v[84:85], 1.0 op_sel_hi:[1,0]
	v_pk_add_f32 v[82:83], v[82:83], 1.0 op_sel_hi:[1,0]
	v_pk_add_f32 v[86:87], v[86:87], 1.0 op_sel_hi:[1,0]
	v_pk_add_f32 v[80:81], v[80:81], 1.0 op_sel_hi:[1,0]
	v_rcp_f32_e32 v84, v84
	v_rcp_f32_e32 v85, v85
	v_rcp_f32_e32 v80, v80
	v_rcp_f32_e32 v81, v81
	v_rcp_f32_e32 v82, v82
	v_rcp_f32_e32 v86, v86
	v_rcp_f32_e32 v83, v83
	v_rcp_f32_e32 v87, v87
	v_pk_mul_f32 v[70:71], v[70:71], v[88:89] op_sel_hi:[1,0]
	v_pk_mul_f32 v[68:69], v[68:69], v[84:85]
	v_pk_mul_f32 v[64:65], v[64:65], v[88:89] op_sel_hi:[1,0]
	v_pk_mul_f32 v[66:67], v[66:67], v[88:89] op_sel_hi:[1,0]
	v_pk_mul_f32 v[70:71], v[70:71], v[82:83]
	v_pk_mul_f32 v[72:73], v[66:67], v[86:87]
	v_pk_mul_f32 v[66:67], v[64:65], v[80:81]
	v_cvt_pk_bf16_f32 v64, v68, v69
	v_mad_i64_i32 v[68:69], s[8:9], v142, s3, v[112:113]
	v_add_u32_e32 v84, 0x80, v140
	v_cvt_pk_bf16_f32 v65, v70, v71
	v_cvt_pk_bf16_f32 v66, v66, v67
	v_cvt_pk_bf16_f32 v67, v72, v73
	v_lshl_add_u64 v[68:69], v[68:69], 0, v[114:115]
	v_ashrrev_i32_e32 v85, 31, v84
	global_store_dwordx4 v[68:69], v[64:67], off
	v_add_u32_e32 v86, 0x90, v140
	v_ashrrev_i32_e32 v87, 31, v86
	v_lshlrev_b64 v[64:65], 6, v[84:85]
	v_lshl_add_u64 v[64:65], v[134:135], 0, v[64:65]
	s_nop 0
	v_lshlrev_b64 v[64:65], 6, v[86:87]
	v_lshl_add_u64 v[64:65], v[134:135], 0, v[64:65]
	s_nop 0
	v_add_u32_e32 v66, 0xa0, v140
	v_ashrrev_i32_e32 v67, 31, v66
	v_lshlrev_b64 v[64:65], 6, v[66:67]
	v_lshl_add_u64 v[64:65], v[134:135], 0, v[64:65]
	s_nop 0
	v_add_u32_e32 v64, 0xb0, v140
	v_ashrrev_i32_e32 v65, 31, v64
	v_lshlrev_b64 v[80:81], 6, v[64:65]
	v_lshl_add_u64 v[80:81], v[134:135], 0, v[80:81]
	s_nop 0
	s_waitcnt lgkmcnt(0)
	s_nop 3
	s_nop 0
	s_nop 4
	s_waitcnt lgkmcnt(0)
	s_nop 3
	s_waitcnt lgkmcnt(0)
	s_nop 0
	s_waitcnt lgkmcnt(0)
	s_nop 4
	s_waitcnt lgkmcnt(0)
	s_nop 1
	s_waitcnt lgkmcnt(0)
	s_nop 1
	s_waitcnt lgkmcnt(0)
	s_nop 1
	v_mov_b32_e32 v65, v234
	s_nop 0
	s_waitcnt lgkmcnt(0)
	s_nop 1
	s_waitcnt lgkmcnt(0)
; __device__ __forceinline__ v4u pack8(const f32x4 a, const f32x4 b) { v4u w; w.x = cvt_pk_bf16(a[0], a[1]); w.y = cvt_pk_bf16(a[2], a[3]); w.z = cvt_pk_bf16(b[0], b[1]); w.w = cvt_pk_bf16(b[2], b[3]); return w; }
;     __device__ __forceinline__ void operator()(const f32x4 (&acc)[2][2][4][2], const pg8::Unit& u, int wr, int wc, int fr, int fq) const {
;     ...
;                 const int row = row0 + ai * 128 + m * 16; const float rs = rsv[m], c = -rs * LOG2E, rs2 = rs * rs;
;                 f32x4 e0 = acc[ai][0][m][0] * c, e1 = acc[ai][0][m][1] * c;
; #pragma unroll
;                 for (int i = 0; i < 4; ++i) { e0[i] = __builtin_amdgcn_exp2f(e0[i]); e1[i] = __builtin_amdgcn_exp2f(e1[i]); }
;                 e0 = e0 + 1.0f; e1 = e1 + 1.0f;
; #pragma unroll
;                 for (int i = 0; i < 4; ++i) { e0[i] = __builtin_amdgcn_rcpf(e0[i]); e1[i] = __builtin_amdgcn_rcpf(e1[i]); }
;                 const f32x4 h0 = (acc[ai][0][m][0] * acc[ai][1][m][0]) * rs2 * e0, h1 = (acc[ai][0][m][1] * acc[ai][1][m][1]) * rs2 * e1;
;                 *(v4u*)(O + (size_t)row * FFH + col0) = pack8(h0, h1);
	s_nop 1
	v_mov_b32_e32 v78, v237
	v_mul_f32_e32 v68, 0xbfb8aa3b, v65
	v_pk_mul_f32 v[72:73], v[60:61], v[68:69] op_sel_hi:[1,0]
	v_mov_b32_e32 v77, v236
	v_pk_mul_f32 v[70:71], v[62:63], v[68:69] op_sel_hi:[1,0]
	v_pk_mul_f32 v[74:75], v[58:59], v[68:69] op_sel_hi:[1,0]
	v_pk_mul_f32 v[68:69], v[56:57], v[68:69] op_sel_hi:[1,0]
	v_exp_f32_e32 v72, v72
	v_exp_f32_e32 v73, v73
	v_exp_f32_e32 v68, v68
	v_exp_f32_e32 v70, v70
	v_exp_f32_e32 v71, v71
	v_exp_f32_e32 v74, v74
	v_exp_f32_e32 v75, v75
	v_exp_f32_e32 v69, v69
	v_pk_add_f32 v[72:73], v[72:73], 1.0 op_sel_hi:[1,0]
	v_pk_add_f32 v[70:71], v[70:71], 1.0 op_sel_hi:[1,0]
	v_pk_add_f32 v[74:75], v[74:75], 1.0 op_sel_hi:[1,0]
	v_pk_add_f32 v[68:69], v[68:69], 1.0 op_sel_hi:[1,0]
	v_rcp_f32_e32 v72, v72
	v_rcp_f32_e32 v73, v73
	v_rcp_f32_e32 v68, v68
	v_rcp_f32_e32 v69, v69
	v_rcp_f32_e32 v70, v70
	v_rcp_f32_e32 v74, v74
	v_rcp_f32_e32 v71, v71
	v_rcp_f32_e32 v75, v75
	v_mul_f32_e32 v76, v65, v65
	v_mov_b32_e32 v67, v235
	v_pk_mul_f32 v[52:53], v[52:53], v[76:77] op_sel_hi:[1,0]
	v_pk_mul_f32 v[54:55], v[54:55], v[76:77] op_sel_hi:[1,0]
	v_pk_mul_f32 v[52:53], v[52:53], v[72:73]
	v_pk_mul_f32 v[48:49], v[48:49], v[76:77] op_sel_hi:[1,0]
	v_pk_mul_f32 v[50:51], v[50:51], v[76:77] op_sel_hi:[1,0]
	v_pk_mul_f32 v[54:55], v[54:55], v[70:71]
	v_pk_mul_f32 v[56:57], v[50:51], v[74:75]
	v_pk_mul_f32 v[50:51], v[48:49], v[68:69]
	v_cvt_pk_bf16_f32 v48, v52, v53
	v_mad_i64_i32 v[52:53], s[8:9], v84, s3, v[112:113]
	v_cvt_pk_bf16_f32 v49, v54, v55
	v_cvt_pk_bf16_f32 v50, v50, v51
	v_cvt_pk_bf16_f32 v51, v56, v57
	v_lshl_add_u64 v[52:53], v[52:53], 0, v[114:115]
	global_store_dwordx4 v[52:53], v[48:51], off
	v_mul_f32_e32 v56, v67, v67
	v_pk_mul_f32 v[36:37], v[36:37], v[56:57] op_sel_hi:[1,0]
	v_mul_f32_e32 v48, 0xbfb8aa3b, v67
	v_pk_mul_f32 v[52:53], v[44:45], v[48:49] op_sel_hi:[1,0]
	v_pk_mul_f32 v[50:51], v[46:47], v[48:49] op_sel_hi:[1,0]
	v_pk_mul_f32 v[54:55], v[42:43], v[48:49] op_sel_hi:[1,0]
	v_pk_mul_f32 v[48:49], v[40:41], v[48:49] op_sel_hi:[1,0]
	v_exp_f32_e32 v52, v52
	v_exp_f32_e32 v53, v53
	v_exp_f32_e32 v48, v48
	v_exp_f32_e32 v50, v50
	v_exp_f32_e32 v51, v51
	v_exp_f32_e32 v54, v54
	v_exp_f32_e32 v55, v55
	v_exp_f32_e32 v49, v49
	v_pk_add_f32 v[52:53], v[52:53], 1.0 op_sel_hi:[1,0]
	v_pk_add_f32 v[50:51], v[50:51], 1.0 op_sel_hi:[1,0]
	v_pk_add_f32 v[54:55], v[54:55], 1.0 op_sel_hi:[1,0]
	v_pk_add_f32 v[48:49], v[48:49], 1.0 op_sel_hi:[1,0]
	v_rcp_f32_e32 v52, v52
	v_rcp_f32_e32 v53, v53
	v_rcp_f32_e32 v48, v48
	v_rcp_f32_e32 v49, v49
	v_rcp_f32_e32 v50, v50
	v_rcp_f32_e32 v54, v54
	v_rcp_f32_e32 v51, v51
	v_rcp_f32_e32 v55, v55
	v_pk_mul_f32 v[38:39], v[38:39], v[56:57] op_sel_hi:[1,0]
	v_pk_mul_f32 v[36:37], v[36:37], v[52:53]
	v_pk_mul_f32 v[32:33], v[32:33], v[56:57] op_sel_hi:[1,0]
	v_pk_mul_f32 v[34:35], v[34:35], v[56:57] op_sel_hi:[1,0]
	v_pk_mul_f32 v[38:39], v[38:39], v[50:51]
	v_pk_mul_f32 v[40:41], v[34:35], v[54:55]
	v_pk_mul_f32 v[34:35], v[32:33], v[48:49]
	v_cvt_pk_bf16_f32 v32, v36, v37
	v_mad_i64_i32 v[36:37], s[8:9], v86, s3, v[112:113]
	v_cvt_pk_bf16_f32 v33, v38, v39
	v_cvt_pk_bf16_f32 v34, v34, v35
	v_cvt_pk_bf16_f32 v35, v40, v41
	v_lshl_add_u64 v[36:37], v[36:37], 0, v[114:115]
	global_store_dwordx4 v[36:37], v[32:35], off
	v_mul_f32_e32 v40, v77, v77
	v_pk_mul_f32 v[20:21], v[20:21], v[40:41] op_sel_hi:[1,0]
	v_mul_f32_e32 v32, 0xbfb8aa3b, v77
	v_pk_mul_f32 v[36:37], v[28:29], v[32:33] op_sel_hi:[1,0]
	v_pk_mul_f32 v[34:35], v[30:31], v[32:33] op_sel_hi:[1,0]
	v_pk_mul_f32 v[38:39], v[26:27], v[32:33] op_sel_hi:[1,0]
	v_pk_mul_f32 v[32:33], v[24:25], v[32:33] op_sel_hi:[1,0]
	v_exp_f32_e32 v36, v36
	v_exp_f32_e32 v37, v37
	v_exp_f32_e32 v32, v32
	v_exp_f32_e32 v34, v34
	v_exp_f32_e32 v35, v35
	v_exp_f32_e32 v38, v38
	v_exp_f32_e32 v39, v39
	v_exp_f32_e32 v33, v33
	v_pk_add_f32 v[36:37], v[36:37], 1.0 op_sel_hi:[1,0]
	v_pk_add_f32 v[34:35], v[34:35], 1.0 op_sel_hi:[1,0]
	v_pk_add_f32 v[38:39], v[38:39], 1.0 op_sel_hi:[1,0]
	v_pk_add_f32 v[32:33], v[32:33], 1.0 op_sel_hi:[1,0]
	v_rcp_f32_e32 v36, v36
	v_rcp_f32_e32 v37, v37
	v_rcp_f32_e32 v32, v32
	v_rcp_f32_e32 v33, v33
	v_rcp_f32_e32 v34, v34
	v_rcp_f32_e32 v38, v38
	v_rcp_f32_e32 v35, v35
	v_rcp_f32_e32 v39, v39
	v_pk_mul_f32 v[22:23], v[22:23], v[40:41] op_sel_hi:[1,0]
	v_pk_mul_f32 v[20:21], v[20:21], v[36:37]
	v_pk_mul_f32 v[16:17], v[16:17], v[40:41] op_sel_hi:[1,0]
	v_pk_mul_f32 v[18:19], v[18:19], v[40:41] op_sel_hi:[1,0]
	v_pk_mul_f32 v[22:23], v[22:23], v[34:35]
	v_pk_mul_f32 v[24:25], v[18:19], v[38:39]
	v_pk_mul_f32 v[18:19], v[16:17], v[32:33]
	v_cvt_pk_bf16_f32 v16, v20, v21
	v_mad_i64_i32 v[20:21], s[8:9], v66, s3, v[112:113]
	v_cvt_pk_bf16_f32 v17, v22, v23
	v_cvt_pk_bf16_f32 v18, v18, v19
	v_cvt_pk_bf16_f32 v19, v24, v25
	v_lshl_add_u64 v[20:21], v[20:21], 0, v[114:115]
	global_store_dwordx4 v[20:21], v[16:19], off
	v_mul_f32_e32 v24, v78, v78
	v_pk_mul_f32 v[4:5], v[4:5], v[24:25] op_sel_hi:[1,0]
	v_mul_f32_e32 v16, 0xbfb8aa3b, v78
	v_pk_mul_f32 v[20:21], v[12:13], v[16:17] op_sel_hi:[1,0]
	v_pk_mul_f32 v[18:19], v[14:15], v[16:17] op_sel_hi:[1,0]
	v_pk_mul_f32 v[22:23], v[10:11], v[16:17] op_sel_hi:[1,0]
	v_pk_mul_f32 v[16:17], v[8:9], v[16:17] op_sel_hi:[1,0]
	v_exp_f32_e32 v20, v20
	v_exp_f32_e32 v21, v21
	v_exp_f32_e32 v16, v16
	v_exp_f32_e32 v18, v18
	v_exp_f32_e32 v19, v19
	v_exp_f32_e32 v22, v22
	v_exp_f32_e32 v23, v23
	v_exp_f32_e32 v17, v17
	v_pk_add_f32 v[20:21], v[20:21], 1.0 op_sel_hi:[1,0]
	v_pk_add_f32 v[18:19], v[18:19], 1.0 op_sel_hi:[1,0]
	v_pk_add_f32 v[22:23], v[22:23], 1.0 op_sel_hi:[1,0]
	v_pk_add_f32 v[16:17], v[16:17], 1.0 op_sel_hi:[1,0]
	v_rcp_f32_e32 v20, v20
	v_rcp_f32_e32 v21, v21
	v_rcp_f32_e32 v16, v16
	v_rcp_f32_e32 v17, v17
	v_rcp_f32_e32 v18, v18
	v_rcp_f32_e32 v22, v22
	v_rcp_f32_e32 v19, v19
	v_rcp_f32_e32 v23, v23
	v_pk_mul_f32 v[6:7], v[6:7], v[24:25] op_sel_hi:[1,0]
	v_pk_mul_f32 v[4:5], v[4:5], v[20:21]
	v_pk_mul_f32 v[0:1], v[0:1], v[24:25] op_sel_hi:[1,0]
	v_pk_mul_f32 v[2:3], v[2:3], v[24:25] op_sel_hi:[1,0]
	v_pk_mul_f32 v[6:7], v[6:7], v[18:19]
	v_pk_mul_f32 v[8:9], v[2:3], v[22:23]
	v_pk_mul_f32 v[2:3], v[0:1], v[16:17]
	v_cvt_pk_bf16_f32 v0, v4, v5
	v_mad_i64_i32 v[4:5], s[8:9], v64, s3, v[112:113]
	v_cvt_pk_bf16_f32 v1, v6, v7
	v_cvt_pk_bf16_f32 v2, v2, v3
	v_cvt_pk_bf16_f32 v3, v8, v9
	v_lshl_add_u64 v[4:5], v[4:5], 0, v[114:115]
	global_store_dwordx4 v[4:5], v[0:3], off
	s_cbranch_vccnz .LBB0_152
	s_andn2_b64 vcc, exec, s[10:11]
	s_cbranch_vccnz .LBB0_151
	s_barrier
	s_branch .LBB0_151

; __device__ __forceinline__ float silu_f(float x) { return x * __builtin_amdgcn_rcpf(1.f + __expf(-x)); }
; __device__ __forceinline__ v4u pack8(const f32x4 a, const f32x4 b) { v4u w; w.x = cvt_pk_bf16(a[0], a[1]); w.y = cvt_pk_bf16(a[2], a[3]); w.z = cvt_pk_bf16(b[0], b[1]); w.w = cvt_pk_bf16(b[2], b[3]); return w; }
; __device__ __forceinline__ float row_rstd(const float* ssq, int row, int fq) {
;     const f32x4 v = *(const f32x4*)(ssq + (size_t)row * 16 + fq * 4);
;     float s = (v[0] + v[1]) + (v[2] + v[3]);
;     s += __shfl_xor(s, 16); s += __shfl_xor(s, 32);
;     return __builtin_amdgcn_rsqf(s * (1.f / DM) + EPS);
; }
;     __device__ __forceinline__ void operator()(const f32x4 (&acc)[2][2][4][2], const pg8::Unit& u, int wr, int wc, int fr, int fq) const {
;     ...
;         const int grp = pn >> 1, cb = (pn & 1) * 256 + cw;
;     ...
;         if (grp == 0) { WIN_LOOP( _Pragma("unroll") for (int i = 0; i < 4; ++i) { a[i] = silu_f(a[i]); b[i] = silu_f(b[i]); } *(v4u*)(QO + (size_t)row * DM + c) = pack8(a, b); ) }
;         else if (grp == 3) { WIN_LOOP( _Pragma("unroll") for (int i = 0; i < 4; ++i) { a[i] = silu_f(a[i]); b[i] = silu_f(b[i]); } *(v4u*)(GH + (size_t)row * 512 + c) = pack8(a, b); ) }
;         else if (grp == 1) {
.LBB0_394:
	v_mov_b32_e32 v128, v166
	v_ashrrev_i32_e32 v129, 31, v128
	v_lshlrev_b64 v[128:129], 6, v[128:129]
	v_lshl_add_u64 v[128:129], v[160:161], 0, v[128:129]
	global_load_dwordx4 v[128:131], v[128:129], off
	v_add_u32_e32 v132, 16, v166
	v_ashrrev_i32_e32 v133, 31, v132
	v_lshlrev_b64 v[132:133], 6, v[132:133]
	v_lshl_add_u64 v[132:133], v[160:161], 0, v[132:133]
	global_load_dwordx4 v[132:135], v[132:133], off
	v_add_u32_e32 v136, 32, v166
	v_ashrrev_i32_e32 v137, 31, v136
	v_lshlrev_b64 v[136:137], 6, v[136:137]
	v_lshl_add_u64 v[136:137], v[160:161], 0, v[136:137]
	global_load_dwordx4 v[136:139], v[136:137], off
	v_add_u32_e32 v140, 48, v166
	v_ashrrev_i32_e32 v141, 31, v140
	v_lshlrev_b64 v[140:141], 6, v[140:141]
	v_lshl_add_u64 v[140:141], v[160:161], 0, v[140:141]
	global_load_dwordx4 v[140:143], v[140:141], off
	v_add_u32_e32 v144, 0x80, v166
	v_ashrrev_i32_e32 v145, 31, v144
	v_lshlrev_b64 v[144:145], 6, v[144:145]
	v_lshl_add_u64 v[144:145], v[160:161], 0, v[144:145]
	global_load_dwordx4 v[144:147], v[144:145], off
	v_add_u32_e32 v148, 0x90, v166
	v_ashrrev_i32_e32 v149, 31, v148
	v_lshlrev_b64 v[148:149], 6, v[148:149]
	v_lshl_add_u64 v[148:149], v[160:161], 0, v[148:149]
	global_load_dwordx4 v[148:151], v[148:149], off
	v_add_u32_e32 v236, 0xa0, v166
	v_ashrrev_i32_e32 v237, 31, v236
	v_lshlrev_b64 v[236:237], 6, v[236:237]
	v_lshl_add_u64 v[236:237], v[160:161], 0, v[236:237]
	global_load_dwordx4 v[236:239], v[236:237], off
	v_add_u32_e32 v246, 0xb0, v166
	v_ashrrev_i32_e32 v247, 31, v246
	v_lshlrev_b64 v[246:247], 6, v[246:247]
	v_lshl_add_u64 v[246:247], v[160:161], 0, v[246:247]
	global_load_dwordx4 v[246:249], v[246:247], off
	s_waitcnt vmcnt(0)
	v_add_f32_e32 v128, v128, v129
	v_add_f32_e32 v130, v130, v131
	v_add_f32_e32 v132, v132, v133
	v_add_f32_e32 v134, v134, v135
	v_add_f32_e32 v136, v136, v137
	v_add_f32_e32 v138, v138, v139
	v_add_f32_e32 v140, v140, v141
	v_add_f32_e32 v142, v142, v143
	v_add_f32_e32 v144, v144, v145
	v_add_f32_e32 v146, v146, v147
	v_add_f32_e32 v148, v148, v149
	v_add_f32_e32 v150, v150, v151
	v_add_f32_e32 v236, v236, v237
	v_add_f32_e32 v238, v238, v239
	v_add_f32_e32 v246, v246, v247
	v_add_f32_e32 v248, v248, v249
	v_add_f32_e32 v128, v128, v130
	v_add_f32_e32 v132, v132, v134
	v_add_f32_e32 v136, v136, v138
	v_add_f32_e32 v140, v140, v142
	v_add_f32_e32 v144, v144, v146
	v_add_f32_e32 v148, v148, v150
	v_add_f32_e32 v236, v236, v238
	v_add_f32_e32 v246, v246, v248
	v_xor_b32_e32 v130, 16, v215
	v_xor_b32_e32 v131, 32, v215
	v_lshlrev_b32_e32 v130, 2, v130
	v_lshlrev_b32_e32 v131, 2, v131
	ds_bpermute_b32 v129, v130, v128
	ds_bpermute_b32 v133, v130, v132
	ds_bpermute_b32 v137, v130, v136
	ds_bpermute_b32 v141, v130, v140
	ds_bpermute_b32 v145, v130, v144
	ds_bpermute_b32 v149, v130, v148
	ds_bpermute_b32 v237, v130, v236
	ds_bpermute_b32 v247, v130, v246
	s_waitcnt lgkmcnt(0)
	v_add_f32_e32 v128, v128, v129
	v_add_f32_e32 v132, v132, v133
	v_add_f32_e32 v136, v136, v137
	v_add_f32_e32 v140, v140, v141
	v_add_f32_e32 v144, v144, v145
	v_add_f32_e32 v148, v148, v149
	v_add_f32_e32 v236, v236, v237
	v_add_f32_e32 v246, v246, v247
	ds_bpermute_b32 v129, v131, v128
	ds_bpermute_b32 v133, v131, v132
	ds_bpermute_b32 v137, v131, v136
	ds_bpermute_b32 v141, v131, v140
	ds_bpermute_b32 v145, v131, v144
	ds_bpermute_b32 v149, v131, v148
	ds_bpermute_b32 v237, v131, v236
	ds_bpermute_b32 v247, v131, v246
	s_waitcnt lgkmcnt(0)
	v_add_f32_e32 v128, v128, v129
	v_add_f32_e32 v132, v132, v133
	v_add_f32_e32 v136, v136, v137
	v_add_f32_e32 v140, v140, v141
	v_add_f32_e32 v144, v144, v145
	v_add_f32_e32 v148, v148, v149
	v_add_f32_e32 v236, v236, v237
	v_add_f32_e32 v246, v246, v247
	v_fmamk_f32 v128, v128, 0x3a800000, v212
	v_fmamk_f32 v132, v132, 0x3a800000, v212
	v_fmamk_f32 v136, v136, 0x3a800000, v212
	v_fmamk_f32 v140, v140, 0x3a800000, v212
	v_fmamk_f32 v144, v144, 0x3a800000, v212
	v_fmamk_f32 v148, v148, 0x3a800000, v212
	v_fmamk_f32 v236, v236, 0x3a800000, v212
	v_fmamk_f32 v246, v246, 0x3a800000, v212
	v_rsq_f32_e32 v250, v128
	v_rsq_f32_e32 v251, v132
	v_rsq_f32_e32 v252, v136
	v_rsq_f32_e32 v253, v140
	v_rsq_f32_e32 v254, v144
	v_rsq_f32_e32 v240, v148
	v_rsq_f32_e32 v241, v236
	v_rsq_f32_e32 v245, v246
	s_nop 0
	s_lshl_b32 s8, s2, 8
	s_and_b32 s8, s8, 0x100
	v_or_b32_e32 v176, s8, v174
	s_cmp_gt_u32 s2, 1
	s_mov_b64 s[8:9], -1
	s_cbranch_scc0 .LBB0_417
	s_ashr_i32 s14, s2, 1
	s_mov_b64 s[12:13], -1
	s_mov_b64 s[8:9], 0
	s_cmp_lt_i32 s14, 3
	s_mov_b64 s[10:11], 0
	s_cbranch_scc1 .LBB0_407
	s_cmp_gt_i32 s14, 3
	s_cbranch_scc0 .LBB0_404
	s_cmp_gt_i32 s14, 4
	s_cbranch_scc0 .LBB0_401
	s_cmp_eq_u32 s14, 5
	s_mov_b64 s[10:11], -1
	s_cbranch_scc0 .LBB0_400
; __device__ __forceinline__ v4u pack8(const f32x4 a, const f32x4 b) { v4u w; w.x = cvt_pk_bf16(a[0], a[1]); w.y = cvt_pk_bf16(a[2], a[3]); w.z = cvt_pk_bf16(b[0], b[1]); w.w = cvt_pk_bf16(b[2], b[3]); return w; }
;     __device__ __forceinline__ void operator()(const f32x4 (&acc)[2][2][4][2], const pg8::Unit& u, int wr, int wc, int fr, int fq) const {
;     ...
;         else if (grp == 5) { WIN_LOOP( *(v4u*)(FK + (size_t)row * 512 + c) = pack8(a, b); ) }
	v_and_b32_e32 v129, 64, v215
	v_xor_b32_e32 v128, 16, v215
	v_add_u32_e32 v129, 64, v129
	v_cmp_lt_i32_e32 vcc, v128, v129
	v_ashrrev_i32_e32 v167, 31, v166
	v_readlane_b32 s10, v255, 41
	v_cndmask_b32_e32 v128, v215, v128, vcc
	v_lshlrev_b32_e32 v130, 2, v128
	v_xor_b32_e32 v128, 32, v215
	v_cmp_lt_i32_e32 vcc, v128, v129
	v_readlane_b32 s11, v255, 42
	v_lshlrev_b32_e32 v192, 1, v176
	v_cndmask_b32_e32 v128, v215, v128, vcc
	v_lshlrev_b32_e32 v131, 2, v128
	v_lshlrev_b64 v[128:129], 6, v[166:167]
	v_lshl_add_u64 v[128:129], v[160:161], 0, v[128:129]
	s_nop 0
	s_waitcnt lgkmcnt(0)
	s_nop 3
	v_lshlrev_b64 v[132:133], 10, v[166:167]
	s_nop 1
	v_lshl_add_u64 v[136:137], s[10:11], 0, v[132:133]
	v_lshl_add_u64 v[136:137], v[136:137], 0, v[192:193]
	s_waitcnt lgkmcnt(0)
	s_nop 1
	s_waitcnt lgkmcnt(0)
	s_nop 1
	v_mov_b32_e32 v128, v250
	s_nop 0
	v_pk_mul_f32 v[134:135], v[62:63], v[128:129] op_sel_hi:[1,0]
	v_pk_mul_f32 v[132:133], v[60:61], v[128:129] op_sel_hi:[1,0]
	v_pk_mul_f32 v[138:139], v[58:59], v[128:129] op_sel_hi:[1,0]
	v_pk_mul_f32 v[140:141], v[56:57], v[128:129] op_sel_hi:[1,0]
	v_cvt_pk_bf16_f32 v132, v132, v133
	v_cvt_pk_bf16_f32 v133, v134, v135
	v_cvt_pk_bf16_f32 v134, v140, v141
	v_cvt_pk_bf16_f32 v135, v138, v139
	global_store_dwordx4 v[136:137], v[132:135], off
	v_pk_mul_f32 v[138:139], v[122:123], v[128:129] op_sel_hi:[1,0]
	s_nop 0
	v_pk_mul_f32 v[134:135], v[126:127], v[128:129] op_sel_hi:[1,0]
	v_pk_mul_f32 v[132:133], v[124:125], v[128:129] op_sel_hi:[1,0]
	v_pk_mul_f32 v[128:129], v[120:121], v[128:129] op_sel_hi:[1,0]
	v_cvt_pk_bf16_f32 v132, v132, v133
	v_cvt_pk_bf16_f32 v133, v134, v135
	v_cvt_pk_bf16_f32 v134, v128, v129
	v_or_b32_e32 v128, 16, v166
	v_cvt_pk_bf16_f32 v135, v138, v139
	v_ashrrev_i32_e32 v129, 31, v128
	global_store_dwordx4 v[136:137], v[132:135], off offset:256
	s_nop 1
	v_lshlrev_b64 v[132:133], 6, v[128:129]
	v_lshl_add_u64 v[132:133], v[160:161], 0, v[132:133]
	s_nop 0
	v_lshlrev_b64 v[128:129], 10, v[128:129]
	v_lshl_add_u64 v[128:129], s[10:11], 0, v[128:129]
	v_lshl_add_u64 v[128:129], v[128:129], 0, v[192:193]
	s_waitcnt lgkmcnt(0)
	s_nop 3
	s_nop 0
	s_nop 1
	s_waitcnt lgkmcnt(0)
	s_nop 1
	s_waitcnt lgkmcnt(0)
	s_nop 1
	v_mov_b32_e32 v136, v251
	s_nop 0
	v_pk_mul_f32 v[134:135], v[54:55], v[136:137] op_sel_hi:[1,0]
	v_pk_mul_f32 v[132:133], v[52:53], v[136:137] op_sel_hi:[1,0]
	v_pk_mul_f32 v[138:139], v[50:51], v[136:137] op_sel_hi:[1,0]
	v_pk_mul_f32 v[140:141], v[48:49], v[136:137] op_sel_hi:[1,0]
	v_cvt_pk_bf16_f32 v132, v132, v133
	v_cvt_pk_bf16_f32 v133, v134, v135
	v_cvt_pk_bf16_f32 v134, v140, v141
	v_cvt_pk_bf16_f32 v135, v138, v139
	global_store_dwordx4 v[128:129], v[132:135], off
	v_pk_mul_f32 v[138:139], v[114:115], v[136:137] op_sel_hi:[1,0]
	s_nop 0
	v_pk_mul_f32 v[134:135], v[118:119], v[136:137] op_sel_hi:[1,0]
	v_pk_mul_f32 v[132:133], v[116:117], v[136:137] op_sel_hi:[1,0]
	v_pk_mul_f32 v[136:137], v[112:113], v[136:137] op_sel_hi:[1,0]
	v_cvt_pk_bf16_f32 v132, v132, v133
	v_cvt_pk_bf16_f32 v133, v134, v135
	v_cvt_pk_bf16_f32 v134, v136, v137
	v_cvt_pk_bf16_f32 v135, v138, v139
	global_store_dwordx4 v[128:129], v[132:135], off offset:256
	v_or_b32_e32 v128, 32, v166
	v_ashrrev_i32_e32 v129, 31, v128
	v_lshlrev_b64 v[132:133], 6, v[128:129]
	v_lshl_add_u64 v[132:133], v[160:161], 0, v[132:133]
	s_nop 0
	v_lshlrev_b64 v[128:129], 10, v[128:129]
	v_lshl_add_u64 v[128:129], s[10:11], 0, v[128:129]
	v_lshl_add_u64 v[128:129], v[128:129], 0, v[192:193]
	s_waitcnt lgkmcnt(0)
	s_nop 3
	s_nop 0
	s_nop 1
	s_waitcnt lgkmcnt(0)
	s_nop 1
	s_waitcnt lgkmcnt(0)
	s_nop 1
	v_mov_b32_e32 v136, v252
	s_nop 0
	v_pk_mul_f32 v[134:135], v[46:47], v[136:137] op_sel_hi:[1,0]
	v_pk_mul_f32 v[132:133], v[44:45], v[136:137] op_sel_hi:[1,0]
	v_pk_mul_f32 v[138:139], v[42:43], v[136:137] op_sel_hi:[1,0]
	v_pk_mul_f32 v[140:141], v[40:41], v[136:137] op_sel_hi:[1,0]
	v_cvt_pk_bf16_f32 v132, v132, v133
	v_cvt_pk_bf16_f32 v133, v134, v135
	v_cvt_pk_bf16_f32 v134, v140, v141
	v_cvt_pk_bf16_f32 v135, v138, v139
	global_store_dwordx4 v[128:129], v[132:135], off
	v_pk_mul_f32 v[138:139], v[106:107], v[136:137] op_sel_hi:[1,0]
	s_nop 0
	v_pk_mul_f32 v[134:135], v[110:111], v[136:137] op_sel_hi:[1,0]
	v_pk_mul_f32 v[132:133], v[108:109], v[136:137] op_sel_hi:[1,0]
	v_pk_mul_f32 v[136:137], v[104:105], v[136:137] op_sel_hi:[1,0]
	v_cvt_pk_bf16_f32 v132, v132, v133
	v_cvt_pk_bf16_f32 v133, v134, v135
	v_cvt_pk_bf16_f32 v134, v136, v137
	v_cvt_pk_bf16_f32 v135, v138, v139
	global_store_dwordx4 v[128:129], v[132:135], off offset:256
	v_or_b32_e32 v128, 48, v166
	v_ashrrev_i32_e32 v129, 31, v128
	v_lshlrev_b64 v[132:133], 6, v[128:129]
	v_lshl_add_u64 v[132:133], v[160:161], 0, v[132:133]
	s_nop 0
	v_lshlrev_b64 v[128:129], 10, v[128:129]
	v_lshl_add_u64 v[128:129], s[10:11], 0, v[128:129]
	v_lshl_add_u64 v[128:129], v[128:129], 0, v[192:193]
	s_waitcnt lgkmcnt(0)
	s_nop 3
	s_nop 0
	s_nop 1
	s_waitcnt lgkmcnt(0)
	s_nop 1
	s_waitcnt lgkmcnt(0)
	s_nop 1
	v_mov_b32_e32 v136, v253
	s_nop 0
	v_pk_mul_f32 v[134:135], v[38:39], v[136:137] op_sel_hi:[1,0]
	v_pk_mul_f32 v[132:133], v[36:37], v[136:137] op_sel_hi:[1,0]
	v_pk_mul_f32 v[138:139], v[34:35], v[136:137] op_sel_hi:[1,0]
	v_pk_mul_f32 v[140:141], v[32:33], v[136:137] op_sel_hi:[1,0]
	v_cvt_pk_bf16_f32 v132, v132, v133
	v_cvt_pk_bf16_f32 v133, v134, v135
	v_cvt_pk_bf16_f32 v134, v140, v141
	v_cvt_pk_bf16_f32 v135, v138, v139
	global_store_dwordx4 v[128:129], v[132:135], off
	v_pk_mul_f32 v[138:139], v[98:99], v[136:137] op_sel_hi:[1,0]
	s_nop 0
	v_pk_mul_f32 v[134:135], v[102:103], v[136:137] op_sel_hi:[1,0]
	v_pk_mul_f32 v[132:133], v[100:101], v[136:137] op_sel_hi:[1,0]
	v_pk_mul_f32 v[136:137], v[96:97], v[136:137] op_sel_hi:[1,0]
	v_cvt_pk_bf16_f32 v132, v132, v133
	v_cvt_pk_bf16_f32 v133, v134, v135
	v_cvt_pk_bf16_f32 v134, v136, v137
	v_cvt_pk_bf16_f32 v135, v138, v139
	global_store_dwordx4 v[128:129], v[132:135], off offset:256
	v_add_u32_e32 v128, 0x80, v166
	v_ashrrev_i32_e32 v129, 31, v128
	v_lshlrev_b64 v[132:133], 6, v[128:129]
	v_lshl_add_u64 v[132:133], v[160:161], 0, v[132:133]
	s_nop 0
	v_lshlrev_b64 v[128:129], 10, v[128:129]
	v_lshl_add_u64 v[128:129], s[10:11], 0, v[128:129]
	v_lshl_add_u64 v[128:129], v[128:129], 0, v[192:193]
	s_waitcnt lgkmcnt(0)
; __device__ __forceinline__ v4u pack8(const f32x4 a, const f32x4 b) { v4u w; w.x = cvt_pk_bf16(a[0], a[1]); w.y = cvt_pk_bf16(a[2], a[3]); w.z = cvt_pk_bf16(b[0], b[1]); w.w = cvt_pk_bf16(b[2], b[3]); return w; }
;     __device__ __forceinline__ void operator()(const f32x4 (&acc)[2][2][4][2], const pg8::Unit& u, int wr, int wc, int fr, int fq) const {
;     ...
;         else if (grp == 5) { WIN_LOOP( *(v4u*)(FK + (size_t)row * 512 + c) = pack8(a, b); ) }
	s_nop 3
	s_nop 0
	s_nop 1
	s_waitcnt lgkmcnt(0)
	s_nop 1
	s_waitcnt lgkmcnt(0)
	s_nop 1
	v_mov_b32_e32 v136, v254
	s_nop 0
	v_pk_mul_f32 v[134:135], v[30:31], v[136:137] op_sel_hi:[1,0]
	v_pk_mul_f32 v[132:133], v[28:29], v[136:137] op_sel_hi:[1,0]
	v_pk_mul_f32 v[138:139], v[26:27], v[136:137] op_sel_hi:[1,0]
	v_pk_mul_f32 v[140:141], v[24:25], v[136:137] op_sel_hi:[1,0]
	v_cvt_pk_bf16_f32 v132, v132, v133
	v_cvt_pk_bf16_f32 v133, v134, v135
	v_cvt_pk_bf16_f32 v134, v140, v141
	v_cvt_pk_bf16_f32 v135, v138, v139
	global_store_dwordx4 v[128:129], v[132:135], off
	v_pk_mul_f32 v[138:139], v[90:91], v[136:137] op_sel_hi:[1,0]
	s_nop 0
	v_pk_mul_f32 v[134:135], v[94:95], v[136:137] op_sel_hi:[1,0]
	v_pk_mul_f32 v[132:133], v[92:93], v[136:137] op_sel_hi:[1,0]
	v_pk_mul_f32 v[136:137], v[88:89], v[136:137] op_sel_hi:[1,0]
	v_cvt_pk_bf16_f32 v132, v132, v133
	v_cvt_pk_bf16_f32 v133, v134, v135
	v_cvt_pk_bf16_f32 v134, v136, v137
	v_cvt_pk_bf16_f32 v135, v138, v139
	global_store_dwordx4 v[128:129], v[132:135], off offset:256
	v_add_u32_e32 v128, 0x90, v166
	v_ashrrev_i32_e32 v129, 31, v128
	v_lshlrev_b64 v[132:133], 6, v[128:129]
	v_lshl_add_u64 v[132:133], v[160:161], 0, v[132:133]
	s_nop 0
	v_lshlrev_b64 v[128:129], 10, v[128:129]
	v_lshl_add_u64 v[128:129], s[10:11], 0, v[128:129]
	v_lshl_add_u64 v[128:129], v[128:129], 0, v[192:193]
	s_waitcnt lgkmcnt(0)
	s_nop 3
	s_nop 0
	s_nop 1
	s_waitcnt lgkmcnt(0)
	s_nop 1
	s_waitcnt lgkmcnt(0)
	s_nop 1
	v_mov_b32_e32 v136, v240
	s_nop 0
	v_pk_mul_f32 v[134:135], v[22:23], v[136:137] op_sel_hi:[1,0]
	v_pk_mul_f32 v[132:133], v[20:21], v[136:137] op_sel_hi:[1,0]
	v_pk_mul_f32 v[138:139], v[18:19], v[136:137] op_sel_hi:[1,0]
	v_pk_mul_f32 v[140:141], v[16:17], v[136:137] op_sel_hi:[1,0]
	v_cvt_pk_bf16_f32 v132, v132, v133
	v_cvt_pk_bf16_f32 v133, v134, v135
	v_cvt_pk_bf16_f32 v134, v140, v141
	v_cvt_pk_bf16_f32 v135, v138, v139
	global_store_dwordx4 v[128:129], v[132:135], off
	v_pk_mul_f32 v[138:139], v[82:83], v[136:137] op_sel_hi:[1,0]
	s_nop 0
	v_pk_mul_f32 v[134:135], v[86:87], v[136:137] op_sel_hi:[1,0]
	v_pk_mul_f32 v[132:133], v[84:85], v[136:137] op_sel_hi:[1,0]
	v_pk_mul_f32 v[136:137], v[80:81], v[136:137] op_sel_hi:[1,0]
	v_cvt_pk_bf16_f32 v132, v132, v133
	v_cvt_pk_bf16_f32 v133, v134, v135
	v_cvt_pk_bf16_f32 v134, v136, v137
	v_cvt_pk_bf16_f32 v135, v138, v139
	global_store_dwordx4 v[128:129], v[132:135], off offset:256
	v_add_u32_e32 v128, 0xa0, v166
	v_ashrrev_i32_e32 v129, 31, v128
	v_lshlrev_b64 v[132:133], 6, v[128:129]
	v_lshl_add_u64 v[132:133], v[160:161], 0, v[132:133]
	s_nop 0
	v_lshlrev_b64 v[128:129], 10, v[128:129]
	v_lshl_add_u64 v[128:129], s[10:11], 0, v[128:129]
	v_lshl_add_u64 v[128:129], v[128:129], 0, v[192:193]
	s_waitcnt lgkmcnt(0)
	s_nop 3
	s_nop 0
	s_nop 1
	s_waitcnt lgkmcnt(0)
	s_nop 1
	s_waitcnt lgkmcnt(0)
	s_nop 1
	v_mov_b32_e32 v136, v241
	s_nop 0
	v_pk_mul_f32 v[134:135], v[14:15], v[136:137] op_sel_hi:[1,0]
	v_pk_mul_f32 v[132:133], v[12:13], v[136:137] op_sel_hi:[1,0]
	v_pk_mul_f32 v[138:139], v[10:11], v[136:137] op_sel_hi:[1,0]
	v_pk_mul_f32 v[140:141], v[8:9], v[136:137] op_sel_hi:[1,0]
	v_cvt_pk_bf16_f32 v132, v132, v133
	v_cvt_pk_bf16_f32 v133, v134, v135
	v_cvt_pk_bf16_f32 v134, v140, v141
	v_cvt_pk_bf16_f32 v135, v138, v139
	global_store_dwordx4 v[128:129], v[132:135], off
	v_pk_mul_f32 v[138:139], v[74:75], v[136:137] op_sel_hi:[1,0]
	s_nop 0
	v_pk_mul_f32 v[134:135], v[78:79], v[136:137] op_sel_hi:[1,0]
	v_pk_mul_f32 v[132:133], v[76:77], v[136:137] op_sel_hi:[1,0]
	v_pk_mul_f32 v[136:137], v[72:73], v[136:137] op_sel_hi:[1,0]
	v_cvt_pk_bf16_f32 v132, v132, v133
	v_cvt_pk_bf16_f32 v133, v134, v135
	v_cvt_pk_bf16_f32 v134, v136, v137
	v_cvt_pk_bf16_f32 v135, v138, v139
	global_store_dwordx4 v[128:129], v[132:135], off offset:256
	v_add_u32_e32 v128, 0xb0, v166
	v_ashrrev_i32_e32 v129, 31, v128
	v_lshlrev_b64 v[132:133], 6, v[128:129]
	v_lshl_add_u64 v[132:133], v[160:161], 0, v[132:133]
	s_nop 0
	v_lshlrev_b64 v[128:129], 10, v[128:129]
	s_waitcnt lgkmcnt(0)
	s_nop 3
	v_lshl_add_u64 v[134:135], s[10:11], 0, v[128:129]
	s_nop 1
	v_lshl_add_u64 v[134:135], v[134:135], 0, v[192:193]
	s_mov_b64 s[10:11], 0
	s_waitcnt lgkmcnt(0)
	s_nop 1
	s_waitcnt lgkmcnt(0)
	s_nop 1
	v_mov_b32_e32 v132, v245
	s_nop 0
	v_pk_mul_f32 v[130:131], v[6:7], v[132:133] op_sel_hi:[1,0]
	v_pk_mul_f32 v[128:129], v[4:5], v[132:133] op_sel_hi:[1,0]
	v_pk_mul_f32 v[136:137], v[2:3], v[132:133] op_sel_hi:[1,0]
	v_pk_mul_f32 v[138:139], v[0:1], v[132:133] op_sel_hi:[1,0]
	v_cvt_pk_bf16_f32 v128, v128, v129
	v_cvt_pk_bf16_f32 v129, v130, v131
	v_cvt_pk_bf16_f32 v130, v138, v139
	v_cvt_pk_bf16_f32 v131, v136, v137
	global_store_dwordx4 v[134:135], v[128:131], off
	v_pk_mul_f32 v[136:137], v[66:67], v[132:133] op_sel_hi:[1,0]
	s_nop 0
	v_pk_mul_f32 v[130:131], v[70:71], v[132:133] op_sel_hi:[1,0]
	v_pk_mul_f32 v[128:129], v[68:69], v[132:133] op_sel_hi:[1,0]
	v_pk_mul_f32 v[132:133], v[64:65], v[132:133] op_sel_hi:[1,0]
	v_cvt_pk_bf16_f32 v128, v128, v129
	v_cvt_pk_bf16_f32 v129, v130, v131
	v_cvt_pk_bf16_f32 v130, v132, v133
	v_cvt_pk_bf16_f32 v131, v136, v137
	global_store_dwordx4 v[134:135], v[128:131], off offset:256

; __device__ __forceinline__ v4u pack8(const f32x4 a, const f32x4 b) { v4u w; w.x = cvt_pk_bf16(a[0], a[1]); w.y = cvt_pk_bf16(a[2], a[3]); w.z = cvt_pk_bf16(b[0], b[1]); w.w = cvt_pk_bf16(b[2], b[3]); return w; }
;     __device__ __forceinline__ void operator()(const f32x4 (&acc)[2][2][4][2], const pg8::Unit& u, int wr, int wc, int fr, int fq) const {
;     ...
;         else if (grp == 4) { WIN_LOOP( *(v4u*)(QO + (size_t)row * DM + 512 + c) = pack8(a * C2Q, b * C2Q); ) }
.LBB0_401:
	s_and_b64 vcc, exec, s[12:13]
	s_cbranch_vccz .LBB0_403
	v_and_b32_e32 v129, 64, v215
	v_xor_b32_e32 v128, 16, v215
	v_add_u32_e32 v129, 64, v129
	v_cmp_lt_i32_e32 vcc, v128, v129
	v_ashrrev_i32_e32 v167, 31, v166
	s_mov_b32 s2, 0x3e38aa3b
	v_cndmask_b32_e32 v128, v215, v128, vcc
	v_lshlrev_b32_e32 v132, 2, v128
	v_xor_b32_e32 v128, 32, v215
	v_cmp_lt_i32_e32 vcc, v128, v129
	v_lshlrev_b32_e32 v192, 1, v176
	s_nop 0
	v_cndmask_b32_e32 v128, v215, v128, vcc
	v_lshlrev_b32_e32 v133, 2, v128
	v_lshlrev_b64 v[128:129], 6, v[166:167]
	v_lshl_add_u64 v[128:129], v[160:161], 0, v[128:129]
	s_nop 0
	s_waitcnt lgkmcnt(0)
	s_nop 3
	s_nop 0
	s_nop 1
	s_waitcnt lgkmcnt(0)
	s_nop 1
	s_waitcnt lgkmcnt(0)
	s_nop 1
	v_mov_b32_e32 v134, v250
	v_lshlrev_b64 v[128:129], 11, v[166:167]
	v_lshl_add_u64 v[136:137], s[44:45], 0, v[128:129]
	v_lshl_add_u64 v[136:137], v[136:137], 0, v[192:193]
	v_pk_mul_f32 v[128:129], v[60:61], v[134:135] op_sel_hi:[1,0]
	v_pk_mul_f32 v[130:131], v[62:63], v[134:135] op_sel_hi:[1,0]
	v_pk_mul_f32 v[138:139], v[56:57], v[134:135] op_sel_hi:[1,0]
	v_pk_mul_f32 v[140:141], v[58:59], v[134:135] op_sel_hi:[1,0]
	v_pk_mul_f32 v[130:131], v[130:131], s[2:3] op_sel_hi:[1,0]
	v_pk_mul_f32 v[128:129], v[128:129], s[2:3] op_sel_hi:[1,0]
	v_pk_mul_f32 v[140:141], v[140:141], s[2:3] op_sel_hi:[1,0]
	v_pk_mul_f32 v[138:139], v[138:139], s[2:3] op_sel_hi:[1,0]
	v_cvt_pk_bf16_f32 v128, v128, v129
	v_cvt_pk_bf16_f32 v129, v130, v131
	v_cvt_pk_bf16_f32 v130, v138, v139
	v_cvt_pk_bf16_f32 v131, v140, v141
	global_store_dwordx4 v[136:137], v[128:131], off offset:1024
	v_pk_mul_f32 v[138:139], v[120:121], v[134:135] op_sel_hi:[1,0]
	s_nop 0
	v_pk_mul_f32 v[128:129], v[124:125], v[134:135] op_sel_hi:[1,0]
	v_pk_mul_f32 v[130:131], v[126:127], v[134:135] op_sel_hi:[1,0]
	v_pk_mul_f32 v[134:135], v[122:123], v[134:135] op_sel_hi:[1,0]
	v_pk_mul_f32 v[130:131], v[130:131], s[2:3] op_sel_hi:[1,0]
	v_pk_mul_f32 v[128:129], v[128:129], s[2:3] op_sel_hi:[1,0]
	v_pk_mul_f32 v[134:135], v[134:135], s[2:3] op_sel_hi:[1,0]
	v_pk_mul_f32 v[138:139], v[138:139], s[2:3] op_sel_hi:[1,0]
	v_cvt_pk_bf16_f32 v128, v128, v129
	v_cvt_pk_bf16_f32 v129, v130, v131
	v_cvt_pk_bf16_f32 v131, v134, v135
	v_or_b32_e32 v134, 16, v166
	v_cvt_pk_bf16_f32 v130, v138, v139
	v_ashrrev_i32_e32 v135, 31, v134
	global_store_dwordx4 v[136:137], v[128:131], off offset:1280
	s_nop 1
	v_lshlrev_b64 v[128:129], 6, v[134:135]
	v_lshl_add_u64 v[128:129], v[160:161], 0, v[128:129]
	s_nop 0
	s_waitcnt lgkmcnt(0)
	s_nop 3
	s_nop 0
	s_nop 1
	s_waitcnt lgkmcnt(0)
	s_nop 1
	s_waitcnt lgkmcnt(0)
	s_nop 1
	v_mov_b32_e32 v136, v251
	v_lshlrev_b64 v[128:129], 11, v[134:135]
	v_lshl_add_u64 v[134:135], s[44:45], 0, v[128:129]
	v_lshl_add_u64 v[134:135], v[134:135], 0, v[192:193]
	v_pk_mul_f32 v[128:129], v[52:53], v[136:137] op_sel_hi:[1,0]
	v_pk_mul_f32 v[130:131], v[54:55], v[136:137] op_sel_hi:[1,0]
	v_pk_mul_f32 v[138:139], v[48:49], v[136:137] op_sel_hi:[1,0]
	v_pk_mul_f32 v[140:141], v[50:51], v[136:137] op_sel_hi:[1,0]
	v_pk_mul_f32 v[130:131], v[130:131], s[2:3] op_sel_hi:[1,0]
	v_pk_mul_f32 v[128:129], v[128:129], s[2:3] op_sel_hi:[1,0]
	v_pk_mul_f32 v[140:141], v[140:141], s[2:3] op_sel_hi:[1,0]
	v_pk_mul_f32 v[138:139], v[138:139], s[2:3] op_sel_hi:[1,0]
	v_cvt_pk_bf16_f32 v128, v128, v129
	v_cvt_pk_bf16_f32 v129, v130, v131
	v_cvt_pk_bf16_f32 v130, v138, v139
	v_cvt_pk_bf16_f32 v131, v140, v141
	global_store_dwordx4 v[134:135], v[128:131], off offset:1024
	v_pk_mul_f32 v[138:139], v[112:113], v[136:137] op_sel_hi:[1,0]
	s_nop 0
	v_pk_mul_f32 v[128:129], v[116:117], v[136:137] op_sel_hi:[1,0]
	v_pk_mul_f32 v[130:131], v[118:119], v[136:137] op_sel_hi:[1,0]
	v_pk_mul_f32 v[136:137], v[114:115], v[136:137] op_sel_hi:[1,0]
	v_pk_mul_f32 v[130:131], v[130:131], s[2:3] op_sel_hi:[1,0]
	v_pk_mul_f32 v[128:129], v[128:129], s[2:3] op_sel_hi:[1,0]
	v_pk_mul_f32 v[136:137], v[136:137], s[2:3] op_sel_hi:[1,0]
	v_pk_mul_f32 v[138:139], v[138:139], s[2:3] op_sel_hi:[1,0]
	v_cvt_pk_bf16_f32 v128, v128, v129
	v_cvt_pk_bf16_f32 v129, v130, v131
	v_cvt_pk_bf16_f32 v130, v138, v139
	v_cvt_pk_bf16_f32 v131, v136, v137
	global_store_dwordx4 v[134:135], v[128:131], off offset:1280
	v_or_b32_e32 v134, 32, v166
	v_ashrrev_i32_e32 v135, 31, v134
	v_lshlrev_b64 v[128:129], 6, v[134:135]
	v_lshl_add_u64 v[128:129], v[160:161], 0, v[128:129]
	s_nop 0
	s_waitcnt lgkmcnt(0)
	s_nop 3
	s_nop 0
	s_nop 1
	s_waitcnt lgkmcnt(0)
	s_nop 1
	s_waitcnt lgkmcnt(0)
	s_nop 1
	v_mov_b32_e32 v136, v252
	v_lshlrev_b64 v[128:129], 11, v[134:135]
	v_lshl_add_u64 v[134:135], s[44:45], 0, v[128:129]
	v_lshl_add_u64 v[134:135], v[134:135], 0, v[192:193]
	v_pk_mul_f32 v[128:129], v[44:45], v[136:137] op_sel_hi:[1,0]
	v_pk_mul_f32 v[130:131], v[46:47], v[136:137] op_sel_hi:[1,0]
	v_pk_mul_f32 v[138:139], v[40:41], v[136:137] op_sel_hi:[1,0]
	v_pk_mul_f32 v[140:141], v[42:43], v[136:137] op_sel_hi:[1,0]
	v_pk_mul_f32 v[130:131], v[130:131], s[2:3] op_sel_hi:[1,0]
	v_pk_mul_f32 v[128:129], v[128:129], s[2:3] op_sel_hi:[1,0]
	v_pk_mul_f32 v[140:141], v[140:141], s[2:3] op_sel_hi:[1,0]
	v_pk_mul_f32 v[138:139], v[138:139], s[2:3] op_sel_hi:[1,0]
	v_cvt_pk_bf16_f32 v128, v128, v129
	v_cvt_pk_bf16_f32 v129, v130, v131
	v_cvt_pk_bf16_f32 v130, v138, v139
	v_cvt_pk_bf16_f32 v131, v140, v141
	global_store_dwordx4 v[134:135], v[128:131], off offset:1024
	v_pk_mul_f32 v[138:139], v[104:105], v[136:137] op_sel_hi:[1,0]
	s_nop 0
	v_pk_mul_f32 v[128:129], v[108:109], v[136:137] op_sel_hi:[1,0]
	v_pk_mul_f32 v[130:131], v[110:111], v[136:137] op_sel_hi:[1,0]
	v_pk_mul_f32 v[136:137], v[106:107], v[136:137] op_sel_hi:[1,0]
	v_pk_mul_f32 v[130:131], v[130:131], s[2:3] op_sel_hi:[1,0]
	v_pk_mul_f32 v[128:129], v[128:129], s[2:3] op_sel_hi:[1,0]
	v_pk_mul_f32 v[136:137], v[136:137], s[2:3] op_sel_hi:[1,0]
	v_pk_mul_f32 v[138:139], v[138:139], s[2:3] op_sel_hi:[1,0]
	v_cvt_pk_bf16_f32 v128, v128, v129
	v_cvt_pk_bf16_f32 v129, v130, v131
	v_cvt_pk_bf16_f32 v130, v138, v139
	v_cvt_pk_bf16_f32 v131, v136, v137
	global_store_dwordx4 v[134:135], v[128:131], off offset:1280
	v_or_b32_e32 v134, 48, v166
	v_ashrrev_i32_e32 v135, 31, v134
	v_lshlrev_b64 v[128:129], 6, v[134:135]
	v_lshl_add_u64 v[128:129], v[160:161], 0, v[128:129]
	s_nop 0
	s_waitcnt lgkmcnt(0)
; __device__ __forceinline__ v4u pack8(const f32x4 a, const f32x4 b) { v4u w; w.x = cvt_pk_bf16(a[0], a[1]); w.y = cvt_pk_bf16(a[2], a[3]); w.z = cvt_pk_bf16(b[0], b[1]); w.w = cvt_pk_bf16(b[2], b[3]); return w; }
;     __device__ __forceinline__ void operator()(const f32x4 (&acc)[2][2][4][2], const pg8::Unit& u, int wr, int wc, int fr, int fq) const {
;     ...
;         else if (grp == 4) { WIN_LOOP( *(v4u*)(QO + (size_t)row * DM + 512 + c) = pack8(a * C2Q, b * C2Q); ) }
	s_nop 3
	s_nop 0
	s_nop 1
	s_waitcnt lgkmcnt(0)
	s_nop 1
	s_waitcnt lgkmcnt(0)
	s_nop 1
	v_mov_b32_e32 v136, v253
	v_lshlrev_b64 v[128:129], 11, v[134:135]
	v_lshl_add_u64 v[134:135], s[44:45], 0, v[128:129]
	v_lshl_add_u64 v[134:135], v[134:135], 0, v[192:193]
	v_pk_mul_f32 v[128:129], v[36:37], v[136:137] op_sel_hi:[1,0]
	v_pk_mul_f32 v[130:131], v[38:39], v[136:137] op_sel_hi:[1,0]
	v_pk_mul_f32 v[138:139], v[32:33], v[136:137] op_sel_hi:[1,0]
	v_pk_mul_f32 v[140:141], v[34:35], v[136:137] op_sel_hi:[1,0]
	v_pk_mul_f32 v[130:131], v[130:131], s[2:3] op_sel_hi:[1,0]
	v_pk_mul_f32 v[128:129], v[128:129], s[2:3] op_sel_hi:[1,0]
	v_pk_mul_f32 v[140:141], v[140:141], s[2:3] op_sel_hi:[1,0]
	v_pk_mul_f32 v[138:139], v[138:139], s[2:3] op_sel_hi:[1,0]
	v_cvt_pk_bf16_f32 v128, v128, v129
	v_cvt_pk_bf16_f32 v129, v130, v131
	v_cvt_pk_bf16_f32 v130, v138, v139
	v_cvt_pk_bf16_f32 v131, v140, v141
	global_store_dwordx4 v[134:135], v[128:131], off offset:1024
	v_pk_mul_f32 v[138:139], v[96:97], v[136:137] op_sel_hi:[1,0]
	s_nop 0
	v_pk_mul_f32 v[128:129], v[100:101], v[136:137] op_sel_hi:[1,0]
	v_pk_mul_f32 v[130:131], v[102:103], v[136:137] op_sel_hi:[1,0]
	v_pk_mul_f32 v[136:137], v[98:99], v[136:137] op_sel_hi:[1,0]
	v_pk_mul_f32 v[130:131], v[130:131], s[2:3] op_sel_hi:[1,0]
	v_pk_mul_f32 v[128:129], v[128:129], s[2:3] op_sel_hi:[1,0]
	v_pk_mul_f32 v[136:137], v[136:137], s[2:3] op_sel_hi:[1,0]
	v_pk_mul_f32 v[138:139], v[138:139], s[2:3] op_sel_hi:[1,0]
	v_cvt_pk_bf16_f32 v128, v128, v129
	v_cvt_pk_bf16_f32 v129, v130, v131
	v_cvt_pk_bf16_f32 v130, v138, v139
	v_cvt_pk_bf16_f32 v131, v136, v137
	global_store_dwordx4 v[134:135], v[128:131], off offset:1280
	s_nop 1
	v_add_u32_e32 v128, 0x80, v166
	v_ashrrev_i32_e32 v129, 31, v128
	v_lshlrev_b64 v[130:131], 6, v[128:129]
	v_lshl_add_u64 v[130:131], v[160:161], 0, v[130:131]
	s_nop 0
	v_lshlrev_b64 v[128:129], 11, v[128:129]
	s_waitcnt lgkmcnt(0)
	s_nop 3
	v_lshl_add_u64 v[136:137], s[44:45], 0, v[128:129]
	s_nop 1
	v_lshl_add_u64 v[136:137], v[136:137], 0, v[192:193]
	s_waitcnt lgkmcnt(0)
	s_nop 1
	s_waitcnt lgkmcnt(0)
	s_nop 1
	v_mov_b32_e32 v134, v254
	s_nop 0
	v_pk_mul_f32 v[128:129], v[28:29], v[134:135] op_sel_hi:[1,0]
	v_pk_mul_f32 v[130:131], v[30:31], v[134:135] op_sel_hi:[1,0]
	v_pk_mul_f32 v[138:139], v[24:25], v[134:135] op_sel_hi:[1,0]
	v_pk_mul_f32 v[140:141], v[26:27], v[134:135] op_sel_hi:[1,0]
	v_pk_mul_f32 v[130:131], v[130:131], s[2:3] op_sel_hi:[1,0]
	v_pk_mul_f32 v[128:129], v[128:129], s[2:3] op_sel_hi:[1,0]
	v_pk_mul_f32 v[140:141], v[140:141], s[2:3] op_sel_hi:[1,0]
	v_pk_mul_f32 v[138:139], v[138:139], s[2:3] op_sel_hi:[1,0]
	v_cvt_pk_bf16_f32 v128, v128, v129
	v_cvt_pk_bf16_f32 v129, v130, v131
	v_cvt_pk_bf16_f32 v130, v138, v139
	v_cvt_pk_bf16_f32 v131, v140, v141
	global_store_dwordx4 v[136:137], v[128:131], off offset:1024
	v_pk_mul_f32 v[138:139], v[88:89], v[134:135] op_sel_hi:[1,0]
	s_nop 0
	v_pk_mul_f32 v[128:129], v[92:93], v[134:135] op_sel_hi:[1,0]
	v_pk_mul_f32 v[130:131], v[94:95], v[134:135] op_sel_hi:[1,0]
	v_pk_mul_f32 v[134:135], v[90:91], v[134:135] op_sel_hi:[1,0]
	v_pk_mul_f32 v[130:131], v[130:131], s[2:3] op_sel_hi:[1,0]
	v_pk_mul_f32 v[128:129], v[128:129], s[2:3] op_sel_hi:[1,0]
	v_pk_mul_f32 v[134:135], v[134:135], s[2:3] op_sel_hi:[1,0]
	v_pk_mul_f32 v[138:139], v[138:139], s[2:3] op_sel_hi:[1,0]
	v_cvt_pk_bf16_f32 v128, v128, v129
	v_cvt_pk_bf16_f32 v129, v130, v131
	v_cvt_pk_bf16_f32 v131, v134, v135
	v_add_u32_e32 v134, 0x90, v166
	v_cvt_pk_bf16_f32 v130, v138, v139
	v_ashrrev_i32_e32 v135, 31, v134
	global_store_dwordx4 v[136:137], v[128:131], off offset:1280
	s_nop 1
	v_lshlrev_b64 v[128:129], 6, v[134:135]
	v_lshl_add_u64 v[128:129], v[160:161], 0, v[128:129]
	s_nop 0
	s_waitcnt lgkmcnt(0)
	s_nop 3
	s_nop 0
	s_nop 1
	s_waitcnt lgkmcnt(0)
	s_nop 1
	s_waitcnt lgkmcnt(0)
; __device__ __forceinline__ v4u pack8(const f32x4 a, const f32x4 b) { v4u w; w.x = cvt_pk_bf16(a[0], a[1]); w.y = cvt_pk_bf16(a[2], a[3]); w.z = cvt_pk_bf16(b[0], b[1]); w.w = cvt_pk_bf16(b[2], b[3]); return w; }
;     __device__ __forceinline__ void operator()(const f32x4 (&acc)[2][2][4][2], const pg8::Unit& u, int wr, int wc, int fr, int fq) const {
;     ...
;         else if (grp == 4) { WIN_LOOP( *(v4u*)(QO + (size_t)row * DM + 512 + c) = pack8(a * C2Q, b * C2Q); ) }
	s_nop 1
	v_mov_b32_e32 v136, v240
	v_lshlrev_b64 v[128:129], 11, v[134:135]
	v_lshl_add_u64 v[134:135], s[44:45], 0, v[128:129]
	v_lshl_add_u64 v[134:135], v[134:135], 0, v[192:193]
	v_pk_mul_f32 v[128:129], v[20:21], v[136:137] op_sel_hi:[1,0]
	v_pk_mul_f32 v[130:131], v[22:23], v[136:137] op_sel_hi:[1,0]
	v_pk_mul_f32 v[138:139], v[16:17], v[136:137] op_sel_hi:[1,0]
	v_pk_mul_f32 v[140:141], v[18:19], v[136:137] op_sel_hi:[1,0]
	v_pk_mul_f32 v[130:131], v[130:131], s[2:3] op_sel_hi:[1,0]
	v_pk_mul_f32 v[128:129], v[128:129], s[2:3] op_sel_hi:[1,0]
	v_pk_mul_f32 v[140:141], v[140:141], s[2:3] op_sel_hi:[1,0]
	v_pk_mul_f32 v[138:139], v[138:139], s[2:3] op_sel_hi:[1,0]
	v_cvt_pk_bf16_f32 v128, v128, v129
	v_cvt_pk_bf16_f32 v129, v130, v131
	v_cvt_pk_bf16_f32 v130, v138, v139
	v_cvt_pk_bf16_f32 v131, v140, v141
	global_store_dwordx4 v[134:135], v[128:131], off offset:1024
	v_pk_mul_f32 v[138:139], v[80:81], v[136:137] op_sel_hi:[1,0]
	s_nop 0
	v_pk_mul_f32 v[128:129], v[84:85], v[136:137] op_sel_hi:[1,0]
	v_pk_mul_f32 v[130:131], v[86:87], v[136:137] op_sel_hi:[1,0]
	v_pk_mul_f32 v[136:137], v[82:83], v[136:137] op_sel_hi:[1,0]
	v_pk_mul_f32 v[130:131], v[130:131], s[2:3] op_sel_hi:[1,0]
	v_pk_mul_f32 v[128:129], v[128:129], s[2:3] op_sel_hi:[1,0]
	v_pk_mul_f32 v[136:137], v[136:137], s[2:3] op_sel_hi:[1,0]
	v_pk_mul_f32 v[138:139], v[138:139], s[2:3] op_sel_hi:[1,0]
	v_cvt_pk_bf16_f32 v128, v128, v129
	v_cvt_pk_bf16_f32 v129, v130, v131
	v_cvt_pk_bf16_f32 v130, v138, v139
	v_cvt_pk_bf16_f32 v131, v136, v137
	global_store_dwordx4 v[134:135], v[128:131], off offset:1280
	v_add_u32_e32 v134, 0xa0, v166
	v_ashrrev_i32_e32 v135, 31, v134
	v_lshlrev_b64 v[128:129], 6, v[134:135]
	v_lshl_add_u64 v[128:129], v[160:161], 0, v[128:129]
	s_nop 0
	s_waitcnt lgkmcnt(0)
	s_nop 3
	s_nop 0
	s_nop 1
	s_waitcnt lgkmcnt(0)
	s_nop 1
	s_waitcnt lgkmcnt(0)
	s_nop 1
	v_mov_b32_e32 v136, v241
	v_lshlrev_b64 v[128:129], 11, v[134:135]
	v_lshl_add_u64 v[134:135], s[44:45], 0, v[128:129]
	v_lshl_add_u64 v[134:135], v[134:135], 0, v[192:193]
	v_pk_mul_f32 v[128:129], v[12:13], v[136:137] op_sel_hi:[1,0]
	v_pk_mul_f32 v[130:131], v[14:15], v[136:137] op_sel_hi:[1,0]
	v_pk_mul_f32 v[138:139], v[8:9], v[136:137] op_sel_hi:[1,0]
	v_pk_mul_f32 v[140:141], v[10:11], v[136:137] op_sel_hi:[1,0]
	v_pk_mul_f32 v[130:131], v[130:131], s[2:3] op_sel_hi:[1,0]
	v_pk_mul_f32 v[128:129], v[128:129], s[2:3] op_sel_hi:[1,0]
	v_pk_mul_f32 v[140:141], v[140:141], s[2:3] op_sel_hi:[1,0]
	v_pk_mul_f32 v[138:139], v[138:139], s[2:3] op_sel_hi:[1,0]
	v_cvt_pk_bf16_f32 v128, v128, v129
	v_cvt_pk_bf16_f32 v129, v130, v131
	v_cvt_pk_bf16_f32 v130, v138, v139
	v_cvt_pk_bf16_f32 v131, v140, v141
	global_store_dwordx4 v[134:135], v[128:131], off offset:1024
	v_pk_mul_f32 v[138:139], v[72:73], v[136:137] op_sel_hi:[1,0]
	s_nop 0
	v_pk_mul_f32 v[128:129], v[76:77], v[136:137] op_sel_hi:[1,0]
	v_pk_mul_f32 v[130:131], v[78:79], v[136:137] op_sel_hi:[1,0]
	v_pk_mul_f32 v[136:137], v[74:75], v[136:137] op_sel_hi:[1,0]
	v_pk_mul_f32 v[130:131], v[130:131], s[2:3] op_sel_hi:[1,0]
	v_pk_mul_f32 v[128:129], v[128:129], s[2:3] op_sel_hi:[1,0]
	v_pk_mul_f32 v[136:137], v[136:137], s[2:3] op_sel_hi:[1,0]
	v_pk_mul_f32 v[138:139], v[138:139], s[2:3] op_sel_hi:[1,0]
	v_cvt_pk_bf16_f32 v128, v128, v129
	v_cvt_pk_bf16_f32 v129, v130, v131
	v_cvt_pk_bf16_f32 v130, v138, v139
	v_cvt_pk_bf16_f32 v131, v136, v137
	global_store_dwordx4 v[134:135], v[128:131], off offset:1280
	v_add_u32_e32 v134, 0xb0, v166
	v_ashrrev_i32_e32 v135, 31, v134
	v_lshlrev_b64 v[128:129], 6, v[134:135]
	v_lshl_add_u64 v[128:129], v[160:161], 0, v[128:129]
	s_nop 0
	s_waitcnt lgkmcnt(0)
	s_nop 3
	s_nop 0
	s_nop 1
	s_waitcnt lgkmcnt(0)
	s_nop 1
	s_waitcnt lgkmcnt(0)
	s_nop 1
	v_mov_b32_e32 v132, v245
	v_lshlrev_b64 v[128:129], 11, v[134:135]
	v_lshl_add_u64 v[134:135], s[44:45], 0, v[128:129]
	v_lshl_add_u64 v[134:135], v[134:135], 0, v[192:193]
	v_pk_mul_f32 v[128:129], v[4:5], v[132:133] op_sel_hi:[1,0]
	v_pk_mul_f32 v[130:131], v[6:7], v[132:133] op_sel_hi:[1,0]
	v_pk_mul_f32 v[136:137], v[0:1], v[132:133] op_sel_hi:[1,0]
	v_pk_mul_f32 v[138:139], v[2:3], v[132:133] op_sel_hi:[1,0]
	v_pk_mul_f32 v[130:131], v[130:131], s[2:3] op_sel_hi:[1,0]
	v_pk_mul_f32 v[128:129], v[128:129], s[2:3] op_sel_hi:[1,0]
	v_pk_mul_f32 v[138:139], v[138:139], s[2:3] op_sel_hi:[1,0]
	v_pk_mul_f32 v[136:137], v[136:137], s[2:3] op_sel_hi:[1,0]
	v_cvt_pk_bf16_f32 v128, v128, v129
	v_cvt_pk_bf16_f32 v129, v130, v131
	v_cvt_pk_bf16_f32 v130, v136, v137
	v_cvt_pk_bf16_f32 v131, v138, v139
	global_store_dwordx4 v[134:135], v[128:131], off offset:1024
	v_pk_mul_f32 v[136:137], v[64:65], v[132:133] op_sel_hi:[1,0]
	s_nop 0
	v_pk_mul_f32 v[128:129], v[68:69], v[132:133] op_sel_hi:[1,0]
	v_pk_mul_f32 v[130:131], v[70:71], v[132:133] op_sel_hi:[1,0]
	v_pk_mul_f32 v[132:133], v[66:67], v[132:133] op_sel_hi:[1,0]
	v_pk_mul_f32 v[130:131], v[130:131], s[2:3] op_sel_hi:[1,0]
	v_pk_mul_f32 v[128:129], v[128:129], s[2:3] op_sel_hi:[1,0]
	v_pk_mul_f32 v[132:133], v[132:133], s[2:3] op_sel_hi:[1,0]
	v_pk_mul_f32 v[136:137], v[136:137], s[2:3] op_sel_hi:[1,0]
	v_cvt_pk_bf16_f32 v128, v128, v129
	v_cvt_pk_bf16_f32 v129, v130, v131
	v_cvt_pk_bf16_f32 v130, v136, v137
	v_cvt_pk_bf16_f32 v131, v132, v133
	global_store_dwordx4 v[134:135], v[128:131], off offset:1280

; __device__ __forceinline__ v4u pack8(const f32x4 a, const f32x4 b) { v4u w; w.x = cvt_pk_bf16(a[0], a[1]); w.y = cvt_pk_bf16(a[2], a[3]); w.z = cvt_pk_bf16(b[0], b[1]); w.w = cvt_pk_bf16(b[2], b[3]); return w; }
; __device__ __forceinline__ float silu_f(float x) { return x * __builtin_amdgcn_rcpf(1.f + __expf(-x)); }
;     __device__ __forceinline__ void operator()(const f32x4 (&acc)[2][2][4][2], const pg8::Unit& u, int wr, int wc, int fr, int fq) const {
;     ...
;         if (grp == 0) { WIN_LOOP( _Pragma("unroll") for (int i = 0; i < 4; ++i) { a[i] = silu_f(a[i]); b[i] = silu_f(b[i]); } *(v4u*)(QO + (size_t)row * DM + c) = pack8(a, b); ) }
;         else if (grp == 3) { WIN_LOOP( _Pragma("unroll") for (int i = 0; i < 4; ++i) { a[i] = silu_f(a[i]); b[i] = silu_f(b[i]); } *(v4u*)(GH + (size_t)row * 512 + c) = pack8(a, b); ) }
.LBB0_404:
	s_and_b64 vcc, exec, s[12:13]
	s_cbranch_vccz .LBB0_406
	v_and_b32_e32 v129, 64, v215
	v_xor_b32_e32 v128, 16, v215
	v_add_u32_e32 v129, 64, v129
	v_cmp_lt_i32_e32 vcc, v128, v129
	v_ashrrev_i32_e32 v167, 31, v166
	v_readlane_b32 s12, v255, 39
	v_cndmask_b32_e32 v128, v215, v128, vcc
	v_lshlrev_b32_e32 v140, 2, v128
	v_xor_b32_e32 v128, 32, v215
	v_cmp_lt_i32_e32 vcc, v128, v129
	v_readlane_b32 s13, v255, 40
	v_lshlrev_b32_e32 v192, 1, v176
	v_cndmask_b32_e32 v128, v215, v128, vcc
	v_lshlrev_b32_e32 v141, 2, v128
	v_lshlrev_b64 v[128:129], 6, v[166:167]
	v_lshl_add_u64 v[128:129], v[160:161], 0, v[128:129]
	s_nop 0
	s_waitcnt lgkmcnt(0)
	s_nop 3
	s_nop 0
	s_nop 1
	s_waitcnt lgkmcnt(0)
	s_nop 1
	s_waitcnt lgkmcnt(0)
	s_nop 1
	v_mov_b32_e32 v132, v250
	v_lshlrev_b64 v[128:129], 10, v[166:167]
	v_lshl_add_u64 v[134:135], s[12:13], 0, v[128:129]
	v_lshl_add_u64 v[134:135], v[134:135], 0, v[192:193]
	v_pk_mul_f32 v[130:131], v[60:61], v[132:133] op_sel_hi:[1,0]
	v_pk_mul_f32 v[128:129], v[62:63], v[132:133] op_sel_hi:[1,0]
	v_pk_mul_f32 v[136:137], v[58:59], v[132:133] op_sel_hi:[1,0]
	v_pk_mul_f32 v[138:139], v[56:57], v[132:133] op_sel_hi:[1,0]
	v_mul_f32_e32 v133, 0xbfb8aa3b, v130
	v_exp_f32_e32 v133, v133
	s_nop 0
	v_add_f32_e32 v133, 1.0, v133
	v_rcp_f32_e32 v142, v133
	v_mul_f32_e32 v133, 0xbfb8aa3b, v138
	v_exp_f32_e32 v133, v133
	s_nop 0
	v_add_f32_e32 v133, 1.0, v133
	v_rcp_f32_e32 v144, v133
	v_mul_f32_e32 v133, 0xbfb8aa3b, v131
	v_exp_f32_e32 v133, v133
	s_nop 0
	v_add_f32_e32 v133, 1.0, v133
	v_rcp_f32_e32 v143, v133
	v_mul_f32_e32 v133, 0xbfb8aa3b, v139
	v_exp_f32_e32 v133, v133
	v_pk_mul_f32 v[130:131], v[130:131], v[142:143]
	v_add_f32_e32 v133, 1.0, v133
	v_rcp_f32_e32 v145, v133
	v_mul_f32_e32 v133, 0xbfb8aa3b, v128
	v_exp_f32_e32 v133, v133
	v_pk_mul_f32 v[138:139], v[138:139], v[144:145]
	v_add_f32_e32 v133, 1.0, v133
	v_rcp_f32_e32 v142, v133
	v_mul_f32_e32 v133, 0xbfb8aa3b, v136
	v_exp_f32_e32 v133, v133
	s_nop 0
	v_add_f32_e32 v133, 1.0, v133
	v_rcp_f32_e32 v144, v133
	v_mul_f32_e32 v133, 0xbfb8aa3b, v129
	v_exp_f32_e32 v133, v133
	s_nop 0
	v_add_f32_e32 v133, 1.0, v133
	v_rcp_f32_e32 v143, v133
	s_nop 0
	v_pk_mul_f32 v[142:143], v[128:129], v[142:143]
	v_mul_f32_e32 v128, 0xbfb8aa3b, v137
	v_exp_f32_e32 v128, v128
	v_cvt_pk_bf16_f32 v129, v142, v143
	v_add_f32_e32 v128, 1.0, v128
	v_rcp_f32_e32 v145, v128
	v_cvt_pk_bf16_f32 v128, v130, v131
	v_cvt_pk_bf16_f32 v130, v138, v139
	v_pk_mul_f32 v[136:137], v[136:137], v[144:145]
	s_nop 0
	v_cvt_pk_bf16_f32 v131, v136, v137
	global_store_dwordx4 v[134:135], v[128:131], off
	v_pk_mul_f32 v[136:137], v[122:123], v[132:133] op_sel_hi:[1,0]
	s_nop 0
	v_pk_mul_f32 v[128:129], v[126:127], v[132:133] op_sel_hi:[1,0]
	v_pk_mul_f32 v[130:131], v[124:125], v[132:133] op_sel_hi:[1,0]
	v_pk_mul_f32 v[132:133], v[120:121], v[132:133] op_sel_hi:[1,0]
	v_mul_f32_e32 v138, 0xbfb8aa3b, v130
	v_mul_f32_e32 v139, 0xbfb8aa3b, v132
	v_exp_f32_e32 v139, v139
	v_exp_f32_e32 v138, v138
	v_add_f32_e32 v139, 1.0, v139
	v_rcp_f32_e32 v142, v139
	v_mul_f32_e32 v139, 0xbfb8aa3b, v131
	v_exp_f32_e32 v139, v139
	v_add_f32_e32 v138, 1.0, v138
	v_rcp_f32_e32 v138, v138
	v_add_f32_e32 v139, 1.0, v139
	v_rcp_f32_e32 v139, v139
	s_nop 0
	v_pk_mul_f32 v[130:131], v[130:131], v[138:139]
	v_mul_f32_e32 v138, 0xbfb8aa3b, v133
	v_exp_f32_e32 v138, v138
	v_mul_f32_e32 v139, 0xbfb8aa3b, v136
	v_exp_f32_e32 v139, v139
	v_add_f32_e32 v138, 1.0, v138
	v_rcp_f32_e32 v143, v138
	v_add_f32_e32 v139, 1.0, v139
	v_mul_f32_e32 v138, 0xbfb8aa3b, v128
	v_exp_f32_e32 v138, v138
	v_pk_mul_f32 v[132:133], v[132:133], v[142:143]
	v_rcp_f32_e32 v142, v139
	v_mul_f32_e32 v139, 0xbfb8aa3b, v129
	v_exp_f32_e32 v139, v139
	v_add_f32_e32 v138, 1.0, v138
	v_rcp_f32_e32 v138, v138
	v_add_f32_e32 v139, 1.0, v139
	v_rcp_f32_e32 v139, v139
	s_nop 0
	v_pk_mul_f32 v[138:139], v[128:129], v[138:139]
	v_mul_f32_e32 v128, 0xbfb8aa3b, v137
	v_exp_f32_e32 v128, v128
	v_cvt_pk_bf16_f32 v129, v138, v139
	v_add_f32_e32 v128, 1.0, v128
	v_rcp_f32_e32 v143, v128
	v_cvt_pk_bf16_f32 v128, v130, v131
	v_cvt_pk_bf16_f32 v130, v132, v133
	v_pk_mul_f32 v[136:137], v[136:137], v[142:143]
	s_nop 0
	v_cvt_pk_bf16_f32 v131, v136, v137
	global_store_dwordx4 v[134:135], v[128:131], off offset:256
	v_or_b32_e32 v134, 16, v166
	v_ashrrev_i32_e32 v135, 31, v134
	v_lshlrev_b64 v[128:129], 6, v[134:135]
	v_lshl_add_u64 v[128:129], v[160:161], 0, v[128:129]
	s_nop 0
	s_waitcnt lgkmcnt(0)
	s_nop 3
	s_nop 0
	s_nop 1
	s_waitcnt lgkmcnt(0)
	s_nop 1
	s_waitcnt lgkmcnt(0)
; __device__ __forceinline__ v4u pack8(const f32x4 a, const f32x4 b) { v4u w; w.x = cvt_pk_bf16(a[0], a[1]); w.y = cvt_pk_bf16(a[2], a[3]); w.z = cvt_pk_bf16(b[0], b[1]); w.w = cvt_pk_bf16(b[2], b[3]); return w; }
; __device__ __forceinline__ float silu_f(float x) { return x * __builtin_amdgcn_rcpf(1.f + __expf(-x)); }
;     __device__ __forceinline__ void operator()(const f32x4 (&acc)[2][2][4][2], const pg8::Unit& u, int wr, int wc, int fr, int fq) const {
;     ...
;         if (grp == 0) { WIN_LOOP( _Pragma("unroll") for (int i = 0; i < 4; ++i) { a[i] = silu_f(a[i]); b[i] = silu_f(b[i]); } *(v4u*)(QO + (size_t)row * DM + c) = pack8(a, b); ) }
;         else if (grp == 3) { WIN_LOOP( _Pragma("unroll") for (int i = 0; i < 4; ++i) { a[i] = silu_f(a[i]); b[i] = silu_f(b[i]); } *(v4u*)(GH + (size_t)row * 512 + c) = pack8(a, b); ) }
	s_nop 1
	v_mov_b32_e32 v132, v251
	v_lshlrev_b64 v[128:129], 10, v[134:135]
	v_lshl_add_u64 v[128:129], s[12:13], 0, v[128:129]
	v_lshl_add_u64 v[128:129], v[128:129], 0, v[192:193]
	v_pk_mul_f32 v[134:135], v[52:53], v[132:133] op_sel_hi:[1,0]
	v_pk_mul_f32 v[130:131], v[54:55], v[132:133] op_sel_hi:[1,0]
	v_pk_mul_f32 v[136:137], v[50:51], v[132:133] op_sel_hi:[1,0]
	v_pk_mul_f32 v[138:139], v[48:49], v[132:133] op_sel_hi:[1,0]
	v_mul_f32_e32 v133, 0xbfb8aa3b, v134
	v_exp_f32_e32 v133, v133
	s_nop 0
	v_add_f32_e32 v133, 1.0, v133
	v_rcp_f32_e32 v142, v133
	v_mul_f32_e32 v133, 0xbfb8aa3b, v138
	v_exp_f32_e32 v133, v133
	s_nop 0
	v_add_f32_e32 v133, 1.0, v133
	v_rcp_f32_e32 v144, v133
	v_mul_f32_e32 v133, 0xbfb8aa3b, v135
	v_exp_f32_e32 v133, v133
	s_nop 0
	v_add_f32_e32 v133, 1.0, v133
	v_rcp_f32_e32 v143, v133
	v_mul_f32_e32 v133, 0xbfb8aa3b, v139
	v_exp_f32_e32 v133, v133
	v_pk_mul_f32 v[134:135], v[134:135], v[142:143]
	s_nop 0
	v_cvt_pk_bf16_f32 v134, v134, v135
	v_add_f32_e32 v133, 1.0, v133
	v_rcp_f32_e32 v145, v133
	v_mul_f32_e32 v133, 0xbfb8aa3b, v130
	v_exp_f32_e32 v133, v133
	v_pk_mul_f32 v[138:139], v[138:139], v[144:145]
	v_add_f32_e32 v133, 1.0, v133
	v_rcp_f32_e32 v142, v133
	v_mul_f32_e32 v133, 0xbfb8aa3b, v136
	v_exp_f32_e32 v133, v133
	s_nop 0
	v_add_f32_e32 v133, 1.0, v133
	v_rcp_f32_e32 v144, v133
	v_mul_f32_e32 v133, 0xbfb8aa3b, v131
	v_exp_f32_e32 v133, v133
	s_nop 0
	v_add_f32_e32 v133, 1.0, v133
	v_rcp_f32_e32 v143, v133
	v_mul_f32_e32 v133, 0xbfb8aa3b, v137
	v_exp_f32_e32 v133, v133
	v_pk_mul_f32 v[130:131], v[130:131], v[142:143]
	s_nop 0
	v_cvt_pk_bf16_f32 v135, v130, v131
	v_add_f32_e32 v133, 1.0, v133
	v_rcp_f32_e32 v145, v133
	v_pk_mul_f32 v[130:131], v[114:115], v[132:133] op_sel_hi:[1,0]
	v_pk_mul_f32 v[142:143], v[136:137], v[144:145]
	v_cvt_pk_bf16_f32 v136, v138, v139
	v_cvt_pk_bf16_f32 v137, v142, v143
	global_store_dwordx4 v[128:129], v[134:137], off
	v_pk_mul_f32 v[138:139], v[118:119], v[132:133] op_sel_hi:[1,0]
	s_nop 0
	v_pk_mul_f32 v[136:137], v[112:113], v[132:133] op_sel_hi:[1,0]
	v_pk_mul_f32 v[134:135], v[116:117], v[132:133] op_sel_hi:[1,0]
	v_mul_f32_e32 v133, 0xbfb8aa3b, v136
	v_exp_f32_e32 v133, v133
	v_mul_f32_e32 v132, 0xbfb8aa3b, v134
	v_exp_f32_e32 v132, v132
	v_add_f32_e32 v133, 1.0, v133
	v_rcp_f32_e32 v142, v133
	v_mul_f32_e32 v133, 0xbfb8aa3b, v135
	v_exp_f32_e32 v133, v133
	v_add_f32_e32 v132, 1.0, v132
	v_rcp_f32_e32 v132, v132
	v_add_f32_e32 v133, 1.0, v133
	v_rcp_f32_e32 v133, v133
	s_nop 0
	v_pk_mul_f32 v[132:133], v[134:135], v[132:133]
	v_mul_f32_e32 v134, 0xbfb8aa3b, v137
	v_exp_f32_e32 v134, v134
	s_nop 0
	v_add_f32_e32 v134, 1.0, v134
	v_rcp_f32_e32 v143, v134
	s_nop 0
	v_pk_mul_f32 v[134:135], v[136:137], v[142:143]
	v_mul_f32_e32 v136, 0xbfb8aa3b, v138
	v_mul_f32_e32 v137, 0xbfb8aa3b, v139
	v_exp_f32_e32 v136, v136
	v_exp_f32_e32 v137, v137
	v_add_f32_e32 v136, 1.0, v136
	v_add_f32_e32 v137, 1.0, v137
	v_rcp_f32_e32 v142, v136
	v_mul_f32_e32 v136, 0xbfb8aa3b, v130
	v_rcp_f32_e32 v143, v137
	v_mul_f32_e32 v137, 0xbfb8aa3b, v131
	v_exp_f32_e32 v136, v136
	v_exp_f32_e32 v137, v137
	v_pk_mul_f32 v[138:139], v[138:139], v[142:143]
	v_add_f32_e32 v136, 1.0, v136
	v_add_f32_e32 v137, 1.0, v137
	v_rcp_f32_e32 v136, v136
	v_rcp_f32_e32 v137, v137
	s_nop 0
	v_pk_mul_f32 v[136:137], v[130:131], v[136:137]
	v_cvt_pk_bf16_f32 v130, v132, v133
	v_cvt_pk_bf16_f32 v131, v138, v139
	v_cvt_pk_bf16_f32 v132, v134, v135
	v_cvt_pk_bf16_f32 v133, v136, v137
	global_store_dwordx4 v[128:129], v[130:133], off offset:256
	s_nop 1
	v_or_b32_e32 v132, 32, v166
	v_ashrrev_i32_e32 v133, 31, v132
	v_lshlrev_b64 v[128:129], 6, v[132:133]
	v_lshl_add_u64 v[128:129], v[160:161], 0, v[128:129]
	s_nop 0
	s_waitcnt lgkmcnt(0)
	s_nop 3
	s_nop 0
	s_nop 1
	s_waitcnt lgkmcnt(0)
	s_nop 1
	s_waitcnt lgkmcnt(0)
	s_nop 1
	v_mov_b32_e32 v134, v252
	v_lshlrev_b64 v[128:129], 10, v[132:133]
	v_lshl_add_u64 v[128:129], s[12:13], 0, v[128:129]
	v_lshl_add_u64 v[128:129], v[128:129], 0, v[192:193]
	v_pk_mul_f32 v[132:133], v[44:45], v[134:135] op_sel_hi:[1,0]
	v_pk_mul_f32 v[130:131], v[46:47], v[134:135] op_sel_hi:[1,0]
	v_pk_mul_f32 v[136:137], v[42:43], v[134:135] op_sel_hi:[1,0]
	v_pk_mul_f32 v[138:139], v[40:41], v[134:135] op_sel_hi:[1,0]
	v_mul_f32_e32 v135, 0xbfb8aa3b, v132
	v_exp_f32_e32 v135, v135
	s_nop 0
	v_add_f32_e32 v135, 1.0, v135
	v_rcp_f32_e32 v142, v135
	v_mul_f32_e32 v135, 0xbfb8aa3b, v138
	v_exp_f32_e32 v135, v135
	s_nop 0
	v_add_f32_e32 v135, 1.0, v135
	v_rcp_f32_e32 v144, v135
	v_mul_f32_e32 v135, 0xbfb8aa3b, v133
	v_exp_f32_e32 v135, v135
	s_nop 0
	v_add_f32_e32 v135, 1.0, v135
	v_rcp_f32_e32 v143, v135
	v_mul_f32_e32 v135, 0xbfb8aa3b, v139
	v_exp_f32_e32 v135, v135
	v_pk_mul_f32 v[132:133], v[132:133], v[142:143]
	v_add_f32_e32 v135, 1.0, v135
	v_rcp_f32_e32 v145, v135
	v_mul_f32_e32 v135, 0xbfb8aa3b, v130
	v_exp_f32_e32 v135, v135
	v_pk_mul_f32 v[138:139], v[138:139], v[144:145]
	v_add_f32_e32 v135, 1.0, v135
	v_rcp_f32_e32 v142, v135
	v_mul_f32_e32 v135, 0xbfb8aa3b, v136
	v_exp_f32_e32 v135, v135
	s_nop 0
	v_add_f32_e32 v135, 1.0, v135
	v_rcp_f32_e32 v144, v135
	v_mul_f32_e32 v135, 0xbfb8aa3b, v131
	v_exp_f32_e32 v135, v135
	s_nop 0
	v_add_f32_e32 v135, 1.0, v135
	v_rcp_f32_e32 v143, v135
	s_nop 0
	v_pk_mul_f32 v[142:143], v[130:131], v[142:143]
	v_mul_f32_e32 v130, 0xbfb8aa3b, v137
	v_exp_f32_e32 v130, v130
	v_cvt_pk_bf16_f32 v131, v142, v143
	v_add_f32_e32 v130, 1.0, v130
	v_rcp_f32_e32 v145, v130
	v_cvt_pk_bf16_f32 v130, v132, v133
	v_cvt_pk_bf16_f32 v132, v138, v139
	v_pk_mul_f32 v[138:139], v[104:105], v[134:135] op_sel_hi:[1,0]
	v_pk_mul_f32 v[136:137], v[136:137], v[144:145]
	s_nop 0
; __device__ __forceinline__ v4u pack8(const f32x4 a, const f32x4 b) { v4u w; w.x = cvt_pk_bf16(a[0], a[1]); w.y = cvt_pk_bf16(a[2], a[3]); w.z = cvt_pk_bf16(b[0], b[1]); w.w = cvt_pk_bf16(b[2], b[3]); return w; }
; __device__ __forceinline__ float silu_f(float x) { return x * __builtin_amdgcn_rcpf(1.f + __expf(-x)); }
;     __device__ __forceinline__ void operator()(const f32x4 (&acc)[2][2][4][2], const pg8::Unit& u, int wr, int wc, int fr, int fq) const {
;     ...
;         if (grp == 0) { WIN_LOOP( _Pragma("unroll") for (int i = 0; i < 4; ++i) { a[i] = silu_f(a[i]); b[i] = silu_f(b[i]); } *(v4u*)(QO + (size_t)row * DM + c) = pack8(a, b); ) }
;         else if (grp == 3) { WIN_LOOP( _Pragma("unroll") for (int i = 0; i < 4; ++i) { a[i] = silu_f(a[i]); b[i] = silu_f(b[i]); } *(v4u*)(GH + (size_t)row * 512 + c) = pack8(a, b); ) }
	v_cvt_pk_bf16_f32 v133, v136, v137
	global_store_dwordx4 v[128:129], v[130:133], off
	v_pk_mul_f32 v[136:137], v[108:109], v[134:135] op_sel_hi:[1,0]
	s_nop 0
	v_pk_mul_f32 v[132:133], v[110:111], v[134:135] op_sel_hi:[1,0]
	v_pk_mul_f32 v[130:131], v[106:107], v[134:135] op_sel_hi:[1,0]
	v_mul_f32_e32 v135, 0xbfb8aa3b, v138
	v_exp_f32_e32 v135, v135
	v_mul_f32_e32 v134, 0xbfb8aa3b, v136
	v_exp_f32_e32 v134, v134
	v_add_f32_e32 v135, 1.0, v135
	v_rcp_f32_e32 v142, v135
	v_mul_f32_e32 v135, 0xbfb8aa3b, v137
	v_exp_f32_e32 v135, v135
	v_add_f32_e32 v134, 1.0, v134
	v_rcp_f32_e32 v134, v134
	v_add_f32_e32 v135, 1.0, v135
	v_rcp_f32_e32 v135, v135
	s_nop 0
	v_pk_mul_f32 v[134:135], v[136:137], v[134:135]
	v_mul_f32_e32 v136, 0xbfb8aa3b, v139
	v_exp_f32_e32 v136, v136
	s_nop 0
	v_add_f32_e32 v136, 1.0, v136
	v_rcp_f32_e32 v143, v136
	s_nop 0
	v_pk_mul_f32 v[136:137], v[138:139], v[142:143]
	v_mul_f32_e32 v138, 0xbfb8aa3b, v132
	v_mul_f32_e32 v139, 0xbfb8aa3b, v133
	v_exp_f32_e32 v138, v138
	v_exp_f32_e32 v139, v139
	v_add_f32_e32 v138, 1.0, v138
	v_add_f32_e32 v139, 1.0, v139
	v_rcp_f32_e32 v142, v138
	v_mul_f32_e32 v138, 0xbfb8aa3b, v130
	v_rcp_f32_e32 v143, v139
	v_mul_f32_e32 v139, 0xbfb8aa3b, v131
	v_exp_f32_e32 v138, v138
	v_exp_f32_e32 v139, v139
	v_pk_mul_f32 v[132:133], v[132:133], v[142:143]
	v_add_f32_e32 v138, 1.0, v138
	v_add_f32_e32 v139, 1.0, v139
	v_rcp_f32_e32 v138, v138
	v_rcp_f32_e32 v139, v139
	s_nop 0
	v_pk_mul_f32 v[138:139], v[130:131], v[138:139]
	v_cvt_pk_bf16_f32 v130, v134, v135
	v_cvt_pk_bf16_f32 v131, v132, v133
	v_cvt_pk_bf16_f32 v132, v136, v137
	v_cvt_pk_bf16_f32 v133, v138, v139
	global_store_dwordx4 v[128:129], v[130:133], off offset:256
	s_nop 1
	v_or_b32_e32 v132, 48, v166
	v_ashrrev_i32_e32 v133, 31, v132
	v_lshlrev_b64 v[128:129], 6, v[132:133]
	v_lshl_add_u64 v[128:129], v[160:161], 0, v[128:129]
	s_nop 0
	s_waitcnt lgkmcnt(0)
	s_nop 3
	s_nop 0
	s_nop 1
	s_waitcnt lgkmcnt(0)
	s_nop 1
	s_waitcnt lgkmcnt(0)
	s_nop 1
	v_mov_b32_e32 v134, v253
	v_lshlrev_b64 v[128:129], 10, v[132:133]
	v_lshl_add_u64 v[132:133], s[12:13], 0, v[128:129]
	v_lshl_add_u64 v[132:133], v[132:133], 0, v[192:193]
	v_pk_mul_f32 v[130:131], v[36:37], v[134:135] op_sel_hi:[1,0]
	v_pk_mul_f32 v[128:129], v[38:39], v[134:135] op_sel_hi:[1,0]
	v_pk_mul_f32 v[136:137], v[34:35], v[134:135] op_sel_hi:[1,0]
	v_pk_mul_f32 v[138:139], v[32:33], v[134:135] op_sel_hi:[1,0]
	v_mul_f32_e32 v135, 0xbfb8aa3b, v130
	v_exp_f32_e32 v135, v135
	s_nop 0
	v_add_f32_e32 v135, 1.0, v135
	v_rcp_f32_e32 v142, v135
	v_mul_f32_e32 v135, 0xbfb8aa3b, v138
	v_exp_f32_e32 v135, v135
	s_nop 0
	v_add_f32_e32 v135, 1.0, v135
	v_rcp_f32_e32 v144, v135
	v_mul_f32_e32 v135, 0xbfb8aa3b, v131
	v_exp_f32_e32 v135, v135
	s_nop 0
	v_add_f32_e32 v135, 1.0, v135
	v_rcp_f32_e32 v143, v135
	v_mul_f32_e32 v135, 0xbfb8aa3b, v139
	v_exp_f32_e32 v135, v135
	v_pk_mul_f32 v[130:131], v[130:131], v[142:143]
	v_add_f32_e32 v135, 1.0, v135
	v_rcp_f32_e32 v145, v135
	v_mul_f32_e32 v135, 0xbfb8aa3b, v128
	v_exp_f32_e32 v135, v135
	v_pk_mul_f32 v[138:139], v[138:139], v[144:145]
	v_add_f32_e32 v135, 1.0, v135
	v_rcp_f32_e32 v142, v135
	v_mul_f32_e32 v135, 0xbfb8aa3b, v136
	v_exp_f32_e32 v135, v135
	s_nop 0
	v_add_f32_e32 v135, 1.0, v135
	v_rcp_f32_e32 v144, v135
	v_mul_f32_e32 v135, 0xbfb8aa3b, v129
	v_exp_f32_e32 v135, v135
	s_nop 0
	v_add_f32_e32 v135, 1.0, v135
	v_rcp_f32_e32 v143, v135
	s_nop 0
	v_pk_mul_f32 v[142:143], v[128:129], v[142:143]
	v_mul_f32_e32 v128, 0xbfb8aa3b, v137
	v_exp_f32_e32 v128, v128
	v_cvt_pk_bf16_f32 v129, v142, v143
	v_add_f32_e32 v128, 1.0, v128
	v_rcp_f32_e32 v145, v128
	v_cvt_pk_bf16_f32 v128, v130, v131
	v_cvt_pk_bf16_f32 v130, v138, v139
	v_pk_mul_f32 v[136:137], v[136:137], v[144:145]
	s_nop 0
	v_cvt_pk_bf16_f32 v131, v136, v137
	global_store_dwordx4 v[132:133], v[128:131], off
	v_pk_mul_f32 v[136:137], v[98:99], v[134:135] op_sel_hi:[1,0]
	s_nop 0
	v_pk_mul_f32 v[128:129], v[102:103], v[134:135] op_sel_hi:[1,0]
	v_pk_mul_f32 v[130:131], v[100:101], v[134:135] op_sel_hi:[1,0]
	v_pk_mul_f32 v[134:135], v[96:97], v[134:135] op_sel_hi:[1,0]
	v_mul_f32_e32 v138, 0xbfb8aa3b, v130
	v_mul_f32_e32 v139, 0xbfb8aa3b, v134
	v_exp_f32_e32 v139, v139
	v_exp_f32_e32 v138, v138
	v_add_f32_e32 v139, 1.0, v139
	v_rcp_f32_e32 v142, v139
	v_mul_f32_e32 v139, 0xbfb8aa3b, v131
	v_exp_f32_e32 v139, v139
	v_add_f32_e32 v138, 1.0, v138
	v_rcp_f32_e32 v138, v138
	v_add_f32_e32 v139, 1.0, v139
	v_rcp_f32_e32 v139, v139
	s_nop 0
	v_pk_mul_f32 v[130:131], v[130:131], v[138:139]
	v_mul_f32_e32 v138, 0xbfb8aa3b, v135
	v_exp_f32_e32 v138, v138
	v_mul_f32_e32 v139, 0xbfb8aa3b, v136
	v_exp_f32_e32 v139, v139
	v_add_f32_e32 v138, 1.0, v138
	v_rcp_f32_e32 v143, v138
	v_add_f32_e32 v139, 1.0, v139
	v_mul_f32_e32 v138, 0xbfb8aa3b, v128
	v_exp_f32_e32 v138, v138
	v_pk_mul_f32 v[134:135], v[134:135], v[142:143]
	v_rcp_f32_e32 v142, v139
	v_mul_f32_e32 v139, 0xbfb8aa3b, v129
	v_exp_f32_e32 v139, v139
	v_add_f32_e32 v138, 1.0, v138
	v_rcp_f32_e32 v138, v138
	v_add_f32_e32 v139, 1.0, v139
	v_rcp_f32_e32 v139, v139
	s_nop 0
	v_pk_mul_f32 v[138:139], v[128:129], v[138:139]
	v_mul_f32_e32 v128, 0xbfb8aa3b, v137
	v_exp_f32_e32 v128, v128
	v_cvt_pk_bf16_f32 v129, v138, v139
	v_add_f32_e32 v128, 1.0, v128
	v_rcp_f32_e32 v143, v128
	v_cvt_pk_bf16_f32 v128, v130, v131
	v_cvt_pk_bf16_f32 v130, v134, v135
	v_pk_mul_f32 v[136:137], v[136:137], v[142:143]
	s_nop 0
	v_cvt_pk_bf16_f32 v131, v136, v137
	global_store_dwordx4 v[132:133], v[128:131], off offset:256
	v_add_u32_e32 v132, 0x80, v166
	v_ashrrev_i32_e32 v133, 31, v132
	v_lshlrev_b64 v[128:129], 6, v[132:133]
	v_lshl_add_u64 v[128:129], v[160:161], 0, v[128:129]
	s_nop 0
	s_waitcnt lgkmcnt(0)
; __device__ __forceinline__ v4u pack8(const f32x4 a, const f32x4 b) { v4u w; w.x = cvt_pk_bf16(a[0], a[1]); w.y = cvt_pk_bf16(a[2], a[3]); w.z = cvt_pk_bf16(b[0], b[1]); w.w = cvt_pk_bf16(b[2], b[3]); return w; }
; __device__ __forceinline__ float silu_f(float x) { return x * __builtin_amdgcn_rcpf(1.f + __expf(-x)); }
;     __device__ __forceinline__ void operator()(const f32x4 (&acc)[2][2][4][2], const pg8::Unit& u, int wr, int wc, int fr, int fq) const {
;     ...
;         if (grp == 0) { WIN_LOOP( _Pragma("unroll") for (int i = 0; i < 4; ++i) { a[i] = silu_f(a[i]); b[i] = silu_f(b[i]); } *(v4u*)(QO + (size_t)row * DM + c) = pack8(a, b); ) }
;         else if (grp == 3) { WIN_LOOP( _Pragma("unroll") for (int i = 0; i < 4; ++i) { a[i] = silu_f(a[i]); b[i] = silu_f(b[i]); } *(v4u*)(GH + (size_t)row * 512 + c) = pack8(a, b); ) }
	s_nop 3
	s_nop 0
	s_nop 1
	s_waitcnt lgkmcnt(0)
	s_nop 1
	s_waitcnt lgkmcnt(0)
	s_nop 1
	v_mov_b32_e32 v134, v254
	v_lshlrev_b64 v[128:129], 10, v[132:133]
	v_lshl_add_u64 v[132:133], s[12:13], 0, v[128:129]
	v_lshl_add_u64 v[132:133], v[132:133], 0, v[192:193]
	v_pk_mul_f32 v[130:131], v[28:29], v[134:135] op_sel_hi:[1,0]
	v_pk_mul_f32 v[128:129], v[30:31], v[134:135] op_sel_hi:[1,0]
	v_pk_mul_f32 v[136:137], v[26:27], v[134:135] op_sel_hi:[1,0]
	v_pk_mul_f32 v[138:139], v[24:25], v[134:135] op_sel_hi:[1,0]
	v_mul_f32_e32 v135, 0xbfb8aa3b, v130
	v_exp_f32_e32 v135, v135
	s_nop 0
	v_add_f32_e32 v135, 1.0, v135
	v_rcp_f32_e32 v142, v135
	v_mul_f32_e32 v135, 0xbfb8aa3b, v138
	v_exp_f32_e32 v135, v135
	s_nop 0
	v_add_f32_e32 v135, 1.0, v135
	v_rcp_f32_e32 v144, v135
	v_mul_f32_e32 v135, 0xbfb8aa3b, v131
	v_exp_f32_e32 v135, v135
	s_nop 0
	v_add_f32_e32 v135, 1.0, v135
	v_rcp_f32_e32 v143, v135
	v_mul_f32_e32 v135, 0xbfb8aa3b, v139
	v_exp_f32_e32 v135, v135
	v_pk_mul_f32 v[130:131], v[130:131], v[142:143]
	v_add_f32_e32 v135, 1.0, v135
	v_rcp_f32_e32 v145, v135
	v_mul_f32_e32 v135, 0xbfb8aa3b, v128
	v_exp_f32_e32 v135, v135
	v_pk_mul_f32 v[138:139], v[138:139], v[144:145]
	v_add_f32_e32 v135, 1.0, v135
	v_rcp_f32_e32 v142, v135
	v_mul_f32_e32 v135, 0xbfb8aa3b, v136
	v_exp_f32_e32 v135, v135
	s_nop 0
	v_add_f32_e32 v135, 1.0, v135
	v_rcp_f32_e32 v144, v135
	v_mul_f32_e32 v135, 0xbfb8aa3b, v129
	v_exp_f32_e32 v135, v135
	s_nop 0
	v_add_f32_e32 v135, 1.0, v135
	v_rcp_f32_e32 v143, v135
	s_nop 0
	v_pk_mul_f32 v[142:143], v[128:129], v[142:143]
	v_mul_f32_e32 v128, 0xbfb8aa3b, v137
	v_exp_f32_e32 v128, v128
	v_cvt_pk_bf16_f32 v129, v142, v143
	v_add_f32_e32 v128, 1.0, v128
	v_rcp_f32_e32 v145, v128
	v_cvt_pk_bf16_f32 v128, v130, v131
	v_cvt_pk_bf16_f32 v130, v138, v139
	v_pk_mul_f32 v[136:137], v[136:137], v[144:145]
	s_nop 0
	v_cvt_pk_bf16_f32 v131, v136, v137
	global_store_dwordx4 v[132:133], v[128:131], off
	v_pk_mul_f32 v[136:137], v[90:91], v[134:135] op_sel_hi:[1,0]
	s_nop 0
	v_pk_mul_f32 v[128:129], v[94:95], v[134:135] op_sel_hi:[1,0]
	v_pk_mul_f32 v[130:131], v[92:93], v[134:135] op_sel_hi:[1,0]
	v_pk_mul_f32 v[134:135], v[88:89], v[134:135] op_sel_hi:[1,0]
	v_mul_f32_e32 v138, 0xbfb8aa3b, v130
	v_mul_f32_e32 v139, 0xbfb8aa3b, v134
	v_exp_f32_e32 v139, v139
	v_exp_f32_e32 v138, v138
	v_add_f32_e32 v139, 1.0, v139
	v_rcp_f32_e32 v142, v139
	v_mul_f32_e32 v139, 0xbfb8aa3b, v131
	v_exp_f32_e32 v139, v139
	v_add_f32_e32 v138, 1.0, v138
	v_rcp_f32_e32 v138, v138
	v_add_f32_e32 v139, 1.0, v139
	v_rcp_f32_e32 v139, v139
	s_nop 0
	v_pk_mul_f32 v[130:131], v[130:131], v[138:139]
	v_mul_f32_e32 v138, 0xbfb8aa3b, v135
	v_exp_f32_e32 v138, v138
	v_mul_f32_e32 v139, 0xbfb8aa3b, v136
	v_exp_f32_e32 v139, v139
	v_add_f32_e32 v138, 1.0, v138
	v_rcp_f32_e32 v143, v138
	v_add_f32_e32 v139, 1.0, v139
	v_mul_f32_e32 v138, 0xbfb8aa3b, v128
	v_exp_f32_e32 v138, v138
	v_pk_mul_f32 v[134:135], v[134:135], v[142:143]
	v_rcp_f32_e32 v142, v139
	v_mul_f32_e32 v139, 0xbfb8aa3b, v129
	v_exp_f32_e32 v139, v139
	v_add_f32_e32 v138, 1.0, v138
	v_rcp_f32_e32 v138, v138
	v_add_f32_e32 v139, 1.0, v139
	v_rcp_f32_e32 v139, v139
	s_nop 0
	v_pk_mul_f32 v[138:139], v[128:129], v[138:139]
	v_mul_f32_e32 v128, 0xbfb8aa3b, v137
	v_exp_f32_e32 v128, v128
	v_cvt_pk_bf16_f32 v129, v138, v139
	v_add_f32_e32 v128, 1.0, v128
	v_rcp_f32_e32 v143, v128
	v_cvt_pk_bf16_f32 v128, v130, v131
	v_cvt_pk_bf16_f32 v130, v134, v135
	v_pk_mul_f32 v[136:137], v[136:137], v[142:143]
	s_nop 0
	v_cvt_pk_bf16_f32 v131, v136, v137
	global_store_dwordx4 v[132:133], v[128:131], off offset:256
	v_add_u32_e32 v132, 0x90, v166
	v_ashrrev_i32_e32 v133, 31, v132
	v_lshlrev_b64 v[128:129], 6, v[132:133]
	v_lshl_add_u64 v[128:129], v[160:161], 0, v[128:129]
	s_nop 0
	s_waitcnt lgkmcnt(0)
	s_nop 3
	s_nop 0
	s_nop 1
	s_waitcnt lgkmcnt(0)
	s_nop 1
	s_waitcnt lgkmcnt(0)
	s_nop 1
	v_mov_b32_e32 v134, v240
	v_lshlrev_b64 v[128:129], 10, v[132:133]
	v_lshl_add_u64 v[132:133], s[12:13], 0, v[128:129]
	v_lshl_add_u64 v[132:133], v[132:133], 0, v[192:193]
	v_pk_mul_f32 v[130:131], v[20:21], v[134:135] op_sel_hi:[1,0]
	v_pk_mul_f32 v[128:129], v[22:23], v[134:135] op_sel_hi:[1,0]
	v_pk_mul_f32 v[136:137], v[18:19], v[134:135] op_sel_hi:[1,0]
	v_pk_mul_f32 v[138:139], v[16:17], v[134:135] op_sel_hi:[1,0]
	v_mul_f32_e32 v135, 0xbfb8aa3b, v130
	v_exp_f32_e32 v135, v135
	s_nop 0
	v_add_f32_e32 v135, 1.0, v135
	v_rcp_f32_e32 v142, v135
	v_mul_f32_e32 v135, 0xbfb8aa3b, v138
	v_exp_f32_e32 v135, v135
	s_nop 0
	v_add_f32_e32 v135, 1.0, v135
	v_rcp_f32_e32 v144, v135
	v_mul_f32_e32 v135, 0xbfb8aa3b, v131
	v_exp_f32_e32 v135, v135
	s_nop 0
	v_add_f32_e32 v135, 1.0, v135
	v_rcp_f32_e32 v143, v135
	v_mul_f32_e32 v135, 0xbfb8aa3b, v139
	v_exp_f32_e32 v135, v135
	v_pk_mul_f32 v[130:131], v[130:131], v[142:143]
	v_add_f32_e32 v135, 1.0, v135
	v_rcp_f32_e32 v145, v135
	v_mul_f32_e32 v135, 0xbfb8aa3b, v128
	v_exp_f32_e32 v135, v135
	v_pk_mul_f32 v[138:139], v[138:139], v[144:145]
	v_add_f32_e32 v135, 1.0, v135
	v_rcp_f32_e32 v142, v135
	v_mul_f32_e32 v135, 0xbfb8aa3b, v136
	v_exp_f32_e32 v135, v135
	s_nop 0
	v_add_f32_e32 v135, 1.0, v135
	v_rcp_f32_e32 v144, v135
	v_mul_f32_e32 v135, 0xbfb8aa3b, v129
	v_exp_f32_e32 v135, v135
	s_nop 0
	v_add_f32_e32 v135, 1.0, v135
	v_rcp_f32_e32 v143, v135
	s_nop 0
	v_pk_mul_f32 v[142:143], v[128:129], v[142:143]
	v_mul_f32_e32 v128, 0xbfb8aa3b, v137
	v_exp_f32_e32 v128, v128
	v_cvt_pk_bf16_f32 v129, v142, v143
	v_add_f32_e32 v128, 1.0, v128
	v_rcp_f32_e32 v145, v128
	v_cvt_pk_bf16_f32 v128, v130, v131
	v_cvt_pk_bf16_f32 v130, v138, v139
	v_pk_mul_f32 v[136:137], v[136:137], v[144:145]
	s_nop 0
; __device__ __forceinline__ v4u pack8(const f32x4 a, const f32x4 b) { v4u w; w.x = cvt_pk_bf16(a[0], a[1]); w.y = cvt_pk_bf16(a[2], a[3]); w.z = cvt_pk_bf16(b[0], b[1]); w.w = cvt_pk_bf16(b[2], b[3]); return w; }
; __device__ __forceinline__ float silu_f(float x) { return x * __builtin_amdgcn_rcpf(1.f + __expf(-x)); }
;     __device__ __forceinline__ void operator()(const f32x4 (&acc)[2][2][4][2], const pg8::Unit& u, int wr, int wc, int fr, int fq) const {
;     ...
;         if (grp == 0) { WIN_LOOP( _Pragma("unroll") for (int i = 0; i < 4; ++i) { a[i] = silu_f(a[i]); b[i] = silu_f(b[i]); } *(v4u*)(QO + (size_t)row * DM + c) = pack8(a, b); ) }
;         else if (grp == 3) { WIN_LOOP( _Pragma("unroll") for (int i = 0; i < 4; ++i) { a[i] = silu_f(a[i]); b[i] = silu_f(b[i]); } *(v4u*)(GH + (size_t)row * 512 + c) = pack8(a, b); ) }
	v_cvt_pk_bf16_f32 v131, v136, v137
	global_store_dwordx4 v[132:133], v[128:131], off
	v_pk_mul_f32 v[136:137], v[82:83], v[134:135] op_sel_hi:[1,0]
	s_nop 0
	v_pk_mul_f32 v[128:129], v[86:87], v[134:135] op_sel_hi:[1,0]
	v_pk_mul_f32 v[130:131], v[84:85], v[134:135] op_sel_hi:[1,0]
	v_pk_mul_f32 v[134:135], v[80:81], v[134:135] op_sel_hi:[1,0]
	v_mul_f32_e32 v138, 0xbfb8aa3b, v130
	v_mul_f32_e32 v139, 0xbfb8aa3b, v134
	v_exp_f32_e32 v139, v139
	v_exp_f32_e32 v138, v138
	v_add_f32_e32 v139, 1.0, v139
	v_rcp_f32_e32 v142, v139
	v_mul_f32_e32 v139, 0xbfb8aa3b, v131
	v_exp_f32_e32 v139, v139
	v_add_f32_e32 v138, 1.0, v138
	v_rcp_f32_e32 v138, v138
	v_add_f32_e32 v139, 1.0, v139
	v_rcp_f32_e32 v139, v139
	s_nop 0
	v_pk_mul_f32 v[130:131], v[130:131], v[138:139]
	v_mul_f32_e32 v138, 0xbfb8aa3b, v135
	v_exp_f32_e32 v138, v138
	v_mul_f32_e32 v139, 0xbfb8aa3b, v136
	v_exp_f32_e32 v139, v139
	v_add_f32_e32 v138, 1.0, v138
	v_rcp_f32_e32 v143, v138
	v_add_f32_e32 v139, 1.0, v139
	v_mul_f32_e32 v138, 0xbfb8aa3b, v128
	v_exp_f32_e32 v138, v138
	v_pk_mul_f32 v[134:135], v[134:135], v[142:143]
	v_rcp_f32_e32 v142, v139
	v_mul_f32_e32 v139, 0xbfb8aa3b, v129
	v_exp_f32_e32 v139, v139
	v_add_f32_e32 v138, 1.0, v138
	v_rcp_f32_e32 v138, v138
	v_add_f32_e32 v139, 1.0, v139
	v_rcp_f32_e32 v139, v139
	s_nop 0
	v_pk_mul_f32 v[138:139], v[128:129], v[138:139]
	v_mul_f32_e32 v128, 0xbfb8aa3b, v137
	v_exp_f32_e32 v128, v128
	v_cvt_pk_bf16_f32 v129, v138, v139
	v_add_f32_e32 v128, 1.0, v128
	v_rcp_f32_e32 v143, v128
	v_cvt_pk_bf16_f32 v128, v130, v131
	v_cvt_pk_bf16_f32 v130, v134, v135
	v_pk_mul_f32 v[136:137], v[136:137], v[142:143]
	s_nop 0
	v_cvt_pk_bf16_f32 v131, v136, v137
	global_store_dwordx4 v[132:133], v[128:131], off offset:256
	v_add_u32_e32 v132, 0xa0, v166
	v_ashrrev_i32_e32 v133, 31, v132
	v_lshlrev_b64 v[128:129], 6, v[132:133]
	v_lshl_add_u64 v[128:129], v[160:161], 0, v[128:129]
	s_nop 0
	s_waitcnt lgkmcnt(0)
	s_nop 3
	s_nop 0
	s_nop 1
	s_waitcnt lgkmcnt(0)
	s_nop 1
	s_waitcnt lgkmcnt(0)
	s_nop 1
	v_mov_b32_e32 v134, v241
	v_lshlrev_b64 v[128:129], 10, v[132:133]
	v_lshl_add_u64 v[132:133], s[12:13], 0, v[128:129]
	v_lshl_add_u64 v[132:133], v[132:133], 0, v[192:193]
	v_pk_mul_f32 v[130:131], v[12:13], v[134:135] op_sel_hi:[1,0]
	v_pk_mul_f32 v[128:129], v[14:15], v[134:135] op_sel_hi:[1,0]
	v_pk_mul_f32 v[136:137], v[10:11], v[134:135] op_sel_hi:[1,0]
	v_pk_mul_f32 v[138:139], v[8:9], v[134:135] op_sel_hi:[1,0]
	v_mul_f32_e32 v135, 0xbfb8aa3b, v130
	v_exp_f32_e32 v135, v135
	s_nop 0
	v_add_f32_e32 v135, 1.0, v135
	v_rcp_f32_e32 v142, v135
	v_mul_f32_e32 v135, 0xbfb8aa3b, v138
	v_exp_f32_e32 v135, v135
	s_nop 0
	v_add_f32_e32 v135, 1.0, v135
	v_rcp_f32_e32 v144, v135
	v_mul_f32_e32 v135, 0xbfb8aa3b, v131
	v_exp_f32_e32 v135, v135
	s_nop 0
	v_add_f32_e32 v135, 1.0, v135
	v_rcp_f32_e32 v143, v135
	v_mul_f32_e32 v135, 0xbfb8aa3b, v139
	v_exp_f32_e32 v135, v135
	v_pk_mul_f32 v[130:131], v[130:131], v[142:143]
	v_add_f32_e32 v135, 1.0, v135
	v_rcp_f32_e32 v145, v135
	v_mul_f32_e32 v135, 0xbfb8aa3b, v128
	v_exp_f32_e32 v135, v135
	v_pk_mul_f32 v[138:139], v[138:139], v[144:145]
	v_add_f32_e32 v135, 1.0, v135
	v_rcp_f32_e32 v142, v135
	v_mul_f32_e32 v135, 0xbfb8aa3b, v136
	v_exp_f32_e32 v135, v135
	s_nop 0
	v_add_f32_e32 v135, 1.0, v135
	v_rcp_f32_e32 v144, v135
	v_mul_f32_e32 v135, 0xbfb8aa3b, v129
	v_exp_f32_e32 v135, v135
	s_nop 0
	v_add_f32_e32 v135, 1.0, v135
	v_rcp_f32_e32 v143, v135
	s_nop 0
	v_pk_mul_f32 v[142:143], v[128:129], v[142:143]
	v_mul_f32_e32 v128, 0xbfb8aa3b, v137
	v_exp_f32_e32 v128, v128
	v_cvt_pk_bf16_f32 v129, v142, v143
	v_add_f32_e32 v128, 1.0, v128
	v_rcp_f32_e32 v145, v128
	v_cvt_pk_bf16_f32 v128, v130, v131
	v_cvt_pk_bf16_f32 v130, v138, v139
	v_pk_mul_f32 v[136:137], v[136:137], v[144:145]
	s_nop 0
	v_cvt_pk_bf16_f32 v131, v136, v137
	global_store_dwordx4 v[132:133], v[128:131], off
	v_pk_mul_f32 v[136:137], v[74:75], v[134:135] op_sel_hi:[1,0]
	s_nop 0
	v_pk_mul_f32 v[128:129], v[78:79], v[134:135] op_sel_hi:[1,0]
	v_pk_mul_f32 v[130:131], v[76:77], v[134:135] op_sel_hi:[1,0]
	v_pk_mul_f32 v[134:135], v[72:73], v[134:135] op_sel_hi:[1,0]
	v_mul_f32_e32 v138, 0xbfb8aa3b, v130
	v_mul_f32_e32 v139, 0xbfb8aa3b, v134
	v_exp_f32_e32 v139, v139
	v_exp_f32_e32 v138, v138
	v_add_f32_e32 v139, 1.0, v139
	v_rcp_f32_e32 v142, v139
	v_mul_f32_e32 v139, 0xbfb8aa3b, v131
	v_exp_f32_e32 v139, v139
	v_add_f32_e32 v138, 1.0, v138
	v_rcp_f32_e32 v138, v138
	v_add_f32_e32 v139, 1.0, v139
	v_rcp_f32_e32 v139, v139
	s_nop 0
	v_pk_mul_f32 v[130:131], v[130:131], v[138:139]
	v_mul_f32_e32 v138, 0xbfb8aa3b, v135
	v_exp_f32_e32 v138, v138
	v_mul_f32_e32 v139, 0xbfb8aa3b, v136
	v_exp_f32_e32 v139, v139
	v_add_f32_e32 v138, 1.0, v138
	v_rcp_f32_e32 v143, v138
	v_add_f32_e32 v139, 1.0, v139
	v_mul_f32_e32 v138, 0xbfb8aa3b, v128
	v_exp_f32_e32 v138, v138
	v_pk_mul_f32 v[134:135], v[134:135], v[142:143]
	v_rcp_f32_e32 v142, v139
	v_mul_f32_e32 v139, 0xbfb8aa3b, v129
	v_exp_f32_e32 v139, v139
	v_add_f32_e32 v138, 1.0, v138
	v_rcp_f32_e32 v138, v138
	v_add_f32_e32 v139, 1.0, v139
	v_rcp_f32_e32 v139, v139
	s_nop 0
	v_pk_mul_f32 v[138:139], v[128:129], v[138:139]
	v_mul_f32_e32 v128, 0xbfb8aa3b, v137
	v_exp_f32_e32 v128, v128
	v_cvt_pk_bf16_f32 v129, v138, v139
	v_add_f32_e32 v128, 1.0, v128
	v_rcp_f32_e32 v143, v128
	v_cvt_pk_bf16_f32 v128, v130, v131
	v_cvt_pk_bf16_f32 v130, v134, v135
	v_pk_mul_f32 v[136:137], v[136:137], v[142:143]
	s_nop 0
	v_cvt_pk_bf16_f32 v131, v136, v137
	global_store_dwordx4 v[132:133], v[128:131], off offset:256
	v_add_u32_e32 v132, 0xb0, v166
	v_ashrrev_i32_e32 v133, 31, v132
	v_lshlrev_b64 v[128:129], 6, v[132:133]
	v_lshl_add_u64 v[128:129], v[160:161], 0, v[128:129]
	s_nop 0
	s_waitcnt lgkmcnt(0)
; __device__ __forceinline__ v4u pack8(const f32x4 a, const f32x4 b) { v4u w; w.x = cvt_pk_bf16(a[0], a[1]); w.y = cvt_pk_bf16(a[2], a[3]); w.z = cvt_pk_bf16(b[0], b[1]); w.w = cvt_pk_bf16(b[2], b[3]); return w; }
; __device__ __forceinline__ float silu_f(float x) { return x * __builtin_amdgcn_rcpf(1.f + __expf(-x)); }
;     __device__ __forceinline__ void operator()(const f32x4 (&acc)[2][2][4][2], const pg8::Unit& u, int wr, int wc, int fr, int fq) const {
;     ...
;         if (grp == 0) { WIN_LOOP( _Pragma("unroll") for (int i = 0; i < 4; ++i) { a[i] = silu_f(a[i]); b[i] = silu_f(b[i]); } *(v4u*)(QO + (size_t)row * DM + c) = pack8(a, b); ) }
;         else if (grp == 3) { WIN_LOOP( _Pragma("unroll") for (int i = 0; i < 4; ++i) { a[i] = silu_f(a[i]); b[i] = silu_f(b[i]); } *(v4u*)(GH + (size_t)row * 512 + c) = pack8(a, b); ) }
	s_nop 3
	s_nop 0
	s_nop 1
	s_waitcnt lgkmcnt(0)
	s_nop 1
	s_waitcnt lgkmcnt(0)
	s_nop 1
	v_mov_b32_e32 v134, v245
	v_lshlrev_b64 v[128:129], 10, v[132:133]
	v_lshl_add_u64 v[132:133], s[12:13], 0, v[128:129]
	v_lshl_add_u64 v[132:133], v[132:133], 0, v[192:193]
	v_pk_mul_f32 v[130:131], v[4:5], v[134:135] op_sel_hi:[1,0]
	v_pk_mul_f32 v[128:129], v[6:7], v[134:135] op_sel_hi:[1,0]
	v_pk_mul_f32 v[136:137], v[2:3], v[134:135] op_sel_hi:[1,0]
	v_pk_mul_f32 v[138:139], v[0:1], v[134:135] op_sel_hi:[1,0]
	v_mul_f32_e32 v135, 0xbfb8aa3b, v130
	v_exp_f32_e32 v135, v135
	s_nop 0
	v_add_f32_e32 v135, 1.0, v135
	v_rcp_f32_e32 v140, v135
	v_mul_f32_e32 v135, 0xbfb8aa3b, v138
	v_exp_f32_e32 v135, v135
	s_nop 0
	v_add_f32_e32 v135, 1.0, v135
	v_rcp_f32_e32 v142, v135
	v_mul_f32_e32 v135, 0xbfb8aa3b, v131
	v_exp_f32_e32 v135, v135
	s_nop 0
	v_add_f32_e32 v135, 1.0, v135
	v_rcp_f32_e32 v141, v135
	v_mul_f32_e32 v135, 0xbfb8aa3b, v139
	v_exp_f32_e32 v135, v135
	v_pk_mul_f32 v[130:131], v[130:131], v[140:141]
	v_add_f32_e32 v135, 1.0, v135
	v_rcp_f32_e32 v143, v135
	v_mul_f32_e32 v135, 0xbfb8aa3b, v128
	v_exp_f32_e32 v135, v135
	v_pk_mul_f32 v[138:139], v[138:139], v[142:143]
	v_add_f32_e32 v135, 1.0, v135
	v_rcp_f32_e32 v140, v135
	v_mul_f32_e32 v135, 0xbfb8aa3b, v136
	v_exp_f32_e32 v135, v135
	s_nop 0
	v_add_f32_e32 v135, 1.0, v135
	v_rcp_f32_e32 v142, v135
	v_mul_f32_e32 v135, 0xbfb8aa3b, v129
	v_exp_f32_e32 v135, v135
	s_nop 0
	v_add_f32_e32 v135, 1.0, v135
	v_rcp_f32_e32 v141, v135
	s_nop 0
	v_pk_mul_f32 v[140:141], v[128:129], v[140:141]
	v_mul_f32_e32 v128, 0xbfb8aa3b, v137
	v_exp_f32_e32 v128, v128
	v_cvt_pk_bf16_f32 v129, v140, v141
	v_add_f32_e32 v128, 1.0, v128
	v_rcp_f32_e32 v143, v128
	v_cvt_pk_bf16_f32 v128, v130, v131
	v_cvt_pk_bf16_f32 v130, v138, v139
	v_pk_mul_f32 v[136:137], v[136:137], v[142:143]
	s_nop 0
	v_cvt_pk_bf16_f32 v131, v136, v137
	global_store_dwordx4 v[132:133], v[128:131], off
	v_pk_mul_f32 v[136:137], v[66:67], v[134:135] op_sel_hi:[1,0]
	s_nop 0
	v_pk_mul_f32 v[128:129], v[70:71], v[134:135] op_sel_hi:[1,0]
	v_pk_mul_f32 v[130:131], v[68:69], v[134:135] op_sel_hi:[1,0]
	v_pk_mul_f32 v[134:135], v[64:65], v[134:135] op_sel_hi:[1,0]
	v_mul_f32_e32 v138, 0xbfb8aa3b, v130
	v_mul_f32_e32 v139, 0xbfb8aa3b, v134
	v_exp_f32_e32 v139, v139
	v_exp_f32_e32 v138, v138
	v_add_f32_e32 v139, 1.0, v139
	v_rcp_f32_e32 v140, v139
	v_mul_f32_e32 v139, 0xbfb8aa3b, v131
	v_exp_f32_e32 v139, v139
	v_add_f32_e32 v138, 1.0, v138
	v_rcp_f32_e32 v138, v138
	v_add_f32_e32 v139, 1.0, v139
	v_rcp_f32_e32 v139, v139
	s_nop 0
	v_pk_mul_f32 v[130:131], v[130:131], v[138:139]
	v_mul_f32_e32 v138, 0xbfb8aa3b, v135
	v_exp_f32_e32 v138, v138
	v_mul_f32_e32 v139, 0xbfb8aa3b, v136
	v_exp_f32_e32 v139, v139
	v_add_f32_e32 v138, 1.0, v138
	v_rcp_f32_e32 v141, v138
	v_add_f32_e32 v139, 1.0, v139
	v_mul_f32_e32 v138, 0xbfb8aa3b, v128
	v_exp_f32_e32 v138, v138
	v_pk_mul_f32 v[134:135], v[134:135], v[140:141]
	v_rcp_f32_e32 v140, v139
	v_mul_f32_e32 v139, 0xbfb8aa3b, v129
	v_exp_f32_e32 v139, v139
	v_add_f32_e32 v138, 1.0, v138
	v_rcp_f32_e32 v138, v138
	v_add_f32_e32 v139, 1.0, v139
	v_rcp_f32_e32 v139, v139
	s_nop 0
	v_pk_mul_f32 v[138:139], v[128:129], v[138:139]
	v_mul_f32_e32 v128, 0xbfb8aa3b, v137
	v_exp_f32_e32 v128, v128
	v_cvt_pk_bf16_f32 v129, v138, v139
	v_add_f32_e32 v128, 1.0, v128
	v_rcp_f32_e32 v141, v128
	v_cvt_pk_bf16_f32 v128, v130, v131
	v_cvt_pk_bf16_f32 v130, v134, v135
	v_pk_mul_f32 v[136:137], v[136:137], v[140:141]
	s_nop 0
	v_cvt_pk_bf16_f32 v131, v136, v137
	global_store_dwordx4 v[132:133], v[128:131], off offset:256

; __device__ __forceinline__ v4u pack8(const f32x4 a, const f32x4 b) { v4u w; w.x = cvt_pk_bf16(a[0], a[1]); w.y = cvt_pk_bf16(a[2], a[3]); w.z = cvt_pk_bf16(b[0], b[1]); w.w = cvt_pk_bf16(b[2], b[3]); return w; }
;     __device__ __forceinline__ void operator()(const f32x4 (&acc)[2][2][4][2], const pg8::Unit& u, int wr, int wc, int fr, int fq) const {
;     ...
;         else if (grp == 2) { WIN_LOOP( *(v4u*)(VH + (size_t)row * 512 + c) = pack8(a, b); ) }
;         else if (grp == 4) { WIN_LOOP( *(v4u*)(QO + (size_t)row * DM + 512 + c) = pack8(a * C2Q, b * C2Q); ) }
;         else if (grp == 5) { WIN_LOOP( *(v4u*)(FK + (size_t)row * 512 + c) = pack8(a, b); ) }
;         else { WIN_LOOP( *(v4u*)(FV + (size_t)row * 512 + c) = pack8(a, b); ) }
.LBB0_407:
	s_and_b64 vcc, exec, s[12:13]
	s_cbranch_vccz .LBB0_412
	s_cmp_gt_i32 s14, 1
	s_mov_b64 s[8:9], -1
	s_cbranch_scc0 .LBB0_410
	v_and_b32_e32 v129, 64, v215
	v_xor_b32_e32 v128, 16, v215
	v_add_u32_e32 v129, 64, v129
	v_cmp_lt_i32_e32 vcc, v128, v129
	v_ashrrev_i32_e32 v167, 31, v166
	v_readlane_b32 s8, v255, 37
	v_cndmask_b32_e32 v128, v215, v128, vcc
	v_lshlrev_b32_e32 v130, 2, v128
	v_xor_b32_e32 v128, 32, v215
	v_cmp_lt_i32_e32 vcc, v128, v129
	v_readlane_b32 s9, v255, 38
	v_lshlrev_b32_e32 v192, 1, v176
	v_cndmask_b32_e32 v128, v215, v128, vcc
	v_lshlrev_b32_e32 v131, 2, v128
	v_lshlrev_b64 v[128:129], 6, v[166:167]
	v_lshl_add_u64 v[128:129], v[160:161], 0, v[128:129]
	s_nop 0
	s_waitcnt lgkmcnt(0)
	s_nop 3
	v_lshlrev_b64 v[132:133], 10, v[166:167]
	s_nop 1
	v_lshl_add_u64 v[136:137], s[8:9], 0, v[132:133]
	v_lshl_add_u64 v[136:137], v[136:137], 0, v[192:193]
	s_waitcnt lgkmcnt(0)
	s_nop 1
	s_waitcnt lgkmcnt(0)
	s_nop 1
	v_mov_b32_e32 v128, v250
	s_nop 0
	v_pk_mul_f32 v[134:135], v[62:63], v[128:129] op_sel_hi:[1,0]
	v_pk_mul_f32 v[132:133], v[60:61], v[128:129] op_sel_hi:[1,0]
	v_pk_mul_f32 v[138:139], v[58:59], v[128:129] op_sel_hi:[1,0]
	v_pk_mul_f32 v[140:141], v[56:57], v[128:129] op_sel_hi:[1,0]
	v_cvt_pk_bf16_f32 v132, v132, v133
	v_cvt_pk_bf16_f32 v133, v134, v135
	v_cvt_pk_bf16_f32 v134, v140, v141
	v_cvt_pk_bf16_f32 v135, v138, v139
	global_store_dwordx4 v[136:137], v[132:135], off
	v_pk_mul_f32 v[138:139], v[122:123], v[128:129] op_sel_hi:[1,0]
	s_nop 0
	v_pk_mul_f32 v[134:135], v[126:127], v[128:129] op_sel_hi:[1,0]
	v_pk_mul_f32 v[132:133], v[124:125], v[128:129] op_sel_hi:[1,0]
	v_pk_mul_f32 v[128:129], v[120:121], v[128:129] op_sel_hi:[1,0]
	v_cvt_pk_bf16_f32 v132, v132, v133
	v_cvt_pk_bf16_f32 v133, v134, v135
	v_cvt_pk_bf16_f32 v134, v128, v129
	v_or_b32_e32 v128, 16, v166
	v_cvt_pk_bf16_f32 v135, v138, v139
	v_ashrrev_i32_e32 v129, 31, v128
	global_store_dwordx4 v[136:137], v[132:135], off offset:256
	s_nop 1
	v_lshlrev_b64 v[132:133], 6, v[128:129]
	v_lshl_add_u64 v[132:133], v[160:161], 0, v[132:133]
	s_nop 0
	v_lshlrev_b64 v[128:129], 10, v[128:129]
	v_lshl_add_u64 v[128:129], s[8:9], 0, v[128:129]
	v_lshl_add_u64 v[128:129], v[128:129], 0, v[192:193]
	s_waitcnt lgkmcnt(0)
	s_nop 3
	s_nop 0
	s_nop 1
	s_waitcnt lgkmcnt(0)
	s_nop 1
	s_waitcnt lgkmcnt(0)
	s_nop 1
	v_mov_b32_e32 v136, v251
	s_nop 0
	v_pk_mul_f32 v[134:135], v[54:55], v[136:137] op_sel_hi:[1,0]
	v_pk_mul_f32 v[132:133], v[52:53], v[136:137] op_sel_hi:[1,0]
	v_pk_mul_f32 v[138:139], v[50:51], v[136:137] op_sel_hi:[1,0]
	v_pk_mul_f32 v[140:141], v[48:49], v[136:137] op_sel_hi:[1,0]
	v_cvt_pk_bf16_f32 v132, v132, v133
	v_cvt_pk_bf16_f32 v133, v134, v135
	v_cvt_pk_bf16_f32 v134, v140, v141
	v_cvt_pk_bf16_f32 v135, v138, v139
	global_store_dwordx4 v[128:129], v[132:135], off
	v_pk_mul_f32 v[138:139], v[114:115], v[136:137] op_sel_hi:[1,0]
	s_nop 0
	v_pk_mul_f32 v[134:135], v[118:119], v[136:137] op_sel_hi:[1,0]
	v_pk_mul_f32 v[132:133], v[116:117], v[136:137] op_sel_hi:[1,0]
	v_pk_mul_f32 v[136:137], v[112:113], v[136:137] op_sel_hi:[1,0]
	v_cvt_pk_bf16_f32 v132, v132, v133
	v_cvt_pk_bf16_f32 v133, v134, v135
	v_cvt_pk_bf16_f32 v134, v136, v137
	v_cvt_pk_bf16_f32 v135, v138, v139
	global_store_dwordx4 v[128:129], v[132:135], off offset:256
	v_or_b32_e32 v128, 32, v166
	v_ashrrev_i32_e32 v129, 31, v128
	v_lshlrev_b64 v[132:133], 6, v[128:129]
	v_lshl_add_u64 v[132:133], v[160:161], 0, v[132:133]
	s_nop 0
	v_lshlrev_b64 v[128:129], 10, v[128:129]
	v_lshl_add_u64 v[128:129], s[8:9], 0, v[128:129]
	v_lshl_add_u64 v[128:129], v[128:129], 0, v[192:193]
	s_waitcnt lgkmcnt(0)
	s_nop 3
	s_nop 0
	s_nop 1
	s_waitcnt lgkmcnt(0)
	s_nop 1
	s_waitcnt lgkmcnt(0)
	s_nop 1
	v_mov_b32_e32 v136, v252
	s_nop 0
	v_pk_mul_f32 v[134:135], v[46:47], v[136:137] op_sel_hi:[1,0]
	v_pk_mul_f32 v[132:133], v[44:45], v[136:137] op_sel_hi:[1,0]
	v_pk_mul_f32 v[138:139], v[42:43], v[136:137] op_sel_hi:[1,0]
	v_pk_mul_f32 v[140:141], v[40:41], v[136:137] op_sel_hi:[1,0]
	v_cvt_pk_bf16_f32 v132, v132, v133
	v_cvt_pk_bf16_f32 v133, v134, v135
	v_cvt_pk_bf16_f32 v134, v140, v141
	v_cvt_pk_bf16_f32 v135, v138, v139
	global_store_dwordx4 v[128:129], v[132:135], off
	v_pk_mul_f32 v[138:139], v[106:107], v[136:137] op_sel_hi:[1,0]
	s_nop 0
	v_pk_mul_f32 v[134:135], v[110:111], v[136:137] op_sel_hi:[1,0]
	v_pk_mul_f32 v[132:133], v[108:109], v[136:137] op_sel_hi:[1,0]
	v_pk_mul_f32 v[136:137], v[104:105], v[136:137] op_sel_hi:[1,0]
	v_cvt_pk_bf16_f32 v132, v132, v133
	v_cvt_pk_bf16_f32 v133, v134, v135
	v_cvt_pk_bf16_f32 v134, v136, v137
	v_cvt_pk_bf16_f32 v135, v138, v139
	global_store_dwordx4 v[128:129], v[132:135], off offset:256
	v_or_b32_e32 v128, 48, v166
	v_ashrrev_i32_e32 v129, 31, v128
	v_lshlrev_b64 v[132:133], 6, v[128:129]
	v_lshl_add_u64 v[132:133], v[160:161], 0, v[132:133]
	s_nop 0
	v_lshlrev_b64 v[128:129], 10, v[128:129]
	v_lshl_add_u64 v[128:129], s[8:9], 0, v[128:129]
	v_lshl_add_u64 v[128:129], v[128:129], 0, v[192:193]
	s_waitcnt lgkmcnt(0)
	s_nop 3
	s_nop 0
	s_nop 1
	s_waitcnt lgkmcnt(0)
	s_nop 1
	s_waitcnt lgkmcnt(0)
; __device__ __forceinline__ v4u pack8(const f32x4 a, const f32x4 b) { v4u w; w.x = cvt_pk_bf16(a[0], a[1]); w.y = cvt_pk_bf16(a[2], a[3]); w.z = cvt_pk_bf16(b[0], b[1]); w.w = cvt_pk_bf16(b[2], b[3]); return w; }
;     __device__ __forceinline__ void operator()(const f32x4 (&acc)[2][2][4][2], const pg8::Unit& u, int wr, int wc, int fr, int fq) const {
;     ...
;         else if (grp == 2) { WIN_LOOP( *(v4u*)(VH + (size_t)row * 512 + c) = pack8(a, b); ) }
;         else if (grp == 4) { WIN_LOOP( *(v4u*)(QO + (size_t)row * DM + 512 + c) = pack8(a * C2Q, b * C2Q); ) }
;         else if (grp == 5) { WIN_LOOP( *(v4u*)(FK + (size_t)row * 512 + c) = pack8(a, b); ) }
;         else { WIN_LOOP( *(v4u*)(FV + (size_t)row * 512 + c) = pack8(a, b); ) }
	s_nop 1
	v_mov_b32_e32 v136, v253
	s_nop 0
	v_pk_mul_f32 v[134:135], v[38:39], v[136:137] op_sel_hi:[1,0]
	v_pk_mul_f32 v[132:133], v[36:37], v[136:137] op_sel_hi:[1,0]
	v_pk_mul_f32 v[138:139], v[34:35], v[136:137] op_sel_hi:[1,0]
	v_pk_mul_f32 v[140:141], v[32:33], v[136:137] op_sel_hi:[1,0]
	v_cvt_pk_bf16_f32 v132, v132, v133
	v_cvt_pk_bf16_f32 v133, v134, v135
	v_cvt_pk_bf16_f32 v134, v140, v141
	v_cvt_pk_bf16_f32 v135, v138, v139
	global_store_dwordx4 v[128:129], v[132:135], off
	v_pk_mul_f32 v[138:139], v[98:99], v[136:137] op_sel_hi:[1,0]
	s_nop 0
	v_pk_mul_f32 v[134:135], v[102:103], v[136:137] op_sel_hi:[1,0]
	v_pk_mul_f32 v[132:133], v[100:101], v[136:137] op_sel_hi:[1,0]
	v_pk_mul_f32 v[136:137], v[96:97], v[136:137] op_sel_hi:[1,0]
	v_cvt_pk_bf16_f32 v132, v132, v133
	v_cvt_pk_bf16_f32 v133, v134, v135
	v_cvt_pk_bf16_f32 v134, v136, v137
	v_cvt_pk_bf16_f32 v135, v138, v139
	global_store_dwordx4 v[128:129], v[132:135], off offset:256
	v_add_u32_e32 v128, 0x80, v166
	v_ashrrev_i32_e32 v129, 31, v128
	v_lshlrev_b64 v[132:133], 6, v[128:129]
	v_lshl_add_u64 v[132:133], v[160:161], 0, v[132:133]
	s_nop 0
	v_lshlrev_b64 v[128:129], 10, v[128:129]
	v_lshl_add_u64 v[128:129], s[8:9], 0, v[128:129]
	v_lshl_add_u64 v[128:129], v[128:129], 0, v[192:193]
	s_waitcnt lgkmcnt(0)
	s_nop 3
	s_nop 0
	s_nop 1
	s_waitcnt lgkmcnt(0)
	s_nop 1
	s_waitcnt lgkmcnt(0)
	s_nop 1
	v_mov_b32_e32 v136, v254
	s_nop 0
	v_pk_mul_f32 v[134:135], v[30:31], v[136:137] op_sel_hi:[1,0]
	v_pk_mul_f32 v[132:133], v[28:29], v[136:137] op_sel_hi:[1,0]
	v_pk_mul_f32 v[138:139], v[26:27], v[136:137] op_sel_hi:[1,0]
	v_pk_mul_f32 v[140:141], v[24:25], v[136:137] op_sel_hi:[1,0]
	v_cvt_pk_bf16_f32 v132, v132, v133
	v_cvt_pk_bf16_f32 v133, v134, v135
	v_cvt_pk_bf16_f32 v134, v140, v141
	v_cvt_pk_bf16_f32 v135, v138, v139
	global_store_dwordx4 v[128:129], v[132:135], off
	v_pk_mul_f32 v[138:139], v[90:91], v[136:137] op_sel_hi:[1,0]
	s_nop 0
	v_pk_mul_f32 v[134:135], v[94:95], v[136:137] op_sel_hi:[1,0]
	v_pk_mul_f32 v[132:133], v[92:93], v[136:137] op_sel_hi:[1,0]
	v_pk_mul_f32 v[136:137], v[88:89], v[136:137] op_sel_hi:[1,0]
	v_cvt_pk_bf16_f32 v132, v132, v133
	v_cvt_pk_bf16_f32 v133, v134, v135
	v_cvt_pk_bf16_f32 v134, v136, v137
	v_cvt_pk_bf16_f32 v135, v138, v139
	global_store_dwordx4 v[128:129], v[132:135], off offset:256
	v_add_u32_e32 v128, 0x90, v166
	v_ashrrev_i32_e32 v129, 31, v128
	v_lshlrev_b64 v[132:133], 6, v[128:129]
	v_lshl_add_u64 v[132:133], v[160:161], 0, v[132:133]
	s_nop 0
	v_lshlrev_b64 v[128:129], 10, v[128:129]
	v_lshl_add_u64 v[128:129], s[8:9], 0, v[128:129]
	v_lshl_add_u64 v[128:129], v[128:129], 0, v[192:193]
	s_waitcnt lgkmcnt(0)
	s_nop 3
	s_nop 0
	s_nop 1
	s_waitcnt lgkmcnt(0)
	s_nop 1
	s_waitcnt lgkmcnt(0)
	s_nop 1
	v_mov_b32_e32 v136, v240
	s_nop 0
	v_pk_mul_f32 v[134:135], v[22:23], v[136:137] op_sel_hi:[1,0]
	v_pk_mul_f32 v[132:133], v[20:21], v[136:137] op_sel_hi:[1,0]
	v_pk_mul_f32 v[138:139], v[18:19], v[136:137] op_sel_hi:[1,0]
	v_pk_mul_f32 v[140:141], v[16:17], v[136:137] op_sel_hi:[1,0]
	v_cvt_pk_bf16_f32 v132, v132, v133
	v_cvt_pk_bf16_f32 v133, v134, v135
	v_cvt_pk_bf16_f32 v134, v140, v141
	v_cvt_pk_bf16_f32 v135, v138, v139
	global_store_dwordx4 v[128:129], v[132:135], off
	v_pk_mul_f32 v[138:139], v[82:83], v[136:137] op_sel_hi:[1,0]
	s_nop 0
	v_pk_mul_f32 v[134:135], v[86:87], v[136:137] op_sel_hi:[1,0]
	v_pk_mul_f32 v[132:133], v[84:85], v[136:137] op_sel_hi:[1,0]
	v_pk_mul_f32 v[136:137], v[80:81], v[136:137] op_sel_hi:[1,0]
	v_cvt_pk_bf16_f32 v132, v132, v133
	v_cvt_pk_bf16_f32 v133, v134, v135
	v_cvt_pk_bf16_f32 v134, v136, v137
	v_cvt_pk_bf16_f32 v135, v138, v139
	global_store_dwordx4 v[128:129], v[132:135], off offset:256
	v_add_u32_e32 v128, 0xa0, v166
	v_ashrrev_i32_e32 v129, 31, v128
	v_lshlrev_b64 v[132:133], 6, v[128:129]
	v_lshl_add_u64 v[132:133], v[160:161], 0, v[132:133]
	s_nop 0
	v_lshlrev_b64 v[128:129], 10, v[128:129]
	v_lshl_add_u64 v[128:129], s[8:9], 0, v[128:129]
	v_lshl_add_u64 v[128:129], v[128:129], 0, v[192:193]
	s_waitcnt lgkmcnt(0)
	s_nop 3
	s_nop 0
	s_nop 1
	s_waitcnt lgkmcnt(0)
	s_nop 1
	s_waitcnt lgkmcnt(0)
	s_nop 1
	v_mov_b32_e32 v136, v241
	s_nop 0
	v_pk_mul_f32 v[134:135], v[14:15], v[136:137] op_sel_hi:[1,0]
	v_pk_mul_f32 v[132:133], v[12:13], v[136:137] op_sel_hi:[1,0]
	v_pk_mul_f32 v[138:139], v[10:11], v[136:137] op_sel_hi:[1,0]
	v_pk_mul_f32 v[140:141], v[8:9], v[136:137] op_sel_hi:[1,0]
	v_cvt_pk_bf16_f32 v132, v132, v133
	v_cvt_pk_bf16_f32 v133, v134, v135
	v_cvt_pk_bf16_f32 v134, v140, v141
	v_cvt_pk_bf16_f32 v135, v138, v139
	global_store_dwordx4 v[128:129], v[132:135], off
	v_pk_mul_f32 v[138:139], v[74:75], v[136:137] op_sel_hi:[1,0]
	s_nop 0
	v_pk_mul_f32 v[134:135], v[78:79], v[136:137] op_sel_hi:[1,0]
	v_pk_mul_f32 v[132:133], v[76:77], v[136:137] op_sel_hi:[1,0]
	v_pk_mul_f32 v[136:137], v[72:73], v[136:137] op_sel_hi:[1,0]
	v_cvt_pk_bf16_f32 v132, v132, v133
	v_cvt_pk_bf16_f32 v133, v134, v135
	v_cvt_pk_bf16_f32 v134, v136, v137
	v_cvt_pk_bf16_f32 v135, v138, v139
	global_store_dwordx4 v[128:129], v[132:135], off offset:256
	v_add_u32_e32 v128, 0xb0, v166
	v_ashrrev_i32_e32 v129, 31, v128
	v_lshlrev_b64 v[132:133], 6, v[128:129]
	v_lshl_add_u64 v[132:133], v[160:161], 0, v[132:133]
	s_nop 0
	v_lshlrev_b64 v[128:129], 10, v[128:129]
	s_waitcnt lgkmcnt(0)
	s_nop 3
	v_lshl_add_u64 v[134:135], s[8:9], 0, v[128:129]
	s_nop 1
	v_lshl_add_u64 v[134:135], v[134:135], 0, v[192:193]
	s_mov_b64 s[8:9], 0
	s_waitcnt lgkmcnt(0)
	s_nop 1
	s_waitcnt lgkmcnt(0)
	s_nop 1
	v_mov_b32_e32 v132, v245
	s_nop 0
	v_pk_mul_f32 v[130:131], v[6:7], v[132:133] op_sel_hi:[1,0]
	v_pk_mul_f32 v[128:129], v[4:5], v[132:133] op_sel_hi:[1,0]
	v_pk_mul_f32 v[136:137], v[2:3], v[132:133] op_sel_hi:[1,0]
	v_pk_mul_f32 v[138:139], v[0:1], v[132:133] op_sel_hi:[1,0]
	v_cvt_pk_bf16_f32 v128, v128, v129
	v_cvt_pk_bf16_f32 v129, v130, v131
	v_cvt_pk_bf16_f32 v130, v138, v139
	v_cvt_pk_bf16_f32 v131, v136, v137
	global_store_dwordx4 v[134:135], v[128:131], off
	v_pk_mul_f32 v[136:137], v[66:67], v[132:133] op_sel_hi:[1,0]
	s_nop 0
	v_pk_mul_f32 v[130:131], v[70:71], v[132:133] op_sel_hi:[1,0]
	v_pk_mul_f32 v[128:129], v[68:69], v[132:133] op_sel_hi:[1,0]
	v_pk_mul_f32 v[132:133], v[64:65], v[132:133] op_sel_hi:[1,0]
	v_cvt_pk_bf16_f32 v128, v128, v129
	v_cvt_pk_bf16_f32 v129, v130, v131
	v_cvt_pk_bf16_f32 v130, v132, v133
	v_cvt_pk_bf16_f32 v131, v136, v137
	global_store_dwordx4 v[134:135], v[128:131], off offset:256

; __device__ __forceinline__ v4u pack8(const f32x4 a, const f32x4 b) { v4u w; w.x = cvt_pk_bf16(a[0], a[1]); w.y = cvt_pk_bf16(a[2], a[3]); w.z = cvt_pk_bf16(b[0], b[1]); w.w = cvt_pk_bf16(b[2], b[3]); return w; }
;     __device__ __forceinline__ void operator()(const f32x4 (&acc)[2][2][4][2], const pg8::Unit& u, int wr, int wc, int fr, int fq) const {
;     ...
;         else if (grp == 2) { WIN_LOOP( *(v4u*)(VH + (size_t)row * 512 + c) = pack8(a, b); ) }
;         else if (grp == 4) { WIN_LOOP( *(v4u*)(QO + (size_t)row * DM + 512 + c) = pack8(a * C2Q, b * C2Q); ) }
;         else if (grp == 5) { WIN_LOOP( *(v4u*)(FK + (size_t)row * 512 + c) = pack8(a, b); ) }
;         else { WIN_LOOP( *(v4u*)(FV + (size_t)row * 512 + c) = pack8(a, b); ) }
.LBB0_412:
	s_and_b64 vcc, exec, s[10:11]
	s_cbranch_vccz .LBB0_414
	v_and_b32_e32 v129, 64, v215
	v_xor_b32_e32 v128, 16, v215
	v_add_u32_e32 v129, 64, v129
	v_cmp_lt_i32_e32 vcc, v128, v129
	v_ashrrev_i32_e32 v167, 31, v166
	v_readlane_b32 s8, v255, 43
	v_cndmask_b32_e32 v128, v215, v128, vcc
	v_lshlrev_b32_e32 v130, 2, v128
	v_xor_b32_e32 v128, 32, v215
	v_cmp_lt_i32_e32 vcc, v128, v129
	v_readlane_b32 s9, v255, 44
	v_lshlrev_b32_e32 v192, 1, v176
	v_cndmask_b32_e32 v128, v215, v128, vcc
	v_lshlrev_b32_e32 v131, 2, v128
	v_lshlrev_b64 v[128:129], 6, v[166:167]
	v_lshl_add_u64 v[128:129], v[160:161], 0, v[128:129]
	s_nop 0
	s_waitcnt lgkmcnt(0)
	s_nop 3
	v_lshlrev_b64 v[132:133], 10, v[166:167]
	s_nop 1
	v_lshl_add_u64 v[136:137], s[8:9], 0, v[132:133]
	v_lshl_add_u64 v[136:137], v[136:137], 0, v[192:193]
	s_waitcnt lgkmcnt(0)
	s_nop 1
	s_waitcnt lgkmcnt(0)
	s_nop 1
	v_mov_b32_e32 v128, v250
	s_nop 0
	v_pk_mul_f32 v[134:135], v[62:63], v[128:129] op_sel_hi:[1,0]
	v_pk_mul_f32 v[132:133], v[60:61], v[128:129] op_sel_hi:[1,0]
	v_pk_mul_f32 v[138:139], v[58:59], v[128:129] op_sel_hi:[1,0]
	v_pk_mul_f32 v[140:141], v[56:57], v[128:129] op_sel_hi:[1,0]
	v_cvt_pk_bf16_f32 v132, v132, v133
	v_cvt_pk_bf16_f32 v133, v134, v135
	v_cvt_pk_bf16_f32 v134, v140, v141
	v_cvt_pk_bf16_f32 v135, v138, v139
	global_store_dwordx4 v[136:137], v[132:135], off
	v_pk_mul_f32 v[138:139], v[122:123], v[128:129] op_sel_hi:[1,0]
	s_nop 0
	v_pk_mul_f32 v[134:135], v[126:127], v[128:129] op_sel_hi:[1,0]
	v_pk_mul_f32 v[132:133], v[124:125], v[128:129] op_sel_hi:[1,0]
	v_pk_mul_f32 v[128:129], v[120:121], v[128:129] op_sel_hi:[1,0]
	v_cvt_pk_bf16_f32 v132, v132, v133
	v_cvt_pk_bf16_f32 v133, v134, v135
	v_cvt_pk_bf16_f32 v134, v128, v129
	v_or_b32_e32 v128, 16, v166
	v_cvt_pk_bf16_f32 v135, v138, v139
	v_ashrrev_i32_e32 v129, 31, v128
	global_store_dwordx4 v[136:137], v[132:135], off offset:256
	s_nop 1
	v_lshlrev_b64 v[132:133], 6, v[128:129]
	v_lshl_add_u64 v[132:133], v[160:161], 0, v[132:133]
	s_nop 0
	v_lshlrev_b64 v[128:129], 10, v[128:129]
	v_lshl_add_u64 v[128:129], s[8:9], 0, v[128:129]
	v_lshl_add_u64 v[128:129], v[128:129], 0, v[192:193]
	s_waitcnt lgkmcnt(0)
	s_nop 3
	s_nop 0
	s_nop 1
	s_waitcnt lgkmcnt(0)
	s_nop 1
	s_waitcnt lgkmcnt(0)
	s_nop 1
	v_mov_b32_e32 v136, v251
	s_nop 0
	v_pk_mul_f32 v[134:135], v[54:55], v[136:137] op_sel_hi:[1,0]
	v_pk_mul_f32 v[132:133], v[52:53], v[136:137] op_sel_hi:[1,0]
	v_pk_mul_f32 v[138:139], v[50:51], v[136:137] op_sel_hi:[1,0]
	v_pk_mul_f32 v[140:141], v[48:49], v[136:137] op_sel_hi:[1,0]
	v_cvt_pk_bf16_f32 v132, v132, v133
	v_cvt_pk_bf16_f32 v133, v134, v135
	v_cvt_pk_bf16_f32 v134, v140, v141
	v_cvt_pk_bf16_f32 v135, v138, v139
	global_store_dwordx4 v[128:129], v[132:135], off
	v_pk_mul_f32 v[138:139], v[114:115], v[136:137] op_sel_hi:[1,0]
	s_nop 0
	v_pk_mul_f32 v[134:135], v[118:119], v[136:137] op_sel_hi:[1,0]
	v_pk_mul_f32 v[132:133], v[116:117], v[136:137] op_sel_hi:[1,0]
	v_pk_mul_f32 v[136:137], v[112:113], v[136:137] op_sel_hi:[1,0]
	v_cvt_pk_bf16_f32 v132, v132, v133
	v_cvt_pk_bf16_f32 v133, v134, v135
	v_cvt_pk_bf16_f32 v134, v136, v137
	v_cvt_pk_bf16_f32 v135, v138, v139
	global_store_dwordx4 v[128:129], v[132:135], off offset:256
	v_or_b32_e32 v128, 32, v166
	v_ashrrev_i32_e32 v129, 31, v128
	v_lshlrev_b64 v[132:133], 6, v[128:129]
	v_lshl_add_u64 v[132:133], v[160:161], 0, v[132:133]
	s_nop 0
	v_lshlrev_b64 v[128:129], 10, v[128:129]
	v_lshl_add_u64 v[128:129], s[8:9], 0, v[128:129]
	v_lshl_add_u64 v[128:129], v[128:129], 0, v[192:193]
	s_waitcnt lgkmcnt(0)
	s_nop 3
	s_nop 0
	s_nop 1
	s_waitcnt lgkmcnt(0)
	s_nop 1
	s_waitcnt lgkmcnt(0)
	s_nop 1
	v_mov_b32_e32 v136, v252
	s_nop 0
	v_pk_mul_f32 v[134:135], v[46:47], v[136:137] op_sel_hi:[1,0]
	v_pk_mul_f32 v[132:133], v[44:45], v[136:137] op_sel_hi:[1,0]
	v_pk_mul_f32 v[138:139], v[42:43], v[136:137] op_sel_hi:[1,0]
	v_pk_mul_f32 v[140:141], v[40:41], v[136:137] op_sel_hi:[1,0]
	v_cvt_pk_bf16_f32 v132, v132, v133
	v_cvt_pk_bf16_f32 v133, v134, v135
	v_cvt_pk_bf16_f32 v134, v140, v141
	v_cvt_pk_bf16_f32 v135, v138, v139
	global_store_dwordx4 v[128:129], v[132:135], off
	v_pk_mul_f32 v[138:139], v[106:107], v[136:137] op_sel_hi:[1,0]
	s_nop 0
	v_pk_mul_f32 v[134:135], v[110:111], v[136:137] op_sel_hi:[1,0]
	v_pk_mul_f32 v[132:133], v[108:109], v[136:137] op_sel_hi:[1,0]
	v_pk_mul_f32 v[136:137], v[104:105], v[136:137] op_sel_hi:[1,0]
	v_cvt_pk_bf16_f32 v132, v132, v133
	v_cvt_pk_bf16_f32 v133, v134, v135
	v_cvt_pk_bf16_f32 v134, v136, v137
	v_cvt_pk_bf16_f32 v135, v138, v139
	global_store_dwordx4 v[128:129], v[132:135], off offset:256
	v_or_b32_e32 v128, 48, v166
	v_ashrrev_i32_e32 v129, 31, v128
	v_lshlrev_b64 v[132:133], 6, v[128:129]
	v_lshl_add_u64 v[132:133], v[160:161], 0, v[132:133]
	s_nop 0
	v_lshlrev_b64 v[128:129], 10, v[128:129]
	v_lshl_add_u64 v[128:129], s[8:9], 0, v[128:129]
	v_lshl_add_u64 v[128:129], v[128:129], 0, v[192:193]
	s_waitcnt lgkmcnt(0)
	s_nop 3
	s_nop 0
	s_nop 1
	s_waitcnt lgkmcnt(0)
	s_nop 1
	s_waitcnt lgkmcnt(0)
; __device__ __forceinline__ v4u pack8(const f32x4 a, const f32x4 b) { v4u w; w.x = cvt_pk_bf16(a[0], a[1]); w.y = cvt_pk_bf16(a[2], a[3]); w.z = cvt_pk_bf16(b[0], b[1]); w.w = cvt_pk_bf16(b[2], b[3]); return w; }
;     __device__ __forceinline__ void operator()(const f32x4 (&acc)[2][2][4][2], const pg8::Unit& u, int wr, int wc, int fr, int fq) const {
;     ...
;         else if (grp == 2) { WIN_LOOP( *(v4u*)(VH + (size_t)row * 512 + c) = pack8(a, b); ) }
;         else if (grp == 4) { WIN_LOOP( *(v4u*)(QO + (size_t)row * DM + 512 + c) = pack8(a * C2Q, b * C2Q); ) }
;         else if (grp == 5) { WIN_LOOP( *(v4u*)(FK + (size_t)row * 512 + c) = pack8(a, b); ) }
;         else { WIN_LOOP( *(v4u*)(FV + (size_t)row * 512 + c) = pack8(a, b); ) }
	s_nop 1
	v_mov_b32_e32 v136, v253
	s_nop 0
	v_pk_mul_f32 v[134:135], v[38:39], v[136:137] op_sel_hi:[1,0]
	v_pk_mul_f32 v[132:133], v[36:37], v[136:137] op_sel_hi:[1,0]
	v_pk_mul_f32 v[138:139], v[34:35], v[136:137] op_sel_hi:[1,0]
	v_pk_mul_f32 v[140:141], v[32:33], v[136:137] op_sel_hi:[1,0]
	v_cvt_pk_bf16_f32 v132, v132, v133
	v_cvt_pk_bf16_f32 v133, v134, v135
	v_cvt_pk_bf16_f32 v134, v140, v141
	v_cvt_pk_bf16_f32 v135, v138, v139
	global_store_dwordx4 v[128:129], v[132:135], off
	v_pk_mul_f32 v[138:139], v[98:99], v[136:137] op_sel_hi:[1,0]
	s_nop 0
	v_pk_mul_f32 v[134:135], v[102:103], v[136:137] op_sel_hi:[1,0]
	v_pk_mul_f32 v[132:133], v[100:101], v[136:137] op_sel_hi:[1,0]
	v_pk_mul_f32 v[136:137], v[96:97], v[136:137] op_sel_hi:[1,0]
	v_cvt_pk_bf16_f32 v132, v132, v133
	v_cvt_pk_bf16_f32 v133, v134, v135
	v_cvt_pk_bf16_f32 v134, v136, v137
	v_cvt_pk_bf16_f32 v135, v138, v139
	global_store_dwordx4 v[128:129], v[132:135], off offset:256
	v_add_u32_e32 v128, 0x80, v166
	v_ashrrev_i32_e32 v129, 31, v128
	v_lshlrev_b64 v[132:133], 6, v[128:129]
	v_lshl_add_u64 v[132:133], v[160:161], 0, v[132:133]
	s_nop 0
	v_lshlrev_b64 v[128:129], 10, v[128:129]
	v_lshl_add_u64 v[128:129], s[8:9], 0, v[128:129]
	v_lshl_add_u64 v[128:129], v[128:129], 0, v[192:193]
	s_waitcnt lgkmcnt(0)
	s_nop 3
	s_nop 0
	s_nop 1
	s_waitcnt lgkmcnt(0)
	s_nop 1
	s_waitcnt lgkmcnt(0)
	s_nop 1
	v_mov_b32_e32 v136, v254
	s_nop 0
	v_pk_mul_f32 v[134:135], v[30:31], v[136:137] op_sel_hi:[1,0]
	v_pk_mul_f32 v[132:133], v[28:29], v[136:137] op_sel_hi:[1,0]
	v_pk_mul_f32 v[138:139], v[26:27], v[136:137] op_sel_hi:[1,0]
	v_pk_mul_f32 v[140:141], v[24:25], v[136:137] op_sel_hi:[1,0]
	v_cvt_pk_bf16_f32 v132, v132, v133
	v_cvt_pk_bf16_f32 v133, v134, v135
	v_cvt_pk_bf16_f32 v134, v140, v141
	v_cvt_pk_bf16_f32 v135, v138, v139
	global_store_dwordx4 v[128:129], v[132:135], off
	v_pk_mul_f32 v[138:139], v[90:91], v[136:137] op_sel_hi:[1,0]
	s_nop 0
	v_pk_mul_f32 v[134:135], v[94:95], v[136:137] op_sel_hi:[1,0]
	v_pk_mul_f32 v[132:133], v[92:93], v[136:137] op_sel_hi:[1,0]
	v_pk_mul_f32 v[136:137], v[88:89], v[136:137] op_sel_hi:[1,0]
	v_cvt_pk_bf16_f32 v132, v132, v133
	v_cvt_pk_bf16_f32 v133, v134, v135
	v_cvt_pk_bf16_f32 v134, v136, v137
	v_cvt_pk_bf16_f32 v135, v138, v139
	global_store_dwordx4 v[128:129], v[132:135], off offset:256
	v_add_u32_e32 v128, 0x90, v166
	v_ashrrev_i32_e32 v129, 31, v128
	v_lshlrev_b64 v[132:133], 6, v[128:129]
	v_lshl_add_u64 v[132:133], v[160:161], 0, v[132:133]
	s_nop 0
	v_lshlrev_b64 v[128:129], 10, v[128:129]
	v_lshl_add_u64 v[128:129], s[8:9], 0, v[128:129]
	v_lshl_add_u64 v[128:129], v[128:129], 0, v[192:193]
	s_waitcnt lgkmcnt(0)
	s_nop 3
	s_nop 0
	s_nop 1
	s_waitcnt lgkmcnt(0)
	s_nop 1
	s_waitcnt lgkmcnt(0)
	s_nop 1
	v_mov_b32_e32 v136, v240
	s_nop 0
	v_pk_mul_f32 v[134:135], v[22:23], v[136:137] op_sel_hi:[1,0]
	v_pk_mul_f32 v[132:133], v[20:21], v[136:137] op_sel_hi:[1,0]
	v_pk_mul_f32 v[138:139], v[18:19], v[136:137] op_sel_hi:[1,0]
	v_pk_mul_f32 v[140:141], v[16:17], v[136:137] op_sel_hi:[1,0]
	v_cvt_pk_bf16_f32 v132, v132, v133
	v_cvt_pk_bf16_f32 v133, v134, v135
	v_cvt_pk_bf16_f32 v134, v140, v141
	v_cvt_pk_bf16_f32 v135, v138, v139
	global_store_dwordx4 v[128:129], v[132:135], off
	v_pk_mul_f32 v[138:139], v[82:83], v[136:137] op_sel_hi:[1,0]
	s_nop 0
	v_pk_mul_f32 v[134:135], v[86:87], v[136:137] op_sel_hi:[1,0]
	v_pk_mul_f32 v[132:133], v[84:85], v[136:137] op_sel_hi:[1,0]
	v_pk_mul_f32 v[136:137], v[80:81], v[136:137] op_sel_hi:[1,0]
	v_cvt_pk_bf16_f32 v132, v132, v133
	v_cvt_pk_bf16_f32 v133, v134, v135
	v_cvt_pk_bf16_f32 v134, v136, v137
	v_cvt_pk_bf16_f32 v135, v138, v139
	global_store_dwordx4 v[128:129], v[132:135], off offset:256
	v_add_u32_e32 v128, 0xa0, v166
	v_ashrrev_i32_e32 v129, 31, v128
	v_lshlrev_b64 v[132:133], 6, v[128:129]
	v_lshl_add_u64 v[132:133], v[160:161], 0, v[132:133]
	s_nop 0
	v_lshlrev_b64 v[128:129], 10, v[128:129]
	v_lshl_add_u64 v[128:129], s[8:9], 0, v[128:129]
	v_lshl_add_u64 v[128:129], v[128:129], 0, v[192:193]
	s_waitcnt lgkmcnt(0)
	s_nop 3
	s_nop 0
	s_nop 1
	s_waitcnt lgkmcnt(0)
	s_nop 1
	s_waitcnt lgkmcnt(0)
	s_nop 1
	v_mov_b32_e32 v136, v241
	s_nop 0
	v_pk_mul_f32 v[134:135], v[14:15], v[136:137] op_sel_hi:[1,0]
	v_pk_mul_f32 v[132:133], v[12:13], v[136:137] op_sel_hi:[1,0]
	v_pk_mul_f32 v[138:139], v[10:11], v[136:137] op_sel_hi:[1,0]
	v_pk_mul_f32 v[140:141], v[8:9], v[136:137] op_sel_hi:[1,0]
	v_cvt_pk_bf16_f32 v132, v132, v133
	v_cvt_pk_bf16_f32 v133, v134, v135
	v_cvt_pk_bf16_f32 v134, v140, v141
	v_cvt_pk_bf16_f32 v135, v138, v139
	global_store_dwordx4 v[128:129], v[132:135], off
	v_pk_mul_f32 v[138:139], v[74:75], v[136:137] op_sel_hi:[1,0]
	s_nop 0
	v_pk_mul_f32 v[134:135], v[78:79], v[136:137] op_sel_hi:[1,0]
	v_pk_mul_f32 v[132:133], v[76:77], v[136:137] op_sel_hi:[1,0]
	v_pk_mul_f32 v[136:137], v[72:73], v[136:137] op_sel_hi:[1,0]
	v_cvt_pk_bf16_f32 v132, v132, v133
	v_cvt_pk_bf16_f32 v133, v134, v135
	v_cvt_pk_bf16_f32 v134, v136, v137
	v_cvt_pk_bf16_f32 v135, v138, v139
	global_store_dwordx4 v[128:129], v[132:135], off offset:256
	v_add_u32_e32 v128, 0xb0, v166
	v_ashrrev_i32_e32 v129, 31, v128
	v_lshlrev_b64 v[132:133], 6, v[128:129]
	v_lshl_add_u64 v[132:133], v[160:161], 0, v[132:133]
	s_nop 0
	v_lshlrev_b64 v[128:129], 10, v[128:129]
	s_waitcnt lgkmcnt(0)
	s_nop 3
	v_lshl_add_u64 v[134:135], s[8:9], 0, v[128:129]
	s_nop 1
	v_lshl_add_u64 v[134:135], v[134:135], 0, v[192:193]
	s_mov_b64 s[8:9], 0
	s_waitcnt lgkmcnt(0)
	s_nop 1
	s_waitcnt lgkmcnt(0)
	s_nop 1
	v_mov_b32_e32 v132, v245
	s_nop 0
	v_pk_mul_f32 v[130:131], v[6:7], v[132:133] op_sel_hi:[1,0]
	v_pk_mul_f32 v[128:129], v[4:5], v[132:133] op_sel_hi:[1,0]
	v_pk_mul_f32 v[136:137], v[2:3], v[132:133] op_sel_hi:[1,0]
	v_pk_mul_f32 v[138:139], v[0:1], v[132:133] op_sel_hi:[1,0]
	v_cvt_pk_bf16_f32 v128, v128, v129
	v_cvt_pk_bf16_f32 v129, v130, v131
	v_cvt_pk_bf16_f32 v130, v138, v139
	v_cvt_pk_bf16_f32 v131, v136, v137
	global_store_dwordx4 v[134:135], v[128:131], off
	v_pk_mul_f32 v[136:137], v[66:67], v[132:133] op_sel_hi:[1,0]
	s_nop 0
	v_pk_mul_f32 v[130:131], v[70:71], v[132:133] op_sel_hi:[1,0]
	v_pk_mul_f32 v[128:129], v[68:69], v[132:133] op_sel_hi:[1,0]
	v_pk_mul_f32 v[132:133], v[64:65], v[132:133] op_sel_hi:[1,0]
	v_cvt_pk_bf16_f32 v128, v128, v129
	v_cvt_pk_bf16_f32 v129, v130, v131
	v_cvt_pk_bf16_f32 v130, v132, v133
	v_cvt_pk_bf16_f32 v131, v136, v137
	global_store_dwordx4 v[134:135], v[128:131], off offset:256
; __device__ __forceinline__ float logsig_f(float x) { return fminf(x, 0.f) - __logf(1.f + __expf(-fabsf(x))); }
;     __device__ __forceinline__ void operator()(const f32x4 (&acc)[2][2][4][2], const pg8::Unit& u, int wr, int wc, int fr, int fq) const {
;     ...
;         else if (grp == 1) {
;             f32x4 l0[2], l1[2];
; #pragma unroll
;             for (int bj = 0; bj < 2; ++bj) { l0[bj] = *(const f32x4*)(lb + cb + bj * 128); l1[bj] = *(const f32x4*)(lb + cb + bj * 128 + 4); }
;             WIN_LOOP( _Pragma("unroll") for (int i = 0; i < 4; ++i) { const float s0 = fminf(a[i], 0.f) - __logf(1.f + __expf(-fabsf(a[i]))), s1 = fminf(b[i], 0.f) - __logf(1.f + __expf(-fabsf(b[i]))); const float la = l0[bj][i], lbv = l1[bj][i];
;                     a[i] = la > 0.f ? __logf(la + (1.f - la) * __expf(s0)) : s0; b[i] = lbv > 0.f ? __logf(lbv + (1.f - lbv) * __expf(s1)) : s1; }
;                 *(f32x4*)(LF + (size_t)row * 512 + c) = a; *(f32x4*)(LF + (size_t)row * 512 + c + 4) = b; __builtin_amdgcn_sched_barrier(0); ) }
.LBB0_414:
	s_andn2_b64 vcc, exec, s[8:9]
	s_cbranch_vccnz .LBB0_416
	v_ashrrev_i32_e32 v167, 31, v166
	v_lshlrev_b64 v[128:129], 6, v[166:167]
	v_lshl_add_u64 v[128:129], v[160:161], 0, v[128:129]
	s_nop 0
	v_readlane_b32 s8, v255, 35
	v_lshlrev_b32_e32 v192, 2, v176
	v_readlane_b32 s9, v255, 36
	v_and_b32_e32 v133, 64, v215
	v_xor_b32_e32 v132, 16, v215
	v_lshl_add_u64 v[144:145], s[8:9], 0, v[192:193]
	flat_load_dwordx4 v[140:143], v[144:145]
	flat_load_dwordx4 v[136:139], v[144:145] offset:16
	v_add_u32_e32 v134, 64, v133
	v_cmp_lt_i32_e32 vcc, v132, v134
	v_lshlrev_b64 v[146:147], 11, v[166:167]
	v_readlane_b32 s50, v255, 45
	v_cndmask_b32_e32 v132, v215, v132, vcc
	v_lshlrev_b32_e32 v169, 2, v132
	v_readlane_b32 s51, v255, 46
	s_mov_b32 s95, s28
	s_mov_b32 s91, s29
	v_lshl_add_u64 v[170:171], s[50:51], 0, v[146:147]
	v_lshl_add_u64 v[170:171], v[170:171], 0, v[192:193]
	s_waitcnt vmcnt(0) lgkmcnt(0)
	s_nop 3
	v_xor_b32_e32 v130, 32, v215
	s_nop 1
	v_cmp_lt_i32_e32 vcc, v130, v134
	v_sub_f32_e32 v190, 1.0, v140
	v_sub_f32_e32 v191, 1.0, v136
	v_cndmask_b32_e32 v130, v215, v130, vcc
	v_lshlrev_b32_e32 v202, 2, v130
	s_waitcnt lgkmcnt(0)
	s_nop 1
	flat_load_dwordx4 v[132:135], v[144:145] offset:512
	flat_load_dwordx4 v[128:131], v[144:145] offset:528
	v_sub_f32_e32 v188, 1.0, v141
	v_cmp_lt_f32_e64 s[38:39], 0, v140
	v_cmp_lt_f32_e64 s[36:37], 0, v136
	s_waitcnt lgkmcnt(0)
	s_nop 1
	v_mov_b32_e32 v168, v250
	v_sub_f32_e32 v189, 1.0, v137
	v_cmp_lt_f32_e64 s[34:35], 0, v141
	v_cmp_lt_f32_e64 s[30:31], 0, v137
	v_pk_mul_f32 v[144:145], v[60:61], v[168:169] op_sel_hi:[1,0]
	v_pk_mul_f32 v[148:149], v[56:57], v[168:169] op_sel_hi:[1,0]
	v_min_f32_e32 v167, 0, v144
	v_mul_f32_e64 v144, |v144|, s57
	v_min_f32_e32 v177, 0, v148
	v_mul_f32_e64 v148, |v148|, s57
	v_exp_f32_e32 v144, v144
	v_exp_f32_e32 v148, v148
	v_min_f32_e32 v179, 0, v149
	v_mul_f32_e64 v149, |v149|, s57
	v_add_f32_e32 v144, 1.0, v144
	v_exp_f32_e32 v149, v149
	v_add_f32_e32 v148, 1.0, v148
	v_cmp_gt_f32_e64 s[8:9], s97, v144
	v_cmp_gt_f32_e64 s[10:11], s97, v148
	v_min_f32_e32 v178, 0, v145
	v_cndmask_b32_e64 v180, 0, 32, s[8:9]
	v_mul_f32_e64 v145, |v145|, s57
	v_cndmask_b32_e64 v181, 0, 32, s[10:11]
	v_ldexp_f32 v144, v144, v180
	v_exp_f32_e32 v145, v145
	v_ldexp_f32 v148, v148, v181
	v_log_f32_e32 v144, v144
	v_add_f32_e32 v149, 1.0, v149
	v_log_f32_e32 v148, v148
	v_cmp_gt_f32_e32 vcc, s97, v149
	v_add_f32_e32 v145, 1.0, v145
	v_cmp_gt_f32_e64 s[12:13], s97, v145
	v_cndmask_b32_e64 v183, 0, 32, vcc
	v_ldexp_f32 v149, v149, v183
	v_mul_f32_e32 v183, 0x3f317217, v144
	v_mul_f32_e32 v184, 0x3f317217, v148
	v_fma_f32 v183, v144, s52, -v183
	v_cndmask_b32_e64 v182, 0, 32, s[12:13]
	v_fma_f32 v184, v148, s52, -v184
	v_fmac_f32_e32 v183, 0x3377d1cf, v144
	v_cndmask_b32_e64 v180, 0, v216, s[8:9]
	v_ldexp_f32 v145, v145, v182
	v_fmac_f32_e32 v184, 0x3377d1cf, v148
	v_fmac_f32_e32 v183, 0x3f317217, v144
	v_cmp_lt_f32_e64 s[8:9], |v144|, s53
	v_log_f32_e32 v145, v145
	v_fmac_f32_e32 v184, 0x3f317217, v148
	v_cndmask_b32_e64 v144, v144, v183, s[8:9]
	v_cmp_lt_f32_e64 s[8:9], |v148|, s53
	v_cndmask_b32_e64 v181, 0, v216, s[10:11]
	v_log_f32_e32 v149, v149
	v_cndmask_b32_e64 v148, v148, v184, s[8:9]
	v_sub_f32_e32 v144, v144, v180
	v_sub_f32_e32 v148, v148, v181
	v_sub_f32_e32 v144, v167, v144
	v_sub_f32_e32 v167, v177, v148
	v_mul_f32_e32 v148, 0x3fb8aa3b, v144
	v_mul_f32_e32 v185, 0x3f317217, v145
	v_mul_f32_e32 v177, 0x3fb8aa3b, v167
	v_exp_f32_e32 v148, v148
	v_mul_f32_e32 v186, 0x3f317217, v149
	v_fma_f32 v185, v145, s52, -v185
	v_exp_f32_e32 v177, v177
	v_fma_f32 v186, v149, s52, -v186
	v_fmac_f32_e32 v185, 0x3377d1cf, v145
	v_fmac_f32_e32 v186, 0x3377d1cf, v149
	v_fmac_f32_e32 v185, 0x3f317217, v145
	v_cmp_lt_f32_e64 s[8:9], |v145|, s53
	v_fmac_f32_e32 v186, 0x3f317217, v149
	v_fma_f32 v148, v190, v148, v140
	v_cndmask_b32_e64 v145, v145, v185, s[8:9]
	v_cmp_lt_f32_e64 s[8:9], |v149|, s53
	v_fma_f32 v177, v191, v177, v136
	v_cmp_gt_f32_e64 s[10:11], s97, v177
	v_cndmask_b32_e64 v149, v149, v186, s[8:9]
	v_cmp_gt_f32_e64 s[8:9], s97, v148
	v_cndmask_b32_e64 v181, 0, 32, s[10:11]
	v_ldexp_f32 v177, v177, v181
	v_cndmask_b32_e64 v180, 0, 32, s[8:9]
	v_ldexp_f32 v148, v148, v180
	v_log_f32_e32 v148, v148
	v_cndmask_b32_e64 v182, 0, v216, s[12:13]
	v_log_f32_e32 v177, v177
	v_sub_f32_e32 v145, v145, v182
	v_sub_f32_e32 v145, v178, v145
	v_mul_f32_e32 v178, 0x3fb8aa3b, v145
	v_mul_f32_e32 v182, 0x3f317217, v148
	v_exp_f32_e32 v178, v178
	v_mul_f32_e32 v183, 0x3f317217, v177
	v_fma_f32 v182, v148, s52, -v182
	v_fma_f32 v183, v177, s52, -v183
	v_fmac_f32_e32 v182, 0x3377d1cf, v148
	v_cndmask_b32_e64 v180, 0, v216, s[8:9]
	v_fmac_f32_e32 v183, 0x3377d1cf, v177
	v_fmac_f32_e32 v182, 0x3f317217, v148
	v_cmp_lt_f32_e64 s[8:9], |v148|, s53
	v_fmac_f32_e32 v183, 0x3f317217, v177
	v_fma_f32 v178, v188, v178, v141
	v_cndmask_b32_e64 v148, v148, v182, s[8:9]
	v_cmp_lt_f32_e64 s[8:9], |v177|, s53
	v_cndmask_b32_e64 v181, 0, v216, s[10:11]
	v_sub_f32_e32 v148, v148, v180
	v_cndmask_b32_e64 v177, v177, v183, s[8:9]
	v_sub_f32_e32 v177, v177, v181
	v_cmp_gt_f32_e64 s[8:9], s97, v178
	v_cndmask_b32_e64 v148, v144, v148, s[38:39]
	v_cndmask_b32_e64 v144, v167, v177, s[36:37]
	v_cndmask_b32_e64 v167, 0, 32, s[8:9]
	v_ldexp_f32 v167, v178, v167
	v_cndmask_b32_e32 v177, 0, v216, vcc
	v_log_f32_e32 v167, v167
	v_sub_f32_e32 v149, v149, v177
	v_sub_f32_e32 v177, v179, v149
	v_mul_f32_e32 v178, 0x3fb8aa3b, v177
	v_exp_f32_e32 v178, v178
	v_mul_f32_e32 v149, 0x3f317217, v167
	v_fma_f32 v149, v167, s52, -v149
	v_fmac_f32_e32 v149, 0x3377d1cf, v167
	v_fmac_f32_e32 v149, 0x3f317217, v167
; __device__ __forceinline__ float logsig_f(float x) { return fminf(x, 0.f) - __logf(1.f + __expf(-fabsf(x))); }
;     __device__ __forceinline__ void operator()(const f32x4 (&acc)[2][2][4][2], const pg8::Unit& u, int wr, int wc, int fr, int fq) const {
;     ...
;             WIN_LOOP( _Pragma("unroll") for (int i = 0; i < 4; ++i) { const float s0 = fminf(a[i], 0.f) - __logf(1.f + __expf(-fabsf(a[i]))), s1 = fminf(b[i], 0.f) - __logf(1.f + __expf(-fabsf(b[i]))); const float la = l0[bj][i], lbv = l1[bj][i];
;                     a[i] = la > 0.f ? __logf(la + (1.f - la) * __expf(s0)) : s0; b[i] = lbv > 0.f ? __logf(lbv + (1.f - lbv) * __expf(s1)) : s1; }
;                 *(f32x4*)(LF + (size_t)row * 512 + c) = a; *(f32x4*)(LF + (size_t)row * 512 + c + 4) = b; __builtin_amdgcn_sched_barrier(0); ) }
	v_cmp_lt_f32_e64 vcc, |v167|, s53
	v_fma_f32 v178, v189, v178, v137
	v_pk_mul_f32 v[150:151], v[62:63], v[168:169] op_sel_hi:[1,0]
	v_cndmask_b32_e32 v149, v167, v149, vcc
	v_cmp_gt_f32_e32 vcc, s97, v178
	v_cndmask_b32_e64 v167, 0, v216, s[8:9]
	v_sub_f32_e32 v149, v149, v167
	v_cndmask_b32_e64 v179, 0, 32, vcc
	v_ldexp_f32 v178, v178, v179
	v_log_f32_e32 v178, v178
	v_mul_f32_e64 v167, |v150|, s57
	v_exp_f32_e32 v167, v167
	v_cndmask_b32_e64 v149, v145, v149, s[34:35]
	v_mul_f32_e32 v145, 0x3f317217, v178
	v_fma_f32 v145, v178, s52, -v145
	v_fmac_f32_e32 v145, 0x3377d1cf, v178
	v_fmac_f32_e32 v145, 0x3f317217, v178
	v_cmp_lt_f32_e64 s[8:9], |v178|, s53
	v_add_f32_e32 v167, 1.0, v167
	v_pk_mul_f32 v[146:147], v[58:59], v[168:169] op_sel_hi:[1,0]
	v_cndmask_b32_e64 v145, v178, v145, s[8:9]
	v_cndmask_b32_e32 v178, 0, v216, vcc
	v_cmp_gt_f32_e32 vcc, s97, v167
	v_sub_f32_e32 v145, v145, v178
	v_cndmask_b32_e64 v145, v177, v145, s[30:31]
	v_cndmask_b32_e64 v178, 0, 32, vcc
	v_ldexp_f32 v167, v167, v178
	v_log_f32_e32 v167, v167
	v_mul_f32_e64 v178, |v146|, s57
	v_exp_f32_e32 v178, v178
	v_min_f32_e32 v150, 0, v150
	v_mul_f32_e32 v177, 0x3f317217, v167
	v_fma_f32 v177, v167, s52, -v177
	v_fmac_f32_e32 v177, 0x3377d1cf, v167
	v_fmac_f32_e32 v177, 0x3f317217, v167
	v_cmp_lt_f32_e64 s[8:9], |v167|, s53
	v_add_f32_e32 v178, 1.0, v178
	v_sub_f32_e32 v187, 1.0, v142
	v_cndmask_b32_e64 v167, v167, v177, s[8:9]
	v_cndmask_b32_e32 v177, 0, v216, vcc
	v_cmp_gt_f32_e32 vcc, s97, v178
	v_sub_f32_e32 v167, v167, v177
	v_sub_f32_e32 v150, v150, v167
	v_cndmask_b32_e64 v179, 0, 32, vcc
	v_ldexp_f32 v178, v178, v179
	v_log_f32_e32 v178, v178
	v_mul_f32_e32 v177, 0x3fb8aa3b, v150
	v_exp_f32_e32 v177, v177
	v_min_f32_e32 v146, 0, v146
	v_mul_f32_e32 v167, 0x3f317217, v178
	v_fma_f32 v167, v178, s52, -v167
	v_fmac_f32_e32 v167, 0x3377d1cf, v178
	v_fmac_f32_e32 v167, 0x3f317217, v178
	v_cmp_lt_f32_e64 s[8:9], |v178|, s53
	v_fma_f32 v177, v187, v177, v142
	v_sub_f32_e32 v186, 1.0, v138
	v_cndmask_b32_e64 v167, v178, v167, s[8:9]
	v_cmp_gt_f32_e64 s[8:9], s97, v177
	v_cmp_lt_f32_e64 s[28:29], 0, v142
	v_cmp_lt_f32_e64 s[26:27], 0, v138
	v_cndmask_b32_e64 v178, 0, 32, s[8:9]
	v_ldexp_f32 v177, v177, v178
	v_cndmask_b32_e32 v178, 0, v216, vcc
	v_log_f32_e32 v177, v177
	v_sub_f32_e32 v167, v167, v178
	v_sub_f32_e32 v146, v146, v167
	v_mul_f32_e32 v178, 0x3fb8aa3b, v146
	v_exp_f32_e32 v178, v178
	v_mul_f32_e32 v167, 0x3f317217, v177
	v_fma_f32 v167, v177, s52, -v167
	v_fmac_f32_e32 v167, 0x3377d1cf, v177
	v_fmac_f32_e32 v167, 0x3f317217, v177
	v_cmp_lt_f32_e64 vcc, |v177|, s53
	v_fma_f32 v178, v186, v178, v138
	v_sub_f32_e32 v185, 1.0, v143
	v_cndmask_b32_e32 v167, v177, v167, vcc
	v_cmp_gt_f32_e32 vcc, s97, v178
	v_cndmask_b32_e64 v177, 0, v216, s[8:9]
	v_sub_f32_e32 v167, v167, v177
	v_cndmask_b32_e64 v179, 0, 32, vcc
	v_ldexp_f32 v178, v178, v179
	v_log_f32_e32 v178, v178
	v_mul_f32_e64 v177, |v151|, s57
	v_exp_f32_e32 v177, v177
	v_cndmask_b32_e64 v150, v150, v167, s[28:29]
	v_mul_f32_e32 v167, 0x3f317217, v178
	v_fma_f32 v167, v178, s52, -v167
	v_fmac_f32_e32 v167, 0x3377d1cf, v178
	v_fmac_f32_e32 v167, 0x3f317217, v178
	v_cmp_lt_f32_e64 s[8:9], |v178|, s53
	v_add_f32_e32 v177, 1.0, v177
	v_min_f32_e32 v151, 0, v151
	v_cndmask_b32_e64 v167, v178, v167, s[8:9]
	v_cndmask_b32_e32 v178, 0, v216, vcc
	v_cmp_gt_f32_e32 vcc, s97, v177
	v_sub_f32_e32 v167, v167, v178
	v_cndmask_b32_e64 v146, v146, v167, s[26:27]
	v_cndmask_b32_e64 v178, 0, 32, vcc
	v_ldexp_f32 v177, v177, v178
	v_log_f32_e32 v177, v177
	v_mul_f32_e64 v178, |v147|, s57
	v_exp_f32_e32 v178, v178
	v_min_f32_e32 v147, 0, v147
	v_mul_f32_e32 v167, 0x3f317217, v177
	v_fma_f32 v167, v177, s52, -v167
	v_fmac_f32_e32 v167, 0x3377d1cf, v177
	v_fmac_f32_e32 v167, 0x3f317217, v177
	v_cmp_lt_f32_e64 s[8:9], |v177|, s53
	v_add_f32_e32 v178, 1.0, v178
	v_sub_f32_e32 v184, 1.0, v139
	v_cndmask_b32_e64 v167, v177, v167, s[8:9]
	v_cndmask_b32_e32 v177, 0, v216, vcc
	v_cmp_gt_f32_e32 vcc, s97, v178
	v_sub_f32_e32 v167, v167, v177
	v_sub_f32_e32 v151, v151, v167
	v_cndmask_b32_e64 v179, 0, 32, vcc
	v_ldexp_f32 v178, v178, v179
	v_log_f32_e32 v178, v178
	v_mul_f32_e32 v177, 0x3fb8aa3b, v151
	v_exp_f32_e32 v177, v177
	v_cmp_lt_f32_e64 s[24:25], 0, v143
	v_mul_f32_e32 v167, 0x3f317217, v178
	v_fma_f32 v167, v178, s52, -v167
	v_fmac_f32_e32 v167, 0x3377d1cf, v178
	v_fmac_f32_e32 v167, 0x3f317217, v178
	v_cmp_lt_f32_e64 s[8:9], |v178|, s53
	v_fma_f32 v177, v185, v177, v143
	v_cmp_lt_f32_e64 s[22:23], 0, v139
	v_cndmask_b32_e64 v167, v178, v167, s[8:9]
	v_cmp_gt_f32_e64 s[8:9], s97, v177
	s_nop 1
	v_cndmask_b32_e64 v178, 0, 32, s[8:9]
	v_ldexp_f32 v177, v177, v178
	v_cndmask_b32_e32 v178, 0, v216, vcc
	v_log_f32_e32 v177, v177
	v_sub_f32_e32 v167, v167, v178
	v_sub_f32_e32 v147, v147, v167
	v_mul_f32_e32 v178, 0x3fb8aa3b, v147
	v_exp_f32_e32 v178, v178
	v_mul_f32_e32 v167, 0x3f317217, v177
	v_fma_f32 v167, v177, s52, -v167
	v_fmac_f32_e32 v167, 0x3377d1cf, v177
	v_fmac_f32_e32 v167, 0x3f317217, v177
	v_cmp_lt_f32_e64 vcc, |v177|, s53
	v_fma_f32 v178, v184, v178, v139
	s_nop 0
	v_cndmask_b32_e32 v167, v177, v167, vcc
	v_cmp_gt_f32_e32 vcc, s97, v178
	v_cndmask_b32_e64 v177, 0, v216, s[8:9]
	v_sub_f32_e32 v167, v167, v177
	v_cndmask_b32_e64 v179, 0, 32, vcc
	v_ldexp_f32 v178, v178, v179
	v_log_f32_e32 v178, v178
	v_cndmask_b32_e64 v151, v151, v167, s[24:25]
	v_cndmask_b32_e32 v177, 0, v216, vcc
	v_mul_f32_e32 v167, 0x3f317217, v178
	v_fma_f32 v167, v178, s52, -v167
	v_fmac_f32_e32 v167, 0x3377d1cf, v178
	v_fmac_f32_e32 v167, 0x3f317217, v178
	v_cmp_lt_f32_e64 s[8:9], |v178|, s53
	s_nop 1
	v_cndmask_b32_e64 v167, v178, v167, s[8:9]
	v_sub_f32_e32 v167, v167, v177
	v_cndmask_b32_e64 v147, v147, v167, s[22:23]
	global_store_dwordx4 v[170:171], v[148:151], off
	global_store_dwordx4 v[170:171], v[144:147], off offset:16
	s_nop 1
	v_pk_mul_f32 v[144:145], v[124:125], v[168:169] op_sel_hi:[1,0]
	v_pk_mul_f32 v[150:151], v[126:127], v[168:169] op_sel_hi:[1,0]
	v_mul_f32_e64 v146, |v144|, s57
	v_exp_f32_e32 v148, v146
	v_pk_mul_f32 v[146:147], v[122:123], v[168:169] op_sel_hi:[1,0]
	v_min_f32_e32 v144, 0, v144
	s_waitcnt vmcnt(0)
; __device__ __forceinline__ float logsig_f(float x) { return fminf(x, 0.f) - __logf(1.f + __expf(-fabsf(x))); }
;     __device__ __forceinline__ void operator()(const f32x4 (&acc)[2][2][4][2], const pg8::Unit& u, int wr, int wc, int fr, int fq) const {
;     ...
;             WIN_LOOP( _Pragma("unroll") for (int i = 0; i < 4; ++i) { const float s0 = fminf(a[i], 0.f) - __logf(1.f + __expf(-fabsf(a[i]))), s1 = fminf(b[i], 0.f) - __logf(1.f + __expf(-fabsf(b[i]))); const float la = l0[bj][i], lbv = l1[bj][i];
;                     a[i] = la > 0.f ? __logf(la + (1.f - la) * __expf(s0)) : s0; b[i] = lbv > 0.f ? __logf(lbv + (1.f - lbv) * __expf(s1)) : s1; }
;                 *(f32x4*)(LF + (size_t)row * 512 + c) = a; *(f32x4*)(LF + (size_t)row * 512 + c + 4) = b; __builtin_amdgcn_sched_barrier(0); ) }
	v_sub_f32_e32 v183, 1.0, v132
	v_add_f32_e32 v148, 1.0, v148
	v_cmp_gt_f32_e32 vcc, s97, v148
	v_sub_f32_e32 v182, 1.0, v128
	v_cmp_lt_f32_e64 s[20:21], 0, v132
	v_cndmask_b32_e64 v149, 0, 32, vcc
	v_ldexp_f32 v148, v148, v149
	v_log_f32_e32 v167, v148
	v_pk_mul_f32 v[148:149], v[120:121], v[168:169] op_sel_hi:[1,0]
	v_cmp_lt_f32_e64 s[18:19], 0, v128
	v_mul_f32_e64 v168, |v148|, s57
	v_exp_f32_e32 v168, v168
	v_mul_f32_e32 v177, 0x3f317217, v167
	v_fma_f32 v177, v167, s52, -v177
	v_fmac_f32_e32 v177, 0x3377d1cf, v167
	v_fmac_f32_e32 v177, 0x3f317217, v167
	v_cmp_lt_f32_e64 s[8:9], |v167|, s53
	v_add_f32_e32 v168, 1.0, v168
	v_min_f32_e32 v148, 0, v148
	v_cndmask_b32_e64 v167, v167, v177, s[8:9]
	v_cndmask_b32_e32 v177, 0, v216, vcc
	v_cmp_gt_f32_e32 vcc, s97, v168
	v_sub_f32_e32 v167, v167, v177
	v_sub_f32_e32 v144, v144, v167
	v_cndmask_b32_e64 v178, 0, 32, vcc
	v_ldexp_f32 v168, v168, v178
	v_log_f32_e32 v168, v168
	v_mul_f32_e32 v177, 0x3fb8aa3b, v144
	v_exp_f32_e32 v177, v177
	v_sub_f32_e32 v181, 1.0, v133
	v_mul_f32_e32 v167, 0x3f317217, v168
	v_fma_f32 v167, v168, s52, -v167
	v_fmac_f32_e32 v167, 0x3377d1cf, v168
	v_fmac_f32_e32 v167, 0x3f317217, v168
	v_cmp_lt_f32_e64 s[8:9], |v168|, s53
	v_sub_f32_e32 v180, 1.0, v129
	v_cmp_lt_f32_e64 s[16:17], 0, v133
	v_cndmask_b32_e64 v167, v168, v167, s[8:9]
	v_fma_f32 v168, v183, v177, v132
	v_cmp_gt_f32_e64 s[8:9], s97, v168
	v_cmp_lt_f32_e64 s[14:15], 0, v129
	v_sub_f32_e32 v179, 1.0, v134
	v_cndmask_b32_e64 v177, 0, 32, s[8:9]
	v_ldexp_f32 v168, v168, v177
	v_cndmask_b32_e32 v177, 0, v216, vcc
	v_log_f32_e32 v168, v168
	v_sub_f32_e32 v167, v167, v177
	v_sub_f32_e32 v148, v148, v167
	v_mul_f32_e32 v177, 0x3fb8aa3b, v148
	v_exp_f32_e32 v177, v177
	v_mul_f32_e32 v167, 0x3f317217, v168
	v_fma_f32 v167, v168, s52, -v167
	v_fmac_f32_e32 v167, 0x3377d1cf, v168
	v_fmac_f32_e32 v167, 0x3f317217, v168
	v_cmp_lt_f32_e64 vcc, |v168|, s53
	v_fma_f32 v177, v182, v177, v128
	v_cmp_lt_f32_e64 s[12:13], 0, v134
	v_cndmask_b32_e32 v167, v168, v167, vcc
	v_cmp_gt_f32_e32 vcc, s97, v177
	v_cndmask_b32_e64 v168, 0, v216, s[8:9]
	v_sub_f32_e32 v167, v167, v168
	v_cndmask_b32_e64 v178, 0, 32, vcc
	v_ldexp_f32 v177, v177, v178
	v_log_f32_e32 v177, v177
	v_mul_f32_e64 v168, |v145|, s57
	v_exp_f32_e32 v168, v168
	v_cndmask_b32_e64 v144, v144, v167, s[20:21]
	v_mul_f32_e32 v167, 0x3f317217, v177
	v_fma_f32 v167, v177, s52, -v167
	v_fmac_f32_e32 v167, 0x3377d1cf, v177
	v_fmac_f32_e32 v167, 0x3f317217, v177
	v_cmp_lt_f32_e64 s[8:9], |v177|, s53
	v_add_f32_e32 v168, 1.0, v168
	v_min_f32_e32 v145, 0, v145
	v_cndmask_b32_e64 v167, v177, v167, s[8:9]
	v_cndmask_b32_e32 v177, 0, v216, vcc
	v_cmp_gt_f32_e32 vcc, s97, v168
	v_sub_f32_e32 v167, v167, v177
	v_cndmask_b32_e64 v148, v148, v167, s[18:19]
	v_cndmask_b32_e64 v177, 0, 32, vcc
	v_ldexp_f32 v168, v168, v177
	v_log_f32_e32 v168, v168
	v_mul_f32_e64 v177, |v149|, s57
	v_exp_f32_e32 v177, v177
	v_min_f32_e32 v149, 0, v149
	v_mul_f32_e32 v167, 0x3f317217, v168
	v_fma_f32 v167, v168, s52, -v167
	v_fmac_f32_e32 v167, 0x3377d1cf, v168
	v_fmac_f32_e32 v167, 0x3f317217, v168
	v_cmp_lt_f32_e64 s[8:9], |v168|, s53
	v_add_f32_e32 v177, 1.0, v177
	v_cmp_lt_f32_e64 s[10:11], 0, v130
	v_cndmask_b32_e64 v167, v168, v167, s[8:9]
	v_cndmask_b32_e32 v168, 0, v216, vcc
	v_cmp_gt_f32_e32 vcc, s97, v177
	v_sub_f32_e32 v167, v167, v168
	v_sub_f32_e32 v145, v145, v167
	v_cndmask_b32_e64 v178, 0, 32, vcc
	v_ldexp_f32 v177, v177, v178
	v_log_f32_e32 v177, v177
	v_mul_f32_e32 v168, 0x3fb8aa3b, v145
	v_exp_f32_e32 v168, v168
	s_mov_b32 s2, s40
	v_mul_f32_e32 v167, 0x3f317217, v177
	v_fma_f32 v167, v177, s52, -v167
	v_fmac_f32_e32 v167, 0x3377d1cf, v177
	v_fmac_f32_e32 v167, 0x3f317217, v177
	v_cmp_lt_f32_e64 s[8:9], |v177|, s53
	v_fma_f32 v168, v181, v168, v133
	s_nop 0
	v_cndmask_b32_e64 v167, v177, v167, s[8:9]
	v_cmp_gt_f32_e64 s[8:9], s97, v168
	s_nop 1
	v_cndmask_b32_e64 v177, 0, 32, s[8:9]
	v_ldexp_f32 v168, v168, v177
	v_cndmask_b32_e32 v177, 0, v216, vcc
	v_log_f32_e32 v168, v168
	v_sub_f32_e32 v167, v167, v177
	v_sub_f32_e32 v149, v149, v167
	v_mul_f32_e32 v177, 0x3fb8aa3b, v149
	v_exp_f32_e32 v177, v177
	v_mul_f32_e32 v167, 0x3f317217, v168
	v_fma_f32 v167, v168, s52, -v167
	v_fmac_f32_e32 v167, 0x3377d1cf, v168
	v_fmac_f32_e32 v167, 0x3f317217, v168
	v_cmp_lt_f32_e64 vcc, |v168|, s53
	v_fma_f32 v177, v180, v177, v129
	s_nop 0
	v_cndmask_b32_e32 v167, v168, v167, vcc
	v_cmp_gt_f32_e32 vcc, s97, v177
	v_cndmask_b32_e64 v168, 0, v216, s[8:9]
	v_sub_f32_e32 v167, v167, v168
	v_cndmask_b32_e64 v178, 0, 32, vcc
	v_ldexp_f32 v177, v177, v178
	v_log_f32_e32 v177, v177
	v_mul_f32_e64 v168, |v150|, s57
	v_exp_f32_e32 v168, v168
	v_cndmask_b32_e64 v145, v145, v167, s[16:17]
	v_mul_f32_e32 v167, 0x3f317217, v177
	v_fma_f32 v167, v177, s52, -v167
	v_fmac_f32_e32 v167, 0x3377d1cf, v177
	v_fmac_f32_e32 v167, 0x3f317217, v177
	v_cmp_lt_f32_e64 s[8:9], |v177|, s53
	v_add_f32_e32 v168, 1.0, v168
	v_min_f32_e32 v150, 0, v150
	v_cndmask_b32_e64 v167, v177, v167, s[8:9]
	v_cndmask_b32_e32 v177, 0, v216, vcc
	v_cmp_gt_f32_e32 vcc, s97, v168
	v_sub_f32_e32 v167, v167, v177
	v_cndmask_b32_e64 v149, v149, v167, s[14:15]
	v_cndmask_b32_e64 v177, 0, 32, vcc
	v_ldexp_f32 v168, v168, v177
	v_log_f32_e32 v168, v168
	v_mul_f32_e64 v177, |v146|, s57
	v_exp_f32_e32 v177, v177
	v_min_f32_e32 v146, 0, v146
	v_mul_f32_e32 v167, 0x3f317217, v168
	v_fma_f32 v167, v168, s52, -v167
	v_fmac_f32_e32 v167, 0x3377d1cf, v168
	v_fmac_f32_e32 v167, 0x3f317217, v168
	v_cmp_lt_f32_e64 s[8:9], |v168|, s53
	v_add_f32_e32 v177, 1.0, v177
	s_nop 0
	v_cndmask_b32_e64 v167, v168, v167, s[8:9]
	v_cndmask_b32_e32 v168, 0, v216, vcc
;     __device__ __forceinline__ void operator()(const f32x4 (&acc)[2][2][4][2], const pg8::Unit& u, int wr, int wc, int fr, int fq) const {
;     ...
;             WIN_LOOP( _Pragma("unroll") for (int i = 0; i < 4; ++i) { const float s0 = fminf(a[i], 0.f) - __logf(1.f + __expf(-fabsf(a[i]))), s1 = fminf(b[i], 0.f) - __logf(1.f + __expf(-fabsf(b[i]))); const float la = l0[bj][i], lbv = l1[bj][i];
;                     a[i] = la > 0.f ? __logf(la + (1.f - la) * __expf(s0)) : s0; b[i] = lbv > 0.f ? __logf(lbv + (1.f - lbv) * __expf(s1)) : s1; }
;                 *(f32x4*)(LF + (size_t)row * 512 + c) = a; *(f32x4*)(LF + (size_t)row * 512 + c + 4) = b; __builtin_amdgcn_sched_barrier(0); ) }
	v_cmp_gt_f32_e32 vcc, s97, v177
	v_sub_f32_e32 v167, v167, v168
	v_sub_f32_e32 v150, v150, v167
	v_cndmask_b32_e64 v178, 0, 32, vcc
	v_ldexp_f32 v177, v177, v178
	v_log_f32_e32 v177, v177
	v_mul_f32_e32 v168, 0x3fb8aa3b, v150
	v_exp_f32_e32 v168, v168
	v_sub_f32_e32 v178, 1.0, v130
	v_mul_f32_e32 v167, 0x3f317217, v177
	v_fma_f32 v167, v177, s52, -v167
	v_fmac_f32_e32 v167, 0x3377d1cf, v177
	v_fmac_f32_e32 v167, 0x3f317217, v177
	v_cmp_lt_f32_e64 s[8:9], |v177|, s53
	v_fma_f32 v168, v179, v168, v134
	s_nop 0
	v_cndmask_b32_e64 v167, v177, v167, s[8:9]
	v_cmp_gt_f32_e64 s[8:9], s97, v168
	s_nop 1
	v_cndmask_b32_e64 v177, 0, 32, s[8:9]
	v_ldexp_f32 v168, v168, v177
	v_cndmask_b32_e32 v177, 0, v216, vcc
	v_log_f32_e32 v168, v168
	v_sub_f32_e32 v167, v167, v177
	v_sub_f32_e32 v167, v146, v167
	v_mul_f32_e32 v177, 0x3fb8aa3b, v167
	v_exp_f32_e32 v177, v177
	v_mul_f32_e32 v146, 0x3f317217, v168
	v_fma_f32 v146, v168, s52, -v146
	v_fmac_f32_e32 v146, 0x3377d1cf, v168
	v_fmac_f32_e32 v146, 0x3f317217, v168
	v_cmp_lt_f32_e64 vcc, |v168|, s53
	v_fma_f32 v177, v178, v177, v130
	s_nop 0
	v_cndmask_b32_e32 v146, v168, v146, vcc
	v_cmp_gt_f32_e32 vcc, s97, v177
	v_cndmask_b32_e64 v168, 0, v216, s[8:9]
	v_sub_f32_e32 v146, v146, v168
	v_cndmask_b32_e64 v194, 0, 32, vcc
	v_ldexp_f32 v177, v177, v194
	v_log_f32_e32 v177, v177
	v_mul_f32_e64 v168, |v151|, s57
	v_exp_f32_e32 v168, v168
	v_cndmask_b32_e64 v146, v150, v146, s[12:13]
	v_mul_f32_e32 v150, 0x3f317217, v177
	v_fma_f32 v150, v177, s52, -v150
	v_fmac_f32_e32 v150, 0x3377d1cf, v177
	v_fmac_f32_e32 v150, 0x3f317217, v177
	v_cmp_lt_f32_e64 s[8:9], |v177|, s53
	v_add_f32_e32 v168, 1.0, v168
	v_min_f32_e32 v151, 0, v151
	v_cndmask_b32_e64 v150, v177, v150, s[8:9]
	v_cndmask_b32_e32 v177, 0, v216, vcc
	v_cmp_gt_f32_e32 vcc, s97, v168
	v_sub_f32_e32 v150, v150, v177
	v_cndmask_b32_e64 v150, v167, v150, s[10:11]
	v_cndmask_b32_e64 v177, 0, 32, vcc
	v_ldexp_f32 v168, v168, v177
	v_log_f32_e32 v168, v168
	v_mul_f32_e64 v177, |v147|, s57
	v_exp_f32_e32 v177, v177
	v_min_f32_e32 v147, 0, v147
	v_mul_f32_e32 v167, 0x3f317217, v168
	v_fma_f32 v167, v168, s52, -v167
	v_fmac_f32_e32 v167, 0x3377d1cf, v168
	v_fmac_f32_e32 v167, 0x3f317217, v168
	v_cmp_lt_f32_e64 s[8:9], |v168|, s53
	v_add_f32_e32 v177, 1.0, v177
	s_nop 0
	v_cndmask_b32_e64 v167, v168, v167, s[8:9]
	v_cndmask_b32_e32 v168, 0, v216, vcc
	v_cmp_gt_f32_e32 vcc, s97, v177
	v_sub_f32_e32 v167, v167, v168
	v_sub_f32_e32 v151, v151, v167
	v_cndmask_b32_e64 v194, 0, 32, vcc
	v_ldexp_f32 v177, v177, v194
	v_log_f32_e32 v177, v177
	v_mul_f32_e32 v168, 0x3fb8aa3b, v151
	v_exp_f32_e32 v168, v168
	v_mul_f32_e32 v167, 0x3f317217, v177
	v_fma_f32 v167, v177, s52, -v167
	v_fmac_f32_e32 v167, 0x3377d1cf, v177
	v_fmac_f32_e32 v167, 0x3f317217, v177
	v_cmp_lt_f32_e64 s[8:9], |v177|, s53
	s_nop 1
	v_cndmask_b32_e64 v167, v177, v167, s[8:9]
	v_sub_f32_e32 v177, 1.0, v135
	v_fma_f32 v168, v177, v168, v135
	v_cmp_gt_f32_e64 s[8:9], s97, v168
	s_nop 1
	v_cndmask_b32_e64 v194, 0, 32, s[8:9]
	v_ldexp_f32 v168, v168, v194
	v_cndmask_b32_e32 v194, 0, v216, vcc
	v_log_f32_e32 v168, v168
	v_sub_f32_e32 v167, v167, v194
	v_sub_f32_e32 v194, v147, v167
	v_mul_f32_e32 v167, 0x3fb8aa3b, v194
	v_exp_f32_e32 v195, v167
	v_mul_f32_e32 v147, 0x3f317217, v168
	v_fma_f32 v147, v168, s52, -v147
	v_fmac_f32_e32 v147, 0x3377d1cf, v168
	v_sub_f32_e32 v167, 1.0, v131
	v_fmac_f32_e32 v147, 0x3f317217, v168
	v_cmp_lt_f32_e64 vcc, |v168|, s53
	v_fma_f32 v195, v167, v195, v131
	s_nop 0
	v_cndmask_b32_e32 v147, v168, v147, vcc
	v_cmp_gt_f32_e32 vcc, s97, v195
	v_cndmask_b32_e64 v168, 0, v216, s[8:9]
	v_sub_f32_e32 v147, v147, v168
	v_cndmask_b32_e64 v204, 0, 32, vcc
	v_ldexp_f32 v195, v195, v204
	v_log_f32_e32 v195, v195
	v_cmp_lt_f32_e64 s[8:9], 0, v135
	v_cndmask_b32_e32 v168, 0, v216, vcc
	v_cmp_lt_f32_e32 vcc, 0, v131
	v_cndmask_b32_e64 v147, v151, v147, s[8:9]
	v_mul_f32_e32 v151, 0x3f317217, v195
	v_fma_f32 v151, v195, s52, -v151
	v_fmac_f32_e32 v151, 0x3377d1cf, v195
	v_fmac_f32_e32 v151, 0x3f317217, v195
	v_cmp_lt_f32_e64 s[40:41], |v195|, s53
	s_nop 1
	v_cndmask_b32_e64 v151, v195, v151, s[40:41]
	v_sub_f32_e32 v151, v151, v168
	v_cndmask_b32_e32 v151, v194, v151, vcc
	global_store_dwordx4 v[170:171], v[144:147], off offset:512
	global_store_dwordx4 v[170:171], v[148:151], off offset:528
	s_nop 1
	v_or_b32_e32 v148, 16, v166
	v_ashrrev_i32_e32 v149, 31, v148
	v_lshlrev_b64 v[144:145], 6, v[148:149]
	v_lshl_add_u64 v[144:145], v[160:161], 0, v[144:145]
	s_nop 0
	s_waitcnt lgkmcnt(0)
	s_nop 3
	s_nop 0
	s_nop 1
	s_waitcnt lgkmcnt(0)
	s_nop 1
	s_waitcnt lgkmcnt(0)
;     __device__ __forceinline__ void operator()(const f32x4 (&acc)[2][2][4][2], const pg8::Unit& u, int wr, int wc, int fr, int fq) const {
;     ...
;             WIN_LOOP( _Pragma("unroll") for (int i = 0; i < 4; ++i) { const float s0 = fminf(a[i], 0.f) - __logf(1.f + __expf(-fabsf(a[i]))), s1 = fminf(b[i], 0.f) - __logf(1.f + __expf(-fabsf(b[i]))); const float la = l0[bj][i], lbv = l1[bj][i];
;                     a[i] = la > 0.f ? __logf(la + (1.f - la) * __expf(s0)) : s0; b[i] = lbv > 0.f ? __logf(lbv + (1.f - lbv) * __expf(s1)) : s1; }
;                 *(f32x4*)(LF + (size_t)row * 512 + c) = a; *(f32x4*)(LF + (size_t)row * 512 + c + 4) = b; __builtin_amdgcn_sched_barrier(0); ) }
	s_nop 1
	v_mov_b32_e32 v168, v251
	v_lshlrev_b64 v[144:145], 11, v[148:149]
	v_lshl_add_u64 v[170:171], s[50:51], 0, v[144:145]
	v_lshl_add_u64 v[170:171], v[170:171], 0, v[192:193]
	v_pk_mul_f32 v[148:149], v[52:53], v[168:169] op_sel_hi:[1,0]
	v_pk_mul_f32 v[144:145], v[48:49], v[168:169] op_sel_hi:[1,0]
	v_min_f32_e32 v194, 0, v148
	v_mul_f32_e64 v148, |v148|, s57
	v_exp_f32_e32 v148, v148
	v_pk_mul_f32 v[150:151], v[54:55], v[168:169] op_sel_hi:[1,0]
	v_pk_mul_f32 v[146:147], v[50:51], v[168:169] op_sel_hi:[1,0]
	v_add_f32_e32 v148, 1.0, v148
	v_cmp_gt_f32_e64 s[40:41], s97, v148
	s_nop 1
	v_cndmask_b32_e64 v195, 0, 32, s[40:41]
	v_ldexp_f32 v148, v148, v195
	v_log_f32_e32 v148, v148
	s_nop 0
	v_mul_f32_e32 v195, 0x3f317217, v148
	v_fma_f32 v195, v148, s52, -v195
	v_fmac_f32_e32 v195, 0x3377d1cf, v148
	v_fmac_f32_e32 v195, 0x3f317217, v148
	v_cmp_lt_f32_e64 s[42:43], |v148|, s53
	s_nop 1
	v_cndmask_b32_e64 v148, v148, v195, s[42:43]
	v_cndmask_b32_e64 v195, 0, v216, s[40:41]
	v_sub_f32_e32 v148, v148, v195
	v_sub_f32_e32 v148, v194, v148
	v_min_f32_e32 v194, 0, v144
	v_mul_f32_e64 v144, |v144|, s57
	v_exp_f32_e32 v144, v144
	s_nop 0
	v_add_f32_e32 v144, 1.0, v144
	v_cmp_gt_f32_e64 s[40:41], s97, v144
	s_nop 1
	v_cndmask_b32_e64 v195, 0, 32, s[40:41]
	v_ldexp_f32 v144, v144, v195
	v_log_f32_e32 v144, v144
	s_nop 0
	v_mul_f32_e32 v195, 0x3f317217, v144
	v_fma_f32 v195, v144, s52, -v195
	v_fmac_f32_e32 v195, 0x3377d1cf, v144
	v_fmac_f32_e32 v195, 0x3f317217, v144
	v_cmp_lt_f32_e64 s[42:43], |v144|, s53
	s_nop 1
	v_cndmask_b32_e64 v144, v144, v195, s[42:43]
	v_cndmask_b32_e64 v195, 0, v216, s[40:41]
	v_sub_f32_e32 v144, v144, v195
	v_sub_f32_e32 v194, v194, v144
	v_mul_f32_e32 v144, 0x3fb8aa3b, v148
	v_exp_f32_e32 v144, v144
	s_nop 0
	v_fma_f32 v144, v190, v144, v140
	v_cmp_gt_f32_e64 s[40:41], s97, v144
	s_nop 1
	v_cndmask_b32_e64 v195, 0, 32, s[40:41]
	v_ldexp_f32 v144, v144, v195
	v_log_f32_e32 v144, v144
	s_nop 0
	v_mul_f32_e32 v195, 0x3f317217, v144
	v_fma_f32 v195, v144, s52, -v195
	v_fmac_f32_e32 v195, 0x3377d1cf, v144
	v_fmac_f32_e32 v195, 0x3f317217, v144
	v_cmp_lt_f32_e64 s[42:43], |v144|, s53
	s_nop 1
	v_cndmask_b32_e64 v144, v144, v195, s[42:43]
	v_cndmask_b32_e64 v195, 0, v216, s[40:41]
	v_sub_f32_e32 v144, v144, v195
	v_cndmask_b32_e64 v144, v148, v144, s[38:39]
	v_mul_f32_e32 v148, 0x3fb8aa3b, v194
	v_exp_f32_e32 v148, v148
	s_nop 0
	v_fma_f32 v148, v191, v148, v136
	v_cmp_gt_f32_e64 s[40:41], s97, v148
	s_nop 1
	v_cndmask_b32_e64 v195, 0, 32, s[40:41]
	v_ldexp_f32 v148, v148, v195
	v_log_f32_e32 v148, v148
	s_nop 0
	v_mul_f32_e32 v195, 0x3f317217, v148
	v_fma_f32 v195, v148, s52, -v195
	v_fmac_f32_e32 v195, 0x3377d1cf, v148
	v_fmac_f32_e32 v195, 0x3f317217, v148
	v_cmp_lt_f32_e64 s[42:43], |v148|, s53
	s_nop 1
	v_cndmask_b32_e64 v148, v148, v195, s[42:43]
	v_cndmask_b32_e64 v195, 0, v216, s[40:41]
	v_sub_f32_e32 v148, v148, v195
	v_cndmask_b32_e64 v148, v194, v148, s[36:37]
	v_min_f32_e32 v194, 0, v149
	v_mul_f32_e64 v149, |v149|, s57
	v_exp_f32_e32 v149, v149
	s_nop 0
	v_add_f32_e32 v149, 1.0, v149
	v_cmp_gt_f32_e64 s[40:41], s97, v149
	s_nop 1
	v_cndmask_b32_e64 v195, 0, 32, s[40:41]
	v_ldexp_f32 v149, v149, v195
	v_log_f32_e32 v149, v149
	s_nop 0
	v_mul_f32_e32 v195, 0x3f317217, v149
	v_fma_f32 v195, v149, s52, -v195
	v_fmac_f32_e32 v195, 0x3377d1cf, v149
	v_fmac_f32_e32 v195, 0x3f317217, v149
	v_cmp_lt_f32_e64 s[42:43], |v149|, s53
	s_nop 1
	v_cndmask_b32_e64 v149, v149, v195, s[42:43]
	v_cndmask_b32_e64 v195, 0, v216, s[40:41]
	v_sub_f32_e32 v149, v149, v195
	v_sub_f32_e32 v149, v194, v149
	v_min_f32_e32 v194, 0, v145
	v_mul_f32_e64 v145, |v145|, s57
	v_exp_f32_e32 v145, v145
	s_nop 0
	v_add_f32_e32 v145, 1.0, v145
	v_cmp_gt_f32_e64 s[40:41], s97, v145
	s_nop 1
	v_cndmask_b32_e64 v195, 0, 32, s[40:41]
	v_ldexp_f32 v145, v145, v195
	v_log_f32_e32 v145, v145
	s_nop 0
	v_mul_f32_e32 v195, 0x3f317217, v145
	v_fma_f32 v195, v145, s52, -v195
	v_fmac_f32_e32 v195, 0x3377d1cf, v145
	v_fmac_f32_e32 v195, 0x3f317217, v145
	v_cmp_lt_f32_e64 s[42:43], |v145|, s53
	s_nop 1
	v_cndmask_b32_e64 v145, v145, v195, s[42:43]
	v_cndmask_b32_e64 v195, 0, v216, s[40:41]
	v_sub_f32_e32 v145, v145, v195
	v_sub_f32_e32 v194, v194, v145
	v_mul_f32_e32 v145, 0x3fb8aa3b, v149
	v_exp_f32_e32 v145, v145
	s_nop 0
	v_fma_f32 v145, v188, v145, v141
	v_cmp_gt_f32_e64 s[40:41], s97, v145
	s_nop 1
	v_cndmask_b32_e64 v195, 0, 32, s[40:41]
	v_ldexp_f32 v145, v145, v195
	v_log_f32_e32 v145, v145
	s_nop 0
	v_mul_f32_e32 v195, 0x3f317217, v145
	v_fma_f32 v195, v145, s52, -v195
	v_fmac_f32_e32 v195, 0x3377d1cf, v145
	v_fmac_f32_e32 v195, 0x3f317217, v145
	v_cmp_lt_f32_e64 s[42:43], |v145|, s53
	s_nop 1
	v_cndmask_b32_e64 v145, v145, v195, s[42:43]
	v_cndmask_b32_e64 v195, 0, v216, s[40:41]
	v_sub_f32_e32 v145, v145, v195
	v_cndmask_b32_e64 v145, v149, v145, s[34:35]
	v_mul_f32_e32 v149, 0x3fb8aa3b, v194
	v_exp_f32_e32 v149, v149
	s_nop 0
	v_fma_f32 v149, v189, v149, v137
	v_cmp_gt_f32_e64 s[40:41], s97, v149
	s_nop 1
	v_cndmask_b32_e64 v195, 0, 32, s[40:41]
	v_ldexp_f32 v149, v149, v195
	v_log_f32_e32 v149, v149
	s_nop 0
	v_mul_f32_e32 v195, 0x3f317217, v149
	v_fma_f32 v195, v149, s52, -v195
	v_fmac_f32_e32 v195, 0x3377d1cf, v149
	v_fmac_f32_e32 v195, 0x3f317217, v149
	v_cmp_lt_f32_e64 s[42:43], |v149|, s53
	s_nop 1
	v_cndmask_b32_e64 v149, v149, v195, s[42:43]
	v_cndmask_b32_e64 v195, 0, v216, s[40:41]
	v_sub_f32_e32 v149, v149, v195
	v_cndmask_b32_e64 v149, v194, v149, s[30:31]
	v_min_f32_e32 v194, 0, v150
	v_mul_f32_e64 v150, |v150|, s57
	v_exp_f32_e32 v150, v150
	s_nop 0
	v_add_f32_e32 v150, 1.0, v150
	v_cmp_gt_f32_e64 s[40:41], s97, v150
	s_nop 1
; __device__ __forceinline__ float logsig_f(float x) { return fminf(x, 0.f) - __logf(1.f + __expf(-fabsf(x))); }
;     __device__ __forceinline__ void operator()(const f32x4 (&acc)[2][2][4][2], const pg8::Unit& u, int wr, int wc, int fr, int fq) const {
;     ...
;             WIN_LOOP( _Pragma("unroll") for (int i = 0; i < 4; ++i) { const float s0 = fminf(a[i], 0.f) - __logf(1.f + __expf(-fabsf(a[i]))), s1 = fminf(b[i], 0.f) - __logf(1.f + __expf(-fabsf(b[i]))); const float la = l0[bj][i], lbv = l1[bj][i];
;                     a[i] = la > 0.f ? __logf(la + (1.f - la) * __expf(s0)) : s0; b[i] = lbv > 0.f ? __logf(lbv + (1.f - lbv) * __expf(s1)) : s1; }
;                 *(f32x4*)(LF + (size_t)row * 512 + c) = a; *(f32x4*)(LF + (size_t)row * 512 + c + 4) = b; __builtin_amdgcn_sched_barrier(0); ) }
	v_cndmask_b32_e64 v195, 0, 32, s[40:41]
	v_ldexp_f32 v150, v150, v195
	v_log_f32_e32 v150, v150
	s_nop 0
	v_mul_f32_e32 v195, 0x3f317217, v150
	v_fma_f32 v195, v150, s52, -v195
	v_fmac_f32_e32 v195, 0x3377d1cf, v150
	v_fmac_f32_e32 v195, 0x3f317217, v150
	v_cmp_lt_f32_e64 s[42:43], |v150|, s53
	s_nop 1
	v_cndmask_b32_e64 v150, v150, v195, s[42:43]
	v_cndmask_b32_e64 v195, 0, v216, s[40:41]
	v_sub_f32_e32 v150, v150, v195
	v_sub_f32_e32 v150, v194, v150
	v_min_f32_e32 v194, 0, v146
	v_mul_f32_e64 v146, |v146|, s57
	v_exp_f32_e32 v146, v146
	s_nop 0
	v_add_f32_e32 v146, 1.0, v146
	v_cmp_gt_f32_e64 s[40:41], s97, v146
	s_nop 1
	v_cndmask_b32_e64 v195, 0, 32, s[40:41]
	v_ldexp_f32 v146, v146, v195
	v_log_f32_e32 v146, v146
	s_nop 0
	v_mul_f32_e32 v195, 0x3f317217, v146
	v_fma_f32 v195, v146, s52, -v195
	v_fmac_f32_e32 v195, 0x3377d1cf, v146
	v_fmac_f32_e32 v195, 0x3f317217, v146
	v_cmp_lt_f32_e64 s[42:43], |v146|, s53
	s_nop 1
	v_cndmask_b32_e64 v146, v146, v195, s[42:43]
	v_cndmask_b32_e64 v195, 0, v216, s[40:41]
	v_sub_f32_e32 v146, v146, v195
	v_sub_f32_e32 v194, v194, v146
	v_mul_f32_e32 v146, 0x3fb8aa3b, v150
	v_exp_f32_e32 v146, v146
	s_nop 0
	v_fma_f32 v146, v187, v146, v142
	v_cmp_gt_f32_e64 s[40:41], s97, v146
	s_nop 1
	v_cndmask_b32_e64 v195, 0, 32, s[40:41]
	v_ldexp_f32 v146, v146, v195
	v_log_f32_e32 v146, v146
	s_nop 0
	v_mul_f32_e32 v195, 0x3f317217, v146
	v_fma_f32 v195, v146, s52, -v195
	v_fmac_f32_e32 v195, 0x3377d1cf, v146
	v_fmac_f32_e32 v195, 0x3f317217, v146
	v_cmp_lt_f32_e64 s[42:43], |v146|, s53
	s_nop 1
	v_cndmask_b32_e64 v146, v146, v195, s[42:43]
	v_cndmask_b32_e64 v195, 0, v216, s[40:41]
	v_sub_f32_e32 v146, v146, v195
	v_cndmask_b32_e64 v146, v150, v146, s[28:29]
	v_mul_f32_e32 v150, 0x3fb8aa3b, v194
	v_exp_f32_e32 v150, v150
	s_nop 0
	v_fma_f32 v150, v186, v150, v138
	v_cmp_gt_f32_e64 s[40:41], s97, v150
	s_nop 1
	v_cndmask_b32_e64 v195, 0, 32, s[40:41]
	v_ldexp_f32 v150, v150, v195
	v_log_f32_e32 v150, v150
	s_nop 0
	v_mul_f32_e32 v195, 0x3f317217, v150
	v_fma_f32 v195, v150, s52, -v195
	v_fmac_f32_e32 v195, 0x3377d1cf, v150
	v_fmac_f32_e32 v195, 0x3f317217, v150
	v_cmp_lt_f32_e64 s[42:43], |v150|, s53
	s_nop 1
	v_cndmask_b32_e64 v150, v150, v195, s[42:43]
	v_cndmask_b32_e64 v195, 0, v216, s[40:41]
	v_sub_f32_e32 v150, v150, v195
	v_cndmask_b32_e64 v150, v194, v150, s[26:27]
	v_min_f32_e32 v194, 0, v151
	v_mul_f32_e64 v151, |v151|, s57
	v_exp_f32_e32 v151, v151
	s_nop 0
	v_add_f32_e32 v151, 1.0, v151
	v_cmp_gt_f32_e64 s[40:41], s97, v151
	s_nop 1
	v_cndmask_b32_e64 v195, 0, 32, s[40:41]
	v_ldexp_f32 v151, v151, v195
	v_log_f32_e32 v151, v151
	s_nop 0
	v_mul_f32_e32 v195, 0x3f317217, v151
	v_fma_f32 v195, v151, s52, -v195
	v_fmac_f32_e32 v195, 0x3377d1cf, v151
	v_fmac_f32_e32 v195, 0x3f317217, v151
	v_cmp_lt_f32_e64 s[42:43], |v151|, s53
	s_nop 1
	v_cndmask_b32_e64 v151, v151, v195, s[42:43]
	v_cndmask_b32_e64 v195, 0, v216, s[40:41]
	v_sub_f32_e32 v151, v151, v195
	v_sub_f32_e32 v151, v194, v151
	v_min_f32_e32 v194, 0, v147
	v_mul_f32_e64 v147, |v147|, s57
	v_exp_f32_e32 v147, v147
	s_nop 0
	v_add_f32_e32 v147, 1.0, v147
	v_cmp_gt_f32_e64 s[40:41], s97, v147
	s_nop 1
	v_cndmask_b32_e64 v195, 0, 32, s[40:41]
	v_ldexp_f32 v147, v147, v195
	v_log_f32_e32 v147, v147
	s_nop 0
	v_mul_f32_e32 v195, 0x3f317217, v147
	v_fma_f32 v195, v147, s52, -v195
	v_fmac_f32_e32 v195, 0x3377d1cf, v147
	v_fmac_f32_e32 v195, 0x3f317217, v147
	v_cmp_lt_f32_e64 s[42:43], |v147|, s53
	s_nop 1
	v_cndmask_b32_e64 v147, v147, v195, s[42:43]
	v_cndmask_b32_e64 v195, 0, v216, s[40:41]
	v_sub_f32_e32 v147, v147, v195
	v_sub_f32_e32 v194, v194, v147
	v_mul_f32_e32 v147, 0x3fb8aa3b, v151
	v_exp_f32_e32 v147, v147
	s_nop 0
	v_fma_f32 v147, v185, v147, v143
	v_cmp_gt_f32_e64 s[40:41], s97, v147
	s_nop 1
	v_cndmask_b32_e64 v195, 0, 32, s[40:41]
	v_ldexp_f32 v147, v147, v195
	v_log_f32_e32 v147, v147
	s_nop 0
	v_mul_f32_e32 v195, 0x3f317217, v147
	v_fma_f32 v195, v147, s52, -v195
	v_fmac_f32_e32 v195, 0x3377d1cf, v147
	v_fmac_f32_e32 v195, 0x3f317217, v147
	v_cmp_lt_f32_e64 s[42:43], |v147|, s53
	s_nop 1
	v_cndmask_b32_e64 v147, v147, v195, s[42:43]
	v_cndmask_b32_e64 v195, 0, v216, s[40:41]
	v_sub_f32_e32 v147, v147, v195
	v_cndmask_b32_e64 v147, v151, v147, s[24:25]
	v_mul_f32_e32 v151, 0x3fb8aa3b, v194
	v_exp_f32_e32 v151, v151
	s_nop 0
	v_fma_f32 v151, v184, v151, v139
	v_cmp_gt_f32_e64 s[40:41], s97, v151
	s_nop 1
	v_cndmask_b32_e64 v195, 0, 32, s[40:41]
	v_ldexp_f32 v151, v151, v195
	v_log_f32_e32 v151, v151
	s_nop 0
	v_mul_f32_e32 v195, 0x3f317217, v151
	v_fma_f32 v195, v151, s52, -v195
	v_fmac_f32_e32 v195, 0x3377d1cf, v151
	v_fmac_f32_e32 v195, 0x3f317217, v151
	v_cmp_lt_f32_e64 s[42:43], |v151|, s53
	s_nop 1
	v_cndmask_b32_e64 v151, v151, v195, s[42:43]
	v_cndmask_b32_e64 v195, 0, v216, s[40:41]
	v_sub_f32_e32 v151, v151, v195
	v_cndmask_b32_e64 v151, v194, v151, s[22:23]
	global_store_dwordx4 v[170:171], v[144:147], off
	global_store_dwordx4 v[170:171], v[148:151], off offset:16
	s_nop 1
	v_pk_mul_f32 v[148:149], v[116:117], v[168:169] op_sel_hi:[1,0]
	v_pk_mul_f32 v[150:151], v[118:119], v[168:169] op_sel_hi:[1,0]
	v_pk_mul_f32 v[146:147], v[114:115], v[168:169] op_sel_hi:[1,0]
	v_pk_mul_f32 v[144:145], v[112:113], v[168:169] op_sel_hi:[1,0]
	v_min_f32_e32 v168, 0, v148
	v_mul_f32_e64 v148, |v148|, s57
	v_exp_f32_e32 v148, v148
	s_nop 0
	v_add_f32_e32 v148, 1.0, v148
	v_cmp_gt_f32_e64 s[40:41], s97, v148
	s_nop 1
	v_cndmask_b32_e64 v194, 0, 32, s[40:41]
	v_ldexp_f32 v148, v148, v194
	v_log_f32_e32 v148, v148
	s_nop 0
	v_mul_f32_e32 v194, 0x3f317217, v148
	v_fma_f32 v194, v148, s52, -v194
	v_fmac_f32_e32 v194, 0x3377d1cf, v148
; __device__ __forceinline__ float logsig_f(float x) { return fminf(x, 0.f) - __logf(1.f + __expf(-fabsf(x))); }
;     __device__ __forceinline__ void operator()(const f32x4 (&acc)[2][2][4][2], const pg8::Unit& u, int wr, int wc, int fr, int fq) const {
;     ...
;             WIN_LOOP( _Pragma("unroll") for (int i = 0; i < 4; ++i) { const float s0 = fminf(a[i], 0.f) - __logf(1.f + __expf(-fabsf(a[i]))), s1 = fminf(b[i], 0.f) - __logf(1.f + __expf(-fabsf(b[i]))); const float la = l0[bj][i], lbv = l1[bj][i];
;                     a[i] = la > 0.f ? __logf(la + (1.f - la) * __expf(s0)) : s0; b[i] = lbv > 0.f ? __logf(lbv + (1.f - lbv) * __expf(s1)) : s1; }
;                 *(f32x4*)(LF + (size_t)row * 512 + c) = a; *(f32x4*)(LF + (size_t)row * 512 + c + 4) = b; __builtin_amdgcn_sched_barrier(0); ) }
	v_fmac_f32_e32 v194, 0x3f317217, v148
	v_cmp_lt_f32_e64 s[42:43], |v148|, s53
	s_nop 1
	v_cndmask_b32_e64 v148, v148, v194, s[42:43]
	v_cndmask_b32_e64 v194, 0, v216, s[40:41]
	v_sub_f32_e32 v148, v148, v194
	v_sub_f32_e32 v148, v168, v148
	v_min_f32_e32 v168, 0, v144
	v_mul_f32_e64 v144, |v144|, s57
	v_exp_f32_e32 v144, v144
	s_nop 0
	v_add_f32_e32 v144, 1.0, v144
	v_cmp_gt_f32_e64 s[40:41], s97, v144
	s_nop 1
	v_cndmask_b32_e64 v194, 0, 32, s[40:41]
	v_ldexp_f32 v144, v144, v194
	v_log_f32_e32 v144, v144
	s_nop 0
	v_mul_f32_e32 v194, 0x3f317217, v144
	v_fma_f32 v194, v144, s52, -v194
	v_fmac_f32_e32 v194, 0x3377d1cf, v144
	v_fmac_f32_e32 v194, 0x3f317217, v144
	v_cmp_lt_f32_e64 s[42:43], |v144|, s53
	s_nop 1
	v_cndmask_b32_e64 v144, v144, v194, s[42:43]
	v_cndmask_b32_e64 v194, 0, v216, s[40:41]
	v_sub_f32_e32 v144, v144, v194
	v_sub_f32_e32 v168, v168, v144
	v_mul_f32_e32 v144, 0x3fb8aa3b, v148
	v_exp_f32_e32 v144, v144
	s_nop 0
	v_fma_f32 v144, v183, v144, v132
	v_cmp_gt_f32_e64 s[40:41], s97, v144
	s_nop 1
	v_cndmask_b32_e64 v194, 0, 32, s[40:41]
	v_ldexp_f32 v144, v144, v194
	v_log_f32_e32 v144, v144
	s_nop 0
	v_mul_f32_e32 v194, 0x3f317217, v144
	v_fma_f32 v194, v144, s52, -v194
	v_fmac_f32_e32 v194, 0x3377d1cf, v144
	v_fmac_f32_e32 v194, 0x3f317217, v144
	v_cmp_lt_f32_e64 s[42:43], |v144|, s53
	s_nop 1
	v_cndmask_b32_e64 v144, v144, v194, s[42:43]
	v_cndmask_b32_e64 v194, 0, v216, s[40:41]
	v_sub_f32_e32 v144, v144, v194
	v_cndmask_b32_e64 v144, v148, v144, s[20:21]
	v_mul_f32_e32 v148, 0x3fb8aa3b, v168
	v_exp_f32_e32 v148, v148
	s_nop 0
	v_fma_f32 v148, v182, v148, v128
	v_cmp_gt_f32_e64 s[40:41], s97, v148
	s_nop 1
	v_cndmask_b32_e64 v194, 0, 32, s[40:41]
	v_ldexp_f32 v148, v148, v194
	v_log_f32_e32 v148, v148
	s_nop 0
	v_mul_f32_e32 v194, 0x3f317217, v148
	v_fma_f32 v194, v148, s52, -v194
	v_fmac_f32_e32 v194, 0x3377d1cf, v148
	v_fmac_f32_e32 v194, 0x3f317217, v148
	v_cmp_lt_f32_e64 s[42:43], |v148|, s53
	s_nop 1
	v_cndmask_b32_e64 v148, v148, v194, s[42:43]
	v_cndmask_b32_e64 v194, 0, v216, s[40:41]
	v_sub_f32_e32 v148, v148, v194
	v_cndmask_b32_e64 v148, v168, v148, s[18:19]
	v_min_f32_e32 v168, 0, v149
	v_mul_f32_e64 v149, |v149|, s57
	v_exp_f32_e32 v149, v149
	s_nop 0
	v_add_f32_e32 v149, 1.0, v149
	v_cmp_gt_f32_e64 s[40:41], s97, v149
	s_nop 1
	v_cndmask_b32_e64 v194, 0, 32, s[40:41]
	v_ldexp_f32 v149, v149, v194
	v_log_f32_e32 v149, v149
	s_nop 0
	v_mul_f32_e32 v194, 0x3f317217, v149
	v_fma_f32 v194, v149, s52, -v194
	v_fmac_f32_e32 v194, 0x3377d1cf, v149
	v_fmac_f32_e32 v194, 0x3f317217, v149
	v_cmp_lt_f32_e64 s[42:43], |v149|, s53
	s_nop 1
	v_cndmask_b32_e64 v149, v149, v194, s[42:43]
	v_cndmask_b32_e64 v194, 0, v216, s[40:41]
	v_sub_f32_e32 v149, v149, v194
	v_sub_f32_e32 v149, v168, v149
	v_min_f32_e32 v168, 0, v145
	v_mul_f32_e64 v145, |v145|, s57
	v_exp_f32_e32 v145, v145
	s_nop 0
	v_add_f32_e32 v145, 1.0, v145
	v_cmp_gt_f32_e64 s[40:41], s97, v145
	s_nop 1
	v_cndmask_b32_e64 v194, 0, 32, s[40:41]
	v_ldexp_f32 v145, v145, v194
	v_log_f32_e32 v145, v145
	s_nop 0
	v_mul_f32_e32 v194, 0x3f317217, v145
	v_fma_f32 v194, v145, s52, -v194
	v_fmac_f32_e32 v194, 0x3377d1cf, v145
	v_fmac_f32_e32 v194, 0x3f317217, v145
	v_cmp_lt_f32_e64 s[42:43], |v145|, s53
	s_nop 1
	v_cndmask_b32_e64 v145, v145, v194, s[42:43]
	v_cndmask_b32_e64 v194, 0, v216, s[40:41]
	v_sub_f32_e32 v145, v145, v194
	v_sub_f32_e32 v168, v168, v145
	v_mul_f32_e32 v145, 0x3fb8aa3b, v149
	v_exp_f32_e32 v145, v145
	s_nop 0
	v_fma_f32 v145, v181, v145, v133
	v_cmp_gt_f32_e64 s[40:41], s97, v145
	s_nop 1
	v_cndmask_b32_e64 v194, 0, 32, s[40:41]
	v_ldexp_f32 v145, v145, v194
	v_log_f32_e32 v145, v145
	s_nop 0
	v_mul_f32_e32 v194, 0x3f317217, v145
	v_fma_f32 v194, v145, s52, -v194
	v_fmac_f32_e32 v194, 0x3377d1cf, v145
	v_fmac_f32_e32 v194, 0x3f317217, v145
	v_cmp_lt_f32_e64 s[42:43], |v145|, s53
	s_nop 1
	v_cndmask_b32_e64 v145, v145, v194, s[42:43]
	v_cndmask_b32_e64 v194, 0, v216, s[40:41]
	v_sub_f32_e32 v145, v145, v194
	v_cndmask_b32_e64 v145, v149, v145, s[16:17]
	v_mul_f32_e32 v149, 0x3fb8aa3b, v168
	v_exp_f32_e32 v149, v149
	s_nop 0
	v_fma_f32 v149, v180, v149, v129
	v_cmp_gt_f32_e64 s[40:41], s97, v149
	s_nop 1
	v_cndmask_b32_e64 v194, 0, 32, s[40:41]
	v_ldexp_f32 v149, v149, v194
	v_log_f32_e32 v149, v149
	s_nop 0
	v_mul_f32_e32 v194, 0x3f317217, v149
	v_fma_f32 v194, v149, s52, -v194
	v_fmac_f32_e32 v194, 0x3377d1cf, v149
	v_fmac_f32_e32 v194, 0x3f317217, v149
	v_cmp_lt_f32_e64 s[42:43], |v149|, s53
	s_nop 1
	v_cndmask_b32_e64 v149, v149, v194, s[42:43]
	v_cndmask_b32_e64 v194, 0, v216, s[40:41]
	v_sub_f32_e32 v149, v149, v194
	v_cndmask_b32_e64 v149, v168, v149, s[14:15]
	v_min_f32_e32 v168, 0, v150
	v_mul_f32_e64 v150, |v150|, s57
	v_exp_f32_e32 v150, v150
	s_nop 0
	v_add_f32_e32 v150, 1.0, v150
	v_cmp_gt_f32_e64 s[40:41], s97, v150
	s_nop 1
	v_cndmask_b32_e64 v194, 0, 32, s[40:41]
	v_ldexp_f32 v150, v150, v194
	v_log_f32_e32 v150, v150
	s_nop 0
	v_mul_f32_e32 v194, 0x3f317217, v150
	v_fma_f32 v194, v150, s52, -v194
	v_fmac_f32_e32 v194, 0x3377d1cf, v150
	v_fmac_f32_e32 v194, 0x3f317217, v150
	v_cmp_lt_f32_e64 s[42:43], |v150|, s53
	s_nop 1
	v_cndmask_b32_e64 v150, v150, v194, s[42:43]
	v_cndmask_b32_e64 v194, 0, v216, s[40:41]
	v_sub_f32_e32 v150, v150, v194
	v_sub_f32_e32 v150, v168, v150
	v_min_f32_e32 v168, 0, v146
	v_mul_f32_e64 v146, |v146|, s57
	v_exp_f32_e32 v146, v146
	s_nop 0
	v_add_f32_e32 v146, 1.0, v146
	v_cmp_gt_f32_e64 s[40:41], s97, v146
	s_nop 1
	v_cndmask_b32_e64 v194, 0, 32, s[40:41]
	v_ldexp_f32 v146, v146, v194
	v_log_f32_e32 v146, v146
	s_nop 0
	v_mul_f32_e32 v194, 0x3f317217, v146
	v_fma_f32 v194, v146, s52, -v194
;     __device__ __forceinline__ void operator()(const f32x4 (&acc)[2][2][4][2], const pg8::Unit& u, int wr, int wc, int fr, int fq) const {
;     ...
;             WIN_LOOP( _Pragma("unroll") for (int i = 0; i < 4; ++i) { const float s0 = fminf(a[i], 0.f) - __logf(1.f + __expf(-fabsf(a[i]))), s1 = fminf(b[i], 0.f) - __logf(1.f + __expf(-fabsf(b[i]))); const float la = l0[bj][i], lbv = l1[bj][i];
;                     a[i] = la > 0.f ? __logf(la + (1.f - la) * __expf(s0)) : s0; b[i] = lbv > 0.f ? __logf(lbv + (1.f - lbv) * __expf(s1)) : s1; }
;                 *(f32x4*)(LF + (size_t)row * 512 + c) = a; *(f32x4*)(LF + (size_t)row * 512 + c + 4) = b; __builtin_amdgcn_sched_barrier(0); ) }
	v_fmac_f32_e32 v194, 0x3377d1cf, v146
	v_fmac_f32_e32 v194, 0x3f317217, v146
	v_cmp_lt_f32_e64 s[42:43], |v146|, s53
	s_nop 1
	v_cndmask_b32_e64 v146, v146, v194, s[42:43]
	v_cndmask_b32_e64 v194, 0, v216, s[40:41]
	v_sub_f32_e32 v146, v146, v194
	v_sub_f32_e32 v168, v168, v146
	v_mul_f32_e32 v146, 0x3fb8aa3b, v150
	v_exp_f32_e32 v146, v146
	s_nop 0
	v_fma_f32 v146, v179, v146, v134
	v_cmp_gt_f32_e64 s[40:41], s97, v146
	s_nop 1
	v_cndmask_b32_e64 v194, 0, 32, s[40:41]
	v_ldexp_f32 v146, v146, v194
	v_log_f32_e32 v146, v146
	s_nop 0
	v_mul_f32_e32 v194, 0x3f317217, v146
	v_fma_f32 v194, v146, s52, -v194
	v_fmac_f32_e32 v194, 0x3377d1cf, v146
	v_fmac_f32_e32 v194, 0x3f317217, v146
	v_cmp_lt_f32_e64 s[42:43], |v146|, s53
	s_nop 1
	v_cndmask_b32_e64 v146, v146, v194, s[42:43]
	v_cndmask_b32_e64 v194, 0, v216, s[40:41]
	v_sub_f32_e32 v146, v146, v194
	v_cndmask_b32_e64 v146, v150, v146, s[12:13]
	v_mul_f32_e32 v150, 0x3fb8aa3b, v168
	v_exp_f32_e32 v150, v150
	s_nop 0
	v_fma_f32 v150, v178, v150, v130
	v_cmp_gt_f32_e64 s[40:41], s97, v150
	s_nop 1
	v_cndmask_b32_e64 v194, 0, 32, s[40:41]
	v_ldexp_f32 v150, v150, v194
	v_log_f32_e32 v150, v150
	s_nop 0
	v_mul_f32_e32 v194, 0x3f317217, v150
	v_fma_f32 v194, v150, s52, -v194
	v_fmac_f32_e32 v194, 0x3377d1cf, v150
	v_fmac_f32_e32 v194, 0x3f317217, v150
	v_cmp_lt_f32_e64 s[42:43], |v150|, s53
	s_nop 1
	v_cndmask_b32_e64 v150, v150, v194, s[42:43]
	v_cndmask_b32_e64 v194, 0, v216, s[40:41]
	v_sub_f32_e32 v150, v150, v194
	v_cndmask_b32_e64 v150, v168, v150, s[10:11]
	v_min_f32_e32 v168, 0, v151
	v_mul_f32_e64 v151, |v151|, s57
	v_exp_f32_e32 v151, v151
	s_nop 0
	v_add_f32_e32 v151, 1.0, v151
	v_cmp_gt_f32_e64 s[40:41], s97, v151
	s_nop 1
	v_cndmask_b32_e64 v194, 0, 32, s[40:41]
	v_ldexp_f32 v151, v151, v194
	v_log_f32_e32 v151, v151
	s_nop 0
	v_mul_f32_e32 v194, 0x3f317217, v151
	v_fma_f32 v194, v151, s52, -v194
	v_fmac_f32_e32 v194, 0x3377d1cf, v151
	v_fmac_f32_e32 v194, 0x3f317217, v151
	v_cmp_lt_f32_e64 s[42:43], |v151|, s53
	s_nop 1
	v_cndmask_b32_e64 v151, v151, v194, s[42:43]
	v_cndmask_b32_e64 v194, 0, v216, s[40:41]
	v_sub_f32_e32 v151, v151, v194
	v_sub_f32_e32 v151, v168, v151
	v_min_f32_e32 v168, 0, v147
	v_mul_f32_e64 v147, |v147|, s57
	v_exp_f32_e32 v147, v147
	s_nop 0
	v_add_f32_e32 v147, 1.0, v147
	v_cmp_gt_f32_e64 s[40:41], s97, v147
	s_nop 1
	v_cndmask_b32_e64 v194, 0, 32, s[40:41]
	v_ldexp_f32 v147, v147, v194
	v_log_f32_e32 v147, v147
	s_nop 0
	v_mul_f32_e32 v194, 0x3f317217, v147
	v_fma_f32 v194, v147, s52, -v194
	v_fmac_f32_e32 v194, 0x3377d1cf, v147
	v_fmac_f32_e32 v194, 0x3f317217, v147
	v_cmp_lt_f32_e64 s[42:43], |v147|, s53
	s_nop 1
	v_cndmask_b32_e64 v147, v147, v194, s[42:43]
	v_cndmask_b32_e64 v194, 0, v216, s[40:41]
	v_sub_f32_e32 v147, v147, v194
	v_sub_f32_e32 v168, v168, v147
	v_mul_f32_e32 v147, 0x3fb8aa3b, v151
	v_exp_f32_e32 v147, v147
	s_nop 0
	v_fma_f32 v147, v177, v147, v135
	v_cmp_gt_f32_e64 s[40:41], s97, v147
	s_nop 1
	v_cndmask_b32_e64 v194, 0, 32, s[40:41]
	v_ldexp_f32 v147, v147, v194
	v_log_f32_e32 v147, v147
	s_nop 0
	v_mul_f32_e32 v194, 0x3f317217, v147
	v_fma_f32 v194, v147, s52, -v194
	v_fmac_f32_e32 v194, 0x3377d1cf, v147
	v_fmac_f32_e32 v194, 0x3f317217, v147
	v_cmp_lt_f32_e64 s[42:43], |v147|, s53
	s_nop 1
	v_cndmask_b32_e64 v147, v147, v194, s[42:43]
	v_cndmask_b32_e64 v194, 0, v216, s[40:41]
	v_sub_f32_e32 v147, v147, v194
	v_cndmask_b32_e64 v147, v151, v147, s[8:9]
	v_mul_f32_e32 v151, 0x3fb8aa3b, v168
	v_exp_f32_e32 v151, v151
	s_nop 0
	v_fma_f32 v151, v167, v151, v131
	v_cmp_gt_f32_e64 s[40:41], s97, v151
	s_nop 1
	v_cndmask_b32_e64 v194, 0, 32, s[40:41]
	v_ldexp_f32 v151, v151, v194
	v_log_f32_e32 v151, v151
	s_nop 0
	v_mul_f32_e32 v194, 0x3f317217, v151
	v_fma_f32 v194, v151, s52, -v194
	v_fmac_f32_e32 v194, 0x3377d1cf, v151
	v_fmac_f32_e32 v194, 0x3f317217, v151
	v_cmp_lt_f32_e64 s[42:43], |v151|, s53
	s_nop 1
	v_cndmask_b32_e64 v151, v151, v194, s[42:43]
	v_cndmask_b32_e64 v194, 0, v216, s[40:41]
	v_sub_f32_e32 v151, v151, v194
	v_cndmask_b32_e32 v151, v168, v151, vcc
	global_store_dwordx4 v[170:171], v[144:147], off offset:512
	global_store_dwordx4 v[170:171], v[148:151], off offset:528
	s_nop 1
	v_or_b32_e32 v148, 32, v166
	v_ashrrev_i32_e32 v149, 31, v148
	v_lshlrev_b64 v[144:145], 6, v[148:149]
	v_lshl_add_u64 v[144:145], v[160:161], 0, v[144:145]
	s_nop 0
	s_waitcnt lgkmcnt(0)
	s_nop 3
	s_nop 0
	s_nop 1
	s_waitcnt lgkmcnt(0)
	s_nop 1
	s_waitcnt lgkmcnt(0)
;     __device__ __forceinline__ void operator()(const f32x4 (&acc)[2][2][4][2], const pg8::Unit& u, int wr, int wc, int fr, int fq) const {
;     ...
;             WIN_LOOP( _Pragma("unroll") for (int i = 0; i < 4; ++i) { const float s0 = fminf(a[i], 0.f) - __logf(1.f + __expf(-fabsf(a[i]))), s1 = fminf(b[i], 0.f) - __logf(1.f + __expf(-fabsf(b[i]))); const float la = l0[bj][i], lbv = l1[bj][i];
;                     a[i] = la > 0.f ? __logf(la + (1.f - la) * __expf(s0)) : s0; b[i] = lbv > 0.f ? __logf(lbv + (1.f - lbv) * __expf(s1)) : s1; }
;                 *(f32x4*)(LF + (size_t)row * 512 + c) = a; *(f32x4*)(LF + (size_t)row * 512 + c + 4) = b; __builtin_amdgcn_sched_barrier(0); ) }
	s_nop 1
	v_mov_b32_e32 v168, v252
	v_lshlrev_b64 v[144:145], 11, v[148:149]
	v_lshl_add_u64 v[170:171], s[50:51], 0, v[144:145]
	v_lshl_add_u64 v[170:171], v[170:171], 0, v[192:193]
	v_pk_mul_f32 v[148:149], v[44:45], v[168:169] op_sel_hi:[1,0]
	v_pk_mul_f32 v[144:145], v[40:41], v[168:169] op_sel_hi:[1,0]
	v_min_f32_e32 v194, 0, v148
	v_mul_f32_e64 v148, |v148|, s57
	v_exp_f32_e32 v148, v148
	v_pk_mul_f32 v[150:151], v[46:47], v[168:169] op_sel_hi:[1,0]
	v_pk_mul_f32 v[146:147], v[42:43], v[168:169] op_sel_hi:[1,0]
	v_add_f32_e32 v148, 1.0, v148
	v_cmp_gt_f32_e64 s[40:41], s97, v148
	s_nop 1
	v_cndmask_b32_e64 v195, 0, 32, s[40:41]
	v_ldexp_f32 v148, v148, v195
	v_log_f32_e32 v148, v148
	s_nop 0
	v_mul_f32_e32 v195, 0x3f317217, v148
	v_fma_f32 v195, v148, s52, -v195
	v_fmac_f32_e32 v195, 0x3377d1cf, v148
	v_fmac_f32_e32 v195, 0x3f317217, v148
	v_cmp_lt_f32_e64 s[42:43], |v148|, s53
	s_nop 1
	v_cndmask_b32_e64 v148, v148, v195, s[42:43]
	v_cndmask_b32_e64 v195, 0, v216, s[40:41]
	v_sub_f32_e32 v148, v148, v195
	v_sub_f32_e32 v148, v194, v148
	v_min_f32_e32 v194, 0, v144
	v_mul_f32_e64 v144, |v144|, s57
	v_exp_f32_e32 v144, v144
	s_nop 0
	v_add_f32_e32 v144, 1.0, v144
	v_cmp_gt_f32_e64 s[40:41], s97, v144
	s_nop 1
	v_cndmask_b32_e64 v195, 0, 32, s[40:41]
	v_ldexp_f32 v144, v144, v195
	v_log_f32_e32 v144, v144
	s_nop 0
	v_mul_f32_e32 v195, 0x3f317217, v144
	v_fma_f32 v195, v144, s52, -v195
	v_fmac_f32_e32 v195, 0x3377d1cf, v144
	v_fmac_f32_e32 v195, 0x3f317217, v144
	v_cmp_lt_f32_e64 s[42:43], |v144|, s53
	s_nop 1
	v_cndmask_b32_e64 v144, v144, v195, s[42:43]
	v_cndmask_b32_e64 v195, 0, v216, s[40:41]
	v_sub_f32_e32 v144, v144, v195
	v_sub_f32_e32 v194, v194, v144
	v_mul_f32_e32 v144, 0x3fb8aa3b, v148
	v_exp_f32_e32 v144, v144
	s_nop 0
	v_fma_f32 v144, v190, v144, v140
	v_cmp_gt_f32_e64 s[40:41], s97, v144
	s_nop 1
	v_cndmask_b32_e64 v195, 0, 32, s[40:41]
	v_ldexp_f32 v144, v144, v195
	v_log_f32_e32 v144, v144
	s_nop 0
	v_mul_f32_e32 v195, 0x3f317217, v144
	v_fma_f32 v195, v144, s52, -v195
	v_fmac_f32_e32 v195, 0x3377d1cf, v144
	v_fmac_f32_e32 v195, 0x3f317217, v144
	v_cmp_lt_f32_e64 s[42:43], |v144|, s53
	s_nop 1
	v_cndmask_b32_e64 v144, v144, v195, s[42:43]
	v_cndmask_b32_e64 v195, 0, v216, s[40:41]
	v_sub_f32_e32 v144, v144, v195
	v_cndmask_b32_e64 v144, v148, v144, s[38:39]
	v_mul_f32_e32 v148, 0x3fb8aa3b, v194
	v_exp_f32_e32 v148, v148
	s_nop 0
	v_fma_f32 v148, v191, v148, v136
	v_cmp_gt_f32_e64 s[40:41], s97, v148
	s_nop 1
	v_cndmask_b32_e64 v195, 0, 32, s[40:41]
	v_ldexp_f32 v148, v148, v195
	v_log_f32_e32 v148, v148
	s_nop 0
	v_mul_f32_e32 v195, 0x3f317217, v148
	v_fma_f32 v195, v148, s52, -v195
	v_fmac_f32_e32 v195, 0x3377d1cf, v148
	v_fmac_f32_e32 v195, 0x3f317217, v148
	v_cmp_lt_f32_e64 s[42:43], |v148|, s53
	s_nop 1
	v_cndmask_b32_e64 v148, v148, v195, s[42:43]
	v_cndmask_b32_e64 v195, 0, v216, s[40:41]
	v_sub_f32_e32 v148, v148, v195
	v_cndmask_b32_e64 v148, v194, v148, s[36:37]
	v_min_f32_e32 v194, 0, v149
	v_mul_f32_e64 v149, |v149|, s57
	v_exp_f32_e32 v149, v149
	s_nop 0
	v_add_f32_e32 v149, 1.0, v149
	v_cmp_gt_f32_e64 s[40:41], s97, v149
	s_nop 1
	v_cndmask_b32_e64 v195, 0, 32, s[40:41]
	v_ldexp_f32 v149, v149, v195
	v_log_f32_e32 v149, v149
	s_nop 0
	v_mul_f32_e32 v195, 0x3f317217, v149
	v_fma_f32 v195, v149, s52, -v195
	v_fmac_f32_e32 v195, 0x3377d1cf, v149
	v_fmac_f32_e32 v195, 0x3f317217, v149
	v_cmp_lt_f32_e64 s[42:43], |v149|, s53
	s_nop 1
	v_cndmask_b32_e64 v149, v149, v195, s[42:43]
	v_cndmask_b32_e64 v195, 0, v216, s[40:41]
	v_sub_f32_e32 v149, v149, v195
	v_sub_f32_e32 v149, v194, v149
	v_min_f32_e32 v194, 0, v145
	v_mul_f32_e64 v145, |v145|, s57
	v_exp_f32_e32 v145, v145
	s_nop 0
	v_add_f32_e32 v145, 1.0, v145
	v_cmp_gt_f32_e64 s[40:41], s97, v145
	s_nop 1
	v_cndmask_b32_e64 v195, 0, 32, s[40:41]
	v_ldexp_f32 v145, v145, v195
	v_log_f32_e32 v145, v145
	s_nop 0
	v_mul_f32_e32 v195, 0x3f317217, v145
	v_fma_f32 v195, v145, s52, -v195
	v_fmac_f32_e32 v195, 0x3377d1cf, v145
	v_fmac_f32_e32 v195, 0x3f317217, v145
	v_cmp_lt_f32_e64 s[42:43], |v145|, s53
	s_nop 1
	v_cndmask_b32_e64 v145, v145, v195, s[42:43]
	v_cndmask_b32_e64 v195, 0, v216, s[40:41]
	v_sub_f32_e32 v145, v145, v195
	v_sub_f32_e32 v194, v194, v145
	v_mul_f32_e32 v145, 0x3fb8aa3b, v149
	v_exp_f32_e32 v145, v145
	s_nop 0
	v_fma_f32 v145, v188, v145, v141
	v_cmp_gt_f32_e64 s[40:41], s97, v145
	s_nop 1
	v_cndmask_b32_e64 v195, 0, 32, s[40:41]
	v_ldexp_f32 v145, v145, v195
	v_log_f32_e32 v145, v145
	s_nop 0
	v_mul_f32_e32 v195, 0x3f317217, v145
	v_fma_f32 v195, v145, s52, -v195
	v_fmac_f32_e32 v195, 0x3377d1cf, v145
	v_fmac_f32_e32 v195, 0x3f317217, v145
	v_cmp_lt_f32_e64 s[42:43], |v145|, s53
	s_nop 1
	v_cndmask_b32_e64 v145, v145, v195, s[42:43]
	v_cndmask_b32_e64 v195, 0, v216, s[40:41]
	v_sub_f32_e32 v145, v145, v195
	v_cndmask_b32_e64 v145, v149, v145, s[34:35]
	v_mul_f32_e32 v149, 0x3fb8aa3b, v194
	v_exp_f32_e32 v149, v149
	s_nop 0
	v_fma_f32 v149, v189, v149, v137
	v_cmp_gt_f32_e64 s[40:41], s97, v149
	s_nop 1
	v_cndmask_b32_e64 v195, 0, 32, s[40:41]
	v_ldexp_f32 v149, v149, v195
	v_log_f32_e32 v149, v149
	s_nop 0
	v_mul_f32_e32 v195, 0x3f317217, v149
	v_fma_f32 v195, v149, s52, -v195
	v_fmac_f32_e32 v195, 0x3377d1cf, v149
	v_fmac_f32_e32 v195, 0x3f317217, v149
	v_cmp_lt_f32_e64 s[42:43], |v149|, s53
	s_nop 1
	v_cndmask_b32_e64 v149, v149, v195, s[42:43]
	v_cndmask_b32_e64 v195, 0, v216, s[40:41]
	v_sub_f32_e32 v149, v149, v195
	v_cndmask_b32_e64 v149, v194, v149, s[30:31]
	v_min_f32_e32 v194, 0, v150
	v_mul_f32_e64 v150, |v150|, s57
	v_exp_f32_e32 v150, v150
	s_nop 0
	v_add_f32_e32 v150, 1.0, v150
	v_cmp_gt_f32_e64 s[40:41], s97, v150
	s_nop 1
; __device__ __forceinline__ float logsig_f(float x) { return fminf(x, 0.f) - __logf(1.f + __expf(-fabsf(x))); }
;     __device__ __forceinline__ void operator()(const f32x4 (&acc)[2][2][4][2], const pg8::Unit& u, int wr, int wc, int fr, int fq) const {
;     ...
;             WIN_LOOP( _Pragma("unroll") for (int i = 0; i < 4; ++i) { const float s0 = fminf(a[i], 0.f) - __logf(1.f + __expf(-fabsf(a[i]))), s1 = fminf(b[i], 0.f) - __logf(1.f + __expf(-fabsf(b[i]))); const float la = l0[bj][i], lbv = l1[bj][i];
;                     a[i] = la > 0.f ? __logf(la + (1.f - la) * __expf(s0)) : s0; b[i] = lbv > 0.f ? __logf(lbv + (1.f - lbv) * __expf(s1)) : s1; }
;                 *(f32x4*)(LF + (size_t)row * 512 + c) = a; *(f32x4*)(LF + (size_t)row * 512 + c + 4) = b; __builtin_amdgcn_sched_barrier(0); ) }
	v_cndmask_b32_e64 v195, 0, 32, s[40:41]
	v_ldexp_f32 v150, v150, v195
	v_log_f32_e32 v150, v150
	s_nop 0
	v_mul_f32_e32 v195, 0x3f317217, v150
	v_fma_f32 v195, v150, s52, -v195
	v_fmac_f32_e32 v195, 0x3377d1cf, v150
	v_fmac_f32_e32 v195, 0x3f317217, v150
	v_cmp_lt_f32_e64 s[42:43], |v150|, s53
	s_nop 1
	v_cndmask_b32_e64 v150, v150, v195, s[42:43]
	v_cndmask_b32_e64 v195, 0, v216, s[40:41]
	v_sub_f32_e32 v150, v150, v195
	v_sub_f32_e32 v150, v194, v150
	v_min_f32_e32 v194, 0, v146
	v_mul_f32_e64 v146, |v146|, s57
	v_exp_f32_e32 v146, v146
	s_nop 0
	v_add_f32_e32 v146, 1.0, v146
	v_cmp_gt_f32_e64 s[40:41], s97, v146
	s_nop 1
	v_cndmask_b32_e64 v195, 0, 32, s[40:41]
	v_ldexp_f32 v146, v146, v195
	v_log_f32_e32 v146, v146
	s_nop 0
	v_mul_f32_e32 v195, 0x3f317217, v146
	v_fma_f32 v195, v146, s52, -v195
	v_fmac_f32_e32 v195, 0x3377d1cf, v146
	v_fmac_f32_e32 v195, 0x3f317217, v146
	v_cmp_lt_f32_e64 s[42:43], |v146|, s53
	s_nop 1
	v_cndmask_b32_e64 v146, v146, v195, s[42:43]
	v_cndmask_b32_e64 v195, 0, v216, s[40:41]
	v_sub_f32_e32 v146, v146, v195
	v_sub_f32_e32 v194, v194, v146
	v_mul_f32_e32 v146, 0x3fb8aa3b, v150
	v_exp_f32_e32 v146, v146
	s_nop 0
	v_fma_f32 v146, v187, v146, v142
	v_cmp_gt_f32_e64 s[40:41], s97, v146
	s_nop 1
	v_cndmask_b32_e64 v195, 0, 32, s[40:41]
	v_ldexp_f32 v146, v146, v195
	v_log_f32_e32 v146, v146
	s_nop 0
	v_mul_f32_e32 v195, 0x3f317217, v146
	v_fma_f32 v195, v146, s52, -v195
	v_fmac_f32_e32 v195, 0x3377d1cf, v146
	v_fmac_f32_e32 v195, 0x3f317217, v146
	v_cmp_lt_f32_e64 s[42:43], |v146|, s53
	s_nop 1
	v_cndmask_b32_e64 v146, v146, v195, s[42:43]
	v_cndmask_b32_e64 v195, 0, v216, s[40:41]
	v_sub_f32_e32 v146, v146, v195
	v_cndmask_b32_e64 v146, v150, v146, s[28:29]
	v_mul_f32_e32 v150, 0x3fb8aa3b, v194
	v_exp_f32_e32 v150, v150
	s_nop 0
	v_fma_f32 v150, v186, v150, v138
	v_cmp_gt_f32_e64 s[40:41], s97, v150
	s_nop 1
	v_cndmask_b32_e64 v195, 0, 32, s[40:41]
	v_ldexp_f32 v150, v150, v195
	v_log_f32_e32 v150, v150
	s_nop 0
	v_mul_f32_e32 v195, 0x3f317217, v150
	v_fma_f32 v195, v150, s52, -v195
	v_fmac_f32_e32 v195, 0x3377d1cf, v150
	v_fmac_f32_e32 v195, 0x3f317217, v150
	v_cmp_lt_f32_e64 s[42:43], |v150|, s53
	s_nop 1
	v_cndmask_b32_e64 v150, v150, v195, s[42:43]
	v_cndmask_b32_e64 v195, 0, v216, s[40:41]
	v_sub_f32_e32 v150, v150, v195
	v_cndmask_b32_e64 v150, v194, v150, s[26:27]
	v_min_f32_e32 v194, 0, v151
	v_mul_f32_e64 v151, |v151|, s57
	v_exp_f32_e32 v151, v151
	s_nop 0
	v_add_f32_e32 v151, 1.0, v151
	v_cmp_gt_f32_e64 s[40:41], s97, v151
	s_nop 1
	v_cndmask_b32_e64 v195, 0, 32, s[40:41]
	v_ldexp_f32 v151, v151, v195
	v_log_f32_e32 v151, v151
	s_nop 0
	v_mul_f32_e32 v195, 0x3f317217, v151
	v_fma_f32 v195, v151, s52, -v195
	v_fmac_f32_e32 v195, 0x3377d1cf, v151
	v_fmac_f32_e32 v195, 0x3f317217, v151
	v_cmp_lt_f32_e64 s[42:43], |v151|, s53
	s_nop 1
	v_cndmask_b32_e64 v151, v151, v195, s[42:43]
	v_cndmask_b32_e64 v195, 0, v216, s[40:41]
	v_sub_f32_e32 v151, v151, v195
	v_sub_f32_e32 v151, v194, v151
	v_min_f32_e32 v194, 0, v147
	v_mul_f32_e64 v147, |v147|, s57
	v_exp_f32_e32 v147, v147
	s_nop 0
	v_add_f32_e32 v147, 1.0, v147
	v_cmp_gt_f32_e64 s[40:41], s97, v147
	s_nop 1
	v_cndmask_b32_e64 v195, 0, 32, s[40:41]
	v_ldexp_f32 v147, v147, v195
	v_log_f32_e32 v147, v147
	s_nop 0
	v_mul_f32_e32 v195, 0x3f317217, v147
	v_fma_f32 v195, v147, s52, -v195
	v_fmac_f32_e32 v195, 0x3377d1cf, v147
	v_fmac_f32_e32 v195, 0x3f317217, v147
	v_cmp_lt_f32_e64 s[42:43], |v147|, s53
	s_nop 1
	v_cndmask_b32_e64 v147, v147, v195, s[42:43]
	v_cndmask_b32_e64 v195, 0, v216, s[40:41]
	v_sub_f32_e32 v147, v147, v195
	v_sub_f32_e32 v194, v194, v147
	v_mul_f32_e32 v147, 0x3fb8aa3b, v151
	v_exp_f32_e32 v147, v147
	s_nop 0
	v_fma_f32 v147, v185, v147, v143
	v_cmp_gt_f32_e64 s[40:41], s97, v147
	s_nop 1
	v_cndmask_b32_e64 v195, 0, 32, s[40:41]
	v_ldexp_f32 v147, v147, v195
	v_log_f32_e32 v147, v147
	s_nop 0
	v_mul_f32_e32 v195, 0x3f317217, v147
	v_fma_f32 v195, v147, s52, -v195
	v_fmac_f32_e32 v195, 0x3377d1cf, v147
	v_fmac_f32_e32 v195, 0x3f317217, v147
	v_cmp_lt_f32_e64 s[42:43], |v147|, s53
	s_nop 1
	v_cndmask_b32_e64 v147, v147, v195, s[42:43]
	v_cndmask_b32_e64 v195, 0, v216, s[40:41]
	v_sub_f32_e32 v147, v147, v195
	v_cndmask_b32_e64 v147, v151, v147, s[24:25]
	v_mul_f32_e32 v151, 0x3fb8aa3b, v194
	v_exp_f32_e32 v151, v151
	s_nop 0
	v_fma_f32 v151, v184, v151, v139
	v_cmp_gt_f32_e64 s[40:41], s97, v151
	s_nop 1
	v_cndmask_b32_e64 v195, 0, 32, s[40:41]
	v_ldexp_f32 v151, v151, v195
	v_log_f32_e32 v151, v151
	s_nop 0
	v_mul_f32_e32 v195, 0x3f317217, v151
	v_fma_f32 v195, v151, s52, -v195
	v_fmac_f32_e32 v195, 0x3377d1cf, v151
	v_fmac_f32_e32 v195, 0x3f317217, v151
	v_cmp_lt_f32_e64 s[42:43], |v151|, s53
	s_nop 1
	v_cndmask_b32_e64 v151, v151, v195, s[42:43]
	v_cndmask_b32_e64 v195, 0, v216, s[40:41]
	v_sub_f32_e32 v151, v151, v195
	v_cndmask_b32_e64 v151, v194, v151, s[22:23]
	global_store_dwordx4 v[170:171], v[144:147], off
	global_store_dwordx4 v[170:171], v[148:151], off offset:16
	s_nop 1
	v_pk_mul_f32 v[148:149], v[108:109], v[168:169] op_sel_hi:[1,0]
	v_pk_mul_f32 v[150:151], v[110:111], v[168:169] op_sel_hi:[1,0]
	v_pk_mul_f32 v[146:147], v[106:107], v[168:169] op_sel_hi:[1,0]
	v_pk_mul_f32 v[144:145], v[104:105], v[168:169] op_sel_hi:[1,0]
	v_min_f32_e32 v168, 0, v148
	v_mul_f32_e64 v148, |v148|, s57
	v_exp_f32_e32 v148, v148
	s_nop 0
	v_add_f32_e32 v148, 1.0, v148
	v_cmp_gt_f32_e64 s[40:41], s97, v148
	s_nop 1
	v_cndmask_b32_e64 v194, 0, 32, s[40:41]
	v_ldexp_f32 v148, v148, v194
	v_log_f32_e32 v148, v148
	s_nop 0
	v_mul_f32_e32 v194, 0x3f317217, v148
	v_fma_f32 v194, v148, s52, -v194
	v_fmac_f32_e32 v194, 0x3377d1cf, v148
; __device__ __forceinline__ float logsig_f(float x) { return fminf(x, 0.f) - __logf(1.f + __expf(-fabsf(x))); }
;     __device__ __forceinline__ void operator()(const f32x4 (&acc)[2][2][4][2], const pg8::Unit& u, int wr, int wc, int fr, int fq) const {
;     ...
;             WIN_LOOP( _Pragma("unroll") for (int i = 0; i < 4; ++i) { const float s0 = fminf(a[i], 0.f) - __logf(1.f + __expf(-fabsf(a[i]))), s1 = fminf(b[i], 0.f) - __logf(1.f + __expf(-fabsf(b[i]))); const float la = l0[bj][i], lbv = l1[bj][i];
;                     a[i] = la > 0.f ? __logf(la + (1.f - la) * __expf(s0)) : s0; b[i] = lbv > 0.f ? __logf(lbv + (1.f - lbv) * __expf(s1)) : s1; }
;                 *(f32x4*)(LF + (size_t)row * 512 + c) = a; *(f32x4*)(LF + (size_t)row * 512 + c + 4) = b; __builtin_amdgcn_sched_barrier(0); ) }
	v_fmac_f32_e32 v194, 0x3f317217, v148
	v_cmp_lt_f32_e64 s[42:43], |v148|, s53
	s_nop 1
	v_cndmask_b32_e64 v148, v148, v194, s[42:43]
	v_cndmask_b32_e64 v194, 0, v216, s[40:41]
	v_sub_f32_e32 v148, v148, v194
	v_sub_f32_e32 v148, v168, v148
	v_min_f32_e32 v168, 0, v144
	v_mul_f32_e64 v144, |v144|, s57
	v_exp_f32_e32 v144, v144
	s_nop 0
	v_add_f32_e32 v144, 1.0, v144
	v_cmp_gt_f32_e64 s[40:41], s97, v144
	s_nop 1
	v_cndmask_b32_e64 v194, 0, 32, s[40:41]
	v_ldexp_f32 v144, v144, v194
	v_log_f32_e32 v144, v144
	s_nop 0
	v_mul_f32_e32 v194, 0x3f317217, v144
	v_fma_f32 v194, v144, s52, -v194
	v_fmac_f32_e32 v194, 0x3377d1cf, v144
	v_fmac_f32_e32 v194, 0x3f317217, v144
	v_cmp_lt_f32_e64 s[42:43], |v144|, s53
	s_nop 1
	v_cndmask_b32_e64 v144, v144, v194, s[42:43]
	v_cndmask_b32_e64 v194, 0, v216, s[40:41]
	v_sub_f32_e32 v144, v144, v194
	v_sub_f32_e32 v168, v168, v144
	v_mul_f32_e32 v144, 0x3fb8aa3b, v148
	v_exp_f32_e32 v144, v144
	s_nop 0
	v_fma_f32 v144, v183, v144, v132
	v_cmp_gt_f32_e64 s[40:41], s97, v144
	s_nop 1
	v_cndmask_b32_e64 v194, 0, 32, s[40:41]
	v_ldexp_f32 v144, v144, v194
	v_log_f32_e32 v144, v144
	s_nop 0
	v_mul_f32_e32 v194, 0x3f317217, v144
	v_fma_f32 v194, v144, s52, -v194
	v_fmac_f32_e32 v194, 0x3377d1cf, v144
	v_fmac_f32_e32 v194, 0x3f317217, v144
	v_cmp_lt_f32_e64 s[42:43], |v144|, s53
	s_nop 1
	v_cndmask_b32_e64 v144, v144, v194, s[42:43]
	v_cndmask_b32_e64 v194, 0, v216, s[40:41]
	v_sub_f32_e32 v144, v144, v194
	v_cndmask_b32_e64 v144, v148, v144, s[20:21]
	v_mul_f32_e32 v148, 0x3fb8aa3b, v168
	v_exp_f32_e32 v148, v148
	s_nop 0
	v_fma_f32 v148, v182, v148, v128
	v_cmp_gt_f32_e64 s[40:41], s97, v148
	s_nop 1
	v_cndmask_b32_e64 v194, 0, 32, s[40:41]
	v_ldexp_f32 v148, v148, v194
	v_log_f32_e32 v148, v148
	s_nop 0
	v_mul_f32_e32 v194, 0x3f317217, v148
	v_fma_f32 v194, v148, s52, -v194
	v_fmac_f32_e32 v194, 0x3377d1cf, v148
	v_fmac_f32_e32 v194, 0x3f317217, v148
	v_cmp_lt_f32_e64 s[42:43], |v148|, s53
	s_nop 1
	v_cndmask_b32_e64 v148, v148, v194, s[42:43]
	v_cndmask_b32_e64 v194, 0, v216, s[40:41]
	v_sub_f32_e32 v148, v148, v194
	v_cndmask_b32_e64 v148, v168, v148, s[18:19]
	v_min_f32_e32 v168, 0, v149
	v_mul_f32_e64 v149, |v149|, s57
	v_exp_f32_e32 v149, v149
	s_nop 0
	v_add_f32_e32 v149, 1.0, v149
	v_cmp_gt_f32_e64 s[40:41], s97, v149
	s_nop 1
	v_cndmask_b32_e64 v194, 0, 32, s[40:41]
	v_ldexp_f32 v149, v149, v194
	v_log_f32_e32 v149, v149
	s_nop 0
	v_mul_f32_e32 v194, 0x3f317217, v149
	v_fma_f32 v194, v149, s52, -v194
	v_fmac_f32_e32 v194, 0x3377d1cf, v149
	v_fmac_f32_e32 v194, 0x3f317217, v149
	v_cmp_lt_f32_e64 s[42:43], |v149|, s53
	s_nop 1
	v_cndmask_b32_e64 v149, v149, v194, s[42:43]
	v_cndmask_b32_e64 v194, 0, v216, s[40:41]
	v_sub_f32_e32 v149, v149, v194
	v_sub_f32_e32 v149, v168, v149
	v_min_f32_e32 v168, 0, v145
	v_mul_f32_e64 v145, |v145|, s57
	v_exp_f32_e32 v145, v145
	s_nop 0
	v_add_f32_e32 v145, 1.0, v145
	v_cmp_gt_f32_e64 s[40:41], s97, v145
	s_nop 1
	v_cndmask_b32_e64 v194, 0, 32, s[40:41]
	v_ldexp_f32 v145, v145, v194
	v_log_f32_e32 v145, v145
	s_nop 0
	v_mul_f32_e32 v194, 0x3f317217, v145
	v_fma_f32 v194, v145, s52, -v194
	v_fmac_f32_e32 v194, 0x3377d1cf, v145
	v_fmac_f32_e32 v194, 0x3f317217, v145
	v_cmp_lt_f32_e64 s[42:43], |v145|, s53
	s_nop 1
	v_cndmask_b32_e64 v145, v145, v194, s[42:43]
	v_cndmask_b32_e64 v194, 0, v216, s[40:41]
	v_sub_f32_e32 v145, v145, v194
	v_sub_f32_e32 v168, v168, v145
	v_mul_f32_e32 v145, 0x3fb8aa3b, v149
	v_exp_f32_e32 v145, v145
	s_nop 0
	v_fma_f32 v145, v181, v145, v133
	v_cmp_gt_f32_e64 s[40:41], s97, v145
	s_nop 1
	v_cndmask_b32_e64 v194, 0, 32, s[40:41]
	v_ldexp_f32 v145, v145, v194
	v_log_f32_e32 v145, v145
	s_nop 0
	v_mul_f32_e32 v194, 0x3f317217, v145
	v_fma_f32 v194, v145, s52, -v194
	v_fmac_f32_e32 v194, 0x3377d1cf, v145
	v_fmac_f32_e32 v194, 0x3f317217, v145
	v_cmp_lt_f32_e64 s[42:43], |v145|, s53
	s_nop 1
	v_cndmask_b32_e64 v145, v145, v194, s[42:43]
	v_cndmask_b32_e64 v194, 0, v216, s[40:41]
	v_sub_f32_e32 v145, v145, v194
	v_cndmask_b32_e64 v145, v149, v145, s[16:17]
	v_mul_f32_e32 v149, 0x3fb8aa3b, v168
	v_exp_f32_e32 v149, v149
	s_nop 0
	v_fma_f32 v149, v180, v149, v129
	v_cmp_gt_f32_e64 s[40:41], s97, v149
	s_nop 1
	v_cndmask_b32_e64 v194, 0, 32, s[40:41]
	v_ldexp_f32 v149, v149, v194
	v_log_f32_e32 v149, v149
	s_nop 0
	v_mul_f32_e32 v194, 0x3f317217, v149
	v_fma_f32 v194, v149, s52, -v194
	v_fmac_f32_e32 v194, 0x3377d1cf, v149
	v_fmac_f32_e32 v194, 0x3f317217, v149
	v_cmp_lt_f32_e64 s[42:43], |v149|, s53
	s_nop 1
	v_cndmask_b32_e64 v149, v149, v194, s[42:43]
	v_cndmask_b32_e64 v194, 0, v216, s[40:41]
	v_sub_f32_e32 v149, v149, v194
	v_cndmask_b32_e64 v149, v168, v149, s[14:15]
	v_min_f32_e32 v168, 0, v150
	v_mul_f32_e64 v150, |v150|, s57
	v_exp_f32_e32 v150, v150
	s_nop 0
	v_add_f32_e32 v150, 1.0, v150
	v_cmp_gt_f32_e64 s[40:41], s97, v150
	s_nop 1
	v_cndmask_b32_e64 v194, 0, 32, s[40:41]
	v_ldexp_f32 v150, v150, v194
	v_log_f32_e32 v150, v150
	s_nop 0
	v_mul_f32_e32 v194, 0x3f317217, v150
	v_fma_f32 v194, v150, s52, -v194
	v_fmac_f32_e32 v194, 0x3377d1cf, v150
	v_fmac_f32_e32 v194, 0x3f317217, v150
	v_cmp_lt_f32_e64 s[42:43], |v150|, s53
	s_nop 1
	v_cndmask_b32_e64 v150, v150, v194, s[42:43]
	v_cndmask_b32_e64 v194, 0, v216, s[40:41]
	v_sub_f32_e32 v150, v150, v194
	v_sub_f32_e32 v150, v168, v150
	v_min_f32_e32 v168, 0, v146
	v_mul_f32_e64 v146, |v146|, s57
	v_exp_f32_e32 v146, v146
	s_nop 0
	v_add_f32_e32 v146, 1.0, v146
	v_cmp_gt_f32_e64 s[40:41], s97, v146
	s_nop 1
	v_cndmask_b32_e64 v194, 0, 32, s[40:41]
	v_ldexp_f32 v146, v146, v194
	v_log_f32_e32 v146, v146
	s_nop 0
	v_mul_f32_e32 v194, 0x3f317217, v146
	v_fma_f32 v194, v146, s52, -v194
;     __device__ __forceinline__ void operator()(const f32x4 (&acc)[2][2][4][2], const pg8::Unit& u, int wr, int wc, int fr, int fq) const {
;     ...
;             WIN_LOOP( _Pragma("unroll") for (int i = 0; i < 4; ++i) { const float s0 = fminf(a[i], 0.f) - __logf(1.f + __expf(-fabsf(a[i]))), s1 = fminf(b[i], 0.f) - __logf(1.f + __expf(-fabsf(b[i]))); const float la = l0[bj][i], lbv = l1[bj][i];
;                     a[i] = la > 0.f ? __logf(la + (1.f - la) * __expf(s0)) : s0; b[i] = lbv > 0.f ? __logf(lbv + (1.f - lbv) * __expf(s1)) : s1; }
;                 *(f32x4*)(LF + (size_t)row * 512 + c) = a; *(f32x4*)(LF + (size_t)row * 512 + c + 4) = b; __builtin_amdgcn_sched_barrier(0); ) }
	v_fmac_f32_e32 v194, 0x3377d1cf, v146
	v_fmac_f32_e32 v194, 0x3f317217, v146
	v_cmp_lt_f32_e64 s[42:43], |v146|, s53
	s_nop 1
	v_cndmask_b32_e64 v146, v146, v194, s[42:43]
	v_cndmask_b32_e64 v194, 0, v216, s[40:41]
	v_sub_f32_e32 v146, v146, v194
	v_sub_f32_e32 v168, v168, v146
	v_mul_f32_e32 v146, 0x3fb8aa3b, v150
	v_exp_f32_e32 v146, v146
	s_nop 0
	v_fma_f32 v146, v179, v146, v134
	v_cmp_gt_f32_e64 s[40:41], s97, v146
	s_nop 1
	v_cndmask_b32_e64 v194, 0, 32, s[40:41]
	v_ldexp_f32 v146, v146, v194
	v_log_f32_e32 v146, v146
	s_nop 0
	v_mul_f32_e32 v194, 0x3f317217, v146
	v_fma_f32 v194, v146, s52, -v194
	v_fmac_f32_e32 v194, 0x3377d1cf, v146
	v_fmac_f32_e32 v194, 0x3f317217, v146
	v_cmp_lt_f32_e64 s[42:43], |v146|, s53
	s_nop 1
	v_cndmask_b32_e64 v146, v146, v194, s[42:43]
	v_cndmask_b32_e64 v194, 0, v216, s[40:41]
	v_sub_f32_e32 v146, v146, v194
	v_cndmask_b32_e64 v146, v150, v146, s[12:13]
	v_mul_f32_e32 v150, 0x3fb8aa3b, v168
	v_exp_f32_e32 v150, v150
	s_nop 0
	v_fma_f32 v150, v178, v150, v130
	v_cmp_gt_f32_e64 s[40:41], s97, v150
	s_nop 1
	v_cndmask_b32_e64 v194, 0, 32, s[40:41]
	v_ldexp_f32 v150, v150, v194
	v_log_f32_e32 v150, v150
	s_nop 0
	v_mul_f32_e32 v194, 0x3f317217, v150
	v_fma_f32 v194, v150, s52, -v194
	v_fmac_f32_e32 v194, 0x3377d1cf, v150
	v_fmac_f32_e32 v194, 0x3f317217, v150
	v_cmp_lt_f32_e64 s[42:43], |v150|, s53
	s_nop 1
	v_cndmask_b32_e64 v150, v150, v194, s[42:43]
	v_cndmask_b32_e64 v194, 0, v216, s[40:41]
	v_sub_f32_e32 v150, v150, v194
	v_cndmask_b32_e64 v150, v168, v150, s[10:11]
	v_min_f32_e32 v168, 0, v151
	v_mul_f32_e64 v151, |v151|, s57
	v_exp_f32_e32 v151, v151
	s_nop 0
	v_add_f32_e32 v151, 1.0, v151
	v_cmp_gt_f32_e64 s[40:41], s97, v151
	s_nop 1
	v_cndmask_b32_e64 v194, 0, 32, s[40:41]
	v_ldexp_f32 v151, v151, v194
	v_log_f32_e32 v151, v151
	s_nop 0
	v_mul_f32_e32 v194, 0x3f317217, v151
	v_fma_f32 v194, v151, s52, -v194
	v_fmac_f32_e32 v194, 0x3377d1cf, v151
	v_fmac_f32_e32 v194, 0x3f317217, v151
	v_cmp_lt_f32_e64 s[42:43], |v151|, s53
	s_nop 1
	v_cndmask_b32_e64 v151, v151, v194, s[42:43]
	v_cndmask_b32_e64 v194, 0, v216, s[40:41]
	v_sub_f32_e32 v151, v151, v194
	v_sub_f32_e32 v151, v168, v151
	v_min_f32_e32 v168, 0, v147
	v_mul_f32_e64 v147, |v147|, s57
	v_exp_f32_e32 v147, v147
	s_nop 0
	v_add_f32_e32 v147, 1.0, v147
	v_cmp_gt_f32_e64 s[40:41], s97, v147
	s_nop 1
	v_cndmask_b32_e64 v194, 0, 32, s[40:41]
	v_ldexp_f32 v147, v147, v194
	v_log_f32_e32 v147, v147
	s_nop 0
	v_mul_f32_e32 v194, 0x3f317217, v147
	v_fma_f32 v194, v147, s52, -v194
	v_fmac_f32_e32 v194, 0x3377d1cf, v147
	v_fmac_f32_e32 v194, 0x3f317217, v147
	v_cmp_lt_f32_e64 s[42:43], |v147|, s53
	s_nop 1
	v_cndmask_b32_e64 v147, v147, v194, s[42:43]
	v_cndmask_b32_e64 v194, 0, v216, s[40:41]
	v_sub_f32_e32 v147, v147, v194
	v_sub_f32_e32 v168, v168, v147
	v_mul_f32_e32 v147, 0x3fb8aa3b, v151
	v_exp_f32_e32 v147, v147
	s_nop 0
	v_fma_f32 v147, v177, v147, v135
	v_cmp_gt_f32_e64 s[40:41], s97, v147
	s_nop 1
	v_cndmask_b32_e64 v194, 0, 32, s[40:41]
	v_ldexp_f32 v147, v147, v194
	v_log_f32_e32 v147, v147
	s_nop 0
	v_mul_f32_e32 v194, 0x3f317217, v147
	v_fma_f32 v194, v147, s52, -v194
	v_fmac_f32_e32 v194, 0x3377d1cf, v147
	v_fmac_f32_e32 v194, 0x3f317217, v147
	v_cmp_lt_f32_e64 s[42:43], |v147|, s53
	s_nop 1
	v_cndmask_b32_e64 v147, v147, v194, s[42:43]
	v_cndmask_b32_e64 v194, 0, v216, s[40:41]
	v_sub_f32_e32 v147, v147, v194
	v_cndmask_b32_e64 v147, v151, v147, s[8:9]
	v_mul_f32_e32 v151, 0x3fb8aa3b, v168
	v_exp_f32_e32 v151, v151
	s_nop 0
	v_fma_f32 v151, v167, v151, v131
	v_cmp_gt_f32_e64 s[40:41], s97, v151
	s_nop 1
	v_cndmask_b32_e64 v194, 0, 32, s[40:41]
	v_ldexp_f32 v151, v151, v194
	v_log_f32_e32 v151, v151
	s_nop 0
	v_mul_f32_e32 v194, 0x3f317217, v151
	v_fma_f32 v194, v151, s52, -v194
	v_fmac_f32_e32 v194, 0x3377d1cf, v151
	v_fmac_f32_e32 v194, 0x3f317217, v151
	v_cmp_lt_f32_e64 s[42:43], |v151|, s53
	s_nop 1
	v_cndmask_b32_e64 v151, v151, v194, s[42:43]
	v_cndmask_b32_e64 v194, 0, v216, s[40:41]
	v_sub_f32_e32 v151, v151, v194
	v_cndmask_b32_e32 v151, v168, v151, vcc
	global_store_dwordx4 v[170:171], v[144:147], off offset:512
	global_store_dwordx4 v[170:171], v[148:151], off offset:528
	s_nop 1
	v_or_b32_e32 v148, 48, v166
	v_ashrrev_i32_e32 v149, 31, v148
	v_lshlrev_b64 v[144:145], 6, v[148:149]
	v_lshl_add_u64 v[144:145], v[160:161], 0, v[144:145]
	s_nop 0
	s_waitcnt lgkmcnt(0)
	s_nop 3
	s_nop 0
	s_nop 1
	s_waitcnt lgkmcnt(0)
	s_nop 1
	s_waitcnt lgkmcnt(0)
;     __device__ __forceinline__ void operator()(const f32x4 (&acc)[2][2][4][2], const pg8::Unit& u, int wr, int wc, int fr, int fq) const {
;     ...
;             WIN_LOOP( _Pragma("unroll") for (int i = 0; i < 4; ++i) { const float s0 = fminf(a[i], 0.f) - __logf(1.f + __expf(-fabsf(a[i]))), s1 = fminf(b[i], 0.f) - __logf(1.f + __expf(-fabsf(b[i]))); const float la = l0[bj][i], lbv = l1[bj][i];
;                     a[i] = la > 0.f ? __logf(la + (1.f - la) * __expf(s0)) : s0; b[i] = lbv > 0.f ? __logf(lbv + (1.f - lbv) * __expf(s1)) : s1; }
;                 *(f32x4*)(LF + (size_t)row * 512 + c) = a; *(f32x4*)(LF + (size_t)row * 512 + c + 4) = b; __builtin_amdgcn_sched_barrier(0); ) }
	s_nop 1
	v_mov_b32_e32 v168, v253
	v_lshlrev_b64 v[144:145], 11, v[148:149]
	v_lshl_add_u64 v[170:171], s[50:51], 0, v[144:145]
	v_lshl_add_u64 v[170:171], v[170:171], 0, v[192:193]
	v_pk_mul_f32 v[148:149], v[36:37], v[168:169] op_sel_hi:[1,0]
	v_pk_mul_f32 v[144:145], v[32:33], v[168:169] op_sel_hi:[1,0]
	v_min_f32_e32 v194, 0, v148
	v_mul_f32_e64 v148, |v148|, s57
	v_exp_f32_e32 v148, v148
	v_pk_mul_f32 v[150:151], v[38:39], v[168:169] op_sel_hi:[1,0]
	v_pk_mul_f32 v[146:147], v[34:35], v[168:169] op_sel_hi:[1,0]
	v_add_f32_e32 v148, 1.0, v148
	v_cmp_gt_f32_e64 s[40:41], s97, v148
	s_nop 1
	v_cndmask_b32_e64 v195, 0, 32, s[40:41]
	v_ldexp_f32 v148, v148, v195
	v_log_f32_e32 v148, v148
	s_nop 0
	v_mul_f32_e32 v195, 0x3f317217, v148
	v_fma_f32 v195, v148, s52, -v195
	v_fmac_f32_e32 v195, 0x3377d1cf, v148
	v_fmac_f32_e32 v195, 0x3f317217, v148
	v_cmp_lt_f32_e64 s[42:43], |v148|, s53
	s_nop 1
	v_cndmask_b32_e64 v148, v148, v195, s[42:43]
	v_cndmask_b32_e64 v195, 0, v216, s[40:41]
	v_sub_f32_e32 v148, v148, v195
	v_sub_f32_e32 v148, v194, v148
	v_min_f32_e32 v194, 0, v144
	v_mul_f32_e64 v144, |v144|, s57
	v_exp_f32_e32 v144, v144
	s_nop 0
	v_add_f32_e32 v144, 1.0, v144
	v_cmp_gt_f32_e64 s[40:41], s97, v144
	s_nop 1
	v_cndmask_b32_e64 v195, 0, 32, s[40:41]
	v_ldexp_f32 v144, v144, v195
	v_log_f32_e32 v144, v144
	s_nop 0
	v_mul_f32_e32 v195, 0x3f317217, v144
	v_fma_f32 v195, v144, s52, -v195
	v_fmac_f32_e32 v195, 0x3377d1cf, v144
	v_fmac_f32_e32 v195, 0x3f317217, v144
	v_cmp_lt_f32_e64 s[42:43], |v144|, s53
	s_nop 1
	v_cndmask_b32_e64 v144, v144, v195, s[42:43]
	v_cndmask_b32_e64 v195, 0, v216, s[40:41]
	v_sub_f32_e32 v144, v144, v195
	v_sub_f32_e32 v194, v194, v144
	v_mul_f32_e32 v144, 0x3fb8aa3b, v148
	v_exp_f32_e32 v144, v144
	s_nop 0
	v_fma_f32 v144, v190, v144, v140
	v_cmp_gt_f32_e64 s[40:41], s97, v144
	s_nop 1
	v_cndmask_b32_e64 v195, 0, 32, s[40:41]
	v_ldexp_f32 v144, v144, v195
	v_log_f32_e32 v144, v144
	s_nop 0
	v_mul_f32_e32 v195, 0x3f317217, v144
	v_fma_f32 v195, v144, s52, -v195
	v_fmac_f32_e32 v195, 0x3377d1cf, v144
	v_fmac_f32_e32 v195, 0x3f317217, v144
	v_cmp_lt_f32_e64 s[42:43], |v144|, s53
	s_nop 1
	v_cndmask_b32_e64 v144, v144, v195, s[42:43]
	v_cndmask_b32_e64 v195, 0, v216, s[40:41]
	v_sub_f32_e32 v144, v144, v195
	v_cndmask_b32_e64 v144, v148, v144, s[38:39]
	v_mul_f32_e32 v148, 0x3fb8aa3b, v194
	v_exp_f32_e32 v148, v148
	s_nop 0
	v_fma_f32 v148, v191, v148, v136
	v_cmp_gt_f32_e64 s[40:41], s97, v148
	s_nop 1
	v_cndmask_b32_e64 v195, 0, 32, s[40:41]
	v_ldexp_f32 v148, v148, v195
	v_log_f32_e32 v148, v148
	s_nop 0
	v_mul_f32_e32 v195, 0x3f317217, v148
	v_fma_f32 v195, v148, s52, -v195
	v_fmac_f32_e32 v195, 0x3377d1cf, v148
	v_fmac_f32_e32 v195, 0x3f317217, v148
	v_cmp_lt_f32_e64 s[42:43], |v148|, s53
	s_nop 1
	v_cndmask_b32_e64 v148, v148, v195, s[42:43]
	v_cndmask_b32_e64 v195, 0, v216, s[40:41]
	v_sub_f32_e32 v148, v148, v195
	v_cndmask_b32_e64 v148, v194, v148, s[36:37]
	v_min_f32_e32 v194, 0, v149
	v_mul_f32_e64 v149, |v149|, s57
	v_exp_f32_e32 v149, v149
	s_nop 0
	v_add_f32_e32 v149, 1.0, v149
	v_cmp_gt_f32_e64 s[40:41], s97, v149
	s_nop 1
	v_cndmask_b32_e64 v195, 0, 32, s[40:41]
	v_ldexp_f32 v149, v149, v195
	v_log_f32_e32 v149, v149
	s_nop 0
	v_mul_f32_e32 v195, 0x3f317217, v149
	v_fma_f32 v195, v149, s52, -v195
	v_fmac_f32_e32 v195, 0x3377d1cf, v149
	v_fmac_f32_e32 v195, 0x3f317217, v149
	v_cmp_lt_f32_e64 s[42:43], |v149|, s53
	s_nop 1
	v_cndmask_b32_e64 v149, v149, v195, s[42:43]
	v_cndmask_b32_e64 v195, 0, v216, s[40:41]
	v_sub_f32_e32 v149, v149, v195
	v_sub_f32_e32 v149, v194, v149
	v_min_f32_e32 v194, 0, v145
	v_mul_f32_e64 v145, |v145|, s57
	v_exp_f32_e32 v145, v145
	s_nop 0
	v_add_f32_e32 v145, 1.0, v145
	v_cmp_gt_f32_e64 s[40:41], s97, v145
	s_nop 1
	v_cndmask_b32_e64 v195, 0, 32, s[40:41]
	v_ldexp_f32 v145, v145, v195
	v_log_f32_e32 v145, v145
	s_nop 0
	v_mul_f32_e32 v195, 0x3f317217, v145
	v_fma_f32 v195, v145, s52, -v195
	v_fmac_f32_e32 v195, 0x3377d1cf, v145
	v_fmac_f32_e32 v195, 0x3f317217, v145
	v_cmp_lt_f32_e64 s[42:43], |v145|, s53
	s_nop 1
	v_cndmask_b32_e64 v145, v145, v195, s[42:43]
	v_cndmask_b32_e64 v195, 0, v216, s[40:41]
	v_sub_f32_e32 v145, v145, v195
	v_sub_f32_e32 v194, v194, v145
	v_mul_f32_e32 v145, 0x3fb8aa3b, v149
	v_exp_f32_e32 v145, v145
	s_nop 0
	v_fma_f32 v145, v188, v145, v141
	v_cmp_gt_f32_e64 s[40:41], s97, v145
	s_nop 1
	v_cndmask_b32_e64 v195, 0, 32, s[40:41]
	v_ldexp_f32 v145, v145, v195
	v_log_f32_e32 v145, v145
	s_nop 0
	v_mul_f32_e32 v195, 0x3f317217, v145
	v_fma_f32 v195, v145, s52, -v195
	v_fmac_f32_e32 v195, 0x3377d1cf, v145
	v_fmac_f32_e32 v195, 0x3f317217, v145
	v_cmp_lt_f32_e64 s[42:43], |v145|, s53
	s_nop 1
	v_cndmask_b32_e64 v145, v145, v195, s[42:43]
	v_cndmask_b32_e64 v195, 0, v216, s[40:41]
	v_sub_f32_e32 v145, v145, v195
	v_cndmask_b32_e64 v145, v149, v145, s[34:35]
	v_mul_f32_e32 v149, 0x3fb8aa3b, v194
	v_exp_f32_e32 v149, v149
	s_nop 0
	v_fma_f32 v149, v189, v149, v137
	v_cmp_gt_f32_e64 s[40:41], s97, v149
	s_nop 1
	v_cndmask_b32_e64 v195, 0, 32, s[40:41]
	v_ldexp_f32 v149, v149, v195
	v_log_f32_e32 v149, v149
	s_nop 0
	v_mul_f32_e32 v195, 0x3f317217, v149
	v_fma_f32 v195, v149, s52, -v195
	v_fmac_f32_e32 v195, 0x3377d1cf, v149
	v_fmac_f32_e32 v195, 0x3f317217, v149
	v_cmp_lt_f32_e64 s[42:43], |v149|, s53
	s_nop 1
	v_cndmask_b32_e64 v149, v149, v195, s[42:43]
	v_cndmask_b32_e64 v195, 0, v216, s[40:41]
	v_sub_f32_e32 v149, v149, v195
	v_cndmask_b32_e64 v149, v194, v149, s[30:31]
	v_min_f32_e32 v194, 0, v150
	v_mul_f32_e64 v150, |v150|, s57
	v_exp_f32_e32 v150, v150
	s_nop 0
	v_add_f32_e32 v150, 1.0, v150
	v_cmp_gt_f32_e64 s[40:41], s97, v150
	s_nop 1
; __device__ __forceinline__ float logsig_f(float x) { return fminf(x, 0.f) - __logf(1.f + __expf(-fabsf(x))); }
;     __device__ __forceinline__ void operator()(const f32x4 (&acc)[2][2][4][2], const pg8::Unit& u, int wr, int wc, int fr, int fq) const {
;     ...
;             WIN_LOOP( _Pragma("unroll") for (int i = 0; i < 4; ++i) { const float s0 = fminf(a[i], 0.f) - __logf(1.f + __expf(-fabsf(a[i]))), s1 = fminf(b[i], 0.f) - __logf(1.f + __expf(-fabsf(b[i]))); const float la = l0[bj][i], lbv = l1[bj][i];
;                     a[i] = la > 0.f ? __logf(la + (1.f - la) * __expf(s0)) : s0; b[i] = lbv > 0.f ? __logf(lbv + (1.f - lbv) * __expf(s1)) : s1; }
;                 *(f32x4*)(LF + (size_t)row * 512 + c) = a; *(f32x4*)(LF + (size_t)row * 512 + c + 4) = b; __builtin_amdgcn_sched_barrier(0); ) }
	v_cndmask_b32_e64 v195, 0, 32, s[40:41]
	v_ldexp_f32 v150, v150, v195
	v_log_f32_e32 v150, v150
	s_nop 0
	v_mul_f32_e32 v195, 0x3f317217, v150
	v_fma_f32 v195, v150, s52, -v195
	v_fmac_f32_e32 v195, 0x3377d1cf, v150
	v_fmac_f32_e32 v195, 0x3f317217, v150
	v_cmp_lt_f32_e64 s[42:43], |v150|, s53
	s_nop 1
	v_cndmask_b32_e64 v150, v150, v195, s[42:43]
	v_cndmask_b32_e64 v195, 0, v216, s[40:41]
	v_sub_f32_e32 v150, v150, v195
	v_sub_f32_e32 v150, v194, v150
	v_min_f32_e32 v194, 0, v146
	v_mul_f32_e64 v146, |v146|, s57
	v_exp_f32_e32 v146, v146
	s_nop 0
	v_add_f32_e32 v146, 1.0, v146
	v_cmp_gt_f32_e64 s[40:41], s97, v146
	s_nop 1
	v_cndmask_b32_e64 v195, 0, 32, s[40:41]
	v_ldexp_f32 v146, v146, v195
	v_log_f32_e32 v146, v146
	s_nop 0
	v_mul_f32_e32 v195, 0x3f317217, v146
	v_fma_f32 v195, v146, s52, -v195
	v_fmac_f32_e32 v195, 0x3377d1cf, v146
	v_fmac_f32_e32 v195, 0x3f317217, v146
	v_cmp_lt_f32_e64 s[42:43], |v146|, s53
	s_nop 1
	v_cndmask_b32_e64 v146, v146, v195, s[42:43]
	v_cndmask_b32_e64 v195, 0, v216, s[40:41]
	v_sub_f32_e32 v146, v146, v195
	v_sub_f32_e32 v194, v194, v146
	v_mul_f32_e32 v146, 0x3fb8aa3b, v150
	v_exp_f32_e32 v146, v146
	s_nop 0
	v_fma_f32 v146, v187, v146, v142
	v_cmp_gt_f32_e64 s[40:41], s97, v146
	s_nop 1
	v_cndmask_b32_e64 v195, 0, 32, s[40:41]
	v_ldexp_f32 v146, v146, v195
	v_log_f32_e32 v146, v146
	s_nop 0
	v_mul_f32_e32 v195, 0x3f317217, v146
	v_fma_f32 v195, v146, s52, -v195
	v_fmac_f32_e32 v195, 0x3377d1cf, v146
	v_fmac_f32_e32 v195, 0x3f317217, v146
	v_cmp_lt_f32_e64 s[42:43], |v146|, s53
	s_nop 1
	v_cndmask_b32_e64 v146, v146, v195, s[42:43]
	v_cndmask_b32_e64 v195, 0, v216, s[40:41]
	v_sub_f32_e32 v146, v146, v195
	v_cndmask_b32_e64 v146, v150, v146, s[28:29]
	v_mul_f32_e32 v150, 0x3fb8aa3b, v194
	v_exp_f32_e32 v150, v150
	s_nop 0
	v_fma_f32 v150, v186, v150, v138
	v_cmp_gt_f32_e64 s[40:41], s97, v150
	s_nop 1
	v_cndmask_b32_e64 v195, 0, 32, s[40:41]
	v_ldexp_f32 v150, v150, v195
	v_log_f32_e32 v150, v150
	s_nop 0
	v_mul_f32_e32 v195, 0x3f317217, v150
	v_fma_f32 v195, v150, s52, -v195
	v_fmac_f32_e32 v195, 0x3377d1cf, v150
	v_fmac_f32_e32 v195, 0x3f317217, v150
	v_cmp_lt_f32_e64 s[42:43], |v150|, s53
	s_nop 1
	v_cndmask_b32_e64 v150, v150, v195, s[42:43]
	v_cndmask_b32_e64 v195, 0, v216, s[40:41]
	v_sub_f32_e32 v150, v150, v195
	v_cndmask_b32_e64 v150, v194, v150, s[26:27]
	v_min_f32_e32 v194, 0, v151
	v_mul_f32_e64 v151, |v151|, s57
	v_exp_f32_e32 v151, v151
	s_nop 0
	v_add_f32_e32 v151, 1.0, v151
	v_cmp_gt_f32_e64 s[40:41], s97, v151
	s_nop 1
	v_cndmask_b32_e64 v195, 0, 32, s[40:41]
	v_ldexp_f32 v151, v151, v195
	v_log_f32_e32 v151, v151
	s_nop 0
	v_mul_f32_e32 v195, 0x3f317217, v151
	v_fma_f32 v195, v151, s52, -v195
	v_fmac_f32_e32 v195, 0x3377d1cf, v151
	v_fmac_f32_e32 v195, 0x3f317217, v151
	v_cmp_lt_f32_e64 s[42:43], |v151|, s53
	s_nop 1
	v_cndmask_b32_e64 v151, v151, v195, s[42:43]
	v_cndmask_b32_e64 v195, 0, v216, s[40:41]
	v_sub_f32_e32 v151, v151, v195
	v_sub_f32_e32 v151, v194, v151
	v_min_f32_e32 v194, 0, v147
	v_mul_f32_e64 v147, |v147|, s57
	v_exp_f32_e32 v147, v147
	s_nop 0
	v_add_f32_e32 v147, 1.0, v147
	v_cmp_gt_f32_e64 s[40:41], s97, v147
	s_nop 1
	v_cndmask_b32_e64 v195, 0, 32, s[40:41]
	v_ldexp_f32 v147, v147, v195
	v_log_f32_e32 v147, v147
	s_nop 0
	v_mul_f32_e32 v195, 0x3f317217, v147
	v_fma_f32 v195, v147, s52, -v195
	v_fmac_f32_e32 v195, 0x3377d1cf, v147
	v_fmac_f32_e32 v195, 0x3f317217, v147
	v_cmp_lt_f32_e64 s[42:43], |v147|, s53
	s_nop 1
	v_cndmask_b32_e64 v147, v147, v195, s[42:43]
	v_cndmask_b32_e64 v195, 0, v216, s[40:41]
	v_sub_f32_e32 v147, v147, v195
	v_sub_f32_e32 v194, v194, v147
	v_mul_f32_e32 v147, 0x3fb8aa3b, v151
	v_exp_f32_e32 v147, v147
	s_nop 0
	v_fma_f32 v147, v185, v147, v143
	v_cmp_gt_f32_e64 s[40:41], s97, v147
	s_nop 1
	v_cndmask_b32_e64 v195, 0, 32, s[40:41]
	v_ldexp_f32 v147, v147, v195
	v_log_f32_e32 v147, v147
	s_nop 0
	v_mul_f32_e32 v195, 0x3f317217, v147
	v_fma_f32 v195, v147, s52, -v195
	v_fmac_f32_e32 v195, 0x3377d1cf, v147
	v_fmac_f32_e32 v195, 0x3f317217, v147
	v_cmp_lt_f32_e64 s[42:43], |v147|, s53
	s_nop 1
	v_cndmask_b32_e64 v147, v147, v195, s[42:43]
	v_cndmask_b32_e64 v195, 0, v216, s[40:41]
	v_sub_f32_e32 v147, v147, v195
	v_cndmask_b32_e64 v147, v151, v147, s[24:25]
	v_mul_f32_e32 v151, 0x3fb8aa3b, v194
	v_exp_f32_e32 v151, v151
	s_nop 0
	v_fma_f32 v151, v184, v151, v139
	v_cmp_gt_f32_e64 s[40:41], s97, v151
	s_nop 1
	v_cndmask_b32_e64 v195, 0, 32, s[40:41]
	v_ldexp_f32 v151, v151, v195
	v_log_f32_e32 v151, v151
	s_nop 0
	v_mul_f32_e32 v195, 0x3f317217, v151
	v_fma_f32 v195, v151, s52, -v195
	v_fmac_f32_e32 v195, 0x3377d1cf, v151
	v_fmac_f32_e32 v195, 0x3f317217, v151
	v_cmp_lt_f32_e64 s[42:43], |v151|, s53
	s_nop 1
	v_cndmask_b32_e64 v151, v151, v195, s[42:43]
	v_cndmask_b32_e64 v195, 0, v216, s[40:41]
	v_sub_f32_e32 v151, v151, v195
	v_cndmask_b32_e64 v151, v194, v151, s[22:23]
	global_store_dwordx4 v[170:171], v[144:147], off
	global_store_dwordx4 v[170:171], v[148:151], off offset:16
	s_nop 1
	v_pk_mul_f32 v[148:149], v[100:101], v[168:169] op_sel_hi:[1,0]
	v_pk_mul_f32 v[150:151], v[102:103], v[168:169] op_sel_hi:[1,0]
	v_pk_mul_f32 v[146:147], v[98:99], v[168:169] op_sel_hi:[1,0]
	v_pk_mul_f32 v[144:145], v[96:97], v[168:169] op_sel_hi:[1,0]
	v_min_f32_e32 v168, 0, v148
	v_mul_f32_e64 v148, |v148|, s57
	v_exp_f32_e32 v148, v148
	s_nop 0
	v_add_f32_e32 v148, 1.0, v148
	v_cmp_gt_f32_e64 s[40:41], s97, v148
	s_nop 1
	v_cndmask_b32_e64 v194, 0, 32, s[40:41]
	v_ldexp_f32 v148, v148, v194
	v_log_f32_e32 v148, v148
	s_nop 0
	v_mul_f32_e32 v194, 0x3f317217, v148
	v_fma_f32 v194, v148, s52, -v194
	v_fmac_f32_e32 v194, 0x3377d1cf, v148
; __device__ __forceinline__ float logsig_f(float x) { return fminf(x, 0.f) - __logf(1.f + __expf(-fabsf(x))); }
;     __device__ __forceinline__ void operator()(const f32x4 (&acc)[2][2][4][2], const pg8::Unit& u, int wr, int wc, int fr, int fq) const {
;     ...
;             WIN_LOOP( _Pragma("unroll") for (int i = 0; i < 4; ++i) { const float s0 = fminf(a[i], 0.f) - __logf(1.f + __expf(-fabsf(a[i]))), s1 = fminf(b[i], 0.f) - __logf(1.f + __expf(-fabsf(b[i]))); const float la = l0[bj][i], lbv = l1[bj][i];
;                     a[i] = la > 0.f ? __logf(la + (1.f - la) * __expf(s0)) : s0; b[i] = lbv > 0.f ? __logf(lbv + (1.f - lbv) * __expf(s1)) : s1; }
;                 *(f32x4*)(LF + (size_t)row * 512 + c) = a; *(f32x4*)(LF + (size_t)row * 512 + c + 4) = b; __builtin_amdgcn_sched_barrier(0); ) }
	v_fmac_f32_e32 v194, 0x3f317217, v148
	v_cmp_lt_f32_e64 s[42:43], |v148|, s53
	s_nop 1
	v_cndmask_b32_e64 v148, v148, v194, s[42:43]
	v_cndmask_b32_e64 v194, 0, v216, s[40:41]
	v_sub_f32_e32 v148, v148, v194
	v_sub_f32_e32 v148, v168, v148
	v_min_f32_e32 v168, 0, v144
	v_mul_f32_e64 v144, |v144|, s57
	v_exp_f32_e32 v144, v144
	s_nop 0
	v_add_f32_e32 v144, 1.0, v144
	v_cmp_gt_f32_e64 s[40:41], s97, v144
	s_nop 1
	v_cndmask_b32_e64 v194, 0, 32, s[40:41]
	v_ldexp_f32 v144, v144, v194
	v_log_f32_e32 v144, v144
	s_nop 0
	v_mul_f32_e32 v194, 0x3f317217, v144
	v_fma_f32 v194, v144, s52, -v194
	v_fmac_f32_e32 v194, 0x3377d1cf, v144
	v_fmac_f32_e32 v194, 0x3f317217, v144
	v_cmp_lt_f32_e64 s[42:43], |v144|, s53
	s_nop 1
	v_cndmask_b32_e64 v144, v144, v194, s[42:43]
	v_cndmask_b32_e64 v194, 0, v216, s[40:41]
	v_sub_f32_e32 v144, v144, v194
	v_sub_f32_e32 v168, v168, v144
	v_mul_f32_e32 v144, 0x3fb8aa3b, v148
	v_exp_f32_e32 v144, v144
	s_nop 0
	v_fma_f32 v144, v183, v144, v132
	v_cmp_gt_f32_e64 s[40:41], s97, v144
	s_nop 1
	v_cndmask_b32_e64 v194, 0, 32, s[40:41]
	v_ldexp_f32 v144, v144, v194
	v_log_f32_e32 v144, v144
	s_nop 0
	v_mul_f32_e32 v194, 0x3f317217, v144
	v_fma_f32 v194, v144, s52, -v194
	v_fmac_f32_e32 v194, 0x3377d1cf, v144
	v_fmac_f32_e32 v194, 0x3f317217, v144
	v_cmp_lt_f32_e64 s[42:43], |v144|, s53
	s_nop 1
	v_cndmask_b32_e64 v144, v144, v194, s[42:43]
	v_cndmask_b32_e64 v194, 0, v216, s[40:41]
	v_sub_f32_e32 v144, v144, v194
	v_cndmask_b32_e64 v144, v148, v144, s[20:21]
	v_mul_f32_e32 v148, 0x3fb8aa3b, v168
	v_exp_f32_e32 v148, v148
	s_nop 0
	v_fma_f32 v148, v182, v148, v128
	v_cmp_gt_f32_e64 s[40:41], s97, v148
	s_nop 1
	v_cndmask_b32_e64 v194, 0, 32, s[40:41]
	v_ldexp_f32 v148, v148, v194
	v_log_f32_e32 v148, v148
	s_nop 0
	v_mul_f32_e32 v194, 0x3f317217, v148
	v_fma_f32 v194, v148, s52, -v194
	v_fmac_f32_e32 v194, 0x3377d1cf, v148
	v_fmac_f32_e32 v194, 0x3f317217, v148
	v_cmp_lt_f32_e64 s[42:43], |v148|, s53
	s_nop 1
	v_cndmask_b32_e64 v148, v148, v194, s[42:43]
	v_cndmask_b32_e64 v194, 0, v216, s[40:41]
	v_sub_f32_e32 v148, v148, v194
	v_cndmask_b32_e64 v148, v168, v148, s[18:19]
	v_min_f32_e32 v168, 0, v149
	v_mul_f32_e64 v149, |v149|, s57
	v_exp_f32_e32 v149, v149
	s_nop 0
	v_add_f32_e32 v149, 1.0, v149
	v_cmp_gt_f32_e64 s[40:41], s97, v149
	s_nop 1
	v_cndmask_b32_e64 v194, 0, 32, s[40:41]
	v_ldexp_f32 v149, v149, v194
	v_log_f32_e32 v149, v149
	s_nop 0
	v_mul_f32_e32 v194, 0x3f317217, v149
	v_fma_f32 v194, v149, s52, -v194
	v_fmac_f32_e32 v194, 0x3377d1cf, v149
	v_fmac_f32_e32 v194, 0x3f317217, v149
	v_cmp_lt_f32_e64 s[42:43], |v149|, s53
	s_nop 1
	v_cndmask_b32_e64 v149, v149, v194, s[42:43]
	v_cndmask_b32_e64 v194, 0, v216, s[40:41]
	v_sub_f32_e32 v149, v149, v194
	v_sub_f32_e32 v149, v168, v149
	v_min_f32_e32 v168, 0, v145
	v_mul_f32_e64 v145, |v145|, s57
	v_exp_f32_e32 v145, v145
	s_nop 0
	v_add_f32_e32 v145, 1.0, v145
	v_cmp_gt_f32_e64 s[40:41], s97, v145
	s_nop 1
	v_cndmask_b32_e64 v194, 0, 32, s[40:41]
	v_ldexp_f32 v145, v145, v194
	v_log_f32_e32 v145, v145
	s_nop 0
	v_mul_f32_e32 v194, 0x3f317217, v145
	v_fma_f32 v194, v145, s52, -v194
	v_fmac_f32_e32 v194, 0x3377d1cf, v145
	v_fmac_f32_e32 v194, 0x3f317217, v145
	v_cmp_lt_f32_e64 s[42:43], |v145|, s53
	s_nop 1
	v_cndmask_b32_e64 v145, v145, v194, s[42:43]
	v_cndmask_b32_e64 v194, 0, v216, s[40:41]
	v_sub_f32_e32 v145, v145, v194
	v_sub_f32_e32 v168, v168, v145
	v_mul_f32_e32 v145, 0x3fb8aa3b, v149
	v_exp_f32_e32 v145, v145
	s_nop 0
	v_fma_f32 v145, v181, v145, v133
	v_cmp_gt_f32_e64 s[40:41], s97, v145
	s_nop 1
	v_cndmask_b32_e64 v194, 0, 32, s[40:41]
	v_ldexp_f32 v145, v145, v194
	v_log_f32_e32 v145, v145
	s_nop 0
	v_mul_f32_e32 v194, 0x3f317217, v145
	v_fma_f32 v194, v145, s52, -v194
	v_fmac_f32_e32 v194, 0x3377d1cf, v145
	v_fmac_f32_e32 v194, 0x3f317217, v145
	v_cmp_lt_f32_e64 s[42:43], |v145|, s53
	s_nop 1
	v_cndmask_b32_e64 v145, v145, v194, s[42:43]
	v_cndmask_b32_e64 v194, 0, v216, s[40:41]
	v_sub_f32_e32 v145, v145, v194
	v_cndmask_b32_e64 v145, v149, v145, s[16:17]
	v_mul_f32_e32 v149, 0x3fb8aa3b, v168
	v_exp_f32_e32 v149, v149
	s_nop 0
	v_fma_f32 v149, v180, v149, v129
	v_cmp_gt_f32_e64 s[40:41], s97, v149
	s_nop 1
	v_cndmask_b32_e64 v194, 0, 32, s[40:41]
	v_ldexp_f32 v149, v149, v194
	v_log_f32_e32 v149, v149
	s_nop 0
	v_mul_f32_e32 v194, 0x3f317217, v149
	v_fma_f32 v194, v149, s52, -v194
	v_fmac_f32_e32 v194, 0x3377d1cf, v149
	v_fmac_f32_e32 v194, 0x3f317217, v149
	v_cmp_lt_f32_e64 s[42:43], |v149|, s53
	s_nop 1
	v_cndmask_b32_e64 v149, v149, v194, s[42:43]
	v_cndmask_b32_e64 v194, 0, v216, s[40:41]
	v_sub_f32_e32 v149, v149, v194
	v_cndmask_b32_e64 v149, v168, v149, s[14:15]
	v_min_f32_e32 v168, 0, v150
	v_mul_f32_e64 v150, |v150|, s57
	v_exp_f32_e32 v150, v150
	s_nop 0
	v_add_f32_e32 v150, 1.0, v150
	v_cmp_gt_f32_e64 s[40:41], s97, v150
	s_nop 1
	v_cndmask_b32_e64 v194, 0, 32, s[40:41]
	v_ldexp_f32 v150, v150, v194
	v_log_f32_e32 v150, v150
	s_nop 0
	v_mul_f32_e32 v194, 0x3f317217, v150
	v_fma_f32 v194, v150, s52, -v194
	v_fmac_f32_e32 v194, 0x3377d1cf, v150
	v_fmac_f32_e32 v194, 0x3f317217, v150
	v_cmp_lt_f32_e64 s[42:43], |v150|, s53
	s_nop 1
	v_cndmask_b32_e64 v150, v150, v194, s[42:43]
	v_cndmask_b32_e64 v194, 0, v216, s[40:41]
	v_sub_f32_e32 v150, v150, v194
	v_sub_f32_e32 v150, v168, v150
	v_min_f32_e32 v168, 0, v146
	v_mul_f32_e64 v146, |v146|, s57
	v_exp_f32_e32 v146, v146
	s_nop 0
	v_add_f32_e32 v146, 1.0, v146
	v_cmp_gt_f32_e64 s[40:41], s97, v146
	s_nop 1
	v_cndmask_b32_e64 v194, 0, 32, s[40:41]
	v_ldexp_f32 v146, v146, v194
	v_log_f32_e32 v146, v146
	s_nop 0
	v_mul_f32_e32 v194, 0x3f317217, v146
	v_fma_f32 v194, v146, s52, -v194
;     __device__ __forceinline__ void operator()(const f32x4 (&acc)[2][2][4][2], const pg8::Unit& u, int wr, int wc, int fr, int fq) const {
;     ...
;             WIN_LOOP( _Pragma("unroll") for (int i = 0; i < 4; ++i) { const float s0 = fminf(a[i], 0.f) - __logf(1.f + __expf(-fabsf(a[i]))), s1 = fminf(b[i], 0.f) - __logf(1.f + __expf(-fabsf(b[i]))); const float la = l0[bj][i], lbv = l1[bj][i];
;                     a[i] = la > 0.f ? __logf(la + (1.f - la) * __expf(s0)) : s0; b[i] = lbv > 0.f ? __logf(lbv + (1.f - lbv) * __expf(s1)) : s1; }
;                 *(f32x4*)(LF + (size_t)row * 512 + c) = a; *(f32x4*)(LF + (size_t)row * 512 + c + 4) = b; __builtin_amdgcn_sched_barrier(0); ) }
	v_fmac_f32_e32 v194, 0x3377d1cf, v146
	v_fmac_f32_e32 v194, 0x3f317217, v146
	v_cmp_lt_f32_e64 s[42:43], |v146|, s53
	s_nop 1
	v_cndmask_b32_e64 v146, v146, v194, s[42:43]
	v_cndmask_b32_e64 v194, 0, v216, s[40:41]
	v_sub_f32_e32 v146, v146, v194
	v_sub_f32_e32 v168, v168, v146
	v_mul_f32_e32 v146, 0x3fb8aa3b, v150
	v_exp_f32_e32 v146, v146
	s_nop 0
	v_fma_f32 v146, v179, v146, v134
	v_cmp_gt_f32_e64 s[40:41], s97, v146
	s_nop 1
	v_cndmask_b32_e64 v194, 0, 32, s[40:41]
	v_ldexp_f32 v146, v146, v194
	v_log_f32_e32 v146, v146
	s_nop 0
	v_mul_f32_e32 v194, 0x3f317217, v146
	v_fma_f32 v194, v146, s52, -v194
	v_fmac_f32_e32 v194, 0x3377d1cf, v146
	v_fmac_f32_e32 v194, 0x3f317217, v146
	v_cmp_lt_f32_e64 s[42:43], |v146|, s53
	s_nop 1
	v_cndmask_b32_e64 v146, v146, v194, s[42:43]
	v_cndmask_b32_e64 v194, 0, v216, s[40:41]
	v_sub_f32_e32 v146, v146, v194
	v_cndmask_b32_e64 v146, v150, v146, s[12:13]
	v_mul_f32_e32 v150, 0x3fb8aa3b, v168
	v_exp_f32_e32 v150, v150
	s_nop 0
	v_fma_f32 v150, v178, v150, v130
	v_cmp_gt_f32_e64 s[40:41], s97, v150
	s_nop 1
	v_cndmask_b32_e64 v194, 0, 32, s[40:41]
	v_ldexp_f32 v150, v150, v194
	v_log_f32_e32 v150, v150
	s_nop 0
	v_mul_f32_e32 v194, 0x3f317217, v150
	v_fma_f32 v194, v150, s52, -v194
	v_fmac_f32_e32 v194, 0x3377d1cf, v150
	v_fmac_f32_e32 v194, 0x3f317217, v150
	v_cmp_lt_f32_e64 s[42:43], |v150|, s53
	s_nop 1
	v_cndmask_b32_e64 v150, v150, v194, s[42:43]
	v_cndmask_b32_e64 v194, 0, v216, s[40:41]
	v_sub_f32_e32 v150, v150, v194
	v_cndmask_b32_e64 v150, v168, v150, s[10:11]
	v_min_f32_e32 v168, 0, v151
	v_mul_f32_e64 v151, |v151|, s57
	v_exp_f32_e32 v151, v151
	s_nop 0
	v_add_f32_e32 v151, 1.0, v151
	v_cmp_gt_f32_e64 s[40:41], s97, v151
	s_nop 1
	v_cndmask_b32_e64 v194, 0, 32, s[40:41]
	v_ldexp_f32 v151, v151, v194
	v_log_f32_e32 v151, v151
	s_nop 0
	v_mul_f32_e32 v194, 0x3f317217, v151
	v_fma_f32 v194, v151, s52, -v194
	v_fmac_f32_e32 v194, 0x3377d1cf, v151
	v_fmac_f32_e32 v194, 0x3f317217, v151
	v_cmp_lt_f32_e64 s[42:43], |v151|, s53
	s_nop 1
	v_cndmask_b32_e64 v151, v151, v194, s[42:43]
	v_cndmask_b32_e64 v194, 0, v216, s[40:41]
	v_sub_f32_e32 v151, v151, v194
	v_sub_f32_e32 v151, v168, v151
	v_min_f32_e32 v168, 0, v147
	v_mul_f32_e64 v147, |v147|, s57
	v_exp_f32_e32 v147, v147
	s_nop 0
	v_add_f32_e32 v147, 1.0, v147
	v_cmp_gt_f32_e64 s[40:41], s97, v147
	s_nop 1
	v_cndmask_b32_e64 v194, 0, 32, s[40:41]
	v_ldexp_f32 v147, v147, v194
	v_log_f32_e32 v147, v147
	s_nop 0
	v_mul_f32_e32 v194, 0x3f317217, v147
	v_fma_f32 v194, v147, s52, -v194
	v_fmac_f32_e32 v194, 0x3377d1cf, v147
	v_fmac_f32_e32 v194, 0x3f317217, v147
	v_cmp_lt_f32_e64 s[42:43], |v147|, s53
	s_nop 1
	v_cndmask_b32_e64 v147, v147, v194, s[42:43]
	v_cndmask_b32_e64 v194, 0, v216, s[40:41]
	v_sub_f32_e32 v147, v147, v194
	v_sub_f32_e32 v168, v168, v147
	v_mul_f32_e32 v147, 0x3fb8aa3b, v151
	v_exp_f32_e32 v147, v147
	s_nop 0
	v_fma_f32 v147, v177, v147, v135
	v_cmp_gt_f32_e64 s[40:41], s97, v147
	s_nop 1
	v_cndmask_b32_e64 v194, 0, 32, s[40:41]
	v_ldexp_f32 v147, v147, v194
	v_log_f32_e32 v147, v147
	s_nop 0
	v_mul_f32_e32 v194, 0x3f317217, v147
	v_fma_f32 v194, v147, s52, -v194
	v_fmac_f32_e32 v194, 0x3377d1cf, v147
	v_fmac_f32_e32 v194, 0x3f317217, v147
	v_cmp_lt_f32_e64 s[42:43], |v147|, s53
	s_nop 1
	v_cndmask_b32_e64 v147, v147, v194, s[42:43]
	v_cndmask_b32_e64 v194, 0, v216, s[40:41]
	v_sub_f32_e32 v147, v147, v194
	v_cndmask_b32_e64 v147, v151, v147, s[8:9]
	v_mul_f32_e32 v151, 0x3fb8aa3b, v168
	v_exp_f32_e32 v151, v151
	s_nop 0
	v_fma_f32 v151, v167, v151, v131
	v_cmp_gt_f32_e64 s[40:41], s97, v151
	s_nop 1
	v_cndmask_b32_e64 v194, 0, 32, s[40:41]
	v_ldexp_f32 v151, v151, v194
	v_log_f32_e32 v151, v151
	s_nop 0
	v_mul_f32_e32 v194, 0x3f317217, v151
	v_fma_f32 v194, v151, s52, -v194
	v_fmac_f32_e32 v194, 0x3377d1cf, v151
	v_fmac_f32_e32 v194, 0x3f317217, v151
	v_cmp_lt_f32_e64 s[42:43], |v151|, s53
	s_nop 1
	v_cndmask_b32_e64 v151, v151, v194, s[42:43]
	v_cndmask_b32_e64 v194, 0, v216, s[40:41]
	v_sub_f32_e32 v151, v151, v194
	v_cndmask_b32_e32 v151, v168, v151, vcc
	global_store_dwordx4 v[170:171], v[144:147], off offset:512
	global_store_dwordx4 v[170:171], v[148:151], off offset:528
	s_nop 1
	v_add_u32_e32 v148, 0x80, v166
	v_ashrrev_i32_e32 v149, 31, v148
	v_lshlrev_b64 v[144:145], 6, v[148:149]
	v_lshl_add_u64 v[144:145], v[160:161], 0, v[144:145]
	s_nop 0
	s_waitcnt lgkmcnt(0)
	s_nop 3
	s_nop 0
	s_nop 1
	s_waitcnt lgkmcnt(0)
	s_nop 1
	s_waitcnt lgkmcnt(0)
;     __device__ __forceinline__ void operator()(const f32x4 (&acc)[2][2][4][2], const pg8::Unit& u, int wr, int wc, int fr, int fq) const {
;     ...
;             WIN_LOOP( _Pragma("unroll") for (int i = 0; i < 4; ++i) { const float s0 = fminf(a[i], 0.f) - __logf(1.f + __expf(-fabsf(a[i]))), s1 = fminf(b[i], 0.f) - __logf(1.f + __expf(-fabsf(b[i]))); const float la = l0[bj][i], lbv = l1[bj][i];
;                     a[i] = la > 0.f ? __logf(la + (1.f - la) * __expf(s0)) : s0; b[i] = lbv > 0.f ? __logf(lbv + (1.f - lbv) * __expf(s1)) : s1; }
;                 *(f32x4*)(LF + (size_t)row * 512 + c) = a; *(f32x4*)(LF + (size_t)row * 512 + c + 4) = b; __builtin_amdgcn_sched_barrier(0); ) }
	s_nop 1
	v_mov_b32_e32 v168, v254
	v_lshlrev_b64 v[144:145], 11, v[148:149]
	v_lshl_add_u64 v[170:171], s[50:51], 0, v[144:145]
	v_lshl_add_u64 v[170:171], v[170:171], 0, v[192:193]
	v_pk_mul_f32 v[148:149], v[28:29], v[168:169] op_sel_hi:[1,0]
	v_pk_mul_f32 v[144:145], v[24:25], v[168:169] op_sel_hi:[1,0]
	v_min_f32_e32 v194, 0, v148
	v_mul_f32_e64 v148, |v148|, s57
	v_exp_f32_e32 v148, v148
	v_pk_mul_f32 v[150:151], v[30:31], v[168:169] op_sel_hi:[1,0]
	v_pk_mul_f32 v[146:147], v[26:27], v[168:169] op_sel_hi:[1,0]
	v_add_f32_e32 v148, 1.0, v148
	v_cmp_gt_f32_e64 s[40:41], s97, v148
	s_nop 1
	v_cndmask_b32_e64 v195, 0, 32, s[40:41]
	v_ldexp_f32 v148, v148, v195
	v_log_f32_e32 v148, v148
	s_nop 0
	v_mul_f32_e32 v195, 0x3f317217, v148
	v_fma_f32 v195, v148, s52, -v195
	v_fmac_f32_e32 v195, 0x3377d1cf, v148
	v_fmac_f32_e32 v195, 0x3f317217, v148
	v_cmp_lt_f32_e64 s[42:43], |v148|, s53
	s_nop 1
	v_cndmask_b32_e64 v148, v148, v195, s[42:43]
	v_cndmask_b32_e64 v195, 0, v216, s[40:41]
	v_sub_f32_e32 v148, v148, v195
	v_sub_f32_e32 v148, v194, v148
	v_min_f32_e32 v194, 0, v144
	v_mul_f32_e64 v144, |v144|, s57
	v_exp_f32_e32 v144, v144
	s_nop 0
	v_add_f32_e32 v144, 1.0, v144
	v_cmp_gt_f32_e64 s[40:41], s97, v144
	s_nop 1
	v_cndmask_b32_e64 v195, 0, 32, s[40:41]
	v_ldexp_f32 v144, v144, v195
	v_log_f32_e32 v144, v144
	s_nop 0
	v_mul_f32_e32 v195, 0x3f317217, v144
	v_fma_f32 v195, v144, s52, -v195
	v_fmac_f32_e32 v195, 0x3377d1cf, v144
	v_fmac_f32_e32 v195, 0x3f317217, v144
	v_cmp_lt_f32_e64 s[42:43], |v144|, s53
	s_nop 1
	v_cndmask_b32_e64 v144, v144, v195, s[42:43]
	v_cndmask_b32_e64 v195, 0, v216, s[40:41]
	v_sub_f32_e32 v144, v144, v195
	v_sub_f32_e32 v194, v194, v144
	v_mul_f32_e32 v144, 0x3fb8aa3b, v148
	v_exp_f32_e32 v144, v144
	s_nop 0
	v_fma_f32 v144, v190, v144, v140
	v_cmp_gt_f32_e64 s[40:41], s97, v144
	s_nop 1
	v_cndmask_b32_e64 v195, 0, 32, s[40:41]
	v_ldexp_f32 v144, v144, v195
	v_log_f32_e32 v144, v144
	s_nop 0
	v_mul_f32_e32 v195, 0x3f317217, v144
	v_fma_f32 v195, v144, s52, -v195
	v_fmac_f32_e32 v195, 0x3377d1cf, v144
	v_fmac_f32_e32 v195, 0x3f317217, v144
	v_cmp_lt_f32_e64 s[42:43], |v144|, s53
	s_nop 1
	v_cndmask_b32_e64 v144, v144, v195, s[42:43]
	v_cndmask_b32_e64 v195, 0, v216, s[40:41]
	v_sub_f32_e32 v144, v144, v195
	v_cndmask_b32_e64 v144, v148, v144, s[38:39]
	v_mul_f32_e32 v148, 0x3fb8aa3b, v194
	v_exp_f32_e32 v148, v148
	s_nop 0
	v_fma_f32 v148, v191, v148, v136
	v_cmp_gt_f32_e64 s[40:41], s97, v148
	s_nop 1
	v_cndmask_b32_e64 v195, 0, 32, s[40:41]
	v_ldexp_f32 v148, v148, v195
	v_log_f32_e32 v148, v148
	s_nop 0
	v_mul_f32_e32 v195, 0x3f317217, v148
	v_fma_f32 v195, v148, s52, -v195
	v_fmac_f32_e32 v195, 0x3377d1cf, v148
	v_fmac_f32_e32 v195, 0x3f317217, v148
	v_cmp_lt_f32_e64 s[42:43], |v148|, s53
	s_nop 1
	v_cndmask_b32_e64 v148, v148, v195, s[42:43]
	v_cndmask_b32_e64 v195, 0, v216, s[40:41]
	v_sub_f32_e32 v148, v148, v195
	v_cndmask_b32_e64 v148, v194, v148, s[36:37]
	v_min_f32_e32 v194, 0, v149
	v_mul_f32_e64 v149, |v149|, s57
	v_exp_f32_e32 v149, v149
	s_nop 0
	v_add_f32_e32 v149, 1.0, v149
	v_cmp_gt_f32_e64 s[40:41], s97, v149
	s_nop 1
	v_cndmask_b32_e64 v195, 0, 32, s[40:41]
	v_ldexp_f32 v149, v149, v195
	v_log_f32_e32 v149, v149
	s_nop 0
	v_mul_f32_e32 v195, 0x3f317217, v149
	v_fma_f32 v195, v149, s52, -v195
	v_fmac_f32_e32 v195, 0x3377d1cf, v149
	v_fmac_f32_e32 v195, 0x3f317217, v149
	v_cmp_lt_f32_e64 s[42:43], |v149|, s53
	s_nop 1
	v_cndmask_b32_e64 v149, v149, v195, s[42:43]
	v_cndmask_b32_e64 v195, 0, v216, s[40:41]
	v_sub_f32_e32 v149, v149, v195
	v_sub_f32_e32 v149, v194, v149
	v_min_f32_e32 v194, 0, v145
	v_mul_f32_e64 v145, |v145|, s57
	v_exp_f32_e32 v145, v145
	s_nop 0
	v_add_f32_e32 v145, 1.0, v145
	v_cmp_gt_f32_e64 s[40:41], s97, v145
	s_nop 1
	v_cndmask_b32_e64 v195, 0, 32, s[40:41]
	v_ldexp_f32 v145, v145, v195
	v_log_f32_e32 v145, v145
	s_nop 0
	v_mul_f32_e32 v195, 0x3f317217, v145
	v_fma_f32 v195, v145, s52, -v195
	v_fmac_f32_e32 v195, 0x3377d1cf, v145
	v_fmac_f32_e32 v195, 0x3f317217, v145
	v_cmp_lt_f32_e64 s[42:43], |v145|, s53
	s_nop 1
	v_cndmask_b32_e64 v145, v145, v195, s[42:43]
	v_cndmask_b32_e64 v195, 0, v216, s[40:41]
	v_sub_f32_e32 v145, v145, v195
	v_sub_f32_e32 v194, v194, v145
	v_mul_f32_e32 v145, 0x3fb8aa3b, v149
	v_exp_f32_e32 v145, v145
	s_nop 0
	v_fma_f32 v145, v188, v145, v141
	v_cmp_gt_f32_e64 s[40:41], s97, v145
	s_nop 1
	v_cndmask_b32_e64 v195, 0, 32, s[40:41]
	v_ldexp_f32 v145, v145, v195
	v_log_f32_e32 v145, v145
	s_nop 0
	v_mul_f32_e32 v195, 0x3f317217, v145
	v_fma_f32 v195, v145, s52, -v195
	v_fmac_f32_e32 v195, 0x3377d1cf, v145
	v_fmac_f32_e32 v195, 0x3f317217, v145
	v_cmp_lt_f32_e64 s[42:43], |v145|, s53
	s_nop 1
	v_cndmask_b32_e64 v145, v145, v195, s[42:43]
	v_cndmask_b32_e64 v195, 0, v216, s[40:41]
	v_sub_f32_e32 v145, v145, v195
	v_cndmask_b32_e64 v145, v149, v145, s[34:35]
	v_mul_f32_e32 v149, 0x3fb8aa3b, v194
	v_exp_f32_e32 v149, v149
	s_nop 0
	v_fma_f32 v149, v189, v149, v137
	v_cmp_gt_f32_e64 s[40:41], s97, v149
	s_nop 1
	v_cndmask_b32_e64 v195, 0, 32, s[40:41]
	v_ldexp_f32 v149, v149, v195
	v_log_f32_e32 v149, v149
	s_nop 0
	v_mul_f32_e32 v195, 0x3f317217, v149
	v_fma_f32 v195, v149, s52, -v195
	v_fmac_f32_e32 v195, 0x3377d1cf, v149
	v_fmac_f32_e32 v195, 0x3f317217, v149
	v_cmp_lt_f32_e64 s[42:43], |v149|, s53
	s_nop 1
	v_cndmask_b32_e64 v149, v149, v195, s[42:43]
	v_cndmask_b32_e64 v195, 0, v216, s[40:41]
	v_sub_f32_e32 v149, v149, v195
	v_cndmask_b32_e64 v149, v194, v149, s[30:31]
	v_min_f32_e32 v194, 0, v150
	v_mul_f32_e64 v150, |v150|, s57
	v_exp_f32_e32 v150, v150
	s_nop 0
	v_add_f32_e32 v150, 1.0, v150
	v_cmp_gt_f32_e64 s[40:41], s97, v150
	s_nop 1
; __device__ __forceinline__ float silu_f(float x) { return x * __builtin_amdgcn_rcpf(1.f + __expf(-x)); }
; __device__ __forceinline__ v4u pack8(const f32x4 a, const f32x4 b) { v4u w; w.x = cvt_pk_bf16(a[0], a[1]); w.y = cvt_pk_bf16(a[2], a[3]); w.z = cvt_pk_bf16(b[0], b[1]); w.w = cvt_pk_bf16(b[2], b[3]); return w; }
;     __device__ __forceinline__ void operator()(const f32x4 (&acc)[2][2][4][2], const pg8::Unit& u, int wr, int wc, int fr, int fq) const {
;     ...
;         if (grp == 0) { WIN_LOOP( _Pragma("unroll") for (int i = 0; i < 4; ++i) { a[i] = silu_f(a[i]); b[i] = silu_f(b[i]); } *(v4u*)(QO + (size_t)row * DM + c) = pack8(a, b); ) }
;         else if (grp == 3) { WIN_LOOP( _Pragma("unroll") for (int i = 0; i < 4; ++i) { a[i] = silu_f(a[i]); b[i] = silu_f(b[i]); } *(v4u*)(GH + (size_t)row * 512 + c) = pack8(a, b); ) }
;         else if (grp == 1) {
;             f32x4 l0[2], l1[2];
; #pragma unroll
;             for (int bj = 0; bj < 2; ++bj) { l0[bj] = *(const f32x4*)(lb + cb + bj * 128); l1[bj] = *(const f32x4*)(lb + cb + bj * 128 + 4); }
;             WIN_LOOP( _Pragma("unroll") for (int i = 0; i < 4; ++i) { const float s0 = fminf(a[i], 0.f) - __logf(1.f + __expf(-fabsf(a[i]))), s1 = fminf(b[i], 0.f) - __logf(1.f + __expf(-fabsf(b[i]))); const float la = l0[bj][i], lbv = l1[bj][i];
;                     a[i] = la > 0.f ? __logf(la + (1.f - la) * __expf(s0)) : s0; b[i] = lbv > 0.f ? __logf(lbv + (1.f - lbv) * __expf(s1)) : s1; }
;                 *(f32x4*)(LF + (size_t)row * 512 + c) = a; *(f32x4*)(LF + (size_t)row * 512 + c + 4) = b; __builtin_amdgcn_sched_barrier(0); ) }
	v_cndmask_b32_e64 v195, 0, 32, s[40:41]
	v_ldexp_f32 v150, v150, v195
	v_log_f32_e32 v150, v150
	s_nop 0
	v_mul_f32_e32 v195, 0x3f317217, v150
	v_fma_f32 v195, v150, s52, -v195
	v_fmac_f32_e32 v195, 0x3377d1cf, v150
	v_fmac_f32_e32 v195, 0x3f317217, v150
	v_cmp_lt_f32_e64 s[42:43], |v150|, s53
	s_nop 1
	v_cndmask_b32_e64 v150, v150, v195, s[42:43]
	v_cndmask_b32_e64 v195, 0, v216, s[40:41]
	v_sub_f32_e32 v150, v150, v195
	v_sub_f32_e32 v150, v194, v150
	v_min_f32_e32 v194, 0, v146
	v_mul_f32_e64 v146, |v146|, s57
	v_exp_f32_e32 v146, v146
	s_nop 0
	v_add_f32_e32 v146, 1.0, v146
	v_cmp_gt_f32_e64 s[40:41], s97, v146
	s_nop 1
	v_cndmask_b32_e64 v195, 0, 32, s[40:41]
	v_ldexp_f32 v146, v146, v195
	v_log_f32_e32 v146, v146
	s_nop 0
	v_mul_f32_e32 v195, 0x3f317217, v146
	v_fma_f32 v195, v146, s52, -v195
	v_fmac_f32_e32 v195, 0x3377d1cf, v146
	v_fmac_f32_e32 v195, 0x3f317217, v146
	v_cmp_lt_f32_e64 s[42:43], |v146|, s53
	s_nop 1
	v_cndmask_b32_e64 v146, v146, v195, s[42:43]
	v_cndmask_b32_e64 v195, 0, v216, s[40:41]
	v_sub_f32_e32 v146, v146, v195
	v_sub_f32_e32 v194, v194, v146
	v_mul_f32_e32 v146, 0x3fb8aa3b, v150
	v_exp_f32_e32 v146, v146
	s_nop 0
	v_fma_f32 v146, v187, v146, v142
	v_cmp_gt_f32_e64 s[40:41], s97, v146
	s_nop 1
	v_cndmask_b32_e64 v195, 0, 32, s[40:41]
	v_ldexp_f32 v146, v146, v195
	v_log_f32_e32 v146, v146
	s_nop 0
	v_mul_f32_e32 v195, 0x3f317217, v146
	v_fma_f32 v195, v146, s52, -v195
	v_fmac_f32_e32 v195, 0x3377d1cf, v146
	v_fmac_f32_e32 v195, 0x3f317217, v146
	v_cmp_lt_f32_e64 s[42:43], |v146|, s53
	s_nop 1
	v_cndmask_b32_e64 v146, v146, v195, s[42:43]
	v_cndmask_b32_e64 v195, 0, v216, s[40:41]
	v_sub_f32_e32 v146, v146, v195
	v_cndmask_b32_e64 v146, v150, v146, s[28:29]
	v_mul_f32_e32 v150, 0x3fb8aa3b, v194
	v_exp_f32_e32 v150, v150
	s_nop 0
	v_fma_f32 v150, v186, v150, v138
	v_cmp_gt_f32_e64 s[40:41], s97, v150
	s_nop 1
	v_cndmask_b32_e64 v195, 0, 32, s[40:41]
	v_ldexp_f32 v150, v150, v195
	v_log_f32_e32 v150, v150
	s_nop 0
	v_mul_f32_e32 v195, 0x3f317217, v150
	v_fma_f32 v195, v150, s52, -v195
	v_fmac_f32_e32 v195, 0x3377d1cf, v150
	v_fmac_f32_e32 v195, 0x3f317217, v150
	v_cmp_lt_f32_e64 s[42:43], |v150|, s53
	s_nop 1
	v_cndmask_b32_e64 v150, v150, v195, s[42:43]
	v_cndmask_b32_e64 v195, 0, v216, s[40:41]
	v_sub_f32_e32 v150, v150, v195
	v_cndmask_b32_e64 v150, v194, v150, s[26:27]
	v_min_f32_e32 v194, 0, v151
	v_mul_f32_e64 v151, |v151|, s57
	v_exp_f32_e32 v151, v151
	s_nop 0
	v_add_f32_e32 v151, 1.0, v151
	v_cmp_gt_f32_e64 s[40:41], s97, v151
	s_nop 1
	v_cndmask_b32_e64 v195, 0, 32, s[40:41]
	v_ldexp_f32 v151, v151, v195
	v_log_f32_e32 v151, v151
	s_nop 0
	v_mul_f32_e32 v195, 0x3f317217, v151
	v_fma_f32 v195, v151, s52, -v195
	v_fmac_f32_e32 v195, 0x3377d1cf, v151
	v_fmac_f32_e32 v195, 0x3f317217, v151
	v_cmp_lt_f32_e64 s[42:43], |v151|, s53
	s_nop 1
	v_cndmask_b32_e64 v151, v151, v195, s[42:43]
	v_cndmask_b32_e64 v195, 0, v216, s[40:41]
	v_sub_f32_e32 v151, v151, v195
	v_sub_f32_e32 v151, v194, v151
	v_min_f32_e32 v194, 0, v147
	v_mul_f32_e64 v147, |v147|, s57
	v_exp_f32_e32 v147, v147
	s_nop 0
	v_add_f32_e32 v147, 1.0, v147
	v_cmp_gt_f32_e64 s[40:41], s97, v147
	s_nop 1
	v_cndmask_b32_e64 v195, 0, 32, s[40:41]
	v_ldexp_f32 v147, v147, v195
	v_log_f32_e32 v147, v147
	s_nop 0
	v_mul_f32_e32 v195, 0x3f317217, v147
	v_fma_f32 v195, v147, s52, -v195
	v_fmac_f32_e32 v195, 0x3377d1cf, v147
	v_fmac_f32_e32 v195, 0x3f317217, v147
	v_cmp_lt_f32_e64 s[42:43], |v147|, s53
	s_nop 1
	v_cndmask_b32_e64 v147, v147, v195, s[42:43]
	v_cndmask_b32_e64 v195, 0, v216, s[40:41]
	v_sub_f32_e32 v147, v147, v195
	v_sub_f32_e32 v194, v194, v147
	v_mul_f32_e32 v147, 0x3fb8aa3b, v151
	v_exp_f32_e32 v147, v147
	s_nop 0
	v_fma_f32 v147, v185, v147, v143
	v_cmp_gt_f32_e64 s[40:41], s97, v147
	s_nop 1
	v_cndmask_b32_e64 v195, 0, 32, s[40:41]
	v_ldexp_f32 v147, v147, v195
	v_log_f32_e32 v147, v147
	s_nop 0
	v_mul_f32_e32 v195, 0x3f317217, v147
	v_fma_f32 v195, v147, s52, -v195
	v_fmac_f32_e32 v195, 0x3377d1cf, v147
	v_fmac_f32_e32 v195, 0x3f317217, v147
	v_cmp_lt_f32_e64 s[42:43], |v147|, s53
	s_nop 1
	v_cndmask_b32_e64 v147, v147, v195, s[42:43]
	v_cndmask_b32_e64 v195, 0, v216, s[40:41]
	v_sub_f32_e32 v147, v147, v195
	v_cndmask_b32_e64 v147, v151, v147, s[24:25]
	v_mul_f32_e32 v151, 0x3fb8aa3b, v194
	v_exp_f32_e32 v151, v151
	s_nop 0
	v_fma_f32 v151, v184, v151, v139
	v_cmp_gt_f32_e64 s[40:41], s97, v151
	s_nop 1
	v_cndmask_b32_e64 v195, 0, 32, s[40:41]
	v_ldexp_f32 v151, v151, v195
	v_log_f32_e32 v151, v151
	s_nop 0
	v_mul_f32_e32 v195, 0x3f317217, v151
	v_fma_f32 v195, v151, s52, -v195
	v_fmac_f32_e32 v195, 0x3377d1cf, v151
	v_fmac_f32_e32 v195, 0x3f317217, v151
	v_cmp_lt_f32_e64 s[42:43], |v151|, s53
	s_nop 1
	v_cndmask_b32_e64 v151, v151, v195, s[42:43]
	v_cndmask_b32_e64 v195, 0, v216, s[40:41]
	v_sub_f32_e32 v151, v151, v195
	v_cndmask_b32_e64 v151, v194, v151, s[22:23]
	global_store_dwordx4 v[170:171], v[144:147], off
	global_store_dwordx4 v[170:171], v[148:151], off offset:16
	s_nop 1
	v_pk_mul_f32 v[148:149], v[92:93], v[168:169] op_sel_hi:[1,0]
	v_pk_mul_f32 v[150:151], v[94:95], v[168:169] op_sel_hi:[1,0]
	v_pk_mul_f32 v[146:147], v[90:91], v[168:169] op_sel_hi:[1,0]
	v_pk_mul_f32 v[144:145], v[88:89], v[168:169] op_sel_hi:[1,0]
	v_min_f32_e32 v168, 0, v148
	v_mul_f32_e64 v148, |v148|, s57
	v_exp_f32_e32 v148, v148
	s_nop 0
	v_add_f32_e32 v148, 1.0, v148
	v_cmp_gt_f32_e64 s[40:41], s97, v148
	s_nop 1
	v_cndmask_b32_e64 v194, 0, 32, s[40:41]
	v_ldexp_f32 v148, v148, v194
	v_log_f32_e32 v148, v148
	s_nop 0
	v_mul_f32_e32 v194, 0x3f317217, v148
	v_fma_f32 v194, v148, s52, -v194
	v_fmac_f32_e32 v194, 0x3377d1cf, v148
; __device__ __forceinline__ float silu_f(float x) { return x * __builtin_amdgcn_rcpf(1.f + __expf(-x)); }
; __device__ __forceinline__ v4u pack8(const f32x4 a, const f32x4 b) { v4u w; w.x = cvt_pk_bf16(a[0], a[1]); w.y = cvt_pk_bf16(a[2], a[3]); w.z = cvt_pk_bf16(b[0], b[1]); w.w = cvt_pk_bf16(b[2], b[3]); return w; }
;     __device__ __forceinline__ void operator()(const f32x4 (&acc)[2][2][4][2], const pg8::Unit& u, int wr, int wc, int fr, int fq) const {
;     ...
;         if (grp == 0) { WIN_LOOP( _Pragma("unroll") for (int i = 0; i < 4; ++i) { a[i] = silu_f(a[i]); b[i] = silu_f(b[i]); } *(v4u*)(QO + (size_t)row * DM + c) = pack8(a, b); ) }
;         else if (grp == 3) { WIN_LOOP( _Pragma("unroll") for (int i = 0; i < 4; ++i) { a[i] = silu_f(a[i]); b[i] = silu_f(b[i]); } *(v4u*)(GH + (size_t)row * 512 + c) = pack8(a, b); ) }
;         else if (grp == 1) {
;             f32x4 l0[2], l1[2];
; #pragma unroll
;             for (int bj = 0; bj < 2; ++bj) { l0[bj] = *(const f32x4*)(lb + cb + bj * 128); l1[bj] = *(const f32x4*)(lb + cb + bj * 128 + 4); }
;             WIN_LOOP( _Pragma("unroll") for (int i = 0; i < 4; ++i) { const float s0 = fminf(a[i], 0.f) - __logf(1.f + __expf(-fabsf(a[i]))), s1 = fminf(b[i], 0.f) - __logf(1.f + __expf(-fabsf(b[i]))); const float la = l0[bj][i], lbv = l1[bj][i];
;                     a[i] = la > 0.f ? __logf(la + (1.f - la) * __expf(s0)) : s0; b[i] = lbv > 0.f ? __logf(lbv + (1.f - lbv) * __expf(s1)) : s1; }
;                 *(f32x4*)(LF + (size_t)row * 512 + c) = a; *(f32x4*)(LF + (size_t)row * 512 + c + 4) = b; __builtin_amdgcn_sched_barrier(0); ) }
	v_fmac_f32_e32 v194, 0x3f317217, v148
	v_cmp_lt_f32_e64 s[42:43], |v148|, s53
	s_nop 1
	v_cndmask_b32_e64 v148, v148, v194, s[42:43]
	v_cndmask_b32_e64 v194, 0, v216, s[40:41]
	v_sub_f32_e32 v148, v148, v194
	v_sub_f32_e32 v148, v168, v148
	v_min_f32_e32 v168, 0, v144
	v_mul_f32_e64 v144, |v144|, s57
	v_exp_f32_e32 v144, v144
	s_nop 0
	v_add_f32_e32 v144, 1.0, v144
	v_cmp_gt_f32_e64 s[40:41], s97, v144
	s_nop 1
	v_cndmask_b32_e64 v194, 0, 32, s[40:41]
	v_ldexp_f32 v144, v144, v194
	v_log_f32_e32 v144, v144
	s_nop 0
	v_mul_f32_e32 v194, 0x3f317217, v144
	v_fma_f32 v194, v144, s52, -v194
	v_fmac_f32_e32 v194, 0x3377d1cf, v144
	v_fmac_f32_e32 v194, 0x3f317217, v144
	v_cmp_lt_f32_e64 s[42:43], |v144|, s53
	s_nop 1
	v_cndmask_b32_e64 v144, v144, v194, s[42:43]
	v_cndmask_b32_e64 v194, 0, v216, s[40:41]
	v_sub_f32_e32 v144, v144, v194
	v_sub_f32_e32 v168, v168, v144
	v_mul_f32_e32 v144, 0x3fb8aa3b, v148
	v_exp_f32_e32 v144, v144
	s_nop 0
	v_fma_f32 v144, v183, v144, v132
	v_cmp_gt_f32_e64 s[40:41], s97, v144
	s_nop 1
	v_cndmask_b32_e64 v194, 0, 32, s[40:41]
	v_ldexp_f32 v144, v144, v194
	v_log_f32_e32 v144, v144
	s_nop 0
	v_mul_f32_e32 v194, 0x3f317217, v144
	v_fma_f32 v194, v144, s52, -v194
	v_fmac_f32_e32 v194, 0x3377d1cf, v144
	v_fmac_f32_e32 v194, 0x3f317217, v144
	v_cmp_lt_f32_e64 s[42:43], |v144|, s53
	s_nop 1
	v_cndmask_b32_e64 v144, v144, v194, s[42:43]
	v_cndmask_b32_e64 v194, 0, v216, s[40:41]
	v_sub_f32_e32 v144, v144, v194
	v_cndmask_b32_e64 v144, v148, v144, s[20:21]
	v_mul_f32_e32 v148, 0x3fb8aa3b, v168
	v_exp_f32_e32 v148, v148
	s_nop 0
	v_fma_f32 v148, v182, v148, v128
	v_cmp_gt_f32_e64 s[40:41], s97, v148
	s_nop 1
	v_cndmask_b32_e64 v194, 0, 32, s[40:41]
	v_ldexp_f32 v148, v148, v194
	v_log_f32_e32 v148, v148
	s_nop 0
	v_mul_f32_e32 v194, 0x3f317217, v148
	v_fma_f32 v194, v148, s52, -v194
	v_fmac_f32_e32 v194, 0x3377d1cf, v148
	v_fmac_f32_e32 v194, 0x3f317217, v148
	v_cmp_lt_f32_e64 s[42:43], |v148|, s53
	s_nop 1
	v_cndmask_b32_e64 v148, v148, v194, s[42:43]
	v_cndmask_b32_e64 v194, 0, v216, s[40:41]
	v_sub_f32_e32 v148, v148, v194
	v_cndmask_b32_e64 v148, v168, v148, s[18:19]
	v_min_f32_e32 v168, 0, v149
	v_mul_f32_e64 v149, |v149|, s57
	v_exp_f32_e32 v149, v149
	s_nop 0
	v_add_f32_e32 v149, 1.0, v149
	v_cmp_gt_f32_e64 s[40:41], s97, v149
	s_nop 1
	v_cndmask_b32_e64 v194, 0, 32, s[40:41]
	v_ldexp_f32 v149, v149, v194
	v_log_f32_e32 v149, v149
	s_nop 0
	v_mul_f32_e32 v194, 0x3f317217, v149
	v_fma_f32 v194, v149, s52, -v194
	v_fmac_f32_e32 v194, 0x3377d1cf, v149
	v_fmac_f32_e32 v194, 0x3f317217, v149
	v_cmp_lt_f32_e64 s[42:43], |v149|, s53
	s_nop 1
	v_cndmask_b32_e64 v149, v149, v194, s[42:43]
	v_cndmask_b32_e64 v194, 0, v216, s[40:41]
	v_sub_f32_e32 v149, v149, v194
	v_sub_f32_e32 v149, v168, v149
	v_min_f32_e32 v168, 0, v145
	v_mul_f32_e64 v145, |v145|, s57
	v_exp_f32_e32 v145, v145
	s_nop 0
	v_add_f32_e32 v145, 1.0, v145
	v_cmp_gt_f32_e64 s[40:41], s97, v145
	s_nop 1
	v_cndmask_b32_e64 v194, 0, 32, s[40:41]
	v_ldexp_f32 v145, v145, v194
	v_log_f32_e32 v145, v145
	s_nop 0
	v_mul_f32_e32 v194, 0x3f317217, v145
	v_fma_f32 v194, v145, s52, -v194
	v_fmac_f32_e32 v194, 0x3377d1cf, v145
	v_fmac_f32_e32 v194, 0x3f317217, v145
	v_cmp_lt_f32_e64 s[42:43], |v145|, s53
	s_nop 1
	v_cndmask_b32_e64 v145, v145, v194, s[42:43]
	v_cndmask_b32_e64 v194, 0, v216, s[40:41]
	v_sub_f32_e32 v145, v145, v194
	v_sub_f32_e32 v168, v168, v145
	v_mul_f32_e32 v145, 0x3fb8aa3b, v149
	v_exp_f32_e32 v145, v145
	s_nop 0
	v_fma_f32 v145, v181, v145, v133
	v_cmp_gt_f32_e64 s[40:41], s97, v145
	s_nop 1
	v_cndmask_b32_e64 v194, 0, 32, s[40:41]
	v_ldexp_f32 v145, v145, v194
	v_log_f32_e32 v145, v145
	s_nop 0
	v_mul_f32_e32 v194, 0x3f317217, v145
	v_fma_f32 v194, v145, s52, -v194
	v_fmac_f32_e32 v194, 0x3377d1cf, v145
	v_fmac_f32_e32 v194, 0x3f317217, v145
	v_cmp_lt_f32_e64 s[42:43], |v145|, s53
	s_nop 1
	v_cndmask_b32_e64 v145, v145, v194, s[42:43]
	v_cndmask_b32_e64 v194, 0, v216, s[40:41]
	v_sub_f32_e32 v145, v145, v194
	v_cndmask_b32_e64 v145, v149, v145, s[16:17]
	v_mul_f32_e32 v149, 0x3fb8aa3b, v168
	v_exp_f32_e32 v149, v149
	s_nop 0
	v_fma_f32 v149, v180, v149, v129
	v_cmp_gt_f32_e64 s[40:41], s97, v149
	s_nop 1
	v_cndmask_b32_e64 v194, 0, 32, s[40:41]
	v_ldexp_f32 v149, v149, v194
	v_log_f32_e32 v149, v149
	s_nop 0
	v_mul_f32_e32 v194, 0x3f317217, v149
	v_fma_f32 v194, v149, s52, -v194
	v_fmac_f32_e32 v194, 0x3377d1cf, v149
	v_fmac_f32_e32 v194, 0x3f317217, v149
	v_cmp_lt_f32_e64 s[42:43], |v149|, s53
	s_nop 1
	v_cndmask_b32_e64 v149, v149, v194, s[42:43]
	v_cndmask_b32_e64 v194, 0, v216, s[40:41]
	v_sub_f32_e32 v149, v149, v194
	v_cndmask_b32_e64 v149, v168, v149, s[14:15]
	v_min_f32_e32 v168, 0, v150
	v_mul_f32_e64 v150, |v150|, s57
	v_exp_f32_e32 v150, v150
	s_nop 0
	v_add_f32_e32 v150, 1.0, v150
	v_cmp_gt_f32_e64 s[40:41], s97, v150
	s_nop 1
	v_cndmask_b32_e64 v194, 0, 32, s[40:41]
	v_ldexp_f32 v150, v150, v194
	v_log_f32_e32 v150, v150
	s_nop 0
	v_mul_f32_e32 v194, 0x3f317217, v150
	v_fma_f32 v194, v150, s52, -v194
	v_fmac_f32_e32 v194, 0x3377d1cf, v150
	v_fmac_f32_e32 v194, 0x3f317217, v150
	v_cmp_lt_f32_e64 s[42:43], |v150|, s53
	s_nop 1
	v_cndmask_b32_e64 v150, v150, v194, s[42:43]
	v_cndmask_b32_e64 v194, 0, v216, s[40:41]
	v_sub_f32_e32 v150, v150, v194
	v_sub_f32_e32 v150, v168, v150
	v_min_f32_e32 v168, 0, v146
	v_mul_f32_e64 v146, |v146|, s57
	v_exp_f32_e32 v146, v146
	s_nop 0
	v_add_f32_e32 v146, 1.0, v146
	v_cmp_gt_f32_e64 s[40:41], s97, v146
	s_nop 1
	v_cndmask_b32_e64 v194, 0, 32, s[40:41]
	v_ldexp_f32 v146, v146, v194
	v_log_f32_e32 v146, v146
	s_nop 0
	v_mul_f32_e32 v194, 0x3f317217, v146
	v_fma_f32 v194, v146, s52, -v194
; __device__ __forceinline__ float silu_f(float x) { return x * __builtin_amdgcn_rcpf(1.f + __expf(-x)); }
; __device__ __forceinline__ v4u pack8(const f32x4 a, const f32x4 b) { v4u w; w.x = cvt_pk_bf16(a[0], a[1]); w.y = cvt_pk_bf16(a[2], a[3]); w.z = cvt_pk_bf16(b[0], b[1]); w.w = cvt_pk_bf16(b[2], b[3]); return w; }
;     __device__ __forceinline__ void operator()(const f32x4 (&acc)[2][2][4][2], const pg8::Unit& u, int wr, int wc, int fr, int fq) const {
;     ...
;         if (grp == 0) { WIN_LOOP( _Pragma("unroll") for (int i = 0; i < 4; ++i) { a[i] = silu_f(a[i]); b[i] = silu_f(b[i]); } *(v4u*)(QO + (size_t)row * DM + c) = pack8(a, b); ) }
;         else if (grp == 3) { WIN_LOOP( _Pragma("unroll") for (int i = 0; i < 4; ++i) { a[i] = silu_f(a[i]); b[i] = silu_f(b[i]); } *(v4u*)(GH + (size_t)row * 512 + c) = pack8(a, b); ) }
;         else if (grp == 1) {
;             f32x4 l0[2], l1[2];
; #pragma unroll
;             for (int bj = 0; bj < 2; ++bj) { l0[bj] = *(const f32x4*)(lb + cb + bj * 128); l1[bj] = *(const f32x4*)(lb + cb + bj * 128 + 4); }
;             WIN_LOOP( _Pragma("unroll") for (int i = 0; i < 4; ++i) { const float s0 = fminf(a[i], 0.f) - __logf(1.f + __expf(-fabsf(a[i]))), s1 = fminf(b[i], 0.f) - __logf(1.f + __expf(-fabsf(b[i]))); const float la = l0[bj][i], lbv = l1[bj][i];
;                     a[i] = la > 0.f ? __logf(la + (1.f - la) * __expf(s0)) : s0; b[i] = lbv > 0.f ? __logf(lbv + (1.f - lbv) * __expf(s1)) : s1; }
;                 *(f32x4*)(LF + (size_t)row * 512 + c) = a; *(f32x4*)(LF + (size_t)row * 512 + c + 4) = b; __builtin_amdgcn_sched_barrier(0); ) }
	v_fmac_f32_e32 v194, 0x3377d1cf, v146
	v_fmac_f32_e32 v194, 0x3f317217, v146
	v_cmp_lt_f32_e64 s[42:43], |v146|, s53
	s_nop 1
	v_cndmask_b32_e64 v146, v146, v194, s[42:43]
	v_cndmask_b32_e64 v194, 0, v216, s[40:41]
	v_sub_f32_e32 v146, v146, v194
	v_sub_f32_e32 v168, v168, v146
	v_mul_f32_e32 v146, 0x3fb8aa3b, v150
	v_exp_f32_e32 v146, v146
	s_nop 0
	v_fma_f32 v146, v179, v146, v134
	v_cmp_gt_f32_e64 s[40:41], s97, v146
	s_nop 1
	v_cndmask_b32_e64 v194, 0, 32, s[40:41]
	v_ldexp_f32 v146, v146, v194
	v_log_f32_e32 v146, v146
	s_nop 0
	v_mul_f32_e32 v194, 0x3f317217, v146
	v_fma_f32 v194, v146, s52, -v194
	v_fmac_f32_e32 v194, 0x3377d1cf, v146
	v_fmac_f32_e32 v194, 0x3f317217, v146
	v_cmp_lt_f32_e64 s[42:43], |v146|, s53
	s_nop 1
	v_cndmask_b32_e64 v146, v146, v194, s[42:43]
	v_cndmask_b32_e64 v194, 0, v216, s[40:41]
	v_sub_f32_e32 v146, v146, v194
	v_cndmask_b32_e64 v146, v150, v146, s[12:13]
	v_mul_f32_e32 v150, 0x3fb8aa3b, v168
	v_exp_f32_e32 v150, v150
	s_nop 0
	v_fma_f32 v150, v178, v150, v130
	v_cmp_gt_f32_e64 s[40:41], s97, v150
	s_nop 1
	v_cndmask_b32_e64 v194, 0, 32, s[40:41]
	v_ldexp_f32 v150, v150, v194
	v_log_f32_e32 v150, v150
	s_nop 0
	v_mul_f32_e32 v194, 0x3f317217, v150
	v_fma_f32 v194, v150, s52, -v194
	v_fmac_f32_e32 v194, 0x3377d1cf, v150
	v_fmac_f32_e32 v194, 0x3f317217, v150
	v_cmp_lt_f32_e64 s[42:43], |v150|, s53
	s_nop 1
	v_cndmask_b32_e64 v150, v150, v194, s[42:43]
	v_cndmask_b32_e64 v194, 0, v216, s[40:41]
	v_sub_f32_e32 v150, v150, v194
	v_cndmask_b32_e64 v150, v168, v150, s[10:11]
	v_min_f32_e32 v168, 0, v151
	v_mul_f32_e64 v151, |v151|, s57
	v_exp_f32_e32 v151, v151
	s_nop 0
	v_add_f32_e32 v151, 1.0, v151
	v_cmp_gt_f32_e64 s[40:41], s97, v151
	s_nop 1
	v_cndmask_b32_e64 v194, 0, 32, s[40:41]
	v_ldexp_f32 v151, v151, v194
	v_log_f32_e32 v151, v151
	s_nop 0
	v_mul_f32_e32 v194, 0x3f317217, v151
	v_fma_f32 v194, v151, s52, -v194
	v_fmac_f32_e32 v194, 0x3377d1cf, v151
	v_fmac_f32_e32 v194, 0x3f317217, v151
	v_cmp_lt_f32_e64 s[42:43], |v151|, s53
	s_nop 1
	v_cndmask_b32_e64 v151, v151, v194, s[42:43]
	v_cndmask_b32_e64 v194, 0, v216, s[40:41]
	v_sub_f32_e32 v151, v151, v194
	v_sub_f32_e32 v151, v168, v151
	v_min_f32_e32 v168, 0, v147
	v_mul_f32_e64 v147, |v147|, s57
	v_exp_f32_e32 v147, v147
	s_nop 0
	v_add_f32_e32 v147, 1.0, v147
	v_cmp_gt_f32_e64 s[40:41], s97, v147
	s_nop 1
	v_cndmask_b32_e64 v194, 0, 32, s[40:41]
	v_ldexp_f32 v147, v147, v194
	v_log_f32_e32 v147, v147
	s_nop 0
	v_mul_f32_e32 v194, 0x3f317217, v147
	v_fma_f32 v194, v147, s52, -v194
	v_fmac_f32_e32 v194, 0x3377d1cf, v147
	v_fmac_f32_e32 v194, 0x3f317217, v147
	v_cmp_lt_f32_e64 s[42:43], |v147|, s53
	s_nop 1
	v_cndmask_b32_e64 v147, v147, v194, s[42:43]
	v_cndmask_b32_e64 v194, 0, v216, s[40:41]
	v_sub_f32_e32 v147, v147, v194
	v_sub_f32_e32 v168, v168, v147
	v_mul_f32_e32 v147, 0x3fb8aa3b, v151
	v_exp_f32_e32 v147, v147
	s_nop 0
	v_fma_f32 v147, v177, v147, v135
	v_cmp_gt_f32_e64 s[40:41], s97, v147
	s_nop 1
	v_cndmask_b32_e64 v194, 0, 32, s[40:41]
	v_ldexp_f32 v147, v147, v194
	v_log_f32_e32 v147, v147
	s_nop 0
	v_mul_f32_e32 v194, 0x3f317217, v147
	v_fma_f32 v194, v147, s52, -v194
	v_fmac_f32_e32 v194, 0x3377d1cf, v147
	v_fmac_f32_e32 v194, 0x3f317217, v147
	v_cmp_lt_f32_e64 s[42:43], |v147|, s53
	s_nop 1
	v_cndmask_b32_e64 v147, v147, v194, s[42:43]
	v_cndmask_b32_e64 v194, 0, v216, s[40:41]
	v_sub_f32_e32 v147, v147, v194
	v_cndmask_b32_e64 v147, v151, v147, s[8:9]
	v_mul_f32_e32 v151, 0x3fb8aa3b, v168
	v_exp_f32_e32 v151, v151
	s_nop 0
	v_fma_f32 v151, v167, v151, v131
	v_cmp_gt_f32_e64 s[40:41], s97, v151
	s_nop 1
	v_cndmask_b32_e64 v194, 0, 32, s[40:41]
	v_ldexp_f32 v151, v151, v194
	v_log_f32_e32 v151, v151
	s_nop 0
	v_mul_f32_e32 v194, 0x3f317217, v151
	v_fma_f32 v194, v151, s52, -v194
	v_fmac_f32_e32 v194, 0x3377d1cf, v151
	v_fmac_f32_e32 v194, 0x3f317217, v151
	v_cmp_lt_f32_e64 s[42:43], |v151|, s53
	s_nop 1
	v_cndmask_b32_e64 v151, v151, v194, s[42:43]
	v_cndmask_b32_e64 v194, 0, v216, s[40:41]
	v_sub_f32_e32 v151, v151, v194
	v_cndmask_b32_e32 v151, v168, v151, vcc
	global_store_dwordx4 v[170:171], v[144:147], off offset:512
	global_store_dwordx4 v[170:171], v[148:151], off offset:528
	s_nop 1
	v_add_u32_e32 v148, 0x90, v166
	v_ashrrev_i32_e32 v149, 31, v148
	v_lshlrev_b64 v[144:145], 6, v[148:149]
	v_lshl_add_u64 v[144:145], v[160:161], 0, v[144:145]
	s_nop 0
	s_waitcnt lgkmcnt(0)
	s_nop 3
	s_nop 0
	s_nop 1
	s_waitcnt lgkmcnt(0)
	s_nop 1
	s_waitcnt lgkmcnt(0)
; __device__ __forceinline__ float silu_f(float x) { return x * __builtin_amdgcn_rcpf(1.f + __expf(-x)); }
; __device__ __forceinline__ v4u pack8(const f32x4 a, const f32x4 b) { v4u w; w.x = cvt_pk_bf16(a[0], a[1]); w.y = cvt_pk_bf16(a[2], a[3]); w.z = cvt_pk_bf16(b[0], b[1]); w.w = cvt_pk_bf16(b[2], b[3]); return w; }
; __device__ __forceinline__ float row_rstd(const float* ssq, int row, int fq) {
;     const f32x4 v = *(const f32x4*)(ssq + (size_t)row * 16 + fq * 4);
;     float s = (v[0] + v[1]) + (v[2] + v[3]);
;     s += __shfl_xor(s, 16); s += __shfl_xor(s, 32);
;     return __builtin_amdgcn_rsqf(s * (1.f / DM) + EPS);
;     __device__ __forceinline__ void operator()(const f32x4 (&acc)[2][2][4][2], const pg8::Unit& u, int wr, int wc, int fr, int fq) const {
;     ...
;         if (grp == 0) { WIN_LOOP( _Pragma("unroll") for (int i = 0; i < 4; ++i) { a[i] = silu_f(a[i]); b[i] = silu_f(b[i]); } *(v4u*)(QO + (size_t)row * DM + c) = pack8(a, b); ) }
;         else if (grp == 3) { WIN_LOOP( _Pragma("unroll") for (int i = 0; i < 4; ++i) { a[i] = silu_f(a[i]); b[i] = silu_f(b[i]); } *(v4u*)(GH + (size_t)row * 512 + c) = pack8(a, b); ) }
;         else if (grp == 1) {
;             f32x4 l0[2], l1[2];
; #pragma unroll
;             for (int bj = 0; bj < 2; ++bj) { l0[bj] = *(const f32x4*)(lb + cb + bj * 128); l1[bj] = *(const f32x4*)(lb + cb + bj * 128 + 4); }
;             WIN_LOOP( _Pragma("unroll") for (int i = 0; i < 4; ++i) { const float s0 = fminf(a[i], 0.f) - __logf(1.f + __expf(-fabsf(a[i]))), s1 = fminf(b[i], 0.f) - __logf(1.f + __expf(-fabsf(b[i]))); const float la = l0[bj][i], lbv = l1[bj][i];
;                     a[i] = la > 0.f ? __logf(la + (1.f - la) * __expf(s0)) : s0; b[i] = lbv > 0.f ? __logf(lbv + (1.f - lbv) * __expf(s1)) : s1; }
;                 *(f32x4*)(LF + (size_t)row * 512 + c) = a; *(f32x4*)(LF + (size_t)row * 512 + c + 4) = b; __builtin_amdgcn_sched_barrier(0); ) }
	s_nop 1
	v_mov_b32_e32 v168, v240
	v_lshlrev_b64 v[144:145], 11, v[148:149]
	v_lshl_add_u64 v[170:171], s[50:51], 0, v[144:145]
	v_lshl_add_u64 v[170:171], v[170:171], 0, v[192:193]
	v_pk_mul_f32 v[148:149], v[20:21], v[168:169] op_sel_hi:[1,0]
	v_pk_mul_f32 v[144:145], v[16:17], v[168:169] op_sel_hi:[1,0]
	v_min_f32_e32 v194, 0, v148
	v_mul_f32_e64 v148, |v148|, s57
	v_exp_f32_e32 v148, v148
	v_pk_mul_f32 v[150:151], v[22:23], v[168:169] op_sel_hi:[1,0]
	v_pk_mul_f32 v[146:147], v[18:19], v[168:169] op_sel_hi:[1,0]
	v_add_f32_e32 v148, 1.0, v148
	v_cmp_gt_f32_e64 s[40:41], s97, v148
	s_nop 1
	v_cndmask_b32_e64 v195, 0, 32, s[40:41]
	v_ldexp_f32 v148, v148, v195
	v_log_f32_e32 v148, v148
	s_nop 0
	v_mul_f32_e32 v195, 0x3f317217, v148
	v_fma_f32 v195, v148, s52, -v195
	v_fmac_f32_e32 v195, 0x3377d1cf, v148
	v_fmac_f32_e32 v195, 0x3f317217, v148
	v_cmp_lt_f32_e64 s[42:43], |v148|, s53
	s_nop 1
	v_cndmask_b32_e64 v148, v148, v195, s[42:43]
	v_cndmask_b32_e64 v195, 0, v216, s[40:41]
	v_sub_f32_e32 v148, v148, v195
	v_sub_f32_e32 v148, v194, v148
	v_min_f32_e32 v194, 0, v144
	v_mul_f32_e64 v144, |v144|, s57
	v_exp_f32_e32 v144, v144
	s_nop 0
	v_add_f32_e32 v144, 1.0, v144
	v_cmp_gt_f32_e64 s[40:41], s97, v144
	s_nop 1
	v_cndmask_b32_e64 v195, 0, 32, s[40:41]
	v_ldexp_f32 v144, v144, v195
	v_log_f32_e32 v144, v144
	s_nop 0
	v_mul_f32_e32 v195, 0x3f317217, v144
	v_fma_f32 v195, v144, s52, -v195
	v_fmac_f32_e32 v195, 0x3377d1cf, v144
	v_fmac_f32_e32 v195, 0x3f317217, v144
	v_cmp_lt_f32_e64 s[42:43], |v144|, s53
	s_nop 1
	v_cndmask_b32_e64 v144, v144, v195, s[42:43]
	v_cndmask_b32_e64 v195, 0, v216, s[40:41]
	v_sub_f32_e32 v144, v144, v195
	v_sub_f32_e32 v194, v194, v144
	v_mul_f32_e32 v144, 0x3fb8aa3b, v148
	v_exp_f32_e32 v144, v144
	s_nop 0
	v_fma_f32 v144, v190, v144, v140
	v_cmp_gt_f32_e64 s[40:41], s97, v144
	s_nop 1
	v_cndmask_b32_e64 v195, 0, 32, s[40:41]
	v_ldexp_f32 v144, v144, v195
	v_log_f32_e32 v144, v144
	s_nop 0
	v_mul_f32_e32 v195, 0x3f317217, v144
	v_fma_f32 v195, v144, s52, -v195
	v_fmac_f32_e32 v195, 0x3377d1cf, v144
	v_fmac_f32_e32 v195, 0x3f317217, v144
	v_cmp_lt_f32_e64 s[42:43], |v144|, s53
	s_nop 1
	v_cndmask_b32_e64 v144, v144, v195, s[42:43]
	v_cndmask_b32_e64 v195, 0, v216, s[40:41]
	v_sub_f32_e32 v144, v144, v195
	v_cndmask_b32_e64 v144, v148, v144, s[38:39]
	v_mul_f32_e32 v148, 0x3fb8aa3b, v194
	v_exp_f32_e32 v148, v148
	s_nop 0
	v_fma_f32 v148, v191, v148, v136
	v_cmp_gt_f32_e64 s[40:41], s97, v148
	s_nop 1
	v_cndmask_b32_e64 v195, 0, 32, s[40:41]
	v_ldexp_f32 v148, v148, v195
	v_log_f32_e32 v148, v148
	s_nop 0
	v_mul_f32_e32 v195, 0x3f317217, v148
	v_fma_f32 v195, v148, s52, -v195
	v_fmac_f32_e32 v195, 0x3377d1cf, v148
	v_fmac_f32_e32 v195, 0x3f317217, v148
	v_cmp_lt_f32_e64 s[42:43], |v148|, s53
	s_nop 1
	v_cndmask_b32_e64 v148, v148, v195, s[42:43]
	v_cndmask_b32_e64 v195, 0, v216, s[40:41]
	v_sub_f32_e32 v148, v148, v195
	v_cndmask_b32_e64 v148, v194, v148, s[36:37]
	v_min_f32_e32 v194, 0, v149
	v_mul_f32_e64 v149, |v149|, s57
	v_exp_f32_e32 v149, v149
	s_nop 0
	v_add_f32_e32 v149, 1.0, v149
	v_cmp_gt_f32_e64 s[40:41], s97, v149
	s_nop 1
	v_cndmask_b32_e64 v195, 0, 32, s[40:41]
	v_ldexp_f32 v149, v149, v195
	v_log_f32_e32 v149, v149
	s_nop 0
	v_mul_f32_e32 v195, 0x3f317217, v149
	v_fma_f32 v195, v149, s52, -v195
	v_fmac_f32_e32 v195, 0x3377d1cf, v149
	v_fmac_f32_e32 v195, 0x3f317217, v149
	v_cmp_lt_f32_e64 s[42:43], |v149|, s53
	s_nop 1
	v_cndmask_b32_e64 v149, v149, v195, s[42:43]
	v_cndmask_b32_e64 v195, 0, v216, s[40:41]
	v_sub_f32_e32 v149, v149, v195
	v_sub_f32_e32 v149, v194, v149
	v_min_f32_e32 v194, 0, v145
	v_mul_f32_e64 v145, |v145|, s57
	v_exp_f32_e32 v145, v145
	s_nop 0
	v_add_f32_e32 v145, 1.0, v145
	v_cmp_gt_f32_e64 s[40:41], s97, v145
	s_nop 1
	v_cndmask_b32_e64 v195, 0, 32, s[40:41]
	v_ldexp_f32 v145, v145, v195
	v_log_f32_e32 v145, v145
	s_nop 0
	v_mul_f32_e32 v195, 0x3f317217, v145
	v_fma_f32 v195, v145, s52, -v195
	v_fmac_f32_e32 v195, 0x3377d1cf, v145
	v_fmac_f32_e32 v195, 0x3f317217, v145
	v_cmp_lt_f32_e64 s[42:43], |v145|, s53
	s_nop 1
	v_cndmask_b32_e64 v145, v145, v195, s[42:43]
	v_cndmask_b32_e64 v195, 0, v216, s[40:41]
	v_sub_f32_e32 v145, v145, v195
	v_sub_f32_e32 v194, v194, v145
	v_mul_f32_e32 v145, 0x3fb8aa3b, v149
	v_exp_f32_e32 v145, v145
	s_nop 0
	v_fma_f32 v145, v188, v145, v141
	v_cmp_gt_f32_e64 s[40:41], s97, v145
	s_nop 1
	v_cndmask_b32_e64 v195, 0, 32, s[40:41]
	v_ldexp_f32 v145, v145, v195
	v_log_f32_e32 v145, v145
	s_nop 0
	v_mul_f32_e32 v195, 0x3f317217, v145
	v_fma_f32 v195, v145, s52, -v195
	v_fmac_f32_e32 v195, 0x3377d1cf, v145
	v_fmac_f32_e32 v195, 0x3f317217, v145
	v_cmp_lt_f32_e64 s[42:43], |v145|, s53
	s_nop 1
	v_cndmask_b32_e64 v145, v145, v195, s[42:43]
	v_cndmask_b32_e64 v195, 0, v216, s[40:41]
	v_sub_f32_e32 v145, v145, v195
	v_cndmask_b32_e64 v145, v149, v145, s[34:35]
	v_mul_f32_e32 v149, 0x3fb8aa3b, v194
	v_exp_f32_e32 v149, v149
	s_nop 0
	v_fma_f32 v149, v189, v149, v137
	v_cmp_gt_f32_e64 s[40:41], s97, v149
	s_nop 1
	v_cndmask_b32_e64 v195, 0, 32, s[40:41]
	v_ldexp_f32 v149, v149, v195
	v_log_f32_e32 v149, v149
	s_nop 0
	v_mul_f32_e32 v195, 0x3f317217, v149
	v_fma_f32 v195, v149, s52, -v195
	v_fmac_f32_e32 v195, 0x3377d1cf, v149
	v_fmac_f32_e32 v195, 0x3f317217, v149
	v_cmp_lt_f32_e64 s[42:43], |v149|, s53
	s_nop 1
	v_cndmask_b32_e64 v149, v149, v195, s[42:43]
	v_cndmask_b32_e64 v195, 0, v216, s[40:41]
	v_sub_f32_e32 v149, v149, v195
	v_cndmask_b32_e64 v149, v194, v149, s[30:31]
	v_min_f32_e32 v194, 0, v150
	v_mul_f32_e64 v150, |v150|, s57
	v_exp_f32_e32 v150, v150
	s_nop 0
	v_add_f32_e32 v150, 1.0, v150
	v_cmp_gt_f32_e64 s[40:41], s97, v150
	s_nop 1
; __device__ __forceinline__ float silu_f(float x) { return x * __builtin_amdgcn_rcpf(1.f + __expf(-x)); }
; __device__ __forceinline__ v4u pack8(const f32x4 a, const f32x4 b) { v4u w; w.x = cvt_pk_bf16(a[0], a[1]); w.y = cvt_pk_bf16(a[2], a[3]); w.z = cvt_pk_bf16(b[0], b[1]); w.w = cvt_pk_bf16(b[2], b[3]); return w; }
;     __device__ __forceinline__ void operator()(const f32x4 (&acc)[2][2][4][2], const pg8::Unit& u, int wr, int wc, int fr, int fq) const {
;     ...
;         if (grp == 0) { WIN_LOOP( _Pragma("unroll") for (int i = 0; i < 4; ++i) { a[i] = silu_f(a[i]); b[i] = silu_f(b[i]); } *(v4u*)(QO + (size_t)row * DM + c) = pack8(a, b); ) }
;         else if (grp == 3) { WIN_LOOP( _Pragma("unroll") for (int i = 0; i < 4; ++i) { a[i] = silu_f(a[i]); b[i] = silu_f(b[i]); } *(v4u*)(GH + (size_t)row * 512 + c) = pack8(a, b); ) }
;         else if (grp == 1) {
;             f32x4 l0[2], l1[2];
; #pragma unroll
;             for (int bj = 0; bj < 2; ++bj) { l0[bj] = *(const f32x4*)(lb + cb + bj * 128); l1[bj] = *(const f32x4*)(lb + cb + bj * 128 + 4); }
;             WIN_LOOP( _Pragma("unroll") for (int i = 0; i < 4; ++i) { const float s0 = fminf(a[i], 0.f) - __logf(1.f + __expf(-fabsf(a[i]))), s1 = fminf(b[i], 0.f) - __logf(1.f + __expf(-fabsf(b[i]))); const float la = l0[bj][i], lbv = l1[bj][i];
;                     a[i] = la > 0.f ? __logf(la + (1.f - la) * __expf(s0)) : s0; b[i] = lbv > 0.f ? __logf(lbv + (1.f - lbv) * __expf(s1)) : s1; }
;                 *(f32x4*)(LF + (size_t)row * 512 + c) = a; *(f32x4*)(LF + (size_t)row * 512 + c + 4) = b; __builtin_amdgcn_sched_barrier(0); ) }
	v_cndmask_b32_e64 v195, 0, 32, s[40:41]
	v_ldexp_f32 v150, v150, v195
	v_log_f32_e32 v150, v150
	s_nop 0
	v_mul_f32_e32 v195, 0x3f317217, v150
	v_fma_f32 v195, v150, s52, -v195
	v_fmac_f32_e32 v195, 0x3377d1cf, v150
	v_fmac_f32_e32 v195, 0x3f317217, v150
	v_cmp_lt_f32_e64 s[42:43], |v150|, s53
	s_nop 1
	v_cndmask_b32_e64 v150, v150, v195, s[42:43]
	v_cndmask_b32_e64 v195, 0, v216, s[40:41]
	v_sub_f32_e32 v150, v150, v195
	v_sub_f32_e32 v150, v194, v150
	v_min_f32_e32 v194, 0, v146
	v_mul_f32_e64 v146, |v146|, s57
	v_exp_f32_e32 v146, v146
	s_nop 0
	v_add_f32_e32 v146, 1.0, v146
	v_cmp_gt_f32_e64 s[40:41], s97, v146
	s_nop 1
	v_cndmask_b32_e64 v195, 0, 32, s[40:41]
	v_ldexp_f32 v146, v146, v195
	v_log_f32_e32 v146, v146
	s_nop 0
	v_mul_f32_e32 v195, 0x3f317217, v146
	v_fma_f32 v195, v146, s52, -v195
	v_fmac_f32_e32 v195, 0x3377d1cf, v146
	v_fmac_f32_e32 v195, 0x3f317217, v146
	v_cmp_lt_f32_e64 s[42:43], |v146|, s53
	s_nop 1
	v_cndmask_b32_e64 v146, v146, v195, s[42:43]
	v_cndmask_b32_e64 v195, 0, v216, s[40:41]
	v_sub_f32_e32 v146, v146, v195
	v_sub_f32_e32 v194, v194, v146
	v_mul_f32_e32 v146, 0x3fb8aa3b, v150
	v_exp_f32_e32 v146, v146
	s_nop 0
	v_fma_f32 v146, v187, v146, v142
	v_cmp_gt_f32_e64 s[40:41], s97, v146
	s_nop 1
	v_cndmask_b32_e64 v195, 0, 32, s[40:41]
	v_ldexp_f32 v146, v146, v195
	v_log_f32_e32 v146, v146
	s_nop 0
	v_mul_f32_e32 v195, 0x3f317217, v146
	v_fma_f32 v195, v146, s52, -v195
	v_fmac_f32_e32 v195, 0x3377d1cf, v146
	v_fmac_f32_e32 v195, 0x3f317217, v146
	v_cmp_lt_f32_e64 s[42:43], |v146|, s53
	s_nop 1
	v_cndmask_b32_e64 v146, v146, v195, s[42:43]
	v_cndmask_b32_e64 v195, 0, v216, s[40:41]
	v_sub_f32_e32 v146, v146, v195
	v_cndmask_b32_e64 v146, v150, v146, s[28:29]
	v_mul_f32_e32 v150, 0x3fb8aa3b, v194
	v_exp_f32_e32 v150, v150
	s_nop 0
	v_fma_f32 v150, v186, v150, v138
	v_cmp_gt_f32_e64 s[40:41], s97, v150
	s_nop 1
	v_cndmask_b32_e64 v195, 0, 32, s[40:41]
	v_ldexp_f32 v150, v150, v195
	v_log_f32_e32 v150, v150
	s_nop 0
	v_mul_f32_e32 v195, 0x3f317217, v150
	v_fma_f32 v195, v150, s52, -v195
	v_fmac_f32_e32 v195, 0x3377d1cf, v150
	v_fmac_f32_e32 v195, 0x3f317217, v150
	v_cmp_lt_f32_e64 s[42:43], |v150|, s53
	s_nop 1
	v_cndmask_b32_e64 v150, v150, v195, s[42:43]
	v_cndmask_b32_e64 v195, 0, v216, s[40:41]
	v_sub_f32_e32 v150, v150, v195
	v_cndmask_b32_e64 v150, v194, v150, s[26:27]
	v_min_f32_e32 v194, 0, v151
	v_mul_f32_e64 v151, |v151|, s57
	v_exp_f32_e32 v151, v151
	s_nop 0
	v_add_f32_e32 v151, 1.0, v151
	v_cmp_gt_f32_e64 s[40:41], s97, v151
	s_nop 1
	v_cndmask_b32_e64 v195, 0, 32, s[40:41]
	v_ldexp_f32 v151, v151, v195
	v_log_f32_e32 v151, v151
	s_nop 0
	v_mul_f32_e32 v195, 0x3f317217, v151
	v_fma_f32 v195, v151, s52, -v195
	v_fmac_f32_e32 v195, 0x3377d1cf, v151
	v_fmac_f32_e32 v195, 0x3f317217, v151
	v_cmp_lt_f32_e64 s[42:43], |v151|, s53
	s_nop 1
	v_cndmask_b32_e64 v151, v151, v195, s[42:43]
	v_cndmask_b32_e64 v195, 0, v216, s[40:41]
	v_sub_f32_e32 v151, v151, v195
	v_sub_f32_e32 v151, v194, v151
	v_min_f32_e32 v194, 0, v147
	v_mul_f32_e64 v147, |v147|, s57
	v_exp_f32_e32 v147, v147
	s_nop 0
	v_add_f32_e32 v147, 1.0, v147
	v_cmp_gt_f32_e64 s[40:41], s97, v147
	s_nop 1
	v_cndmask_b32_e64 v195, 0, 32, s[40:41]
	v_ldexp_f32 v147, v147, v195
	v_log_f32_e32 v147, v147
	s_nop 0
	v_mul_f32_e32 v195, 0x3f317217, v147
	v_fma_f32 v195, v147, s52, -v195
	v_fmac_f32_e32 v195, 0x3377d1cf, v147
	v_fmac_f32_e32 v195, 0x3f317217, v147
	v_cmp_lt_f32_e64 s[42:43], |v147|, s53
	s_nop 1
	v_cndmask_b32_e64 v147, v147, v195, s[42:43]
	v_cndmask_b32_e64 v195, 0, v216, s[40:41]
	v_sub_f32_e32 v147, v147, v195
	v_sub_f32_e32 v194, v194, v147
	v_mul_f32_e32 v147, 0x3fb8aa3b, v151
	v_exp_f32_e32 v147, v147
	s_nop 0
	v_fma_f32 v147, v185, v147, v143
	v_cmp_gt_f32_e64 s[40:41], s97, v147
	s_nop 1
	v_cndmask_b32_e64 v195, 0, 32, s[40:41]
	v_ldexp_f32 v147, v147, v195
	v_log_f32_e32 v147, v147
	s_nop 0
	v_mul_f32_e32 v195, 0x3f317217, v147
	v_fma_f32 v195, v147, s52, -v195
	v_fmac_f32_e32 v195, 0x3377d1cf, v147
	v_fmac_f32_e32 v195, 0x3f317217, v147
	v_cmp_lt_f32_e64 s[42:43], |v147|, s53
	s_nop 1
	v_cndmask_b32_e64 v147, v147, v195, s[42:43]
	v_cndmask_b32_e64 v195, 0, v216, s[40:41]
	v_sub_f32_e32 v147, v147, v195
	v_cndmask_b32_e64 v147, v151, v147, s[24:25]
	v_mul_f32_e32 v151, 0x3fb8aa3b, v194
	v_exp_f32_e32 v151, v151
	s_nop 0
	v_fma_f32 v151, v184, v151, v139
	v_cmp_gt_f32_e64 s[40:41], s97, v151
	s_nop 1
	v_cndmask_b32_e64 v195, 0, 32, s[40:41]
	v_ldexp_f32 v151, v151, v195
	v_log_f32_e32 v151, v151
	s_nop 0
	v_mul_f32_e32 v195, 0x3f317217, v151
	v_fma_f32 v195, v151, s52, -v195
	v_fmac_f32_e32 v195, 0x3377d1cf, v151
	v_fmac_f32_e32 v195, 0x3f317217, v151
	v_cmp_lt_f32_e64 s[42:43], |v151|, s53
	s_nop 1
	v_cndmask_b32_e64 v151, v151, v195, s[42:43]
	v_cndmask_b32_e64 v195, 0, v216, s[40:41]
	v_sub_f32_e32 v151, v151, v195
	v_cndmask_b32_e64 v151, v194, v151, s[22:23]
	global_store_dwordx4 v[170:171], v[144:147], off
	global_store_dwordx4 v[170:171], v[148:151], off offset:16
	s_nop 1
	v_pk_mul_f32 v[148:149], v[84:85], v[168:169] op_sel_hi:[1,0]
	v_pk_mul_f32 v[150:151], v[86:87], v[168:169] op_sel_hi:[1,0]
	v_pk_mul_f32 v[146:147], v[82:83], v[168:169] op_sel_hi:[1,0]
	v_pk_mul_f32 v[144:145], v[80:81], v[168:169] op_sel_hi:[1,0]
	v_min_f32_e32 v168, 0, v148
	v_mul_f32_e64 v148, |v148|, s57
	v_exp_f32_e32 v148, v148
	s_nop 0
	v_add_f32_e32 v148, 1.0, v148
	v_cmp_gt_f32_e64 s[40:41], s97, v148
	s_nop 1
	v_cndmask_b32_e64 v194, 0, 32, s[40:41]
	v_ldexp_f32 v148, v148, v194
	v_log_f32_e32 v148, v148
	s_nop 0
	v_mul_f32_e32 v194, 0x3f317217, v148
	v_fma_f32 v194, v148, s52, -v194
	v_fmac_f32_e32 v194, 0x3377d1cf, v148
; __device__ __forceinline__ float silu_f(float x) { return x * __builtin_amdgcn_rcpf(1.f + __expf(-x)); }
; __device__ __forceinline__ v4u pack8(const f32x4 a, const f32x4 b) { v4u w; w.x = cvt_pk_bf16(a[0], a[1]); w.y = cvt_pk_bf16(a[2], a[3]); w.z = cvt_pk_bf16(b[0], b[1]); w.w = cvt_pk_bf16(b[2], b[3]); return w; }
;     __device__ __forceinline__ void operator()(const f32x4 (&acc)[2][2][4][2], const pg8::Unit& u, int wr, int wc, int fr, int fq) const {
;     ...
;         if (grp == 0) { WIN_LOOP( _Pragma("unroll") for (int i = 0; i < 4; ++i) { a[i] = silu_f(a[i]); b[i] = silu_f(b[i]); } *(v4u*)(QO + (size_t)row * DM + c) = pack8(a, b); ) }
;         else if (grp == 3) { WIN_LOOP( _Pragma("unroll") for (int i = 0; i < 4; ++i) { a[i] = silu_f(a[i]); b[i] = silu_f(b[i]); } *(v4u*)(GH + (size_t)row * 512 + c) = pack8(a, b); ) }
;         else if (grp == 1) {
;             f32x4 l0[2], l1[2];
; #pragma unroll
;             for (int bj = 0; bj < 2; ++bj) { l0[bj] = *(const f32x4*)(lb + cb + bj * 128); l1[bj] = *(const f32x4*)(lb + cb + bj * 128 + 4); }
;             WIN_LOOP( _Pragma("unroll") for (int i = 0; i < 4; ++i) { const float s0 = fminf(a[i], 0.f) - __logf(1.f + __expf(-fabsf(a[i]))), s1 = fminf(b[i], 0.f) - __logf(1.f + __expf(-fabsf(b[i]))); const float la = l0[bj][i], lbv = l1[bj][i];
;                     a[i] = la > 0.f ? __logf(la + (1.f - la) * __expf(s0)) : s0; b[i] = lbv > 0.f ? __logf(lbv + (1.f - lbv) * __expf(s1)) : s1; }
;                 *(f32x4*)(LF + (size_t)row * 512 + c) = a; *(f32x4*)(LF + (size_t)row * 512 + c + 4) = b; __builtin_amdgcn_sched_barrier(0); ) }
	v_fmac_f32_e32 v194, 0x3f317217, v148
	v_cmp_lt_f32_e64 s[42:43], |v148|, s53
	s_nop 1
	v_cndmask_b32_e64 v148, v148, v194, s[42:43]
	v_cndmask_b32_e64 v194, 0, v216, s[40:41]
	v_sub_f32_e32 v148, v148, v194
	v_sub_f32_e32 v148, v168, v148
	v_min_f32_e32 v168, 0, v144
	v_mul_f32_e64 v144, |v144|, s57
	v_exp_f32_e32 v144, v144
	s_nop 0
	v_add_f32_e32 v144, 1.0, v144
	v_cmp_gt_f32_e64 s[40:41], s97, v144
	s_nop 1
	v_cndmask_b32_e64 v194, 0, 32, s[40:41]
	v_ldexp_f32 v144, v144, v194
	v_log_f32_e32 v144, v144
	s_nop 0
	v_mul_f32_e32 v194, 0x3f317217, v144
	v_fma_f32 v194, v144, s52, -v194
	v_fmac_f32_e32 v194, 0x3377d1cf, v144
	v_fmac_f32_e32 v194, 0x3f317217, v144
	v_cmp_lt_f32_e64 s[42:43], |v144|, s53
	s_nop 1
	v_cndmask_b32_e64 v144, v144, v194, s[42:43]
	v_cndmask_b32_e64 v194, 0, v216, s[40:41]
	v_sub_f32_e32 v144, v144, v194
	v_sub_f32_e32 v168, v168, v144
	v_mul_f32_e32 v144, 0x3fb8aa3b, v148
	v_exp_f32_e32 v144, v144
	s_nop 0
	v_fma_f32 v144, v183, v144, v132
	v_cmp_gt_f32_e64 s[40:41], s97, v144
	s_nop 1
	v_cndmask_b32_e64 v194, 0, 32, s[40:41]
	v_ldexp_f32 v144, v144, v194
	v_log_f32_e32 v144, v144
	s_nop 0
	v_mul_f32_e32 v194, 0x3f317217, v144
	v_fma_f32 v194, v144, s52, -v194
	v_fmac_f32_e32 v194, 0x3377d1cf, v144
	v_fmac_f32_e32 v194, 0x3f317217, v144
	v_cmp_lt_f32_e64 s[42:43], |v144|, s53
	s_nop 1
	v_cndmask_b32_e64 v144, v144, v194, s[42:43]
	v_cndmask_b32_e64 v194, 0, v216, s[40:41]
	v_sub_f32_e32 v144, v144, v194
	v_cndmask_b32_e64 v144, v148, v144, s[20:21]
	v_mul_f32_e32 v148, 0x3fb8aa3b, v168
	v_exp_f32_e32 v148, v148
	s_nop 0
	v_fma_f32 v148, v182, v148, v128
	v_cmp_gt_f32_e64 s[40:41], s97, v148
	s_nop 1
	v_cndmask_b32_e64 v194, 0, 32, s[40:41]
	v_ldexp_f32 v148, v148, v194
	v_log_f32_e32 v148, v148
	s_nop 0
	v_mul_f32_e32 v194, 0x3f317217, v148
	v_fma_f32 v194, v148, s52, -v194
	v_fmac_f32_e32 v194, 0x3377d1cf, v148
	v_fmac_f32_e32 v194, 0x3f317217, v148
	v_cmp_lt_f32_e64 s[42:43], |v148|, s53
	s_nop 1
	v_cndmask_b32_e64 v148, v148, v194, s[42:43]
	v_cndmask_b32_e64 v194, 0, v216, s[40:41]
	v_sub_f32_e32 v148, v148, v194
	v_cndmask_b32_e64 v148, v168, v148, s[18:19]
	v_min_f32_e32 v168, 0, v149
	v_mul_f32_e64 v149, |v149|, s57
	v_exp_f32_e32 v149, v149
	s_nop 0
	v_add_f32_e32 v149, 1.0, v149
	v_cmp_gt_f32_e64 s[40:41], s97, v149
	s_nop 1
	v_cndmask_b32_e64 v194, 0, 32, s[40:41]
	v_ldexp_f32 v149, v149, v194
	v_log_f32_e32 v149, v149
	s_nop 0
	v_mul_f32_e32 v194, 0x3f317217, v149
	v_fma_f32 v194, v149, s52, -v194
	v_fmac_f32_e32 v194, 0x3377d1cf, v149
	v_fmac_f32_e32 v194, 0x3f317217, v149
	v_cmp_lt_f32_e64 s[42:43], |v149|, s53
	s_nop 1
	v_cndmask_b32_e64 v149, v149, v194, s[42:43]
	v_cndmask_b32_e64 v194, 0, v216, s[40:41]
	v_sub_f32_e32 v149, v149, v194
	v_sub_f32_e32 v149, v168, v149
	v_min_f32_e32 v168, 0, v145
	v_mul_f32_e64 v145, |v145|, s57
	v_exp_f32_e32 v145, v145
	s_nop 0
	v_add_f32_e32 v145, 1.0, v145
	v_cmp_gt_f32_e64 s[40:41], s97, v145
	s_nop 1
	v_cndmask_b32_e64 v194, 0, 32, s[40:41]
	v_ldexp_f32 v145, v145, v194
	v_log_f32_e32 v145, v145
	s_nop 0
	v_mul_f32_e32 v194, 0x3f317217, v145
	v_fma_f32 v194, v145, s52, -v194
	v_fmac_f32_e32 v194, 0x3377d1cf, v145
	v_fmac_f32_e32 v194, 0x3f317217, v145
	v_cmp_lt_f32_e64 s[42:43], |v145|, s53
	s_nop 1
	v_cndmask_b32_e64 v145, v145, v194, s[42:43]
	v_cndmask_b32_e64 v194, 0, v216, s[40:41]
	v_sub_f32_e32 v145, v145, v194
	v_sub_f32_e32 v168, v168, v145
	v_mul_f32_e32 v145, 0x3fb8aa3b, v149
	v_exp_f32_e32 v145, v145
	s_nop 0
	v_fma_f32 v145, v181, v145, v133
	v_cmp_gt_f32_e64 s[40:41], s97, v145
	s_nop 1
	v_cndmask_b32_e64 v194, 0, 32, s[40:41]
	v_ldexp_f32 v145, v145, v194
	v_log_f32_e32 v145, v145
	s_nop 0
	v_mul_f32_e32 v194, 0x3f317217, v145
	v_fma_f32 v194, v145, s52, -v194
	v_fmac_f32_e32 v194, 0x3377d1cf, v145
	v_fmac_f32_e32 v194, 0x3f317217, v145
	v_cmp_lt_f32_e64 s[42:43], |v145|, s53
	s_nop 1
	v_cndmask_b32_e64 v145, v145, v194, s[42:43]
	v_cndmask_b32_e64 v194, 0, v216, s[40:41]
	v_sub_f32_e32 v145, v145, v194
	v_cndmask_b32_e64 v145, v149, v145, s[16:17]
	v_mul_f32_e32 v149, 0x3fb8aa3b, v168
	v_exp_f32_e32 v149, v149
	s_nop 0
	v_fma_f32 v149, v180, v149, v129
	v_cmp_gt_f32_e64 s[40:41], s97, v149
	s_nop 1
	v_cndmask_b32_e64 v194, 0, 32, s[40:41]
	v_ldexp_f32 v149, v149, v194
	v_log_f32_e32 v149, v149
	s_nop 0
	v_mul_f32_e32 v194, 0x3f317217, v149
	v_fma_f32 v194, v149, s52, -v194
	v_fmac_f32_e32 v194, 0x3377d1cf, v149
	v_fmac_f32_e32 v194, 0x3f317217, v149
	v_cmp_lt_f32_e64 s[42:43], |v149|, s53
	s_nop 1
	v_cndmask_b32_e64 v149, v149, v194, s[42:43]
	v_cndmask_b32_e64 v194, 0, v216, s[40:41]
	v_sub_f32_e32 v149, v149, v194
	v_cndmask_b32_e64 v149, v168, v149, s[14:15]
	v_min_f32_e32 v168, 0, v150
	v_mul_f32_e64 v150, |v150|, s57
	v_exp_f32_e32 v150, v150
	s_nop 0
	v_add_f32_e32 v150, 1.0, v150
	v_cmp_gt_f32_e64 s[40:41], s97, v150
	s_nop 1
	v_cndmask_b32_e64 v194, 0, 32, s[40:41]
	v_ldexp_f32 v150, v150, v194
	v_log_f32_e32 v150, v150
	s_nop 0
	v_mul_f32_e32 v194, 0x3f317217, v150
	v_fma_f32 v194, v150, s52, -v194
	v_fmac_f32_e32 v194, 0x3377d1cf, v150
	v_fmac_f32_e32 v194, 0x3f317217, v150
	v_cmp_lt_f32_e64 s[42:43], |v150|, s53
	s_nop 1
	v_cndmask_b32_e64 v150, v150, v194, s[42:43]
	v_cndmask_b32_e64 v194, 0, v216, s[40:41]
	v_sub_f32_e32 v150, v150, v194
	v_sub_f32_e32 v150, v168, v150
	v_min_f32_e32 v168, 0, v146
	v_mul_f32_e64 v146, |v146|, s57
	v_exp_f32_e32 v146, v146
	s_nop 0
	v_add_f32_e32 v146, 1.0, v146
	v_cmp_gt_f32_e64 s[40:41], s97, v146
	s_nop 1
	v_cndmask_b32_e64 v194, 0, 32, s[40:41]
	v_ldexp_f32 v146, v146, v194
	v_log_f32_e32 v146, v146
	s_nop 0
	v_mul_f32_e32 v194, 0x3f317217, v146
	v_fma_f32 v194, v146, s52, -v194
; __device__ __forceinline__ float silu_f(float x) { return x * __builtin_amdgcn_rcpf(1.f + __expf(-x)); }
; __device__ __forceinline__ v4u pack8(const f32x4 a, const f32x4 b) { v4u w; w.x = cvt_pk_bf16(a[0], a[1]); w.y = cvt_pk_bf16(a[2], a[3]); w.z = cvt_pk_bf16(b[0], b[1]); w.w = cvt_pk_bf16(b[2], b[3]); return w; }
;     __device__ __forceinline__ void operator()(const f32x4 (&acc)[2][2][4][2], const pg8::Unit& u, int wr, int wc, int fr, int fq) const {
;     ...
;         if (grp == 0) { WIN_LOOP( _Pragma("unroll") for (int i = 0; i < 4; ++i) { a[i] = silu_f(a[i]); b[i] = silu_f(b[i]); } *(v4u*)(QO + (size_t)row * DM + c) = pack8(a, b); ) }
;         else if (grp == 3) { WIN_LOOP( _Pragma("unroll") for (int i = 0; i < 4; ++i) { a[i] = silu_f(a[i]); b[i] = silu_f(b[i]); } *(v4u*)(GH + (size_t)row * 512 + c) = pack8(a, b); ) }
;         else if (grp == 1) {
;             f32x4 l0[2], l1[2];
; #pragma unroll
;             for (int bj = 0; bj < 2; ++bj) { l0[bj] = *(const f32x4*)(lb + cb + bj * 128); l1[bj] = *(const f32x4*)(lb + cb + bj * 128 + 4); }
;             WIN_LOOP( _Pragma("unroll") for (int i = 0; i < 4; ++i) { const float s0 = fminf(a[i], 0.f) - __logf(1.f + __expf(-fabsf(a[i]))), s1 = fminf(b[i], 0.f) - __logf(1.f + __expf(-fabsf(b[i]))); const float la = l0[bj][i], lbv = l1[bj][i];
;                     a[i] = la > 0.f ? __logf(la + (1.f - la) * __expf(s0)) : s0; b[i] = lbv > 0.f ? __logf(lbv + (1.f - lbv) * __expf(s1)) : s1; }
;                 *(f32x4*)(LF + (size_t)row * 512 + c) = a; *(f32x4*)(LF + (size_t)row * 512 + c + 4) = b; __builtin_amdgcn_sched_barrier(0); ) }
	v_fmac_f32_e32 v194, 0x3377d1cf, v146
	v_fmac_f32_e32 v194, 0x3f317217, v146
	v_cmp_lt_f32_e64 s[42:43], |v146|, s53
	s_nop 1
	v_cndmask_b32_e64 v146, v146, v194, s[42:43]
	v_cndmask_b32_e64 v194, 0, v216, s[40:41]
	v_sub_f32_e32 v146, v146, v194
	v_sub_f32_e32 v168, v168, v146
	v_mul_f32_e32 v146, 0x3fb8aa3b, v150
	v_exp_f32_e32 v146, v146
	s_nop 0
	v_fma_f32 v146, v179, v146, v134
	v_cmp_gt_f32_e64 s[40:41], s97, v146
	s_nop 1
	v_cndmask_b32_e64 v194, 0, 32, s[40:41]
	v_ldexp_f32 v146, v146, v194
	v_log_f32_e32 v146, v146
	s_nop 0
	v_mul_f32_e32 v194, 0x3f317217, v146
	v_fma_f32 v194, v146, s52, -v194
	v_fmac_f32_e32 v194, 0x3377d1cf, v146
	v_fmac_f32_e32 v194, 0x3f317217, v146
	v_cmp_lt_f32_e64 s[42:43], |v146|, s53
	s_nop 1
	v_cndmask_b32_e64 v146, v146, v194, s[42:43]
	v_cndmask_b32_e64 v194, 0, v216, s[40:41]
	v_sub_f32_e32 v146, v146, v194
	v_cndmask_b32_e64 v146, v150, v146, s[12:13]
	v_mul_f32_e32 v150, 0x3fb8aa3b, v168
	v_exp_f32_e32 v150, v150
	s_nop 0
	v_fma_f32 v150, v178, v150, v130
	v_cmp_gt_f32_e64 s[40:41], s97, v150
	s_nop 1
	v_cndmask_b32_e64 v194, 0, 32, s[40:41]
	v_ldexp_f32 v150, v150, v194
	v_log_f32_e32 v150, v150
	s_nop 0
	v_mul_f32_e32 v194, 0x3f317217, v150
	v_fma_f32 v194, v150, s52, -v194
	v_fmac_f32_e32 v194, 0x3377d1cf, v150
	v_fmac_f32_e32 v194, 0x3f317217, v150
	v_cmp_lt_f32_e64 s[42:43], |v150|, s53
	s_nop 1
	v_cndmask_b32_e64 v150, v150, v194, s[42:43]
	v_cndmask_b32_e64 v194, 0, v216, s[40:41]
	v_sub_f32_e32 v150, v150, v194
	v_cndmask_b32_e64 v150, v168, v150, s[10:11]
	v_min_f32_e32 v168, 0, v151
	v_mul_f32_e64 v151, |v151|, s57
	v_exp_f32_e32 v151, v151
	s_nop 0
	v_add_f32_e32 v151, 1.0, v151
	v_cmp_gt_f32_e64 s[40:41], s97, v151
	s_nop 1
	v_cndmask_b32_e64 v194, 0, 32, s[40:41]
	v_ldexp_f32 v151, v151, v194
	v_log_f32_e32 v151, v151
	s_nop 0
	v_mul_f32_e32 v194, 0x3f317217, v151
	v_fma_f32 v194, v151, s52, -v194
	v_fmac_f32_e32 v194, 0x3377d1cf, v151
	v_fmac_f32_e32 v194, 0x3f317217, v151
	v_cmp_lt_f32_e64 s[42:43], |v151|, s53
	s_nop 1
	v_cndmask_b32_e64 v151, v151, v194, s[42:43]
	v_cndmask_b32_e64 v194, 0, v216, s[40:41]
	v_sub_f32_e32 v151, v151, v194
	v_sub_f32_e32 v151, v168, v151
	v_min_f32_e32 v168, 0, v147
	v_mul_f32_e64 v147, |v147|, s57
	v_exp_f32_e32 v147, v147
	s_nop 0
	v_add_f32_e32 v147, 1.0, v147
	v_cmp_gt_f32_e64 s[40:41], s97, v147
	s_nop 1
	v_cndmask_b32_e64 v194, 0, 32, s[40:41]
	v_ldexp_f32 v147, v147, v194
	v_log_f32_e32 v147, v147
	s_nop 0
	v_mul_f32_e32 v194, 0x3f317217, v147
	v_fma_f32 v194, v147, s52, -v194
	v_fmac_f32_e32 v194, 0x3377d1cf, v147
	v_fmac_f32_e32 v194, 0x3f317217, v147
	v_cmp_lt_f32_e64 s[42:43], |v147|, s53
	s_nop 1
	v_cndmask_b32_e64 v147, v147, v194, s[42:43]
	v_cndmask_b32_e64 v194, 0, v216, s[40:41]
	v_sub_f32_e32 v147, v147, v194
	v_sub_f32_e32 v168, v168, v147
	v_mul_f32_e32 v147, 0x3fb8aa3b, v151
	v_exp_f32_e32 v147, v147
	s_nop 0
	v_fma_f32 v147, v177, v147, v135
	v_cmp_gt_f32_e64 s[40:41], s97, v147
	s_nop 1
	v_cndmask_b32_e64 v194, 0, 32, s[40:41]
	v_ldexp_f32 v147, v147, v194
	v_log_f32_e32 v147, v147
	s_nop 0
	v_mul_f32_e32 v194, 0x3f317217, v147
	v_fma_f32 v194, v147, s52, -v194
	v_fmac_f32_e32 v194, 0x3377d1cf, v147
	v_fmac_f32_e32 v194, 0x3f317217, v147
	v_cmp_lt_f32_e64 s[42:43], |v147|, s53
	s_nop 1
	v_cndmask_b32_e64 v147, v147, v194, s[42:43]
	v_cndmask_b32_e64 v194, 0, v216, s[40:41]
	v_sub_f32_e32 v147, v147, v194
	v_cndmask_b32_e64 v147, v151, v147, s[8:9]
	v_mul_f32_e32 v151, 0x3fb8aa3b, v168
	v_exp_f32_e32 v151, v151
	s_nop 0
	v_fma_f32 v151, v167, v151, v131
	v_cmp_gt_f32_e64 s[40:41], s97, v151
	s_nop 1
	v_cndmask_b32_e64 v194, 0, 32, s[40:41]
	v_ldexp_f32 v151, v151, v194
	v_log_f32_e32 v151, v151
	s_nop 0
	v_mul_f32_e32 v194, 0x3f317217, v151
	v_fma_f32 v194, v151, s52, -v194
	v_fmac_f32_e32 v194, 0x3377d1cf, v151
	v_fmac_f32_e32 v194, 0x3f317217, v151
	v_cmp_lt_f32_e64 s[42:43], |v151|, s53
	s_nop 1
	v_cndmask_b32_e64 v151, v151, v194, s[42:43]
	v_cndmask_b32_e64 v194, 0, v216, s[40:41]
	v_sub_f32_e32 v151, v151, v194
	v_cndmask_b32_e32 v151, v168, v151, vcc
	global_store_dwordx4 v[170:171], v[144:147], off offset:512
	global_store_dwordx4 v[170:171], v[148:151], off offset:528
	s_nop 1
	v_add_u32_e32 v148, 0xa0, v166
	v_ashrrev_i32_e32 v149, 31, v148
	v_lshlrev_b64 v[144:145], 6, v[148:149]
	v_lshl_add_u64 v[144:145], v[160:161], 0, v[144:145]
	s_nop 0
	s_waitcnt lgkmcnt(0)
	s_nop 3
	s_nop 0
	s_nop 1
	s_waitcnt lgkmcnt(0)
	s_nop 1
	s_waitcnt lgkmcnt(0)
; __device__ __forceinline__ float silu_f(float x) { return x * __builtin_amdgcn_rcpf(1.f + __expf(-x)); }
; __device__ __forceinline__ v4u pack8(const f32x4 a, const f32x4 b) { v4u w; w.x = cvt_pk_bf16(a[0], a[1]); w.y = cvt_pk_bf16(a[2], a[3]); w.z = cvt_pk_bf16(b[0], b[1]); w.w = cvt_pk_bf16(b[2], b[3]); return w; }
;     __device__ __forceinline__ void operator()(const f32x4 (&acc)[2][2][4][2], const pg8::Unit& u, int wr, int wc, int fr, int fq) const {
;     ...
;         if (grp == 0) { WIN_LOOP( _Pragma("unroll") for (int i = 0; i < 4; ++i) { a[i] = silu_f(a[i]); b[i] = silu_f(b[i]); } *(v4u*)(QO + (size_t)row * DM + c) = pack8(a, b); ) }
;         else if (grp == 3) { WIN_LOOP( _Pragma("unroll") for (int i = 0; i < 4; ++i) { a[i] = silu_f(a[i]); b[i] = silu_f(b[i]); } *(v4u*)(GH + (size_t)row * 512 + c) = pack8(a, b); ) }
;         else if (grp == 1) {
;             f32x4 l0[2], l1[2];
; #pragma unroll
;             for (int bj = 0; bj < 2; ++bj) { l0[bj] = *(const f32x4*)(lb + cb + bj * 128); l1[bj] = *(const f32x4*)(lb + cb + bj * 128 + 4); }
;             WIN_LOOP( _Pragma("unroll") for (int i = 0; i < 4; ++i) { const float s0 = fminf(a[i], 0.f) - __logf(1.f + __expf(-fabsf(a[i]))), s1 = fminf(b[i], 0.f) - __logf(1.f + __expf(-fabsf(b[i]))); const float la = l0[bj][i], lbv = l1[bj][i];
;                     a[i] = la > 0.f ? __logf(la + (1.f - la) * __expf(s0)) : s0; b[i] = lbv > 0.f ? __logf(lbv + (1.f - lbv) * __expf(s1)) : s1; }
;                 *(f32x4*)(LF + (size_t)row * 512 + c) = a; *(f32x4*)(LF + (size_t)row * 512 + c + 4) = b; __builtin_amdgcn_sched_barrier(0); ) }
	s_nop 1
	v_mov_b32_e32 v168, v241
	v_lshlrev_b64 v[144:145], 11, v[148:149]
	v_lshl_add_u64 v[170:171], s[50:51], 0, v[144:145]
	v_lshl_add_u64 v[170:171], v[170:171], 0, v[192:193]
	v_pk_mul_f32 v[148:149], v[12:13], v[168:169] op_sel_hi:[1,0]
	v_pk_mul_f32 v[144:145], v[8:9], v[168:169] op_sel_hi:[1,0]
	v_min_f32_e32 v194, 0, v148
	v_mul_f32_e64 v148, |v148|, s57
	v_exp_f32_e32 v148, v148
	v_pk_mul_f32 v[150:151], v[14:15], v[168:169] op_sel_hi:[1,0]
	v_pk_mul_f32 v[146:147], v[10:11], v[168:169] op_sel_hi:[1,0]
	v_add_f32_e32 v148, 1.0, v148
	v_cmp_gt_f32_e64 s[40:41], s97, v148
	s_nop 1
	v_cndmask_b32_e64 v195, 0, 32, s[40:41]
	v_ldexp_f32 v148, v148, v195
	v_log_f32_e32 v148, v148
	s_nop 0
	v_mul_f32_e32 v195, 0x3f317217, v148
	v_fma_f32 v195, v148, s52, -v195
	v_fmac_f32_e32 v195, 0x3377d1cf, v148
	v_fmac_f32_e32 v195, 0x3f317217, v148
	v_cmp_lt_f32_e64 s[42:43], |v148|, s53
	s_nop 1
	v_cndmask_b32_e64 v148, v148, v195, s[42:43]
	v_cndmask_b32_e64 v195, 0, v216, s[40:41]
	v_sub_f32_e32 v148, v148, v195
	v_sub_f32_e32 v148, v194, v148
	v_min_f32_e32 v194, 0, v144
	v_mul_f32_e64 v144, |v144|, s57
	v_exp_f32_e32 v144, v144
	s_nop 0
	v_add_f32_e32 v144, 1.0, v144
	v_cmp_gt_f32_e64 s[40:41], s97, v144
	s_nop 1
	v_cndmask_b32_e64 v195, 0, 32, s[40:41]
	v_ldexp_f32 v144, v144, v195
	v_log_f32_e32 v144, v144
	s_nop 0
	v_mul_f32_e32 v195, 0x3f317217, v144
	v_fma_f32 v195, v144, s52, -v195
	v_fmac_f32_e32 v195, 0x3377d1cf, v144
	v_fmac_f32_e32 v195, 0x3f317217, v144
	v_cmp_lt_f32_e64 s[42:43], |v144|, s53
	s_nop 1
	v_cndmask_b32_e64 v144, v144, v195, s[42:43]
	v_cndmask_b32_e64 v195, 0, v216, s[40:41]
	v_sub_f32_e32 v144, v144, v195
	v_sub_f32_e32 v194, v194, v144
	v_mul_f32_e32 v144, 0x3fb8aa3b, v148
	v_exp_f32_e32 v144, v144
	s_nop 0
	v_fma_f32 v144, v190, v144, v140
	v_cmp_gt_f32_e64 s[40:41], s97, v144
	s_nop 1
	v_cndmask_b32_e64 v195, 0, 32, s[40:41]
	v_ldexp_f32 v144, v144, v195
	v_log_f32_e32 v144, v144
	s_nop 0
	v_mul_f32_e32 v195, 0x3f317217, v144
	v_fma_f32 v195, v144, s52, -v195
	v_fmac_f32_e32 v195, 0x3377d1cf, v144
	v_fmac_f32_e32 v195, 0x3f317217, v144
	v_cmp_lt_f32_e64 s[42:43], |v144|, s53
	s_nop 1
	v_cndmask_b32_e64 v144, v144, v195, s[42:43]
	v_cndmask_b32_e64 v195, 0, v216, s[40:41]
	v_sub_f32_e32 v144, v144, v195
	v_cndmask_b32_e64 v144, v148, v144, s[38:39]
	v_mul_f32_e32 v148, 0x3fb8aa3b, v194
	v_exp_f32_e32 v148, v148
	s_nop 0
	v_fma_f32 v148, v191, v148, v136
	v_cmp_gt_f32_e64 s[40:41], s97, v148
	s_nop 1
	v_cndmask_b32_e64 v195, 0, 32, s[40:41]
	v_ldexp_f32 v148, v148, v195
	v_log_f32_e32 v148, v148
	s_nop 0
	v_mul_f32_e32 v195, 0x3f317217, v148
	v_fma_f32 v195, v148, s52, -v195
	v_fmac_f32_e32 v195, 0x3377d1cf, v148
	v_fmac_f32_e32 v195, 0x3f317217, v148
	v_cmp_lt_f32_e64 s[42:43], |v148|, s53
	s_nop 1
	v_cndmask_b32_e64 v148, v148, v195, s[42:43]
	v_cndmask_b32_e64 v195, 0, v216, s[40:41]
	v_sub_f32_e32 v148, v148, v195
	v_cndmask_b32_e64 v148, v194, v148, s[36:37]
	v_min_f32_e32 v194, 0, v149
	v_mul_f32_e64 v149, |v149|, s57
	v_exp_f32_e32 v149, v149
	s_nop 0
	v_add_f32_e32 v149, 1.0, v149
	v_cmp_gt_f32_e64 s[40:41], s97, v149
	s_nop 1
	v_cndmask_b32_e64 v195, 0, 32, s[40:41]
	v_ldexp_f32 v149, v149, v195
	v_log_f32_e32 v149, v149
	s_nop 0
	v_mul_f32_e32 v195, 0x3f317217, v149
	v_fma_f32 v195, v149, s52, -v195
	v_fmac_f32_e32 v195, 0x3377d1cf, v149
	v_fmac_f32_e32 v195, 0x3f317217, v149
	v_cmp_lt_f32_e64 s[42:43], |v149|, s53
	s_nop 1
	v_cndmask_b32_e64 v149, v149, v195, s[42:43]
	v_cndmask_b32_e64 v195, 0, v216, s[40:41]
	v_sub_f32_e32 v149, v149, v195
	v_sub_f32_e32 v149, v194, v149
	v_min_f32_e32 v194, 0, v145
	v_mul_f32_e64 v145, |v145|, s57
	v_exp_f32_e32 v145, v145
	s_nop 0
	v_add_f32_e32 v145, 1.0, v145
	v_cmp_gt_f32_e64 s[40:41], s97, v145
	s_nop 1
	v_cndmask_b32_e64 v195, 0, 32, s[40:41]
	v_ldexp_f32 v145, v145, v195
	v_log_f32_e32 v145, v145
	s_nop 0
	v_mul_f32_e32 v195, 0x3f317217, v145
	v_fma_f32 v195, v145, s52, -v195
	v_fmac_f32_e32 v195, 0x3377d1cf, v145
	v_fmac_f32_e32 v195, 0x3f317217, v145
	v_cmp_lt_f32_e64 s[42:43], |v145|, s53
	s_nop 1
	v_cndmask_b32_e64 v145, v145, v195, s[42:43]
	v_cndmask_b32_e64 v195, 0, v216, s[40:41]
	v_sub_f32_e32 v145, v145, v195
	v_sub_f32_e32 v194, v194, v145
	v_mul_f32_e32 v145, 0x3fb8aa3b, v149
	v_exp_f32_e32 v145, v145
	s_nop 0
	v_fma_f32 v145, v188, v145, v141
	v_cmp_gt_f32_e64 s[40:41], s97, v145
	s_nop 1
	v_cndmask_b32_e64 v195, 0, 32, s[40:41]
	v_ldexp_f32 v145, v145, v195
	v_log_f32_e32 v145, v145
	s_nop 0
	v_mul_f32_e32 v195, 0x3f317217, v145
	v_fma_f32 v195, v145, s52, -v195
	v_fmac_f32_e32 v195, 0x3377d1cf, v145
	v_fmac_f32_e32 v195, 0x3f317217, v145
	v_cmp_lt_f32_e64 s[42:43], |v145|, s53
	s_nop 1
	v_cndmask_b32_e64 v145, v145, v195, s[42:43]
	v_cndmask_b32_e64 v195, 0, v216, s[40:41]
	v_sub_f32_e32 v145, v145, v195
	v_cndmask_b32_e64 v145, v149, v145, s[34:35]
	v_mul_f32_e32 v149, 0x3fb8aa3b, v194
	v_exp_f32_e32 v149, v149
	s_nop 0
	v_fma_f32 v149, v189, v149, v137
	v_cmp_gt_f32_e64 s[40:41], s97, v149
	s_nop 1
	v_cndmask_b32_e64 v195, 0, 32, s[40:41]
	v_ldexp_f32 v149, v149, v195
	v_log_f32_e32 v149, v149
	s_nop 0
	v_mul_f32_e32 v195, 0x3f317217, v149
	v_fma_f32 v195, v149, s52, -v195
	v_fmac_f32_e32 v195, 0x3377d1cf, v149
	v_fmac_f32_e32 v195, 0x3f317217, v149
	v_cmp_lt_f32_e64 s[42:43], |v149|, s53
	s_nop 1
	v_cndmask_b32_e64 v149, v149, v195, s[42:43]
	v_cndmask_b32_e64 v195, 0, v216, s[40:41]
	v_sub_f32_e32 v149, v149, v195
	v_cndmask_b32_e64 v149, v194, v149, s[30:31]
	v_min_f32_e32 v194, 0, v150
	v_mul_f32_e64 v150, |v150|, s57
	v_exp_f32_e32 v150, v150
	s_nop 0
	v_add_f32_e32 v150, 1.0, v150
	v_cmp_gt_f32_e64 s[40:41], s97, v150
	s_nop 1
; __device__ __forceinline__ float silu_f(float x) { return x * __builtin_amdgcn_rcpf(1.f + __expf(-x)); }
; __device__ __forceinline__ v4u pack8(const f32x4 a, const f32x4 b) { v4u w; w.x = cvt_pk_bf16(a[0], a[1]); w.y = cvt_pk_bf16(a[2], a[3]); w.z = cvt_pk_bf16(b[0], b[1]); w.w = cvt_pk_bf16(b[2], b[3]); return w; }
;     __device__ __forceinline__ void operator()(const f32x4 (&acc)[2][2][4][2], const pg8::Unit& u, int wr, int wc, int fr, int fq) const {
;     ...
;         if (grp == 0) { WIN_LOOP( _Pragma("unroll") for (int i = 0; i < 4; ++i) { a[i] = silu_f(a[i]); b[i] = silu_f(b[i]); } *(v4u*)(QO + (size_t)row * DM + c) = pack8(a, b); ) }
;         else if (grp == 3) { WIN_LOOP( _Pragma("unroll") for (int i = 0; i < 4; ++i) { a[i] = silu_f(a[i]); b[i] = silu_f(b[i]); } *(v4u*)(GH + (size_t)row * 512 + c) = pack8(a, b); ) }
;         else if (grp == 1) {
;             f32x4 l0[2], l1[2];
; #pragma unroll
;             for (int bj = 0; bj < 2; ++bj) { l0[bj] = *(const f32x4*)(lb + cb + bj * 128); l1[bj] = *(const f32x4*)(lb + cb + bj * 128 + 4); }
;             WIN_LOOP( _Pragma("unroll") for (int i = 0; i < 4; ++i) { const float s0 = fminf(a[i], 0.f) - __logf(1.f + __expf(-fabsf(a[i]))), s1 = fminf(b[i], 0.f) - __logf(1.f + __expf(-fabsf(b[i]))); const float la = l0[bj][i], lbv = l1[bj][i];
;                     a[i] = la > 0.f ? __logf(la + (1.f - la) * __expf(s0)) : s0; b[i] = lbv > 0.f ? __logf(lbv + (1.f - lbv) * __expf(s1)) : s1; }
;                 *(f32x4*)(LF + (size_t)row * 512 + c) = a; *(f32x4*)(LF + (size_t)row * 512 + c + 4) = b; __builtin_amdgcn_sched_barrier(0); ) }
	v_cndmask_b32_e64 v195, 0, 32, s[40:41]
	v_ldexp_f32 v150, v150, v195
	v_log_f32_e32 v150, v150
	s_nop 0
	v_mul_f32_e32 v195, 0x3f317217, v150
	v_fma_f32 v195, v150, s52, -v195
	v_fmac_f32_e32 v195, 0x3377d1cf, v150
	v_fmac_f32_e32 v195, 0x3f317217, v150
	v_cmp_lt_f32_e64 s[42:43], |v150|, s53
	s_nop 1
	v_cndmask_b32_e64 v150, v150, v195, s[42:43]
	v_cndmask_b32_e64 v195, 0, v216, s[40:41]
	v_sub_f32_e32 v150, v150, v195
	v_sub_f32_e32 v150, v194, v150
	v_min_f32_e32 v194, 0, v146
	v_mul_f32_e64 v146, |v146|, s57
	v_exp_f32_e32 v146, v146
	s_nop 0
	v_add_f32_e32 v146, 1.0, v146
	v_cmp_gt_f32_e64 s[40:41], s97, v146
	s_nop 1
	v_cndmask_b32_e64 v195, 0, 32, s[40:41]
	v_ldexp_f32 v146, v146, v195
	v_log_f32_e32 v146, v146
	s_nop 0
	v_mul_f32_e32 v195, 0x3f317217, v146
	v_fma_f32 v195, v146, s52, -v195
	v_fmac_f32_e32 v195, 0x3377d1cf, v146
	v_fmac_f32_e32 v195, 0x3f317217, v146
	v_cmp_lt_f32_e64 s[42:43], |v146|, s53
	s_nop 1
	v_cndmask_b32_e64 v146, v146, v195, s[42:43]
	v_cndmask_b32_e64 v195, 0, v216, s[40:41]
	v_sub_f32_e32 v146, v146, v195
	v_sub_f32_e32 v194, v194, v146
	v_mul_f32_e32 v146, 0x3fb8aa3b, v150
	v_exp_f32_e32 v146, v146
	s_nop 0
	v_fma_f32 v146, v187, v146, v142
	v_cmp_gt_f32_e64 s[40:41], s97, v146
	s_nop 1
	v_cndmask_b32_e64 v195, 0, 32, s[40:41]
	v_ldexp_f32 v146, v146, v195
	v_log_f32_e32 v146, v146
	s_nop 0
	v_mul_f32_e32 v195, 0x3f317217, v146
	v_fma_f32 v195, v146, s52, -v195
	v_fmac_f32_e32 v195, 0x3377d1cf, v146
	v_fmac_f32_e32 v195, 0x3f317217, v146
	v_cmp_lt_f32_e64 s[42:43], |v146|, s53
	s_nop 1
	v_cndmask_b32_e64 v146, v146, v195, s[42:43]
	v_cndmask_b32_e64 v195, 0, v216, s[40:41]
	v_sub_f32_e32 v146, v146, v195
	v_cndmask_b32_e64 v146, v150, v146, s[28:29]
	v_mul_f32_e32 v150, 0x3fb8aa3b, v194
	v_exp_f32_e32 v150, v150
	s_nop 0
	v_fma_f32 v150, v186, v150, v138
	v_cmp_gt_f32_e64 s[40:41], s97, v150
	s_nop 1
	v_cndmask_b32_e64 v195, 0, 32, s[40:41]
	v_ldexp_f32 v150, v150, v195
	v_log_f32_e32 v150, v150
	s_nop 0
	v_mul_f32_e32 v195, 0x3f317217, v150
	v_fma_f32 v195, v150, s52, -v195
	v_fmac_f32_e32 v195, 0x3377d1cf, v150
	v_fmac_f32_e32 v195, 0x3f317217, v150
	v_cmp_lt_f32_e64 s[42:43], |v150|, s53
	s_nop 1
	v_cndmask_b32_e64 v150, v150, v195, s[42:43]
	v_cndmask_b32_e64 v195, 0, v216, s[40:41]
	v_sub_f32_e32 v150, v150, v195
	v_cndmask_b32_e64 v150, v194, v150, s[26:27]
	v_min_f32_e32 v194, 0, v151
	v_mul_f32_e64 v151, |v151|, s57
	v_exp_f32_e32 v151, v151
	s_nop 0
	v_add_f32_e32 v151, 1.0, v151
	v_cmp_gt_f32_e64 s[40:41], s97, v151
	s_nop 1
	v_cndmask_b32_e64 v195, 0, 32, s[40:41]
	v_ldexp_f32 v151, v151, v195
	v_log_f32_e32 v151, v151
	s_nop 0
	v_mul_f32_e32 v195, 0x3f317217, v151
	v_fma_f32 v195, v151, s52, -v195
	v_fmac_f32_e32 v195, 0x3377d1cf, v151
	v_fmac_f32_e32 v195, 0x3f317217, v151
	v_cmp_lt_f32_e64 s[42:43], |v151|, s53
	s_nop 1
	v_cndmask_b32_e64 v151, v151, v195, s[42:43]
	v_cndmask_b32_e64 v195, 0, v216, s[40:41]
	v_sub_f32_e32 v151, v151, v195
	v_sub_f32_e32 v151, v194, v151
	v_min_f32_e32 v194, 0, v147
	v_mul_f32_e64 v147, |v147|, s57
	v_exp_f32_e32 v147, v147
	s_nop 0
	v_add_f32_e32 v147, 1.0, v147
	v_cmp_gt_f32_e64 s[40:41], s97, v147
	s_nop 1
	v_cndmask_b32_e64 v195, 0, 32, s[40:41]
	v_ldexp_f32 v147, v147, v195
	v_log_f32_e32 v147, v147
	s_nop 0
	v_mul_f32_e32 v195, 0x3f317217, v147
	v_fma_f32 v195, v147, s52, -v195
	v_fmac_f32_e32 v195, 0x3377d1cf, v147
	v_fmac_f32_e32 v195, 0x3f317217, v147
	v_cmp_lt_f32_e64 s[42:43], |v147|, s53
	s_nop 1
	v_cndmask_b32_e64 v147, v147, v195, s[42:43]
	v_cndmask_b32_e64 v195, 0, v216, s[40:41]
	v_sub_f32_e32 v147, v147, v195
	v_sub_f32_e32 v194, v194, v147
	v_mul_f32_e32 v147, 0x3fb8aa3b, v151
	v_exp_f32_e32 v147, v147
	s_nop 0
	v_fma_f32 v147, v185, v147, v143
	v_cmp_gt_f32_e64 s[40:41], s97, v147
	s_nop 1
	v_cndmask_b32_e64 v195, 0, 32, s[40:41]
	v_ldexp_f32 v147, v147, v195
	v_log_f32_e32 v147, v147
	s_nop 0
	v_mul_f32_e32 v195, 0x3f317217, v147
	v_fma_f32 v195, v147, s52, -v195
	v_fmac_f32_e32 v195, 0x3377d1cf, v147
	v_fmac_f32_e32 v195, 0x3f317217, v147
	v_cmp_lt_f32_e64 s[42:43], |v147|, s53
	s_nop 1
	v_cndmask_b32_e64 v147, v147, v195, s[42:43]
	v_cndmask_b32_e64 v195, 0, v216, s[40:41]
	v_sub_f32_e32 v147, v147, v195
	v_cndmask_b32_e64 v147, v151, v147, s[24:25]
	v_mul_f32_e32 v151, 0x3fb8aa3b, v194
	v_exp_f32_e32 v151, v151
	s_nop 0
	v_fma_f32 v151, v184, v151, v139
	v_cmp_gt_f32_e64 s[40:41], s97, v151
	s_nop 1
	v_cndmask_b32_e64 v195, 0, 32, s[40:41]
	v_ldexp_f32 v151, v151, v195
	v_log_f32_e32 v151, v151
	s_nop 0
	v_mul_f32_e32 v195, 0x3f317217, v151
	v_fma_f32 v195, v151, s52, -v195
	v_fmac_f32_e32 v195, 0x3377d1cf, v151
	v_fmac_f32_e32 v195, 0x3f317217, v151
	v_cmp_lt_f32_e64 s[42:43], |v151|, s53
	s_nop 1
	v_cndmask_b32_e64 v151, v151, v195, s[42:43]
	v_cndmask_b32_e64 v195, 0, v216, s[40:41]
	v_sub_f32_e32 v151, v151, v195
	v_cndmask_b32_e64 v151, v194, v151, s[22:23]
	global_store_dwordx4 v[170:171], v[144:147], off
	global_store_dwordx4 v[170:171], v[148:151], off offset:16
	s_nop 1
	v_pk_mul_f32 v[148:149], v[76:77], v[168:169] op_sel_hi:[1,0]
	v_pk_mul_f32 v[150:151], v[78:79], v[168:169] op_sel_hi:[1,0]
	v_pk_mul_f32 v[146:147], v[74:75], v[168:169] op_sel_hi:[1,0]
	v_pk_mul_f32 v[144:145], v[72:73], v[168:169] op_sel_hi:[1,0]
	v_min_f32_e32 v168, 0, v148
	v_mul_f32_e64 v148, |v148|, s57
	v_exp_f32_e32 v148, v148
	s_nop 0
	v_add_f32_e32 v148, 1.0, v148
	v_cmp_gt_f32_e64 s[40:41], s97, v148
	s_nop 1
	v_cndmask_b32_e64 v194, 0, 32, s[40:41]
	v_ldexp_f32 v148, v148, v194
	v_log_f32_e32 v148, v148
	s_nop 0
	v_mul_f32_e32 v194, 0x3f317217, v148
	v_fma_f32 v194, v148, s52, -v194
	v_fmac_f32_e32 v194, 0x3377d1cf, v148
; __device__ __forceinline__ float silu_f(float x) { return x * __builtin_amdgcn_rcpf(1.f + __expf(-x)); }
; __device__ __forceinline__ v4u pack8(const f32x4 a, const f32x4 b) { v4u w; w.x = cvt_pk_bf16(a[0], a[1]); w.y = cvt_pk_bf16(a[2], a[3]); w.z = cvt_pk_bf16(b[0], b[1]); w.w = cvt_pk_bf16(b[2], b[3]); return w; }
;     __device__ __forceinline__ void operator()(const f32x4 (&acc)[2][2][4][2], const pg8::Unit& u, int wr, int wc, int fr, int fq) const {
;     ...
;         if (grp == 0) { WIN_LOOP( _Pragma("unroll") for (int i = 0; i < 4; ++i) { a[i] = silu_f(a[i]); b[i] = silu_f(b[i]); } *(v4u*)(QO + (size_t)row * DM + c) = pack8(a, b); ) }
;         else if (grp == 3) { WIN_LOOP( _Pragma("unroll") for (int i = 0; i < 4; ++i) { a[i] = silu_f(a[i]); b[i] = silu_f(b[i]); } *(v4u*)(GH + (size_t)row * 512 + c) = pack8(a, b); ) }
;         else if (grp == 1) {
;             f32x4 l0[2], l1[2];
; #pragma unroll
;             for (int bj = 0; bj < 2; ++bj) { l0[bj] = *(const f32x4*)(lb + cb + bj * 128); l1[bj] = *(const f32x4*)(lb + cb + bj * 128 + 4); }
;             WIN_LOOP( _Pragma("unroll") for (int i = 0; i < 4; ++i) { const float s0 = fminf(a[i], 0.f) - __logf(1.f + __expf(-fabsf(a[i]))), s1 = fminf(b[i], 0.f) - __logf(1.f + __expf(-fabsf(b[i]))); const float la = l0[bj][i], lbv = l1[bj][i];
;                     a[i] = la > 0.f ? __logf(la + (1.f - la) * __expf(s0)) : s0; b[i] = lbv > 0.f ? __logf(lbv + (1.f - lbv) * __expf(s1)) : s1; }
;                 *(f32x4*)(LF + (size_t)row * 512 + c) = a; *(f32x4*)(LF + (size_t)row * 512 + c + 4) = b; __builtin_amdgcn_sched_barrier(0); ) }
	v_fmac_f32_e32 v194, 0x3f317217, v148
	v_cmp_lt_f32_e64 s[42:43], |v148|, s53
	s_nop 1
	v_cndmask_b32_e64 v148, v148, v194, s[42:43]
	v_cndmask_b32_e64 v194, 0, v216, s[40:41]
	v_sub_f32_e32 v148, v148, v194
	v_sub_f32_e32 v148, v168, v148
	v_min_f32_e32 v168, 0, v144
	v_mul_f32_e64 v144, |v144|, s57
	v_exp_f32_e32 v144, v144
	s_nop 0
	v_add_f32_e32 v144, 1.0, v144
	v_cmp_gt_f32_e64 s[40:41], s97, v144
	s_nop 1
	v_cndmask_b32_e64 v194, 0, 32, s[40:41]
	v_ldexp_f32 v144, v144, v194
	v_log_f32_e32 v144, v144
	s_nop 0
	v_mul_f32_e32 v194, 0x3f317217, v144
	v_fma_f32 v194, v144, s52, -v194
	v_fmac_f32_e32 v194, 0x3377d1cf, v144
	v_fmac_f32_e32 v194, 0x3f317217, v144
	v_cmp_lt_f32_e64 s[42:43], |v144|, s53
	s_nop 1
	v_cndmask_b32_e64 v144, v144, v194, s[42:43]
	v_cndmask_b32_e64 v194, 0, v216, s[40:41]
	v_sub_f32_e32 v144, v144, v194
	v_sub_f32_e32 v168, v168, v144
	v_mul_f32_e32 v144, 0x3fb8aa3b, v148
	v_exp_f32_e32 v144, v144
	s_nop 0
	v_fma_f32 v144, v183, v144, v132
	v_cmp_gt_f32_e64 s[40:41], s97, v144
	s_nop 1
	v_cndmask_b32_e64 v194, 0, 32, s[40:41]
	v_ldexp_f32 v144, v144, v194
	v_log_f32_e32 v144, v144
	s_nop 0
	v_mul_f32_e32 v194, 0x3f317217, v144
	v_fma_f32 v194, v144, s52, -v194
	v_fmac_f32_e32 v194, 0x3377d1cf, v144
	v_fmac_f32_e32 v194, 0x3f317217, v144
	v_cmp_lt_f32_e64 s[42:43], |v144|, s53
	s_nop 1
	v_cndmask_b32_e64 v144, v144, v194, s[42:43]
	v_cndmask_b32_e64 v194, 0, v216, s[40:41]
	v_sub_f32_e32 v144, v144, v194
	v_cndmask_b32_e64 v144, v148, v144, s[20:21]
	v_mul_f32_e32 v148, 0x3fb8aa3b, v168
	v_exp_f32_e32 v148, v148
	s_nop 0
	v_fma_f32 v148, v182, v148, v128
	v_cmp_gt_f32_e64 s[40:41], s97, v148
	s_nop 1
	v_cndmask_b32_e64 v194, 0, 32, s[40:41]
	v_ldexp_f32 v148, v148, v194
	v_log_f32_e32 v148, v148
	s_nop 0
	v_mul_f32_e32 v194, 0x3f317217, v148
	v_fma_f32 v194, v148, s52, -v194
	v_fmac_f32_e32 v194, 0x3377d1cf, v148
	v_fmac_f32_e32 v194, 0x3f317217, v148
	v_cmp_lt_f32_e64 s[42:43], |v148|, s53
	s_nop 1
	v_cndmask_b32_e64 v148, v148, v194, s[42:43]
	v_cndmask_b32_e64 v194, 0, v216, s[40:41]
	v_sub_f32_e32 v148, v148, v194
	v_cndmask_b32_e64 v148, v168, v148, s[18:19]
	v_min_f32_e32 v168, 0, v149
	v_mul_f32_e64 v149, |v149|, s57
	v_exp_f32_e32 v149, v149
	s_nop 0
	v_add_f32_e32 v149, 1.0, v149
	v_cmp_gt_f32_e64 s[40:41], s97, v149
	s_nop 1
	v_cndmask_b32_e64 v194, 0, 32, s[40:41]
	v_ldexp_f32 v149, v149, v194
	v_log_f32_e32 v149, v149
	s_nop 0
	v_mul_f32_e32 v194, 0x3f317217, v149
	v_fma_f32 v194, v149, s52, -v194
	v_fmac_f32_e32 v194, 0x3377d1cf, v149
	v_fmac_f32_e32 v194, 0x3f317217, v149
	v_cmp_lt_f32_e64 s[42:43], |v149|, s53
	s_nop 1
	v_cndmask_b32_e64 v149, v149, v194, s[42:43]
	v_cndmask_b32_e64 v194, 0, v216, s[40:41]
	v_sub_f32_e32 v149, v149, v194
	v_sub_f32_e32 v149, v168, v149
	v_min_f32_e32 v168, 0, v145
	v_mul_f32_e64 v145, |v145|, s57
	v_exp_f32_e32 v145, v145
	s_nop 0
	v_add_f32_e32 v145, 1.0, v145
	v_cmp_gt_f32_e64 s[40:41], s97, v145
	s_nop 1
	v_cndmask_b32_e64 v194, 0, 32, s[40:41]
	v_ldexp_f32 v145, v145, v194
	v_log_f32_e32 v145, v145
	s_nop 0
	v_mul_f32_e32 v194, 0x3f317217, v145
	v_fma_f32 v194, v145, s52, -v194
	v_fmac_f32_e32 v194, 0x3377d1cf, v145
	v_fmac_f32_e32 v194, 0x3f317217, v145
	v_cmp_lt_f32_e64 s[42:43], |v145|, s53
	s_nop 1
	v_cndmask_b32_e64 v145, v145, v194, s[42:43]
	v_cndmask_b32_e64 v194, 0, v216, s[40:41]
	v_sub_f32_e32 v145, v145, v194
	v_sub_f32_e32 v168, v168, v145
	v_mul_f32_e32 v145, 0x3fb8aa3b, v149
	v_exp_f32_e32 v145, v145
	s_nop 0
	v_fma_f32 v145, v181, v145, v133
	v_cmp_gt_f32_e64 s[40:41], s97, v145
	s_nop 1
	v_cndmask_b32_e64 v194, 0, 32, s[40:41]
	v_ldexp_f32 v145, v145, v194
	v_log_f32_e32 v145, v145
	s_nop 0
	v_mul_f32_e32 v194, 0x3f317217, v145
	v_fma_f32 v194, v145, s52, -v194
	v_fmac_f32_e32 v194, 0x3377d1cf, v145
	v_fmac_f32_e32 v194, 0x3f317217, v145
	v_cmp_lt_f32_e64 s[42:43], |v145|, s53
	s_nop 1
	v_cndmask_b32_e64 v145, v145, v194, s[42:43]
	v_cndmask_b32_e64 v194, 0, v216, s[40:41]
	v_sub_f32_e32 v145, v145, v194
	v_cndmask_b32_e64 v145, v149, v145, s[16:17]
	v_mul_f32_e32 v149, 0x3fb8aa3b, v168
	v_exp_f32_e32 v149, v149
	s_nop 0
	v_fma_f32 v149, v180, v149, v129
	v_cmp_gt_f32_e64 s[40:41], s97, v149
	s_nop 1
	v_cndmask_b32_e64 v194, 0, 32, s[40:41]
	v_ldexp_f32 v149, v149, v194
	v_log_f32_e32 v149, v149
	s_nop 0
	v_mul_f32_e32 v194, 0x3f317217, v149
	v_fma_f32 v194, v149, s52, -v194
	v_fmac_f32_e32 v194, 0x3377d1cf, v149
	v_fmac_f32_e32 v194, 0x3f317217, v149
	v_cmp_lt_f32_e64 s[42:43], |v149|, s53
	s_nop 1
	v_cndmask_b32_e64 v149, v149, v194, s[42:43]
	v_cndmask_b32_e64 v194, 0, v216, s[40:41]
	v_sub_f32_e32 v149, v149, v194
	v_cndmask_b32_e64 v149, v168, v149, s[14:15]
	v_min_f32_e32 v168, 0, v150
	v_mul_f32_e64 v150, |v150|, s57
	v_exp_f32_e32 v150, v150
	s_nop 0
	v_add_f32_e32 v150, 1.0, v150
	v_cmp_gt_f32_e64 s[40:41], s97, v150
	s_nop 1
	v_cndmask_b32_e64 v194, 0, 32, s[40:41]
	v_ldexp_f32 v150, v150, v194
	v_log_f32_e32 v150, v150
	s_nop 0
	v_mul_f32_e32 v194, 0x3f317217, v150
	v_fma_f32 v194, v150, s52, -v194
	v_fmac_f32_e32 v194, 0x3377d1cf, v150
	v_fmac_f32_e32 v194, 0x3f317217, v150
	v_cmp_lt_f32_e64 s[42:43], |v150|, s53
	s_nop 1
	v_cndmask_b32_e64 v150, v150, v194, s[42:43]
	v_cndmask_b32_e64 v194, 0, v216, s[40:41]
	v_sub_f32_e32 v150, v150, v194
	v_sub_f32_e32 v150, v168, v150
	v_min_f32_e32 v168, 0, v146
	v_mul_f32_e64 v146, |v146|, s57
	v_exp_f32_e32 v146, v146
	s_nop 0
	v_add_f32_e32 v146, 1.0, v146
	v_cmp_gt_f32_e64 s[40:41], s97, v146
	s_nop 1
	v_cndmask_b32_e64 v194, 0, 32, s[40:41]
	v_ldexp_f32 v146, v146, v194
	v_log_f32_e32 v146, v146
	s_nop 0
	v_mul_f32_e32 v194, 0x3f317217, v146
	v_fma_f32 v194, v146, s52, -v194
; __device__ __forceinline__ float silu_f(float x) { return x * __builtin_amdgcn_rcpf(1.f + __expf(-x)); }
; __device__ __forceinline__ v4u pack8(const f32x4 a, const f32x4 b) { v4u w; w.x = cvt_pk_bf16(a[0], a[1]); w.y = cvt_pk_bf16(a[2], a[3]); w.z = cvt_pk_bf16(b[0], b[1]); w.w = cvt_pk_bf16(b[2], b[3]); return w; }
;     __device__ __forceinline__ void operator()(const f32x4 (&acc)[2][2][4][2], const pg8::Unit& u, int wr, int wc, int fr, int fq) const {
;     ...
;         if (grp == 0) { WIN_LOOP( _Pragma("unroll") for (int i = 0; i < 4; ++i) { a[i] = silu_f(a[i]); b[i] = silu_f(b[i]); } *(v4u*)(QO + (size_t)row * DM + c) = pack8(a, b); ) }
;         else if (grp == 3) { WIN_LOOP( _Pragma("unroll") for (int i = 0; i < 4; ++i) { a[i] = silu_f(a[i]); b[i] = silu_f(b[i]); } *(v4u*)(GH + (size_t)row * 512 + c) = pack8(a, b); ) }
;         else if (grp == 1) {
;             f32x4 l0[2], l1[2];
; #pragma unroll
;             for (int bj = 0; bj < 2; ++bj) { l0[bj] = *(const f32x4*)(lb + cb + bj * 128); l1[bj] = *(const f32x4*)(lb + cb + bj * 128 + 4); }
;             WIN_LOOP( _Pragma("unroll") for (int i = 0; i < 4; ++i) { const float s0 = fminf(a[i], 0.f) - __logf(1.f + __expf(-fabsf(a[i]))), s1 = fminf(b[i], 0.f) - __logf(1.f + __expf(-fabsf(b[i]))); const float la = l0[bj][i], lbv = l1[bj][i];
;                     a[i] = la > 0.f ? __logf(la + (1.f - la) * __expf(s0)) : s0; b[i] = lbv > 0.f ? __logf(lbv + (1.f - lbv) * __expf(s1)) : s1; }
;                 *(f32x4*)(LF + (size_t)row * 512 + c) = a; *(f32x4*)(LF + (size_t)row * 512 + c + 4) = b; __builtin_amdgcn_sched_barrier(0); ) }
	v_fmac_f32_e32 v194, 0x3377d1cf, v146
	v_fmac_f32_e32 v194, 0x3f317217, v146
	v_cmp_lt_f32_e64 s[42:43], |v146|, s53
	s_nop 1
	v_cndmask_b32_e64 v146, v146, v194, s[42:43]
	v_cndmask_b32_e64 v194, 0, v216, s[40:41]
	v_sub_f32_e32 v146, v146, v194
	v_sub_f32_e32 v168, v168, v146
	v_mul_f32_e32 v146, 0x3fb8aa3b, v150
	v_exp_f32_e32 v146, v146
	s_nop 0
	v_fma_f32 v146, v179, v146, v134
	v_cmp_gt_f32_e64 s[40:41], s97, v146
	s_nop 1
	v_cndmask_b32_e64 v194, 0, 32, s[40:41]
	v_ldexp_f32 v146, v146, v194
	v_log_f32_e32 v146, v146
	s_nop 0
	v_mul_f32_e32 v194, 0x3f317217, v146
	v_fma_f32 v194, v146, s52, -v194
	v_fmac_f32_e32 v194, 0x3377d1cf, v146
	v_fmac_f32_e32 v194, 0x3f317217, v146
	v_cmp_lt_f32_e64 s[42:43], |v146|, s53
	s_nop 1
	v_cndmask_b32_e64 v146, v146, v194, s[42:43]
	v_cndmask_b32_e64 v194, 0, v216, s[40:41]
	v_sub_f32_e32 v146, v146, v194
	v_cndmask_b32_e64 v146, v150, v146, s[12:13]
	v_mul_f32_e32 v150, 0x3fb8aa3b, v168
	v_exp_f32_e32 v150, v150
	s_nop 0
	v_fma_f32 v150, v178, v150, v130
	v_cmp_gt_f32_e64 s[40:41], s97, v150
	s_nop 1
	v_cndmask_b32_e64 v194, 0, 32, s[40:41]
	v_ldexp_f32 v150, v150, v194
	v_log_f32_e32 v150, v150
	s_nop 0
	v_mul_f32_e32 v194, 0x3f317217, v150
	v_fma_f32 v194, v150, s52, -v194
	v_fmac_f32_e32 v194, 0x3377d1cf, v150
	v_fmac_f32_e32 v194, 0x3f317217, v150
	v_cmp_lt_f32_e64 s[42:43], |v150|, s53
	s_nop 1
	v_cndmask_b32_e64 v150, v150, v194, s[42:43]
	v_cndmask_b32_e64 v194, 0, v216, s[40:41]
	v_sub_f32_e32 v150, v150, v194
	v_cndmask_b32_e64 v150, v168, v150, s[10:11]
	v_min_f32_e32 v168, 0, v151
	v_mul_f32_e64 v151, |v151|, s57
	v_exp_f32_e32 v151, v151
	s_nop 0
	v_add_f32_e32 v151, 1.0, v151
	v_cmp_gt_f32_e64 s[40:41], s97, v151
	s_nop 1
	v_cndmask_b32_e64 v194, 0, 32, s[40:41]
	v_ldexp_f32 v151, v151, v194
	v_log_f32_e32 v151, v151
	s_nop 0
	v_mul_f32_e32 v194, 0x3f317217, v151
	v_fma_f32 v194, v151, s52, -v194
	v_fmac_f32_e32 v194, 0x3377d1cf, v151
	v_fmac_f32_e32 v194, 0x3f317217, v151
	v_cmp_lt_f32_e64 s[42:43], |v151|, s53
	s_nop 1
	v_cndmask_b32_e64 v151, v151, v194, s[42:43]
	v_cndmask_b32_e64 v194, 0, v216, s[40:41]
	v_sub_f32_e32 v151, v151, v194
	v_sub_f32_e32 v151, v168, v151
	v_min_f32_e32 v168, 0, v147
	v_mul_f32_e64 v147, |v147|, s57
	v_exp_f32_e32 v147, v147
	s_nop 0
	v_add_f32_e32 v147, 1.0, v147
	v_cmp_gt_f32_e64 s[40:41], s97, v147
	s_nop 1
	v_cndmask_b32_e64 v194, 0, 32, s[40:41]
	v_ldexp_f32 v147, v147, v194
	v_log_f32_e32 v147, v147
	s_nop 0
	v_mul_f32_e32 v194, 0x3f317217, v147
	v_fma_f32 v194, v147, s52, -v194
	v_fmac_f32_e32 v194, 0x3377d1cf, v147
	v_fmac_f32_e32 v194, 0x3f317217, v147
	v_cmp_lt_f32_e64 s[42:43], |v147|, s53
	s_nop 1
	v_cndmask_b32_e64 v147, v147, v194, s[42:43]
	v_cndmask_b32_e64 v194, 0, v216, s[40:41]
	v_sub_f32_e32 v147, v147, v194
	v_sub_f32_e32 v168, v168, v147
	v_mul_f32_e32 v147, 0x3fb8aa3b, v151
	v_exp_f32_e32 v147, v147
	s_nop 0
	v_fma_f32 v147, v177, v147, v135
	v_cmp_gt_f32_e64 s[40:41], s97, v147
	s_nop 1
	v_cndmask_b32_e64 v194, 0, 32, s[40:41]
	v_ldexp_f32 v147, v147, v194
	v_log_f32_e32 v147, v147
	s_nop 0
	v_mul_f32_e32 v194, 0x3f317217, v147
	v_fma_f32 v194, v147, s52, -v194
	v_fmac_f32_e32 v194, 0x3377d1cf, v147
	v_fmac_f32_e32 v194, 0x3f317217, v147
	v_cmp_lt_f32_e64 s[42:43], |v147|, s53
	s_nop 1
	v_cndmask_b32_e64 v147, v147, v194, s[42:43]
	v_cndmask_b32_e64 v194, 0, v216, s[40:41]
	v_sub_f32_e32 v147, v147, v194
	v_cndmask_b32_e64 v147, v151, v147, s[8:9]
	v_mul_f32_e32 v151, 0x3fb8aa3b, v168
	v_exp_f32_e32 v151, v151
	s_nop 0
	v_fma_f32 v151, v167, v151, v131
	v_cmp_gt_f32_e64 s[40:41], s97, v151
	s_nop 1
	v_cndmask_b32_e64 v194, 0, 32, s[40:41]
	v_ldexp_f32 v151, v151, v194
	v_log_f32_e32 v151, v151
	s_nop 0
	v_mul_f32_e32 v194, 0x3f317217, v151
	v_fma_f32 v194, v151, s52, -v194
	v_fmac_f32_e32 v194, 0x3377d1cf, v151
	v_fmac_f32_e32 v194, 0x3f317217, v151
	v_cmp_lt_f32_e64 s[42:43], |v151|, s53
	s_nop 1
	v_cndmask_b32_e64 v151, v151, v194, s[42:43]
	v_cndmask_b32_e64 v194, 0, v216, s[40:41]
	v_sub_f32_e32 v151, v151, v194
	v_cndmask_b32_e32 v151, v168, v151, vcc
	global_store_dwordx4 v[170:171], v[144:147], off offset:512
	global_store_dwordx4 v[170:171], v[148:151], off offset:528
	s_nop 1
	v_add_u32_e32 v148, 0xb0, v166
	v_ashrrev_i32_e32 v149, 31, v148
	v_lshlrev_b64 v[144:145], 6, v[148:149]
	v_lshl_add_u64 v[144:145], v[160:161], 0, v[144:145]
	s_nop 0
	s_waitcnt lgkmcnt(0)
	s_nop 3
	v_lshlrev_b64 v[146:147], 11, v[148:149]
	s_nop 1
	v_lshl_add_u64 v[146:147], s[50:51], 0, v[146:147]
	v_lshl_add_u64 v[146:147], v[146:147], 0, v[192:193]
	s_waitcnt lgkmcnt(0)
	s_nop 1
	s_waitcnt lgkmcnt(0)
; __device__ __forceinline__ float silu_f(float x) { return x * __builtin_amdgcn_rcpf(1.f + __expf(-x)); }
; __device__ __forceinline__ v4u pack8(const f32x4 a, const f32x4 b) { v4u w; w.x = cvt_pk_bf16(a[0], a[1]); w.y = cvt_pk_bf16(a[2], a[3]); w.z = cvt_pk_bf16(b[0], b[1]); w.w = cvt_pk_bf16(b[2], b[3]); return w; }
;     __device__ __forceinline__ void operator()(const f32x4 (&acc)[2][2][4][2], const pg8::Unit& u, int wr, int wc, int fr, int fq) const {
;     ...
;         if (grp == 0) { WIN_LOOP( _Pragma("unroll") for (int i = 0; i < 4; ++i) { a[i] = silu_f(a[i]); b[i] = silu_f(b[i]); } *(v4u*)(QO + (size_t)row * DM + c) = pack8(a, b); ) }
;         else if (grp == 3) { WIN_LOOP( _Pragma("unroll") for (int i = 0; i < 4; ++i) { a[i] = silu_f(a[i]); b[i] = silu_f(b[i]); } *(v4u*)(GH + (size_t)row * 512 + c) = pack8(a, b); ) }
;         else if (grp == 1) {
;             f32x4 l0[2], l1[2];
; #pragma unroll
;             for (int bj = 0; bj < 2; ++bj) { l0[bj] = *(const f32x4*)(lb + cb + bj * 128); l1[bj] = *(const f32x4*)(lb + cb + bj * 128 + 4); }
;             WIN_LOOP( _Pragma("unroll") for (int i = 0; i < 4; ++i) { const float s0 = fminf(a[i], 0.f) - __logf(1.f + __expf(-fabsf(a[i]))), s1 = fminf(b[i], 0.f) - __logf(1.f + __expf(-fabsf(b[i]))); const float la = l0[bj][i], lbv = l1[bj][i];
;                     a[i] = la > 0.f ? __logf(la + (1.f - la) * __expf(s0)) : s0; b[i] = lbv > 0.f ? __logf(lbv + (1.f - lbv) * __expf(s1)) : s1; }
;                 *(f32x4*)(LF + (size_t)row * 512 + c) = a; *(f32x4*)(LF + (size_t)row * 512 + c + 4) = b; __builtin_amdgcn_sched_barrier(0); ) }
	s_nop 1
	v_mov_b32_e32 v144, v245
	s_nop 0
	v_pk_mul_f32 v[170:171], v[4:5], v[144:145] op_sel_hi:[1,0]
	v_pk_mul_f32 v[150:151], v[6:7], v[144:145] op_sel_hi:[1,0]
	v_pk_mul_f32 v[148:149], v[2:3], v[144:145] op_sel_hi:[1,0]
	v_pk_mul_f32 v[168:169], v[0:1], v[144:145] op_sel_hi:[1,0]
	v_min_f32_e32 v145, 0, v170
	v_mul_f32_e64 v170, |v170|, s57
	v_exp_f32_e32 v170, v170
	s_nop 0
	v_add_f32_e32 v170, 1.0, v170
	v_cmp_gt_f32_e64 s[40:41], s97, v170
	s_nop 1
	v_cndmask_b32_e64 v194, 0, 32, s[40:41]
	v_ldexp_f32 v170, v170, v194
	v_log_f32_e32 v170, v170
	s_nop 0
	v_mul_f32_e32 v194, 0x3f317217, v170
	v_fma_f32 v194, v170, s52, -v194
	v_fmac_f32_e32 v194, 0x3377d1cf, v170
	v_fmac_f32_e32 v194, 0x3f317217, v170
	v_cmp_lt_f32_e64 s[42:43], |v170|, s53
	s_nop 1
	v_cndmask_b32_e64 v170, v170, v194, s[42:43]
	v_cndmask_b32_e64 v194, 0, v216, s[40:41]
	v_sub_f32_e32 v170, v170, v194
	v_sub_f32_e32 v145, v145, v170
	v_min_f32_e32 v170, 0, v168
	v_mul_f32_e64 v168, |v168|, s57
	v_exp_f32_e32 v168, v168
	s_nop 0
	v_add_f32_e32 v168, 1.0, v168
	v_cmp_gt_f32_e64 s[40:41], s97, v168
	s_nop 1
	v_cndmask_b32_e64 v194, 0, 32, s[40:41]
	v_ldexp_f32 v168, v168, v194
	v_log_f32_e32 v168, v168
	s_nop 0
	v_mul_f32_e32 v194, 0x3f317217, v168
	v_fma_f32 v194, v168, s52, -v194
	v_fmac_f32_e32 v194, 0x3377d1cf, v168
	v_fmac_f32_e32 v194, 0x3f317217, v168
	v_cmp_lt_f32_e64 s[42:43], |v168|, s53
	s_nop 1
	v_cndmask_b32_e64 v168, v168, v194, s[42:43]
	v_cndmask_b32_e64 v194, 0, v216, s[40:41]
	v_sub_f32_e32 v168, v168, v194
	v_sub_f32_e32 v168, v170, v168
	v_mul_f32_e32 v170, 0x3fb8aa3b, v145
	v_exp_f32_e32 v170, v170
	s_nop 0
	v_fma_f32 v140, v190, v170, v140
	v_cmp_gt_f32_e64 s[40:41], s97, v140
	s_nop 1
	v_cndmask_b32_e64 v170, 0, 32, s[40:41]
	v_ldexp_f32 v140, v140, v170
	v_log_f32_e32 v140, v140
	s_nop 0
	v_mul_f32_e32 v170, 0x3f317217, v140
	v_fma_f32 v170, v140, s52, -v170
	v_fmac_f32_e32 v170, 0x3377d1cf, v140
	v_fmac_f32_e32 v170, 0x3f317217, v140
	v_cmp_lt_f32_e64 s[42:43], |v140|, s53
	s_nop 1
	v_cndmask_b32_e64 v140, v140, v170, s[42:43]
	v_cndmask_b32_e64 v170, 0, v216, s[40:41]
	v_sub_f32_e32 v140, v140, v170
	v_cndmask_b32_e64 v140, v145, v140, s[38:39]
	v_mul_f32_e32 v145, 0x3fb8aa3b, v168
	v_exp_f32_e32 v145, v145
	v_readlane_b32 s42, v255, 57
	v_readlane_b32 s43, v255, 58
	v_fma_f32 v136, v191, v145, v136
	v_cmp_gt_f32_e64 s[38:39], s97, v136
	s_nop 1
	v_cndmask_b32_e64 v145, 0, 32, s[38:39]
	v_ldexp_f32 v136, v136, v145
	v_log_f32_e32 v136, v136
	s_nop 0
	v_mul_f32_e32 v145, 0x3f317217, v136
	v_fma_f32 v145, v136, s52, -v145
	v_fmac_f32_e32 v145, 0x3377d1cf, v136
	v_fmac_f32_e32 v145, 0x3f317217, v136
	v_cmp_lt_f32_e64 s[40:41], |v136|, s53
	s_nop 1
	v_cndmask_b32_e64 v136, v136, v145, s[40:41]
	v_cndmask_b32_e64 v145, 0, v216, s[38:39]
	v_sub_f32_e32 v136, v136, v145
	v_cndmask_b32_e64 v136, v168, v136, s[36:37]
	v_mul_f32_e64 v168, |v171|, s57
	v_exp_f32_e32 v168, v168
	v_min_f32_e32 v145, 0, v171
	s_mov_b32 s40, s2
	v_add_f32_e32 v168, 1.0, v168
	v_cmp_gt_f32_e64 s[36:37], s97, v168
	s_nop 1
	v_cndmask_b32_e64 v170, 0, 32, s[36:37]
	v_ldexp_f32 v168, v168, v170
	v_log_f32_e32 v168, v168
	s_nop 0
	v_mul_f32_e32 v170, 0x3f317217, v168
	v_fma_f32 v170, v168, s52, -v170
	v_fmac_f32_e32 v170, 0x3377d1cf, v168
	v_fmac_f32_e32 v170, 0x3f317217, v168
	v_cmp_lt_f32_e64 s[38:39], |v168|, s53
	s_nop 1
	v_cndmask_b32_e64 v168, v168, v170, s[38:39]
	v_cndmask_b32_e64 v170, 0, v216, s[36:37]
	v_sub_f32_e32 v168, v168, v170
	v_sub_f32_e32 v145, v145, v168
	v_min_f32_e32 v168, 0, v169
	v_mul_f32_e64 v169, |v169|, s57
	v_exp_f32_e32 v169, v169
	s_nop 0
	v_add_f32_e32 v169, 1.0, v169
	v_cmp_gt_f32_e64 s[36:37], s97, v169
	s_nop 1
	v_cndmask_b32_e64 v170, 0, 32, s[36:37]
	v_ldexp_f32 v169, v169, v170
	v_log_f32_e32 v169, v169
	s_nop 0
	v_mul_f32_e32 v170, 0x3f317217, v169
	v_fma_f32 v170, v169, s52, -v170
	v_fmac_f32_e32 v170, 0x3377d1cf, v169
	v_fmac_f32_e32 v170, 0x3f317217, v169
	v_cmp_lt_f32_e64 s[38:39], |v169|, s53
	s_nop 1
	v_cndmask_b32_e64 v169, v169, v170, s[38:39]
	v_cndmask_b32_e64 v170, 0, v216, s[36:37]
	v_sub_f32_e32 v169, v169, v170
	v_sub_f32_e32 v168, v168, v169
	v_mul_f32_e32 v169, 0x3fb8aa3b, v145
	v_exp_f32_e32 v169, v169
	s_nop 0
	v_fma_f32 v141, v188, v169, v141
	v_cmp_gt_f32_e64 s[36:37], s97, v141
	s_nop 1
	v_cndmask_b32_e64 v169, 0, 32, s[36:37]
	v_ldexp_f32 v141, v141, v169
	v_log_f32_e32 v141, v141
	s_nop 0
	v_mul_f32_e32 v169, 0x3f317217, v141
	v_fma_f32 v169, v141, s52, -v169
	v_fmac_f32_e32 v169, 0x3377d1cf, v141
	v_fmac_f32_e32 v169, 0x3f317217, v141
	v_cmp_lt_f32_e64 s[38:39], |v141|, s53
	s_nop 1
	v_cndmask_b32_e64 v141, v141, v169, s[38:39]
	v_cndmask_b32_e64 v169, 0, v216, s[36:37]
	v_sub_f32_e32 v141, v141, v169
	v_cndmask_b32_e64 v141, v145, v141, s[34:35]
	v_mul_f32_e32 v145, 0x3fb8aa3b, v168
	v_exp_f32_e32 v145, v145
	v_readlane_b32 s38, v255, 53
	v_readlane_b32 s39, v255, 54
	v_fma_f32 v137, v189, v145, v137
	v_cmp_gt_f32_e64 s[34:35], s97, v137
	s_nop 1
	v_cndmask_b32_e64 v145, 0, 32, s[34:35]
	v_ldexp_f32 v137, v137, v145
	v_log_f32_e32 v137, v137
	s_nop 0
	v_mul_f32_e32 v145, 0x3f317217, v137
	v_fma_f32 v145, v137, s52, -v145
	v_fmac_f32_e32 v145, 0x3377d1cf, v137
	v_fmac_f32_e32 v145, 0x3f317217, v137
	v_cmp_lt_f32_e64 s[36:37], |v137|, s53
	s_nop 1
	v_cndmask_b32_e64 v137, v137, v145, s[36:37]
	v_cndmask_b32_e64 v145, 0, v216, s[34:35]
	v_sub_f32_e32 v137, v137, v145
	v_min_f32_e32 v145, 0, v150
	v_mul_f32_e64 v150, |v150|, s57
	v_exp_f32_e32 v150, v150
	v_cndmask_b32_e64 v137, v168, v137, s[30:31]
	v_readlane_b32 s36, v255, 51
	v_readlane_b32 s37, v255, 52
	v_add_f32_e32 v150, 1.0, v150
	v_cmp_gt_f32_e64 s[30:31], s97, v150
; __device__ __forceinline__ float silu_f(float x) { return x * __builtin_amdgcn_rcpf(1.f + __expf(-x)); }
; __device__ __forceinline__ v4u pack8(const f32x4 a, const f32x4 b) { v4u w; w.x = cvt_pk_bf16(a[0], a[1]); w.y = cvt_pk_bf16(a[2], a[3]); w.z = cvt_pk_bf16(b[0], b[1]); w.w = cvt_pk_bf16(b[2], b[3]); return w; }
;     __device__ __forceinline__ void operator()(const f32x4 (&acc)[2][2][4][2], const pg8::Unit& u, int wr, int wc, int fr, int fq) const {
;     ...
;         if (grp == 0) { WIN_LOOP( _Pragma("unroll") for (int i = 0; i < 4; ++i) { a[i] = silu_f(a[i]); b[i] = silu_f(b[i]); } *(v4u*)(QO + (size_t)row * DM + c) = pack8(a, b); ) }
;         else if (grp == 3) { WIN_LOOP( _Pragma("unroll") for (int i = 0; i < 4; ++i) { a[i] = silu_f(a[i]); b[i] = silu_f(b[i]); } *(v4u*)(GH + (size_t)row * 512 + c) = pack8(a, b); ) }
;         else if (grp == 1) {
;             f32x4 l0[2], l1[2];
; #pragma unroll
;             for (int bj = 0; bj < 2; ++bj) { l0[bj] = *(const f32x4*)(lb + cb + bj * 128); l1[bj] = *(const f32x4*)(lb + cb + bj * 128 + 4); }
;             WIN_LOOP( _Pragma("unroll") for (int i = 0; i < 4; ++i) { const float s0 = fminf(a[i], 0.f) - __logf(1.f + __expf(-fabsf(a[i]))), s1 = fminf(b[i], 0.f) - __logf(1.f + __expf(-fabsf(b[i]))); const float la = l0[bj][i], lbv = l1[bj][i];
;                     a[i] = la > 0.f ? __logf(la + (1.f - la) * __expf(s0)) : s0; b[i] = lbv > 0.f ? __logf(lbv + (1.f - lbv) * __expf(s1)) : s1; }
;                 *(f32x4*)(LF + (size_t)row * 512 + c) = a; *(f32x4*)(LF + (size_t)row * 512 + c + 4) = b; __builtin_amdgcn_sched_barrier(0); ) }
	s_nop 1
	v_cndmask_b32_e64 v168, 0, 32, s[30:31]
	v_ldexp_f32 v150, v150, v168
	v_log_f32_e32 v150, v150
	s_nop 0
	v_mul_f32_e32 v168, 0x3f317217, v150
	v_fma_f32 v168, v150, s52, -v168
	v_fmac_f32_e32 v168, 0x3377d1cf, v150
	v_fmac_f32_e32 v168, 0x3f317217, v150
	v_cmp_lt_f32_e64 s[34:35], |v150|, s53
	s_nop 1
	v_cndmask_b32_e64 v150, v150, v168, s[34:35]
	v_cndmask_b32_e64 v168, 0, v216, s[30:31]
	v_sub_f32_e32 v150, v150, v168
	v_sub_f32_e32 v145, v145, v150
	v_min_f32_e32 v150, 0, v148
	v_mul_f32_e64 v148, |v148|, s57
	v_exp_f32_e32 v148, v148
	s_nop 0
	v_add_f32_e32 v148, 1.0, v148
	v_cmp_gt_f32_e64 s[30:31], s97, v148
	s_nop 1
	v_cndmask_b32_e64 v168, 0, 32, s[30:31]
	v_ldexp_f32 v148, v148, v168
	v_log_f32_e32 v148, v148
	s_nop 0
	v_mul_f32_e32 v168, 0x3f317217, v148
	v_fma_f32 v168, v148, s52, -v168
	v_fmac_f32_e32 v168, 0x3377d1cf, v148
	v_fmac_f32_e32 v168, 0x3f317217, v148
	v_cmp_lt_f32_e64 s[34:35], |v148|, s53
	s_nop 1
	v_cndmask_b32_e64 v148, v148, v168, s[34:35]
	v_cndmask_b32_e64 v168, 0, v216, s[30:31]
	v_sub_f32_e32 v148, v148, v168
	v_sub_f32_e32 v148, v150, v148
	v_mul_f32_e32 v150, 0x3fb8aa3b, v145
	v_exp_f32_e32 v150, v150
	s_nop 0
	v_fma_f32 v142, v187, v150, v142
	v_cmp_gt_f32_e64 s[30:31], s97, v142
	s_nop 1
	v_cndmask_b32_e64 v150, 0, 32, s[30:31]
	v_ldexp_f32 v142, v142, v150
	v_log_f32_e32 v142, v142
	s_nop 0
	v_mul_f32_e32 v150, 0x3f317217, v142
	v_fma_f32 v150, v142, s52, -v150
	v_fmac_f32_e32 v150, 0x3377d1cf, v142
	v_fmac_f32_e32 v150, 0x3f317217, v142
	v_cmp_lt_f32_e64 s[34:35], |v142|, s53
	s_nop 1
	v_cndmask_b32_e64 v142, v142, v150, s[34:35]
	v_cndmask_b32_e64 v150, 0, v216, s[30:31]
	v_sub_f32_e32 v142, v142, v150
	v_cndmask_b32_e64 v142, v145, v142, s[28:29]
	v_mul_f32_e32 v145, 0x3fb8aa3b, v148
	v_exp_f32_e32 v145, v145
	v_readlane_b32 s34, v255, 49
	v_readlane_b32 s35, v255, 50
	v_fma_f32 v138, v186, v145, v138
	v_cmp_gt_f32_e64 s[28:29], s97, v138
	s_nop 1
	v_cndmask_b32_e64 v145, 0, 32, s[28:29]
	v_ldexp_f32 v138, v138, v145
	v_log_f32_e32 v138, v138
	s_nop 0
	v_mul_f32_e32 v145, 0x3f317217, v138
	v_fma_f32 v145, v138, s52, -v145
	v_fmac_f32_e32 v145, 0x3377d1cf, v138
	v_fmac_f32_e32 v145, 0x3f317217, v138
	v_cmp_lt_f32_e64 s[30:31], |v138|, s53
	s_nop 1
	v_cndmask_b32_e64 v138, v138, v145, s[30:31]
	v_cndmask_b32_e64 v145, 0, v216, s[28:29]
	v_sub_f32_e32 v138, v138, v145
	v_cndmask_b32_e64 v138, v148, v138, s[26:27]
	v_mul_f32_e64 v148, |v151|, s57
	v_exp_f32_e32 v148, v148
	v_min_f32_e32 v145, 0, v151
	v_readlane_b32 s30, v255, 47
	v_readlane_b32 s31, v255, 48
	v_add_f32_e32 v148, 1.0, v148
	v_cmp_gt_f32_e64 s[26:27], s97, v148
	s_nop 1
	v_cndmask_b32_e64 v150, 0, 32, s[26:27]
	v_ldexp_f32 v148, v148, v150
	v_log_f32_e32 v148, v148
	s_nop 0
	v_mul_f32_e32 v150, 0x3f317217, v148
	v_fma_f32 v150, v148, s52, -v150
	v_fmac_f32_e32 v150, 0x3377d1cf, v148
	v_fmac_f32_e32 v150, 0x3f317217, v148
	v_cmp_lt_f32_e64 s[28:29], |v148|, s53
	s_nop 1
	v_cndmask_b32_e64 v148, v148, v150, s[28:29]
	v_cndmask_b32_e64 v150, 0, v216, s[26:27]
	v_sub_f32_e32 v148, v148, v150
	v_sub_f32_e32 v145, v145, v148
	v_min_f32_e32 v148, 0, v149
	v_mul_f32_e64 v149, |v149|, s57
	v_exp_f32_e32 v149, v149
	s_nop 0
	v_add_f32_e32 v149, 1.0, v149
	v_cmp_gt_f32_e64 s[26:27], s97, v149
	s_nop 1
	v_cndmask_b32_e64 v150, 0, 32, s[26:27]
	v_ldexp_f32 v149, v149, v150
	v_log_f32_e32 v149, v149
	s_nop 0
	v_mul_f32_e32 v150, 0x3f317217, v149
	v_fma_f32 v150, v149, s52, -v150
	v_fmac_f32_e32 v150, 0x3377d1cf, v149
	v_fmac_f32_e32 v150, 0x3f317217, v149
	v_cmp_lt_f32_e64 s[28:29], |v149|, s53
	s_nop 1
	v_cndmask_b32_e64 v149, v149, v150, s[28:29]
	v_cndmask_b32_e64 v150, 0, v216, s[26:27]
	v_sub_f32_e32 v149, v149, v150
	v_sub_f32_e32 v148, v148, v149
	v_mul_f32_e32 v149, 0x3fb8aa3b, v145
	v_exp_f32_e32 v149, v149
	s_nop 0
	v_fmac_f32_e32 v143, v185, v149
	v_cmp_gt_f32_e64 s[26:27], s97, v143
	s_nop 1
	v_cndmask_b32_e64 v149, 0, 32, s[26:27]
	v_ldexp_f32 v143, v143, v149
	v_log_f32_e32 v143, v143
	s_nop 0
	v_mul_f32_e32 v149, 0x3f317217, v143
	v_fma_f32 v149, v143, s52, -v149
	v_fmac_f32_e32 v149, 0x3377d1cf, v143
	v_fmac_f32_e32 v149, 0x3f317217, v143
	v_cmp_lt_f32_e64 s[28:29], |v143|, s53
	s_nop 1
	v_cndmask_b32_e64 v143, v143, v149, s[28:29]
	v_cndmask_b32_e64 v149, 0, v216, s[26:27]
	v_sub_f32_e32 v143, v143, v149
	v_cndmask_b32_e64 v143, v145, v143, s[24:25]
	v_mul_f32_e32 v145, 0x3fb8aa3b, v148
	v_exp_f32_e32 v145, v145
	s_mov_b32 s29, s91
	s_mov_b32 s28, s95
	v_fmac_f32_e32 v139, v184, v145
	v_cmp_gt_f32_e64 s[24:25], s97, v139
	s_nop 1
	v_cndmask_b32_e64 v145, 0, 32, s[24:25]
	v_ldexp_f32 v139, v139, v145
	v_log_f32_e32 v139, v139
	s_nop 0
	v_mul_f32_e32 v145, 0x3f317217, v139
	v_fma_f32 v145, v139, s52, -v145
	v_fmac_f32_e32 v145, 0x3377d1cf, v139
	v_fmac_f32_e32 v145, 0x3f317217, v139
	v_cmp_lt_f32_e64 s[26:27], |v139|, s53
	s_nop 1
	v_cndmask_b32_e64 v139, v139, v145, s[26:27]
	v_cndmask_b32_e64 v145, 0, v216, s[24:25]
	v_readlane_b32 s27, v255, 56
	v_readlane_b32 s26, v255, 31
	v_sub_f32_e32 v139, v139, v145
	v_cndmask_b32_e64 v139, v148, v139, s[22:23]
	global_store_dwordx4 v[146:147], v[140:143], off
	global_store_dwordx4 v[146:147], v[136:139], off offset:16
	s_nop 0
	v_pk_mul_f32 v[142:143], v[68:69], v[144:145] op_sel_hi:[1,0]
	v_pk_mul_f32 v[138:139], v[70:71], v[144:145] op_sel_hi:[1,0]
	v_pk_mul_f32 v[136:137], v[66:67], v[144:145] op_sel_hi:[1,0]
	v_pk_mul_f32 v[140:141], v[64:65], v[144:145] op_sel_hi:[1,0]
	v_min_f32_e32 v144, 0, v142
	v_mul_f32_e64 v142, |v142|, s57
	v_exp_f32_e32 v142, v142
	s_nop 0
	v_add_f32_e32 v142, 1.0, v142
	v_cmp_gt_f32_e64 s[22:23], s97, v142
	s_nop 1
	v_cndmask_b32_e64 v145, 0, 32, s[22:23]
; __device__ __forceinline__ float silu_f(float x) { return x * __builtin_amdgcn_rcpf(1.f + __expf(-x)); }
; __device__ __forceinline__ v4u pack8(const f32x4 a, const f32x4 b) { v4u w; w.x = cvt_pk_bf16(a[0], a[1]); w.y = cvt_pk_bf16(a[2], a[3]); w.z = cvt_pk_bf16(b[0], b[1]); w.w = cvt_pk_bf16(b[2], b[3]); return w; }
;     __device__ __forceinline__ void operator()(const f32x4 (&acc)[2][2][4][2], const pg8::Unit& u, int wr, int wc, int fr, int fq) const {
;     ...
;         if (grp == 0) { WIN_LOOP( _Pragma("unroll") for (int i = 0; i < 4; ++i) { a[i] = silu_f(a[i]); b[i] = silu_f(b[i]); } *(v4u*)(QO + (size_t)row * DM + c) = pack8(a, b); ) }
;         else if (grp == 3) { WIN_LOOP( _Pragma("unroll") for (int i = 0; i < 4; ++i) { a[i] = silu_f(a[i]); b[i] = silu_f(b[i]); } *(v4u*)(GH + (size_t)row * 512 + c) = pack8(a, b); ) }
;         else if (grp == 1) {
;             f32x4 l0[2], l1[2];
; #pragma unroll
;             for (int bj = 0; bj < 2; ++bj) { l0[bj] = *(const f32x4*)(lb + cb + bj * 128); l1[bj] = *(const f32x4*)(lb + cb + bj * 128 + 4); }
;             WIN_LOOP( _Pragma("unroll") for (int i = 0; i < 4; ++i) { const float s0 = fminf(a[i], 0.f) - __logf(1.f + __expf(-fabsf(a[i]))), s1 = fminf(b[i], 0.f) - __logf(1.f + __expf(-fabsf(b[i]))); const float la = l0[bj][i], lbv = l1[bj][i];
;                     a[i] = la > 0.f ? __logf(la + (1.f - la) * __expf(s0)) : s0; b[i] = lbv > 0.f ? __logf(lbv + (1.f - lbv) * __expf(s1)) : s1; }
;                 *(f32x4*)(LF + (size_t)row * 512 + c) = a; *(f32x4*)(LF + (size_t)row * 512 + c + 4) = b; __builtin_amdgcn_sched_barrier(0); ) }
	v_ldexp_f32 v142, v142, v145
	v_log_f32_e32 v142, v142
	s_nop 0
	v_mul_f32_e32 v145, 0x3f317217, v142
	v_fma_f32 v145, v142, s52, -v145
	v_fmac_f32_e32 v145, 0x3377d1cf, v142
	v_fmac_f32_e32 v145, 0x3f317217, v142
	v_cmp_lt_f32_e64 s[24:25], |v142|, s53
	s_nop 1
	v_cndmask_b32_e64 v142, v142, v145, s[24:25]
	v_cndmask_b32_e64 v145, 0, v216, s[22:23]
	v_sub_f32_e32 v142, v142, v145
	v_sub_f32_e32 v142, v144, v142
	v_min_f32_e32 v144, 0, v140
	v_mul_f32_e64 v140, |v140|, s57
	v_exp_f32_e32 v140, v140
	s_nop 0
	v_add_f32_e32 v140, 1.0, v140
	v_cmp_gt_f32_e64 s[22:23], s97, v140
	s_nop 1
	v_cndmask_b32_e64 v145, 0, 32, s[22:23]
	v_ldexp_f32 v140, v140, v145
	v_log_f32_e32 v140, v140
	s_nop 0
	v_mul_f32_e32 v145, 0x3f317217, v140
	v_fma_f32 v145, v140, s52, -v145
	v_fmac_f32_e32 v145, 0x3377d1cf, v140
	v_fmac_f32_e32 v145, 0x3f317217, v140
	v_cmp_lt_f32_e64 s[24:25], |v140|, s53
	s_nop 1
	v_cndmask_b32_e64 v140, v140, v145, s[24:25]
	v_cndmask_b32_e64 v145, 0, v216, s[22:23]
	v_sub_f32_e32 v140, v140, v145
	v_sub_f32_e32 v140, v144, v140
	v_mul_f32_e32 v144, 0x3fb8aa3b, v142
	v_exp_f32_e32 v144, v144
	s_nop 0
	v_fma_f32 v132, v183, v144, v132
	v_cmp_gt_f32_e64 s[22:23], s97, v132
	s_nop 1
	v_cndmask_b32_e64 v144, 0, 32, s[22:23]
	v_ldexp_f32 v132, v132, v144
	v_log_f32_e32 v132, v132
	s_nop 0
	v_mul_f32_e32 v144, 0x3f317217, v132
	v_fma_f32 v144, v132, s52, -v144
	v_fmac_f32_e32 v144, 0x3377d1cf, v132
	v_fmac_f32_e32 v144, 0x3f317217, v132
	v_cmp_lt_f32_e64 s[24:25], |v132|, s53
	s_nop 1
	v_cndmask_b32_e64 v132, v132, v144, s[24:25]
	v_cndmask_b32_e64 v144, 0, v216, s[22:23]
	v_sub_f32_e32 v132, v132, v144
	v_cndmask_b32_e64 v132, v142, v132, s[20:21]
	v_mul_f32_e32 v142, 0x3fb8aa3b, v140
	v_exp_f32_e32 v142, v142
	s_nop 0
	v_fma_f32 v128, v182, v142, v128
	v_cmp_gt_f32_e64 s[20:21], s97, v128
	s_nop 1
	v_cndmask_b32_e64 v142, 0, 32, s[20:21]
	v_ldexp_f32 v128, v128, v142
	v_log_f32_e32 v128, v128
	s_nop 0
	v_mul_f32_e32 v142, 0x3f317217, v128
	v_fma_f32 v142, v128, s52, -v142
	v_fmac_f32_e32 v142, 0x3377d1cf, v128
	v_fmac_f32_e32 v142, 0x3f317217, v128
	v_cmp_lt_f32_e64 s[22:23], |v128|, s53
	s_nop 1
	v_cndmask_b32_e64 v128, v128, v142, s[22:23]
	v_cndmask_b32_e64 v142, 0, v216, s[20:21]
	v_sub_f32_e32 v128, v128, v142
	v_mul_f32_e64 v142, |v143|, s57
	v_exp_f32_e32 v142, v142
	v_cndmask_b32_e64 v128, v140, v128, s[18:19]
	v_min_f32_e32 v140, 0, v143
	v_readlane_b32 s23, v255, 55
	v_add_f32_e32 v142, 1.0, v142
	v_cmp_gt_f32_e64 s[18:19], s97, v142
	s_nop 1
	v_cndmask_b32_e64 v143, 0, 32, s[18:19]
	v_ldexp_f32 v142, v142, v143
	v_log_f32_e32 v142, v142
	s_nop 0
	v_mul_f32_e32 v143, 0x3f317217, v142
	v_fma_f32 v143, v142, s52, -v143
	v_fmac_f32_e32 v143, 0x3377d1cf, v142
	v_fmac_f32_e32 v143, 0x3f317217, v142
	v_cmp_lt_f32_e64 s[20:21], |v142|, s53
	s_nop 1
	v_cndmask_b32_e64 v142, v142, v143, s[20:21]
	v_cndmask_b32_e64 v143, 0, v216, s[18:19]
	v_sub_f32_e32 v142, v142, v143
	v_sub_f32_e32 v140, v140, v142
	v_min_f32_e32 v142, 0, v141
	v_mul_f32_e64 v141, |v141|, s57
	v_exp_f32_e32 v141, v141
	s_nop 0
	v_add_f32_e32 v141, 1.0, v141
	v_cmp_gt_f32_e64 s[18:19], s97, v141
	s_nop 1
	v_cndmask_b32_e64 v143, 0, 32, s[18:19]
	v_ldexp_f32 v141, v141, v143
	v_log_f32_e32 v141, v141
	s_nop 0
	v_mul_f32_e32 v143, 0x3f317217, v141
	v_fma_f32 v143, v141, s52, -v143
	v_fmac_f32_e32 v143, 0x3377d1cf, v141
	v_fmac_f32_e32 v143, 0x3f317217, v141
	v_cmp_lt_f32_e64 s[20:21], |v141|, s53
	s_nop 1
	v_cndmask_b32_e64 v141, v141, v143, s[20:21]
	v_cndmask_b32_e64 v143, 0, v216, s[18:19]
	v_sub_f32_e32 v141, v141, v143
	v_sub_f32_e32 v141, v142, v141
	v_mul_f32_e32 v142, 0x3fb8aa3b, v140
	v_exp_f32_e32 v142, v142
	s_nop 0
	v_fma_f32 v133, v181, v142, v133
	v_cmp_gt_f32_e64 s[18:19], s97, v133
	s_nop 1
	v_cndmask_b32_e64 v142, 0, 32, s[18:19]
	v_ldexp_f32 v133, v133, v142
	v_log_f32_e32 v133, v133
	s_nop 0
	v_mul_f32_e32 v142, 0x3f317217, v133
	v_fma_f32 v142, v133, s52, -v142
	v_fmac_f32_e32 v142, 0x3377d1cf, v133
	v_fmac_f32_e32 v142, 0x3f317217, v133
	v_cmp_lt_f32_e64 s[20:21], |v133|, s53
	s_nop 1
	v_cndmask_b32_e64 v133, v133, v142, s[20:21]
	v_cndmask_b32_e64 v142, 0, v216, s[18:19]
	v_sub_f32_e32 v133, v133, v142
	v_cndmask_b32_e64 v133, v140, v133, s[16:17]
	v_mul_f32_e32 v140, 0x3fb8aa3b, v141
	v_exp_f32_e32 v140, v140
	s_nop 0
	v_fma_f32 v129, v180, v140, v129
	v_cmp_gt_f32_e64 s[16:17], s97, v129
	s_nop 1
	v_cndmask_b32_e64 v140, 0, 32, s[16:17]
	v_ldexp_f32 v129, v129, v140
	v_log_f32_e32 v129, v129
	s_nop 0
	v_mul_f32_e32 v140, 0x3f317217, v129
	v_fma_f32 v140, v129, s52, -v140
	v_fmac_f32_e32 v140, 0x3377d1cf, v129
	v_fmac_f32_e32 v140, 0x3f317217, v129
	v_cmp_lt_f32_e64 s[18:19], |v129|, s53
	s_nop 1
	v_cndmask_b32_e64 v129, v129, v140, s[18:19]
	v_cndmask_b32_e64 v140, 0, v216, s[16:17]
	v_sub_f32_e32 v129, v129, v140
	v_min_f32_e32 v140, 0, v138
	v_mul_f32_e64 v138, |v138|, s57
	v_exp_f32_e32 v138, v138
	v_cndmask_b32_e64 v129, v141, v129, s[14:15]
	v_add_f32_e32 v138, 1.0, v138
	v_cmp_gt_f32_e64 s[14:15], s97, v138
; __device__ __forceinline__ float silu_f(float x) { return x * __builtin_amdgcn_rcpf(1.f + __expf(-x)); }
; __device__ __forceinline__ v4u pack8(const f32x4 a, const f32x4 b) { v4u w; w.x = cvt_pk_bf16(a[0], a[1]); w.y = cvt_pk_bf16(a[2], a[3]); w.z = cvt_pk_bf16(b[0], b[1]); w.w = cvt_pk_bf16(b[2], b[3]); return w; }
;     __device__ __forceinline__ void operator()(const f32x4 (&acc)[2][2][4][2], const pg8::Unit& u, int wr, int wc, int fr, int fq) const {
;     ...
;         if (grp == 0) { WIN_LOOP( _Pragma("unroll") for (int i = 0; i < 4; ++i) { a[i] = silu_f(a[i]); b[i] = silu_f(b[i]); } *(v4u*)(QO + (size_t)row * DM + c) = pack8(a, b); ) }
;         else if (grp == 3) { WIN_LOOP( _Pragma("unroll") for (int i = 0; i < 4; ++i) { a[i] = silu_f(a[i]); b[i] = silu_f(b[i]); } *(v4u*)(GH + (size_t)row * 512 + c) = pack8(a, b); ) }
;         else if (grp == 1) {
;             f32x4 l0[2], l1[2];
; #pragma unroll
;             for (int bj = 0; bj < 2; ++bj) { l0[bj] = *(const f32x4*)(lb + cb + bj * 128); l1[bj] = *(const f32x4*)(lb + cb + bj * 128 + 4); }
;             WIN_LOOP( _Pragma("unroll") for (int i = 0; i < 4; ++i) { const float s0 = fminf(a[i], 0.f) - __logf(1.f + __expf(-fabsf(a[i]))), s1 = fminf(b[i], 0.f) - __logf(1.f + __expf(-fabsf(b[i]))); const float la = l0[bj][i], lbv = l1[bj][i];
;                     a[i] = la > 0.f ? __logf(la + (1.f - la) * __expf(s0)) : s0; b[i] = lbv > 0.f ? __logf(lbv + (1.f - lbv) * __expf(s1)) : s1; }
;                 *(f32x4*)(LF + (size_t)row * 512 + c) = a; *(f32x4*)(LF + (size_t)row * 512 + c + 4) = b; __builtin_amdgcn_sched_barrier(0); ) }
	s_nop 1
	v_cndmask_b32_e64 v141, 0, 32, s[14:15]
	v_ldexp_f32 v138, v138, v141
	v_log_f32_e32 v138, v138
	s_nop 0
	v_mul_f32_e32 v141, 0x3f317217, v138
	v_fma_f32 v141, v138, s52, -v141
	v_fmac_f32_e32 v141, 0x3377d1cf, v138
	v_fmac_f32_e32 v141, 0x3f317217, v138
	v_cmp_lt_f32_e64 s[16:17], |v138|, s53
	s_nop 1
	v_cndmask_b32_e64 v138, v138, v141, s[16:17]
	v_cndmask_b32_e64 v141, 0, v216, s[14:15]
	v_sub_f32_e32 v138, v138, v141
	v_sub_f32_e32 v138, v140, v138
	v_min_f32_e32 v140, 0, v136
	v_mul_f32_e64 v136, |v136|, s57
	v_exp_f32_e32 v136, v136
	s_nop 0
	v_add_f32_e32 v136, 1.0, v136
	v_cmp_gt_f32_e64 s[14:15], s97, v136
	s_nop 1
	v_cndmask_b32_e64 v141, 0, 32, s[14:15]
	v_ldexp_f32 v136, v136, v141
	v_log_f32_e32 v136, v136
	s_nop 0
	v_mul_f32_e32 v141, 0x3f317217, v136
	v_fma_f32 v141, v136, s52, -v141
	v_fmac_f32_e32 v141, 0x3377d1cf, v136
	v_fmac_f32_e32 v141, 0x3f317217, v136
	v_cmp_lt_f32_e64 s[16:17], |v136|, s53
	s_nop 1
	v_cndmask_b32_e64 v136, v136, v141, s[16:17]
	v_cndmask_b32_e64 v141, 0, v216, s[14:15]
	v_sub_f32_e32 v136, v136, v141
	v_sub_f32_e32 v136, v140, v136
	v_mul_f32_e32 v140, 0x3fb8aa3b, v138
	v_exp_f32_e32 v140, v140
	s_nop 0
	v_fma_f32 v134, v179, v140, v134
	v_cmp_gt_f32_e64 s[14:15], s97, v134
	s_nop 1
	v_cndmask_b32_e64 v140, 0, 32, s[14:15]
	v_ldexp_f32 v134, v134, v140
	v_log_f32_e32 v134, v134
	s_nop 0
	v_mul_f32_e32 v140, 0x3f317217, v134
	v_fma_f32 v140, v134, s52, -v140
	v_fmac_f32_e32 v140, 0x3377d1cf, v134
	v_fmac_f32_e32 v140, 0x3f317217, v134
	v_cmp_lt_f32_e64 s[16:17], |v134|, s53
	s_nop 1
	v_cndmask_b32_e64 v134, v134, v140, s[16:17]
	v_cndmask_b32_e64 v140, 0, v216, s[14:15]
	v_sub_f32_e32 v134, v134, v140
	v_cndmask_b32_e64 v134, v138, v134, s[12:13]
	v_mul_f32_e32 v138, 0x3fb8aa3b, v136
	v_exp_f32_e32 v138, v138
	s_nop 0
	v_fma_f32 v130, v178, v138, v130
	v_cmp_gt_f32_e64 s[12:13], s97, v130
	s_nop 1
	v_cndmask_b32_e64 v138, 0, 32, s[12:13]
	v_ldexp_f32 v130, v130, v138
	v_log_f32_e32 v130, v130
	s_nop 0
	v_mul_f32_e32 v138, 0x3f317217, v130
	v_fma_f32 v138, v130, s52, -v138
	v_fmac_f32_e32 v138, 0x3377d1cf, v130
	v_fmac_f32_e32 v138, 0x3f317217, v130
	v_cmp_lt_f32_e64 s[14:15], |v130|, s53
	s_nop 1
	v_cndmask_b32_e64 v130, v130, v138, s[14:15]
	v_cndmask_b32_e64 v138, 0, v216, s[12:13]
	v_sub_f32_e32 v130, v130, v138
	v_mul_f32_e64 v138, |v139|, s57
	v_exp_f32_e32 v138, v138
	v_cndmask_b32_e64 v130, v136, v130, s[10:11]
	v_min_f32_e32 v136, 0, v139
	v_add_f32_e32 v138, 1.0, v138
	v_cmp_gt_f32_e64 s[10:11], s97, v138
	s_nop 1
	v_cndmask_b32_e64 v139, 0, 32, s[10:11]
	v_ldexp_f32 v138, v138, v139
	v_log_f32_e32 v138, v138
	s_nop 0
	v_mul_f32_e32 v139, 0x3f317217, v138
	v_fma_f32 v139, v138, s52, -v139
	v_fmac_f32_e32 v139, 0x3377d1cf, v138
	v_fmac_f32_e32 v139, 0x3f317217, v138
	v_cmp_lt_f32_e64 s[12:13], |v138|, s53
	s_nop 1
	v_cndmask_b32_e64 v138, v138, v139, s[12:13]
	v_cndmask_b32_e64 v139, 0, v216, s[10:11]
	v_sub_f32_e32 v138, v138, v139
	v_sub_f32_e32 v136, v136, v138
	v_min_f32_e32 v138, 0, v137
	v_mul_f32_e64 v137, |v137|, s57
	v_exp_f32_e32 v137, v137
	s_nop 0
	v_add_f32_e32 v137, 1.0, v137
	v_cmp_gt_f32_e64 s[10:11], s97, v137
	s_nop 1
	v_cndmask_b32_e64 v139, 0, 32, s[10:11]
	v_ldexp_f32 v137, v137, v139
	v_log_f32_e32 v137, v137
	s_nop 0
	v_mul_f32_e32 v139, 0x3f317217, v137
	v_fma_f32 v139, v137, s52, -v139
	v_fmac_f32_e32 v139, 0x3377d1cf, v137
	v_fmac_f32_e32 v139, 0x3f317217, v137
	v_cmp_lt_f32_e64 s[12:13], |v137|, s53
	s_nop 1
	v_cndmask_b32_e64 v137, v137, v139, s[12:13]
	v_cndmask_b32_e64 v139, 0, v216, s[10:11]
	v_sub_f32_e32 v137, v137, v139
	v_sub_f32_e32 v137, v138, v137
	v_mul_f32_e32 v138, 0x3fb8aa3b, v136
	v_exp_f32_e32 v138, v138
	s_nop 0
	v_fmac_f32_e32 v135, v177, v138
	v_cmp_gt_f32_e64 s[10:11], s97, v135
	s_nop 1
	v_cndmask_b32_e64 v138, 0, 32, s[10:11]
	v_ldexp_f32 v135, v135, v138
	v_log_f32_e32 v135, v135
	s_nop 0
	v_mul_f32_e32 v138, 0x3f317217, v135
	v_fma_f32 v138, v135, s52, -v138
	v_fmac_f32_e32 v138, 0x3377d1cf, v135
	v_fmac_f32_e32 v138, 0x3f317217, v135
	v_cmp_lt_f32_e64 s[12:13], |v135|, s53
	s_nop 1
	v_cndmask_b32_e64 v135, v135, v138, s[12:13]
	v_cndmask_b32_e64 v138, 0, v216, s[10:11]
	v_sub_f32_e32 v135, v135, v138
	v_cndmask_b32_e64 v135, v136, v135, s[8:9]
	v_mul_f32_e32 v136, 0x3fb8aa3b, v137
	v_exp_f32_e32 v136, v136
	s_nop 0
	v_fmac_f32_e32 v131, v167, v136
	v_cmp_gt_f32_e64 s[8:9], s97, v131
	s_nop 1
	v_cndmask_b32_e64 v136, 0, 32, s[8:9]
	v_ldexp_f32 v131, v131, v136
	v_log_f32_e32 v131, v131
	s_nop 0
	v_mul_f32_e32 v136, 0x3f317217, v131
	v_fma_f32 v136, v131, s52, -v136
	v_fmac_f32_e32 v136, 0x3377d1cf, v131
	v_fmac_f32_e32 v136, 0x3f317217, v131
	v_cmp_lt_f32_e64 s[10:11], |v131|, s53
	s_nop 1
	v_cndmask_b32_e64 v131, v131, v136, s[10:11]
	v_cndmask_b32_e64 v136, 0, v216, s[8:9]
	v_sub_f32_e32 v131, v131, v136
	v_cndmask_b32_e32 v131, v137, v131, vcc
	global_store_dwordx4 v[146:147], v[132:135], off offset:512
	global_store_dwordx4 v[146:147], v[128:131], off offset:528

; __device__ __forceinline__ v4u pack8(const f32x4 a, const f32x4 b) { v4u w; w.x = cvt_pk_bf16(a[0], a[1]); w.y = cvt_pk_bf16(a[2], a[3]); w.z = cvt_pk_bf16(b[0], b[1]); w.w = cvt_pk_bf16(b[2], b[3]); return w; }
; __device__ __forceinline__ float silu_f(float x) { return x * __builtin_amdgcn_rcpf(1.f + __expf(-x)); }
;     __device__ __forceinline__ void operator()(const f32x4 (&acc)[2][2][4][2], const pg8::Unit& u, int wr, int wc, int fr, int fq) const {
;     ...
;         if (grp == 0) { WIN_LOOP( _Pragma("unroll") for (int i = 0; i < 4; ++i) { a[i] = silu_f(a[i]); b[i] = silu_f(b[i]); } *(v4u*)(QO + (size_t)row * DM + c) = pack8(a, b); ) }
.LBB0_417:
	s_and_b64 vcc, exec, s[8:9]
	s_cbranch_vccz .LBB0_419
	v_and_b32_e32 v129, 64, v215
	v_xor_b32_e32 v128, 16, v215
	v_add_u32_e32 v129, 64, v129
	v_cmp_lt_i32_e32 vcc, v128, v129
	v_xor_b32_e32 v130, 32, v215
	v_ashrrev_i32_e32 v167, 31, v166
	v_cndmask_b32_e32 v128, v215, v128, vcc
	v_cmp_lt_i32_e32 vcc, v130, v129
	v_lshlrev_b32_e32 v128, 2, v128
	v_lshlrev_b32_e32 v192, 1, v176
	v_cndmask_b32_e32 v129, v215, v130, vcc
	v_lshlrev_b64 v[130:131], 6, v[166:167]
	v_lshl_add_u64 v[130:131], v[160:161], 0, v[130:131]
	s_nop 0
	v_lshlrev_b32_e32 v129, 2, v129
	s_waitcnt lgkmcnt(0)
	s_nop 3
	s_nop 0
	s_nop 1
	s_waitcnt lgkmcnt(0)
	s_nop 1
	s_waitcnt lgkmcnt(0)
	s_nop 1
	v_mov_b32_e32 v134, v250
	v_lshlrev_b64 v[130:131], 11, v[166:167]
	v_lshl_add_u64 v[136:137], s[44:45], 0, v[130:131]
	v_lshl_add_u64 v[136:137], v[136:137], 0, v[192:193]
	v_pk_mul_f32 v[132:133], v[60:61], v[134:135] op_sel_hi:[1,0]
	v_pk_mul_f32 v[130:131], v[62:63], v[134:135] op_sel_hi:[1,0]
	v_pk_mul_f32 v[138:139], v[58:59], v[134:135] op_sel_hi:[1,0]
	v_pk_mul_f32 v[140:141], v[56:57], v[134:135] op_sel_hi:[1,0]
	v_mul_f32_e32 v135, 0xbfb8aa3b, v132
	v_exp_f32_e32 v135, v135
	s_nop 0
	v_add_f32_e32 v135, 1.0, v135
	v_rcp_f32_e32 v142, v135
	v_mul_f32_e32 v135, 0xbfb8aa3b, v140
	v_exp_f32_e32 v135, v135
	s_nop 0
	v_add_f32_e32 v135, 1.0, v135
	v_rcp_f32_e32 v144, v135
	v_mul_f32_e32 v135, 0xbfb8aa3b, v133
	v_exp_f32_e32 v135, v135
	s_nop 0
	v_add_f32_e32 v135, 1.0, v135
	v_rcp_f32_e32 v143, v135
	v_mul_f32_e32 v135, 0xbfb8aa3b, v141
	v_exp_f32_e32 v135, v135
	v_pk_mul_f32 v[132:133], v[132:133], v[142:143]
	v_add_f32_e32 v135, 1.0, v135
	v_rcp_f32_e32 v145, v135
	v_mul_f32_e32 v135, 0xbfb8aa3b, v130
	v_exp_f32_e32 v135, v135
	v_pk_mul_f32 v[140:141], v[140:141], v[144:145]
	v_add_f32_e32 v135, 1.0, v135
	v_rcp_f32_e32 v142, v135
	v_mul_f32_e32 v135, 0xbfb8aa3b, v138
	v_exp_f32_e32 v135, v135
	s_nop 0
	v_add_f32_e32 v135, 1.0, v135
	v_rcp_f32_e32 v144, v135
	v_mul_f32_e32 v135, 0xbfb8aa3b, v131
	v_exp_f32_e32 v135, v135
	s_nop 0
	v_add_f32_e32 v135, 1.0, v135
	v_rcp_f32_e32 v143, v135
	v_pk_mul_f32 v[120:121], v[120:121], v[134:135] op_sel_hi:[1,0]
	v_pk_mul_f32 v[124:125], v[124:125], v[134:135] op_sel_hi:[1,0]
	v_pk_mul_f32 v[122:123], v[122:123], v[134:135] op_sel_hi:[1,0]
	v_pk_mul_f32 v[142:143], v[130:131], v[142:143]
	v_mul_f32_e32 v130, 0xbfb8aa3b, v139
	v_exp_f32_e32 v130, v130
	v_cvt_pk_bf16_f32 v131, v142, v143
	v_pk_mul_f32 v[126:127], v[126:127], v[134:135] op_sel_hi:[1,0]
	v_add_f32_e32 v130, 1.0, v130
	v_rcp_f32_e32 v145, v130
	v_cvt_pk_bf16_f32 v130, v132, v133
	v_cvt_pk_bf16_f32 v132, v140, v141
	v_pk_mul_f32 v[138:139], v[138:139], v[144:145]
	s_nop 0
	v_cvt_pk_bf16_f32 v133, v138, v139
	global_store_dwordx4 v[136:137], v[130:133], off
	s_nop 1
	v_mul_f32_e32 v131, 0xbfb8aa3b, v120
	v_exp_f32_e32 v131, v131
	v_mul_f32_e32 v130, 0xbfb8aa3b, v124
	v_exp_f32_e32 v130, v130
	v_add_f32_e32 v131, 1.0, v131
	v_rcp_f32_e32 v132, v131
	v_mul_f32_e32 v131, 0xbfb8aa3b, v125
	v_exp_f32_e32 v131, v131
	v_add_f32_e32 v130, 1.0, v130
	v_rcp_f32_e32 v130, v130
	v_add_f32_e32 v131, 1.0, v131
	v_rcp_f32_e32 v131, v131
	s_nop 0
	v_pk_mul_f32 v[124:125], v[124:125], v[130:131]
	v_mul_f32_e32 v130, 0xbfb8aa3b, v121
	v_exp_f32_e32 v130, v130
	s_nop 0
	v_add_f32_e32 v130, 1.0, v130
	v_rcp_f32_e32 v133, v130
	s_nop 0
	v_pk_mul_f32 v[130:131], v[120:121], v[132:133]
	v_mul_f32_e32 v121, 0xbfb8aa3b, v122
	v_exp_f32_e32 v121, v121
	v_mul_f32_e32 v120, 0xbfb8aa3b, v126
	v_exp_f32_e32 v120, v120
	v_add_f32_e32 v121, 1.0, v121
	v_rcp_f32_e32 v132, v121
	v_mul_f32_e32 v121, 0xbfb8aa3b, v127
	v_exp_f32_e32 v121, v121
	v_add_f32_e32 v120, 1.0, v120
	v_rcp_f32_e32 v120, v120
	v_add_f32_e32 v121, 1.0, v121
	v_rcp_f32_e32 v121, v121
	s_nop 0
	v_pk_mul_f32 v[126:127], v[126:127], v[120:121]
	v_mul_f32_e32 v120, 0xbfb8aa3b, v123
	v_exp_f32_e32 v120, v120
	v_cvt_pk_bf16_f32 v121, v126, v127
	v_add_f32_e32 v120, 1.0, v120
	v_rcp_f32_e32 v133, v120
	v_cvt_pk_bf16_f32 v120, v124, v125
	v_or_b32_e32 v124, 16, v166
	v_ashrrev_i32_e32 v125, 31, v124
	v_pk_mul_f32 v[132:133], v[122:123], v[132:133]
	v_cvt_pk_bf16_f32 v122, v130, v131
	v_cvt_pk_bf16_f32 v123, v132, v133
	global_store_dwordx4 v[136:137], v[120:123], off offset:256
	s_nop 1
	v_lshlrev_b64 v[120:121], 6, v[124:125]
	v_lshl_add_u64 v[120:121], v[160:161], 0, v[120:121]
	s_nop 0
	s_waitcnt lgkmcnt(0)
	s_nop 3
	s_nop 0
	s_nop 1
	s_waitcnt lgkmcnt(0)
	s_nop 1
	s_waitcnt lgkmcnt(0)
; __device__ __forceinline__ v4u pack8(const f32x4 a, const f32x4 b) { v4u w; w.x = cvt_pk_bf16(a[0], a[1]); w.y = cvt_pk_bf16(a[2], a[3]); w.z = cvt_pk_bf16(b[0], b[1]); w.w = cvt_pk_bf16(b[2], b[3]); return w; }
; __device__ __forceinline__ float silu_f(float x) { return x * __builtin_amdgcn_rcpf(1.f + __expf(-x)); }
;     __device__ __forceinline__ void operator()(const f32x4 (&acc)[2][2][4][2], const pg8::Unit& u, int wr, int wc, int fr, int fq) const {
;     ...
;         if (grp == 0) { WIN_LOOP( _Pragma("unroll") for (int i = 0; i < 4; ++i) { a[i] = silu_f(a[i]); b[i] = silu_f(b[i]); } *(v4u*)(QO + (size_t)row * DM + c) = pack8(a, b); ) }
	s_nop 1
	v_mov_b32_e32 v122, v251
	v_lshlrev_b64 v[120:121], 11, v[124:125]
	v_lshl_add_u64 v[120:121], s[44:45], 0, v[120:121]
	v_lshl_add_u64 v[120:121], v[120:121], 0, v[192:193]
	v_pk_mul_f32 v[126:127], v[52:53], v[122:123] op_sel_hi:[1,0]
	v_pk_mul_f32 v[124:125], v[54:55], v[122:123] op_sel_hi:[1,0]
	v_pk_mul_f32 v[130:131], v[50:51], v[122:123] op_sel_hi:[1,0]
	v_pk_mul_f32 v[132:133], v[48:49], v[122:123] op_sel_hi:[1,0]
	v_mul_f32_e32 v123, 0xbfb8aa3b, v126
	v_exp_f32_e32 v123, v123
	s_nop 0
	v_add_f32_e32 v123, 1.0, v123
	v_rcp_f32_e32 v134, v123
	v_mul_f32_e32 v123, 0xbfb8aa3b, v132
	v_exp_f32_e32 v123, v123
	s_nop 0
	v_add_f32_e32 v123, 1.0, v123
	v_rcp_f32_e32 v136, v123
	v_mul_f32_e32 v123, 0xbfb8aa3b, v127
	v_exp_f32_e32 v123, v123
	s_nop 0
	v_add_f32_e32 v123, 1.0, v123
	v_rcp_f32_e32 v135, v123
	v_mul_f32_e32 v123, 0xbfb8aa3b, v133
	v_exp_f32_e32 v123, v123
	v_pk_mul_f32 v[126:127], v[126:127], v[134:135]
	v_add_f32_e32 v123, 1.0, v123
	v_rcp_f32_e32 v137, v123
	v_mul_f32_e32 v123, 0xbfb8aa3b, v124
	v_exp_f32_e32 v123, v123
	v_pk_mul_f32 v[132:133], v[132:133], v[136:137]
	v_add_f32_e32 v123, 1.0, v123
	v_rcp_f32_e32 v134, v123
	v_mul_f32_e32 v123, 0xbfb8aa3b, v130
	v_exp_f32_e32 v123, v123
	s_nop 0
	v_add_f32_e32 v123, 1.0, v123
	v_rcp_f32_e32 v136, v123
	v_mul_f32_e32 v123, 0xbfb8aa3b, v125
	v_exp_f32_e32 v123, v123
	s_nop 0
	v_add_f32_e32 v123, 1.0, v123
	v_rcp_f32_e32 v135, v123
	v_mul_f32_e32 v123, 0xbfb8aa3b, v131
	v_exp_f32_e32 v123, v123
	v_pk_mul_f32 v[134:135], v[124:125], v[134:135]
	v_cvt_pk_bf16_f32 v124, v126, v127
	v_add_f32_e32 v123, 1.0, v123
	v_rcp_f32_e32 v137, v123
	v_cvt_pk_bf16_f32 v125, v134, v135
	v_cvt_pk_bf16_f32 v126, v132, v133
	v_pk_mul_f32 v[116:117], v[116:117], v[122:123] op_sel_hi:[1,0]
	v_pk_mul_f32 v[130:131], v[130:131], v[136:137]
	v_pk_mul_f32 v[114:115], v[114:115], v[122:123] op_sel_hi:[1,0]
	v_cvt_pk_bf16_f32 v127, v130, v131
	global_store_dwordx4 v[120:121], v[124:127], off
	s_nop 1
	v_pk_mul_f32 v[124:125], v[118:119], v[122:123] op_sel_hi:[1,0]
	v_pk_mul_f32 v[118:119], v[112:113], v[122:123] op_sel_hi:[1,0]
	v_mul_f32_e32 v112, 0xbfb8aa3b, v116
	v_mul_f32_e32 v113, 0xbfb8aa3b, v118
	v_exp_f32_e32 v113, v113
	v_exp_f32_e32 v112, v112
	v_add_f32_e32 v113, 1.0, v113
	v_rcp_f32_e32 v122, v113
	v_mul_f32_e32 v113, 0xbfb8aa3b, v117
	v_exp_f32_e32 v113, v113
	v_add_f32_e32 v112, 1.0, v112
	v_rcp_f32_e32 v112, v112
	v_add_f32_e32 v113, 1.0, v113
	v_rcp_f32_e32 v113, v113
	s_nop 0
	v_pk_mul_f32 v[112:113], v[116:117], v[112:113]
	v_mul_f32_e32 v116, 0xbfb8aa3b, v119
	v_exp_f32_e32 v116, v116
	v_cvt_pk_bf16_f32 v112, v112, v113
	v_add_f32_e32 v116, 1.0, v116
	v_rcp_f32_e32 v123, v116
	s_nop 0
	v_pk_mul_f32 v[116:117], v[118:119], v[122:123]
	v_mul_f32_e32 v118, 0xbfb8aa3b, v124
	v_mul_f32_e32 v119, 0xbfb8aa3b, v125
	v_exp_f32_e32 v118, v118
	v_exp_f32_e32 v119, v119
	v_add_f32_e32 v118, 1.0, v118
	v_add_f32_e32 v119, 1.0, v119
	v_rcp_f32_e32 v122, v118
	v_mul_f32_e32 v118, 0xbfb8aa3b, v114
	v_rcp_f32_e32 v123, v119
	v_mul_f32_e32 v119, 0xbfb8aa3b, v115
	v_exp_f32_e32 v118, v118
	v_exp_f32_e32 v119, v119
	v_pk_mul_f32 v[122:123], v[124:125], v[122:123]
	v_add_f32_e32 v118, 1.0, v118
	v_add_f32_e32 v119, 1.0, v119
	v_rcp_f32_e32 v118, v118
	v_rcp_f32_e32 v119, v119
	v_cvt_pk_bf16_f32 v113, v122, v123
	v_pk_mul_f32 v[118:119], v[114:115], v[118:119]
	v_cvt_pk_bf16_f32 v114, v116, v117
	v_or_b32_e32 v116, 32, v166
	v_cvt_pk_bf16_f32 v115, v118, v119
	v_ashrrev_i32_e32 v117, 31, v116
	global_store_dwordx4 v[120:121], v[112:115], off offset:256
	s_nop 1
	v_lshlrev_b64 v[112:113], 6, v[116:117]
	v_lshl_add_u64 v[112:113], v[160:161], 0, v[112:113]
	s_nop 0
	s_waitcnt lgkmcnt(0)
	s_nop 3
	s_nop 0
	s_nop 1
	s_waitcnt lgkmcnt(0)
	s_nop 1
	s_waitcnt lgkmcnt(0)
	s_nop 1
	v_mov_b32_e32 v114, v252
	v_lshlrev_b64 v[112:113], 11, v[116:117]
	v_lshl_add_u64 v[112:113], s[44:45], 0, v[112:113]
	v_lshl_add_u64 v[112:113], v[112:113], 0, v[192:193]
	v_pk_mul_f32 v[118:119], v[44:45], v[114:115] op_sel_hi:[1,0]
	v_pk_mul_f32 v[116:117], v[46:47], v[114:115] op_sel_hi:[1,0]
	v_pk_mul_f32 v[120:121], v[42:43], v[114:115] op_sel_hi:[1,0]
	v_pk_mul_f32 v[122:123], v[40:41], v[114:115] op_sel_hi:[1,0]
	v_mul_f32_e32 v115, 0xbfb8aa3b, v118
	v_exp_f32_e32 v115, v115
	s_nop 0
	v_add_f32_e32 v115, 1.0, v115
	v_rcp_f32_e32 v124, v115
	v_mul_f32_e32 v115, 0xbfb8aa3b, v122
	v_exp_f32_e32 v115, v115
	s_nop 0
	v_add_f32_e32 v115, 1.0, v115
	v_rcp_f32_e32 v126, v115
	v_mul_f32_e32 v115, 0xbfb8aa3b, v119
	v_exp_f32_e32 v115, v115
	s_nop 0
	v_add_f32_e32 v115, 1.0, v115
	v_rcp_f32_e32 v125, v115
	v_mul_f32_e32 v115, 0xbfb8aa3b, v123
	v_exp_f32_e32 v115, v115
	v_pk_mul_f32 v[118:119], v[118:119], v[124:125]
	v_add_f32_e32 v115, 1.0, v115
	v_rcp_f32_e32 v127, v115
	v_mul_f32_e32 v115, 0xbfb8aa3b, v116
	v_exp_f32_e32 v115, v115
	v_pk_mul_f32 v[122:123], v[122:123], v[126:127]
	v_add_f32_e32 v115, 1.0, v115
	v_rcp_f32_e32 v124, v115
	v_mul_f32_e32 v115, 0xbfb8aa3b, v120
	v_exp_f32_e32 v115, v115
	s_nop 0
	v_add_f32_e32 v115, 1.0, v115
	v_rcp_f32_e32 v126, v115
	v_mul_f32_e32 v115, 0xbfb8aa3b, v117
	v_exp_f32_e32 v115, v115
	s_nop 0
	v_add_f32_e32 v115, 1.0, v115
	v_rcp_f32_e32 v125, v115
	v_mul_f32_e32 v115, 0xbfb8aa3b, v121
	v_exp_f32_e32 v115, v115
	v_pk_mul_f32 v[124:125], v[116:117], v[124:125]
	v_cvt_pk_bf16_f32 v116, v118, v119
	v_add_f32_e32 v115, 1.0, v115
	v_rcp_f32_e32 v127, v115
	v_pk_mul_f32 v[110:111], v[110:111], v[114:115] op_sel_hi:[1,0]
	v_pk_mul_f32 v[108:109], v[108:109], v[114:115] op_sel_hi:[1,0]
	v_pk_mul_f32 v[106:107], v[106:107], v[114:115] op_sel_hi:[1,0]
	v_pk_mul_f32 v[114:115], v[104:105], v[114:115] op_sel_hi:[1,0]
; __device__ __forceinline__ v4u pack8(const f32x4 a, const f32x4 b) { v4u w; w.x = cvt_pk_bf16(a[0], a[1]); w.y = cvt_pk_bf16(a[2], a[3]); w.z = cvt_pk_bf16(b[0], b[1]); w.w = cvt_pk_bf16(b[2], b[3]); return w; }
; __device__ __forceinline__ float silu_f(float x) { return x * __builtin_amdgcn_rcpf(1.f + __expf(-x)); }
;     __device__ __forceinline__ void operator()(const f32x4 (&acc)[2][2][4][2], const pg8::Unit& u, int wr, int wc, int fr, int fq) const {
;     ...
;         if (grp == 0) { WIN_LOOP( _Pragma("unroll") for (int i = 0; i < 4; ++i) { a[i] = silu_f(a[i]); b[i] = silu_f(b[i]); } *(v4u*)(QO + (size_t)row * DM + c) = pack8(a, b); ) }
	v_pk_mul_f32 v[120:121], v[120:121], v[126:127]
	v_mul_f32_e32 v105, 0xbfb8aa3b, v114
	v_exp_f32_e32 v105, v105
	v_cvt_pk_bf16_f32 v117, v124, v125
	v_cvt_pk_bf16_f32 v118, v122, v123
	v_cvt_pk_bf16_f32 v119, v120, v121
	v_add_f32_e32 v105, 1.0, v105
	global_store_dwordx4 v[112:113], v[116:119], off
	v_mul_f32_e32 v104, 0xbfb8aa3b, v108
	v_exp_f32_e32 v104, v104
	v_rcp_f32_e32 v116, v105
	v_mul_f32_e32 v105, 0xbfb8aa3b, v109
	v_exp_f32_e32 v105, v105
	v_add_f32_e32 v104, 1.0, v104
	v_rcp_f32_e32 v104, v104
	v_add_f32_e32 v105, 1.0, v105
	v_rcp_f32_e32 v105, v105
	s_nop 0
	v_pk_mul_f32 v[104:105], v[108:109], v[104:105]
	v_mul_f32_e32 v108, 0xbfb8aa3b, v115
	v_exp_f32_e32 v108, v108
	v_cvt_pk_bf16_f32 v104, v104, v105
	v_add_f32_e32 v108, 1.0, v108
	v_rcp_f32_e32 v117, v108
	s_nop 0
	v_pk_mul_f32 v[108:109], v[114:115], v[116:117]
	v_mul_f32_e32 v114, 0xbfb8aa3b, v110
	v_mul_f32_e32 v115, 0xbfb8aa3b, v111
	v_exp_f32_e32 v114, v114
	v_exp_f32_e32 v115, v115
	v_add_f32_e32 v114, 1.0, v114
	v_add_f32_e32 v115, 1.0, v115
	v_rcp_f32_e32 v116, v114
	v_mul_f32_e32 v114, 0xbfb8aa3b, v106
	v_rcp_f32_e32 v117, v115
	v_mul_f32_e32 v115, 0xbfb8aa3b, v107
	v_exp_f32_e32 v114, v114
	v_exp_f32_e32 v115, v115
	v_pk_mul_f32 v[110:111], v[110:111], v[116:117]
	v_add_f32_e32 v114, 1.0, v114
	v_add_f32_e32 v115, 1.0, v115
	v_rcp_f32_e32 v114, v114
	v_rcp_f32_e32 v115, v115
	v_cvt_pk_bf16_f32 v105, v110, v111
	v_pk_mul_f32 v[114:115], v[106:107], v[114:115]
	v_cvt_pk_bf16_f32 v106, v108, v109
	v_or_b32_e32 v108, 48, v166
	v_cvt_pk_bf16_f32 v107, v114, v115
	v_ashrrev_i32_e32 v109, 31, v108
	global_store_dwordx4 v[112:113], v[104:107], off offset:256
	s_nop 1
	v_lshlrev_b64 v[104:105], 6, v[108:109]
	v_lshl_add_u64 v[104:105], v[160:161], 0, v[104:105]
	s_nop 0
	s_waitcnt lgkmcnt(0)
	s_nop 3
	s_nop 0
	s_nop 1
	s_waitcnt lgkmcnt(0)
	s_nop 1
	s_waitcnt lgkmcnt(0)
	s_nop 1
	v_mov_b32_e32 v110, v253
	v_lshlrev_b64 v[104:105], 11, v[108:109]
	v_lshl_add_u64 v[108:109], s[44:45], 0, v[104:105]
	v_lshl_add_u64 v[108:109], v[108:109], 0, v[192:193]
	v_pk_mul_f32 v[106:107], v[36:37], v[110:111] op_sel_hi:[1,0]
	v_pk_mul_f32 v[104:105], v[38:39], v[110:111] op_sel_hi:[1,0]
	v_pk_mul_f32 v[112:113], v[34:35], v[110:111] op_sel_hi:[1,0]
	v_pk_mul_f32 v[114:115], v[32:33], v[110:111] op_sel_hi:[1,0]
	v_mul_f32_e32 v111, 0xbfb8aa3b, v106
	v_exp_f32_e32 v111, v111
	s_nop 0
	v_add_f32_e32 v111, 1.0, v111
	v_rcp_f32_e32 v116, v111
	v_mul_f32_e32 v111, 0xbfb8aa3b, v114
	v_exp_f32_e32 v111, v111
	s_nop 0
	v_add_f32_e32 v111, 1.0, v111
	v_rcp_f32_e32 v118, v111
	v_mul_f32_e32 v111, 0xbfb8aa3b, v107
	v_exp_f32_e32 v111, v111
	s_nop 0
	v_add_f32_e32 v111, 1.0, v111
	v_rcp_f32_e32 v117, v111
	v_mul_f32_e32 v111, 0xbfb8aa3b, v115
	v_exp_f32_e32 v111, v111
	v_pk_mul_f32 v[106:107], v[106:107], v[116:117]
	v_add_f32_e32 v111, 1.0, v111
	v_rcp_f32_e32 v119, v111
	v_mul_f32_e32 v111, 0xbfb8aa3b, v104
	v_exp_f32_e32 v111, v111
	v_pk_mul_f32 v[114:115], v[114:115], v[118:119]
	v_add_f32_e32 v111, 1.0, v111
	v_rcp_f32_e32 v116, v111
	v_mul_f32_e32 v111, 0xbfb8aa3b, v112
	v_exp_f32_e32 v111, v111
	s_nop 0
	v_add_f32_e32 v111, 1.0, v111
	v_rcp_f32_e32 v118, v111
	v_mul_f32_e32 v111, 0xbfb8aa3b, v105
	v_exp_f32_e32 v111, v111
	s_nop 0
	v_add_f32_e32 v111, 1.0, v111
	v_rcp_f32_e32 v117, v111
	v_pk_mul_f32 v[96:97], v[96:97], v[110:111] op_sel_hi:[1,0]
	v_pk_mul_f32 v[100:101], v[100:101], v[110:111] op_sel_hi:[1,0]
	v_pk_mul_f32 v[98:99], v[98:99], v[110:111] op_sel_hi:[1,0]
	v_pk_mul_f32 v[116:117], v[104:105], v[116:117]
	v_mul_f32_e32 v104, 0xbfb8aa3b, v113
	v_exp_f32_e32 v104, v104
	v_cvt_pk_bf16_f32 v105, v116, v117
	v_pk_mul_f32 v[102:103], v[102:103], v[110:111] op_sel_hi:[1,0]
	v_add_f32_e32 v104, 1.0, v104
	v_rcp_f32_e32 v119, v104
	v_cvt_pk_bf16_f32 v104, v106, v107
	v_cvt_pk_bf16_f32 v106, v114, v115
	v_pk_mul_f32 v[112:113], v[112:113], v[118:119]
	s_nop 0
	v_cvt_pk_bf16_f32 v107, v112, v113
	global_store_dwordx4 v[108:109], v[104:107], off
	s_nop 1
	v_mul_f32_e32 v105, 0xbfb8aa3b, v96
	v_exp_f32_e32 v105, v105
	v_mul_f32_e32 v104, 0xbfb8aa3b, v100
	v_exp_f32_e32 v104, v104
	v_add_f32_e32 v105, 1.0, v105
	v_rcp_f32_e32 v106, v105
	v_mul_f32_e32 v105, 0xbfb8aa3b, v101
	v_exp_f32_e32 v105, v105
	v_add_f32_e32 v104, 1.0, v104
	v_rcp_f32_e32 v104, v104
	v_add_f32_e32 v105, 1.0, v105
	v_rcp_f32_e32 v105, v105
	s_nop 0
	v_pk_mul_f32 v[100:101], v[100:101], v[104:105]
	v_mul_f32_e32 v104, 0xbfb8aa3b, v97
	v_exp_f32_e32 v104, v104
	s_nop 0
	v_add_f32_e32 v104, 1.0, v104
	v_rcp_f32_e32 v107, v104
	s_nop 0
	v_pk_mul_f32 v[104:105], v[96:97], v[106:107]
	v_mul_f32_e32 v97, 0xbfb8aa3b, v98
	v_exp_f32_e32 v97, v97
	v_mul_f32_e32 v96, 0xbfb8aa3b, v102
	v_exp_f32_e32 v96, v96
	v_add_f32_e32 v97, 1.0, v97
	v_rcp_f32_e32 v106, v97
	v_mul_f32_e32 v97, 0xbfb8aa3b, v103
	v_exp_f32_e32 v97, v97
	v_add_f32_e32 v96, 1.0, v96
	v_rcp_f32_e32 v96, v96
	v_add_f32_e32 v97, 1.0, v97
	v_rcp_f32_e32 v97, v97
	s_nop 0
	v_pk_mul_f32 v[102:103], v[102:103], v[96:97]
	v_mul_f32_e32 v96, 0xbfb8aa3b, v99
	v_exp_f32_e32 v96, v96
	v_cvt_pk_bf16_f32 v97, v102, v103
	v_add_f32_e32 v96, 1.0, v96
	v_rcp_f32_e32 v107, v96
	v_cvt_pk_bf16_f32 v96, v100, v101
	v_add_u32_e32 v100, 0x80, v166
	v_ashrrev_i32_e32 v101, 31, v100
	v_pk_mul_f32 v[106:107], v[98:99], v[106:107]
	v_cvt_pk_bf16_f32 v98, v104, v105
	v_cvt_pk_bf16_f32 v99, v106, v107
	global_store_dwordx4 v[108:109], v[96:99], off offset:256
	s_nop 1
	v_lshlrev_b64 v[96:97], 6, v[100:101]
	v_lshl_add_u64 v[96:97], v[160:161], 0, v[96:97]
	s_nop 0
	s_waitcnt lgkmcnt(0)
	s_nop 3
	s_nop 0
	s_nop 1
	s_waitcnt lgkmcnt(0)
	s_nop 1
	s_waitcnt lgkmcnt(0)
; __device__ __forceinline__ v4u pack8(const f32x4 a, const f32x4 b) { v4u w; w.x = cvt_pk_bf16(a[0], a[1]); w.y = cvt_pk_bf16(a[2], a[3]); w.z = cvt_pk_bf16(b[0], b[1]); w.w = cvt_pk_bf16(b[2], b[3]); return w; }
; __device__ __forceinline__ float silu_f(float x) { return x * __builtin_amdgcn_rcpf(1.f + __expf(-x)); }
;     __device__ __forceinline__ void operator()(const f32x4 (&acc)[2][2][4][2], const pg8::Unit& u, int wr, int wc, int fr, int fq) const {
;     ...
;         if (grp == 0) { WIN_LOOP( _Pragma("unroll") for (int i = 0; i < 4; ++i) { a[i] = silu_f(a[i]); b[i] = silu_f(b[i]); } *(v4u*)(QO + (size_t)row * DM + c) = pack8(a, b); ) }
	s_nop 1
	v_mov_b32_e32 v102, v254
	v_lshlrev_b64 v[96:97], 11, v[100:101]
	v_lshl_add_u64 v[100:101], s[44:45], 0, v[96:97]
	v_lshl_add_u64 v[100:101], v[100:101], 0, v[192:193]
	v_pk_mul_f32 v[98:99], v[28:29], v[102:103] op_sel_hi:[1,0]
	v_pk_mul_f32 v[96:97], v[30:31], v[102:103] op_sel_hi:[1,0]
	v_pk_mul_f32 v[104:105], v[26:27], v[102:103] op_sel_hi:[1,0]
	v_pk_mul_f32 v[106:107], v[24:25], v[102:103] op_sel_hi:[1,0]
	v_mul_f32_e32 v103, 0xbfb8aa3b, v98
	v_exp_f32_e32 v103, v103
	s_nop 0
	v_add_f32_e32 v103, 1.0, v103
	v_rcp_f32_e32 v108, v103
	v_mul_f32_e32 v103, 0xbfb8aa3b, v106
	v_exp_f32_e32 v103, v103
	s_nop 0
	v_add_f32_e32 v103, 1.0, v103
	v_rcp_f32_e32 v110, v103
	v_mul_f32_e32 v103, 0xbfb8aa3b, v99
	v_exp_f32_e32 v103, v103
	s_nop 0
	v_add_f32_e32 v103, 1.0, v103
	v_rcp_f32_e32 v109, v103
	v_mul_f32_e32 v103, 0xbfb8aa3b, v107
	v_exp_f32_e32 v103, v103
	v_pk_mul_f32 v[98:99], v[98:99], v[108:109]
	v_add_f32_e32 v103, 1.0, v103
	v_rcp_f32_e32 v111, v103
	v_mul_f32_e32 v103, 0xbfb8aa3b, v96
	v_exp_f32_e32 v103, v103
	v_pk_mul_f32 v[106:107], v[106:107], v[110:111]
	v_add_f32_e32 v103, 1.0, v103
	v_rcp_f32_e32 v108, v103
	v_mul_f32_e32 v103, 0xbfb8aa3b, v104
	v_exp_f32_e32 v103, v103
	s_nop 0
	v_add_f32_e32 v103, 1.0, v103
	v_rcp_f32_e32 v110, v103
	v_mul_f32_e32 v103, 0xbfb8aa3b, v97
	v_exp_f32_e32 v103, v103
	s_nop 0
	v_add_f32_e32 v103, 1.0, v103
	v_rcp_f32_e32 v109, v103
	v_pk_mul_f32 v[88:89], v[88:89], v[102:103] op_sel_hi:[1,0]
	v_pk_mul_f32 v[92:93], v[92:93], v[102:103] op_sel_hi:[1,0]
	v_pk_mul_f32 v[90:91], v[90:91], v[102:103] op_sel_hi:[1,0]
	v_pk_mul_f32 v[108:109], v[96:97], v[108:109]
	v_mul_f32_e32 v96, 0xbfb8aa3b, v105
	v_exp_f32_e32 v96, v96
	v_cvt_pk_bf16_f32 v97, v108, v109
	v_pk_mul_f32 v[94:95], v[94:95], v[102:103] op_sel_hi:[1,0]
	v_add_f32_e32 v96, 1.0, v96
	v_rcp_f32_e32 v111, v96
	v_cvt_pk_bf16_f32 v96, v98, v99
	v_cvt_pk_bf16_f32 v98, v106, v107
	v_pk_mul_f32 v[104:105], v[104:105], v[110:111]
	s_nop 0
	v_cvt_pk_bf16_f32 v99, v104, v105
	global_store_dwordx4 v[100:101], v[96:99], off
	s_nop 1
	v_mul_f32_e32 v97, 0xbfb8aa3b, v88
	v_exp_f32_e32 v97, v97
	v_mul_f32_e32 v96, 0xbfb8aa3b, v92
	v_exp_f32_e32 v96, v96
	v_add_f32_e32 v97, 1.0, v97
	v_rcp_f32_e32 v98, v97
	v_mul_f32_e32 v97, 0xbfb8aa3b, v93
	v_exp_f32_e32 v97, v97
	v_add_f32_e32 v96, 1.0, v96
	v_rcp_f32_e32 v96, v96
	v_add_f32_e32 v97, 1.0, v97
	v_rcp_f32_e32 v97, v97
	s_nop 0
	v_pk_mul_f32 v[92:93], v[92:93], v[96:97]
	v_mul_f32_e32 v96, 0xbfb8aa3b, v89
	v_exp_f32_e32 v96, v96
	s_nop 0
	v_add_f32_e32 v96, 1.0, v96
	v_rcp_f32_e32 v99, v96
	s_nop 0
	v_pk_mul_f32 v[96:97], v[88:89], v[98:99]
	v_mul_f32_e32 v89, 0xbfb8aa3b, v90
	v_exp_f32_e32 v89, v89
	v_mul_f32_e32 v88, 0xbfb8aa3b, v94
	v_exp_f32_e32 v88, v88
	v_add_f32_e32 v89, 1.0, v89
	v_rcp_f32_e32 v98, v89
	v_mul_f32_e32 v89, 0xbfb8aa3b, v95
	v_exp_f32_e32 v89, v89
	v_add_f32_e32 v88, 1.0, v88
	v_rcp_f32_e32 v88, v88
	v_add_f32_e32 v89, 1.0, v89
	v_rcp_f32_e32 v89, v89
	s_nop 0
	v_pk_mul_f32 v[94:95], v[94:95], v[88:89]
	v_mul_f32_e32 v88, 0xbfb8aa3b, v91
	v_exp_f32_e32 v88, v88
	v_cvt_pk_bf16_f32 v89, v94, v95
	v_add_f32_e32 v88, 1.0, v88
	v_rcp_f32_e32 v99, v88
	v_cvt_pk_bf16_f32 v88, v92, v93
	v_add_u32_e32 v92, 0x90, v166
	v_ashrrev_i32_e32 v93, 31, v92
	v_pk_mul_f32 v[98:99], v[90:91], v[98:99]
	v_cvt_pk_bf16_f32 v90, v96, v97
	v_cvt_pk_bf16_f32 v91, v98, v99
	global_store_dwordx4 v[100:101], v[88:91], off offset:256
	s_nop 1
	v_lshlrev_b64 v[88:89], 6, v[92:93]
	v_lshl_add_u64 v[88:89], v[160:161], 0, v[88:89]
	s_nop 0
	s_waitcnt lgkmcnt(0)
	s_nop 3
	s_nop 0
	s_nop 1
	s_waitcnt lgkmcnt(0)
	s_nop 1
	s_waitcnt lgkmcnt(0)
	s_nop 1
	v_mov_b32_e32 v94, v240
	v_lshlrev_b64 v[88:89], 11, v[92:93]
	v_lshl_add_u64 v[92:93], s[44:45], 0, v[88:89]
	v_lshl_add_u64 v[92:93], v[92:93], 0, v[192:193]
	v_pk_mul_f32 v[90:91], v[20:21], v[94:95] op_sel_hi:[1,0]
	v_pk_mul_f32 v[88:89], v[22:23], v[94:95] op_sel_hi:[1,0]
	v_pk_mul_f32 v[96:97], v[18:19], v[94:95] op_sel_hi:[1,0]
	v_pk_mul_f32 v[98:99], v[16:17], v[94:95] op_sel_hi:[1,0]
	v_mul_f32_e32 v95, 0xbfb8aa3b, v90
	v_exp_f32_e32 v95, v95
	s_nop 0
	v_add_f32_e32 v95, 1.0, v95
	v_rcp_f32_e32 v100, v95
	v_mul_f32_e32 v95, 0xbfb8aa3b, v98
	v_exp_f32_e32 v95, v95
	s_nop 0
	v_add_f32_e32 v95, 1.0, v95
	v_rcp_f32_e32 v102, v95
	v_mul_f32_e32 v95, 0xbfb8aa3b, v91
	v_exp_f32_e32 v95, v95
	s_nop 0
	v_add_f32_e32 v95, 1.0, v95
	v_rcp_f32_e32 v101, v95
	v_mul_f32_e32 v95, 0xbfb8aa3b, v99
	v_exp_f32_e32 v95, v95
	v_pk_mul_f32 v[90:91], v[90:91], v[100:101]
	v_add_f32_e32 v95, 1.0, v95
	v_rcp_f32_e32 v103, v95
	v_mul_f32_e32 v95, 0xbfb8aa3b, v88
	v_exp_f32_e32 v95, v95
	v_pk_mul_f32 v[98:99], v[98:99], v[102:103]
	v_add_f32_e32 v95, 1.0, v95
	v_rcp_f32_e32 v100, v95
	v_mul_f32_e32 v95, 0xbfb8aa3b, v96
	v_exp_f32_e32 v95, v95
	s_nop 0
	v_add_f32_e32 v95, 1.0, v95
	v_rcp_f32_e32 v102, v95
	v_mul_f32_e32 v95, 0xbfb8aa3b, v89
	v_exp_f32_e32 v95, v95
	s_nop 0
	v_add_f32_e32 v95, 1.0, v95
	v_rcp_f32_e32 v101, v95
	v_pk_mul_f32 v[80:81], v[80:81], v[94:95] op_sel_hi:[1,0]
	v_pk_mul_f32 v[84:85], v[84:85], v[94:95] op_sel_hi:[1,0]
	v_pk_mul_f32 v[82:83], v[82:83], v[94:95] op_sel_hi:[1,0]
	v_pk_mul_f32 v[100:101], v[88:89], v[100:101]
	v_mul_f32_e32 v88, 0xbfb8aa3b, v97
	v_exp_f32_e32 v88, v88
	v_cvt_pk_bf16_f32 v89, v100, v101
	v_pk_mul_f32 v[86:87], v[86:87], v[94:95] op_sel_hi:[1,0]
	v_add_f32_e32 v88, 1.0, v88
	v_rcp_f32_e32 v103, v88
	v_cvt_pk_bf16_f32 v88, v90, v91
	v_cvt_pk_bf16_f32 v90, v98, v99
	v_pk_mul_f32 v[96:97], v[96:97], v[102:103]
	s_nop 0
	v_cvt_pk_bf16_f32 v91, v96, v97
	global_store_dwordx4 v[92:93], v[88:91], off
	s_nop 1
	v_mul_f32_e32 v89, 0xbfb8aa3b, v80
; __device__ __forceinline__ v4u pack8(const f32x4 a, const f32x4 b) { v4u w; w.x = cvt_pk_bf16(a[0], a[1]); w.y = cvt_pk_bf16(a[2], a[3]); w.z = cvt_pk_bf16(b[0], b[1]); w.w = cvt_pk_bf16(b[2], b[3]); return w; }
; __device__ __forceinline__ float silu_f(float x) { return x * __builtin_amdgcn_rcpf(1.f + __expf(-x)); }
;     __device__ __forceinline__ void operator()(const f32x4 (&acc)[2][2][4][2], const pg8::Unit& u, int wr, int wc, int fr, int fq) const {
;     ...
;         if (grp == 0) { WIN_LOOP( _Pragma("unroll") for (int i = 0; i < 4; ++i) { a[i] = silu_f(a[i]); b[i] = silu_f(b[i]); } *(v4u*)(QO + (size_t)row * DM + c) = pack8(a, b); ) }
	v_exp_f32_e32 v89, v89
	v_mul_f32_e32 v88, 0xbfb8aa3b, v84
	v_exp_f32_e32 v88, v88
	v_add_f32_e32 v89, 1.0, v89
	v_rcp_f32_e32 v90, v89
	v_mul_f32_e32 v89, 0xbfb8aa3b, v85
	v_exp_f32_e32 v89, v89
	v_add_f32_e32 v88, 1.0, v88
	v_rcp_f32_e32 v88, v88
	v_add_f32_e32 v89, 1.0, v89
	v_rcp_f32_e32 v89, v89
	s_nop 0
	v_pk_mul_f32 v[84:85], v[84:85], v[88:89]
	v_mul_f32_e32 v88, 0xbfb8aa3b, v81
	v_exp_f32_e32 v88, v88
	s_nop 0
	v_add_f32_e32 v88, 1.0, v88
	v_rcp_f32_e32 v91, v88
	s_nop 0
	v_pk_mul_f32 v[88:89], v[80:81], v[90:91]
	v_mul_f32_e32 v81, 0xbfb8aa3b, v82
	v_exp_f32_e32 v81, v81
	v_mul_f32_e32 v80, 0xbfb8aa3b, v86
	v_exp_f32_e32 v80, v80
	v_add_f32_e32 v81, 1.0, v81
	v_rcp_f32_e32 v90, v81
	v_mul_f32_e32 v81, 0xbfb8aa3b, v87
	v_exp_f32_e32 v81, v81
	v_add_f32_e32 v80, 1.0, v80
	v_rcp_f32_e32 v80, v80
	v_add_f32_e32 v81, 1.0, v81
	v_rcp_f32_e32 v81, v81
	s_nop 0
	v_pk_mul_f32 v[86:87], v[86:87], v[80:81]
	v_mul_f32_e32 v80, 0xbfb8aa3b, v83
	v_exp_f32_e32 v80, v80
	v_cvt_pk_bf16_f32 v81, v86, v87
	v_add_f32_e32 v80, 1.0, v80
	v_rcp_f32_e32 v91, v80
	v_cvt_pk_bf16_f32 v80, v84, v85
	v_add_u32_e32 v84, 0xa0, v166
	v_ashrrev_i32_e32 v85, 31, v84
	v_pk_mul_f32 v[90:91], v[82:83], v[90:91]
	v_cvt_pk_bf16_f32 v82, v88, v89
	v_cvt_pk_bf16_f32 v83, v90, v91
	global_store_dwordx4 v[92:93], v[80:83], off offset:256
	s_nop 1
	v_lshlrev_b64 v[80:81], 6, v[84:85]
	v_lshl_add_u64 v[80:81], v[160:161], 0, v[80:81]
	s_nop 0
	s_waitcnt lgkmcnt(0)
	s_nop 3
	s_nop 0
	s_nop 1
	s_waitcnt lgkmcnt(0)
	s_nop 1
	s_waitcnt lgkmcnt(0)
	s_nop 1
	v_mov_b32_e32 v86, v241
	v_lshlrev_b64 v[80:81], 11, v[84:85]
	v_lshl_add_u64 v[84:85], s[44:45], 0, v[80:81]
	v_lshl_add_u64 v[84:85], v[84:85], 0, v[192:193]
	v_pk_mul_f32 v[82:83], v[12:13], v[86:87] op_sel_hi:[1,0]
	v_pk_mul_f32 v[80:81], v[14:15], v[86:87] op_sel_hi:[1,0]
	v_pk_mul_f32 v[88:89], v[10:11], v[86:87] op_sel_hi:[1,0]
	v_pk_mul_f32 v[90:91], v[8:9], v[86:87] op_sel_hi:[1,0]
	v_mul_f32_e32 v87, 0xbfb8aa3b, v82
	v_exp_f32_e32 v87, v87
	s_nop 0
	v_add_f32_e32 v87, 1.0, v87
	v_rcp_f32_e32 v92, v87
	v_mul_f32_e32 v87, 0xbfb8aa3b, v90
	v_exp_f32_e32 v87, v87
	s_nop 0
	v_add_f32_e32 v87, 1.0, v87
	v_rcp_f32_e32 v94, v87
	v_mul_f32_e32 v87, 0xbfb8aa3b, v83
	v_exp_f32_e32 v87, v87
	s_nop 0
	v_add_f32_e32 v87, 1.0, v87
	v_rcp_f32_e32 v93, v87
	v_mul_f32_e32 v87, 0xbfb8aa3b, v91
	v_exp_f32_e32 v87, v87
	v_pk_mul_f32 v[82:83], v[82:83], v[92:93]
	v_add_f32_e32 v87, 1.0, v87
	v_rcp_f32_e32 v95, v87
	v_mul_f32_e32 v87, 0xbfb8aa3b, v80
	v_exp_f32_e32 v87, v87
	v_pk_mul_f32 v[90:91], v[90:91], v[94:95]
	v_add_f32_e32 v87, 1.0, v87
	v_rcp_f32_e32 v92, v87
	v_mul_f32_e32 v87, 0xbfb8aa3b, v88
	v_exp_f32_e32 v87, v87
	s_nop 0
	v_add_f32_e32 v87, 1.0, v87
	v_rcp_f32_e32 v94, v87
	v_mul_f32_e32 v87, 0xbfb8aa3b, v81
	v_exp_f32_e32 v87, v87
	s_nop 0
	v_add_f32_e32 v87, 1.0, v87
	v_rcp_f32_e32 v93, v87
	v_pk_mul_f32 v[72:73], v[72:73], v[86:87] op_sel_hi:[1,0]
	v_pk_mul_f32 v[76:77], v[76:77], v[86:87] op_sel_hi:[1,0]
	v_pk_mul_f32 v[74:75], v[74:75], v[86:87] op_sel_hi:[1,0]
	v_pk_mul_f32 v[92:93], v[80:81], v[92:93]
	v_mul_f32_e32 v80, 0xbfb8aa3b, v89
	v_exp_f32_e32 v80, v80
	v_cvt_pk_bf16_f32 v81, v92, v93
	v_pk_mul_f32 v[78:79], v[78:79], v[86:87] op_sel_hi:[1,0]
	v_add_f32_e32 v80, 1.0, v80
	v_rcp_f32_e32 v95, v80
	v_cvt_pk_bf16_f32 v80, v82, v83
	v_cvt_pk_bf16_f32 v82, v90, v91
	v_pk_mul_f32 v[88:89], v[88:89], v[94:95]
	s_nop 0
	v_cvt_pk_bf16_f32 v83, v88, v89
	global_store_dwordx4 v[84:85], v[80:83], off
	s_nop 1
	v_mul_f32_e32 v81, 0xbfb8aa3b, v72
	v_exp_f32_e32 v81, v81
	v_mul_f32_e32 v80, 0xbfb8aa3b, v76
	v_exp_f32_e32 v80, v80
	v_add_f32_e32 v81, 1.0, v81
	v_rcp_f32_e32 v82, v81
	v_mul_f32_e32 v81, 0xbfb8aa3b, v77
	v_exp_f32_e32 v81, v81
	v_add_f32_e32 v80, 1.0, v80
	v_rcp_f32_e32 v80, v80
	v_add_f32_e32 v81, 1.0, v81
	v_rcp_f32_e32 v81, v81
	s_nop 0
	v_pk_mul_f32 v[76:77], v[76:77], v[80:81]
	v_mul_f32_e32 v80, 0xbfb8aa3b, v73
	v_exp_f32_e32 v80, v80
	s_nop 0
	v_add_f32_e32 v80, 1.0, v80
	v_rcp_f32_e32 v83, v80
	s_nop 0
	v_pk_mul_f32 v[80:81], v[72:73], v[82:83]
	v_mul_f32_e32 v73, 0xbfb8aa3b, v74
	v_exp_f32_e32 v73, v73
	v_mul_f32_e32 v72, 0xbfb8aa3b, v78
	v_exp_f32_e32 v72, v72
	v_add_f32_e32 v73, 1.0, v73
	v_rcp_f32_e32 v82, v73
	v_mul_f32_e32 v73, 0xbfb8aa3b, v79
	v_exp_f32_e32 v73, v73
	v_add_f32_e32 v72, 1.0, v72
	v_rcp_f32_e32 v72, v72
	v_add_f32_e32 v73, 1.0, v73
	v_rcp_f32_e32 v73, v73
	s_nop 0
	v_pk_mul_f32 v[78:79], v[78:79], v[72:73]
	v_mul_f32_e32 v72, 0xbfb8aa3b, v75
	v_exp_f32_e32 v72, v72
	v_cvt_pk_bf16_f32 v73, v78, v79
	v_add_f32_e32 v72, 1.0, v72
	v_rcp_f32_e32 v83, v72
	v_cvt_pk_bf16_f32 v72, v76, v77
	v_add_u32_e32 v76, 0xb0, v166
	v_ashrrev_i32_e32 v77, 31, v76
	v_pk_mul_f32 v[82:83], v[74:75], v[82:83]
	v_cvt_pk_bf16_f32 v74, v80, v81
	v_cvt_pk_bf16_f32 v75, v82, v83
	global_store_dwordx4 v[84:85], v[72:75], off offset:256
	s_nop 1
	v_lshlrev_b64 v[72:73], 6, v[76:77]
	v_lshl_add_u64 v[72:73], v[160:161], 0, v[72:73]
	s_nop 0
	s_waitcnt lgkmcnt(0)
; __device__ __forceinline__ v4u pack8(const f32x4 a, const f32x4 b) { v4u w; w.x = cvt_pk_bf16(a[0], a[1]); w.y = cvt_pk_bf16(a[2], a[3]); w.z = cvt_pk_bf16(b[0], b[1]); w.w = cvt_pk_bf16(b[2], b[3]); return w; }
; __device__ __forceinline__ float silu_f(float x) { return x * __builtin_amdgcn_rcpf(1.f + __expf(-x)); }
;     __device__ __forceinline__ void operator()(const f32x4 (&acc)[2][2][4][2], const pg8::Unit& u, int wr, int wc, int fr, int fq) const {
;     ...
;         if (grp == 0) { WIN_LOOP( _Pragma("unroll") for (int i = 0; i < 4; ++i) { a[i] = silu_f(a[i]); b[i] = silu_f(b[i]); } *(v4u*)(QO + (size_t)row * DM + c) = pack8(a, b); ) }
	s_nop 3
	s_nop 0
	s_nop 1
	s_waitcnt lgkmcnt(0)
	s_nop 1
	s_waitcnt lgkmcnt(0)
	s_nop 1
	v_mov_b32_e32 v78, v245
	v_lshlrev_b64 v[72:73], 11, v[76:77]
	v_lshl_add_u64 v[76:77], s[44:45], 0, v[72:73]
	v_lshl_add_u64 v[76:77], v[76:77], 0, v[192:193]
	v_pk_mul_f32 v[74:75], v[4:5], v[78:79] op_sel_hi:[1,0]
	v_pk_mul_f32 v[72:73], v[6:7], v[78:79] op_sel_hi:[1,0]
	v_pk_mul_f32 v[80:81], v[2:3], v[78:79] op_sel_hi:[1,0]
	v_pk_mul_f32 v[82:83], v[0:1], v[78:79] op_sel_hi:[1,0]
	v_mul_f32_e32 v79, 0xbfb8aa3b, v74
	v_exp_f32_e32 v79, v79
	s_nop 0
	v_add_f32_e32 v79, 1.0, v79
	v_rcp_f32_e32 v84, v79
	v_mul_f32_e32 v79, 0xbfb8aa3b, v82
	v_exp_f32_e32 v79, v79
	s_nop 0
	v_add_f32_e32 v79, 1.0, v79
	v_rcp_f32_e32 v86, v79
	v_mul_f32_e32 v79, 0xbfb8aa3b, v75
	v_exp_f32_e32 v79, v79
	s_nop 0
	v_add_f32_e32 v79, 1.0, v79
	v_rcp_f32_e32 v85, v79
	v_mul_f32_e32 v79, 0xbfb8aa3b, v83
	v_exp_f32_e32 v79, v79
	v_pk_mul_f32 v[74:75], v[74:75], v[84:85]
	v_add_f32_e32 v79, 1.0, v79
	v_rcp_f32_e32 v87, v79
	v_mul_f32_e32 v79, 0xbfb8aa3b, v72
	v_exp_f32_e32 v79, v79
	v_pk_mul_f32 v[82:83], v[82:83], v[86:87]
	v_add_f32_e32 v79, 1.0, v79
	v_rcp_f32_e32 v84, v79
	v_mul_f32_e32 v79, 0xbfb8aa3b, v80
	v_exp_f32_e32 v79, v79
	s_nop 0
	v_add_f32_e32 v79, 1.0, v79
	v_rcp_f32_e32 v86, v79
	v_mul_f32_e32 v79, 0xbfb8aa3b, v73
	v_exp_f32_e32 v79, v79
	s_nop 0
	v_add_f32_e32 v79, 1.0, v79
	v_rcp_f32_e32 v85, v79
	v_pk_mul_f32 v[64:65], v[64:65], v[78:79] op_sel_hi:[1,0]
	v_pk_mul_f32 v[68:69], v[68:69], v[78:79] op_sel_hi:[1,0]
	v_pk_mul_f32 v[66:67], v[66:67], v[78:79] op_sel_hi:[1,0]
	v_pk_mul_f32 v[84:85], v[72:73], v[84:85]
	v_mul_f32_e32 v72, 0xbfb8aa3b, v81
	v_exp_f32_e32 v72, v72
	v_cvt_pk_bf16_f32 v73, v84, v85
	v_pk_mul_f32 v[70:71], v[70:71], v[78:79] op_sel_hi:[1,0]
	v_add_f32_e32 v72, 1.0, v72
	v_rcp_f32_e32 v87, v72
	v_cvt_pk_bf16_f32 v72, v74, v75
	v_cvt_pk_bf16_f32 v74, v82, v83
	v_pk_mul_f32 v[80:81], v[80:81], v[86:87]
	s_nop 0
	v_cvt_pk_bf16_f32 v75, v80, v81
	global_store_dwordx4 v[76:77], v[72:75], off
	s_nop 1
	v_mul_f32_e32 v73, 0xbfb8aa3b, v64
	v_exp_f32_e32 v73, v73
	v_mul_f32_e32 v72, 0xbfb8aa3b, v68
	v_exp_f32_e32 v72, v72
	v_add_f32_e32 v73, 1.0, v73
	v_rcp_f32_e32 v74, v73
	v_mul_f32_e32 v73, 0xbfb8aa3b, v69
	v_exp_f32_e32 v73, v73
	v_add_f32_e32 v72, 1.0, v72
	v_rcp_f32_e32 v72, v72
	v_add_f32_e32 v73, 1.0, v73
	v_rcp_f32_e32 v73, v73
	s_nop 0
	v_pk_mul_f32 v[68:69], v[68:69], v[72:73]
	v_mul_f32_e32 v72, 0xbfb8aa3b, v65
	v_exp_f32_e32 v72, v72
	s_nop 0
	v_add_f32_e32 v72, 1.0, v72
	v_rcp_f32_e32 v75, v72
	s_nop 0
	v_pk_mul_f32 v[72:73], v[64:65], v[74:75]
	v_mul_f32_e32 v65, 0xbfb8aa3b, v66
	v_exp_f32_e32 v65, v65
	v_mul_f32_e32 v64, 0xbfb8aa3b, v70
	v_exp_f32_e32 v64, v64
	v_add_f32_e32 v65, 1.0, v65
	v_rcp_f32_e32 v74, v65
	v_mul_f32_e32 v65, 0xbfb8aa3b, v71
	v_exp_f32_e32 v65, v65
	v_add_f32_e32 v64, 1.0, v64
	v_rcp_f32_e32 v64, v64
	v_add_f32_e32 v65, 1.0, v65
	v_rcp_f32_e32 v65, v65
	s_nop 0
	v_pk_mul_f32 v[70:71], v[70:71], v[64:65]
	v_mul_f32_e32 v64, 0xbfb8aa3b, v67
	v_exp_f32_e32 v64, v64
	v_cvt_pk_bf16_f32 v65, v70, v71
	v_add_f32_e32 v64, 1.0, v64
	v_rcp_f32_e32 v75, v64
	v_cvt_pk_bf16_f32 v64, v68, v69
	v_pk_mul_f32 v[74:75], v[66:67], v[74:75]
	v_cvt_pk_bf16_f32 v66, v72, v73
	v_cvt_pk_bf16_f32 v67, v74, v75
	global_store_dwordx4 v[76:77], v[64:67], off offset:256

; __device__ __forceinline__ float row_rstd(const float* ssq, int row, int fq) {
;     const f32x4 v = *(const f32x4*)(ssq + (size_t)row * 16 + fq * 4);
;     float s = (v[0] + v[1]) + (v[2] + v[3]);
;     s += __shfl_xor(s, 16); s += __shfl_xor(s, 32);
;     return __builtin_amdgcn_rsqf(s * (1.f / DM) + EPS);
;     __device__ __forceinline__ void operator()(const f32x4 (&acc_)[2][2][4][2], const pg8::Unit& u, int wr, int wc, int fr, int fq) const {
;     ...
;         const int row0 = u.pm * 256 + wr * 64 + fr, lrow0 = wr * 64 + fr;
; #pragma unroll
;         for (int ai = 0; ai < 2; ++ai)
; #pragma unroll
;             for (int m = 0; m < 4; ++m) { const float rs = row_rstd(ssq, row0 + ai * 128 + m * 16, fq); float mx = -3.0e38f;
; #pragma unroll
;                 for (int bj = 0; bj < 2; ++bj)
; #pragma unroll
;                     for (int n = 0; n < 2; ++n) { const f32x4 a = acc[ai][bj][m][n]; mx = fmaxf(mx, fmaxf(fmaxf(a[0], a[1]), fmaxf(a[2], a[3]))); }
;                 mx *= rs; mx = fmaxf(mx, __shfl_xor(mx, 16)); mx = fmaxf(mx, __shfl_xor(mx, 32));
;                 if (fq == 0) xch[(lrow0 + ai * 128 + m * 16) * 4 + wc] = mx; }
.LBB0_998:
	v_lshl_add_u32 v228, s24, 8, v174
	v_mov_b32_e32 v144, v228
	v_ashrrev_i32_e32 v145, 31, v144
	v_lshlrev_b64 v[144:145], 6, v[144:145]
	v_lshl_add_u64 v[144:145], v[136:137], 0, v[144:145]
	global_load_dwordx4 v[144:147], v[144:145], off
	v_add_u32_e32 v148, 16, v228
	v_ashrrev_i32_e32 v149, 31, v148
	v_lshlrev_b64 v[148:149], 6, v[148:149]
	v_lshl_add_u64 v[148:149], v[136:137], 0, v[148:149]
	global_load_dwordx4 v[148:151], v[148:149], off
	v_add_u32_e32 v152, 32, v228
	v_ashrrev_i32_e32 v153, 31, v152
	v_lshlrev_b64 v[152:153], 6, v[152:153]
	v_lshl_add_u64 v[152:153], v[136:137], 0, v[152:153]
	global_load_dwordx4 v[152:155], v[152:153], off
	v_add_u32_e32 v156, 48, v228
	v_ashrrev_i32_e32 v157, 31, v156
	v_lshlrev_b64 v[156:157], 6, v[156:157]
	v_lshl_add_u64 v[156:157], v[136:137], 0, v[156:157]
	global_load_dwordx4 v[156:159], v[156:157], off
	v_add_u32_e32 v160, 0x80, v228
	v_ashrrev_i32_e32 v161, 31, v160
	v_lshlrev_b64 v[160:161], 6, v[160:161]
	v_lshl_add_u64 v[160:161], v[136:137], 0, v[160:161]
	global_load_dwordx4 v[160:163], v[160:161], off
	v_add_u32_e32 v164, 0x90, v228
	v_ashrrev_i32_e32 v165, 31, v164
	v_lshlrev_b64 v[164:165], 6, v[164:165]
	v_lshl_add_u64 v[164:165], v[136:137], 0, v[164:165]
	global_load_dwordx4 v[164:167], v[164:165], off
	v_add_u32_e32 v168, 0xa0, v228
	v_ashrrev_i32_e32 v169, 31, v168
	v_lshlrev_b64 v[168:169], 6, v[168:169]
	v_lshl_add_u64 v[168:169], v[136:137], 0, v[168:169]
	global_load_dwordx4 v[168:171], v[168:169], off
	v_add_u32_e32 v222, 0xb0, v228
	v_ashrrev_i32_e32 v223, 31, v222
	v_lshlrev_b64 v[222:223], 6, v[222:223]
	v_lshl_add_u64 v[222:223], v[136:137], 0, v[222:223]
	global_load_dwordx4 v[222:225], v[222:223], off
	v_xor_b32_e32 v226, 16, v215
	v_xor_b32_e32 v227, 32, v215
	v_lshlrev_b32_e32 v226, 2, v226
	v_lshlrev_b32_e32 v227, 2, v227
	s_waitcnt vmcnt(0)
	v_add_f32_e32 v144, v144, v145
	v_add_f32_e32 v146, v146, v147
	v_add_f32_e32 v148, v148, v149
	v_add_f32_e32 v150, v150, v151
	v_add_f32_e32 v152, v152, v153
	v_add_f32_e32 v154, v154, v155
	v_add_f32_e32 v156, v156, v157
	v_add_f32_e32 v158, v158, v159
	v_add_f32_e32 v160, v160, v161
	v_add_f32_e32 v162, v162, v163
	v_add_f32_e32 v164, v164, v165
	v_add_f32_e32 v166, v166, v167
	v_add_f32_e32 v168, v168, v169
	v_add_f32_e32 v170, v170, v171
	v_add_f32_e32 v222, v222, v223
	v_add_f32_e32 v224, v224, v225
	v_add_f32_e32 v144, v144, v146
	v_add_f32_e32 v148, v148, v150
	v_add_f32_e32 v152, v152, v154
	v_add_f32_e32 v156, v156, v158
	v_add_f32_e32 v160, v160, v162
	v_add_f32_e32 v164, v164, v166
	v_add_f32_e32 v168, v168, v170
	v_add_f32_e32 v222, v222, v224
	ds_bpermute_b32 v145, v226, v144
	ds_bpermute_b32 v149, v226, v148
	ds_bpermute_b32 v153, v226, v152
	ds_bpermute_b32 v157, v226, v156
	ds_bpermute_b32 v161, v226, v160
	ds_bpermute_b32 v165, v226, v164
	ds_bpermute_b32 v169, v226, v168
	ds_bpermute_b32 v223, v226, v222
	s_waitcnt lgkmcnt(0)
	v_add_f32_e32 v144, v144, v145
	v_add_f32_e32 v148, v148, v149
	v_add_f32_e32 v152, v152, v153
	v_add_f32_e32 v156, v156, v157
	v_add_f32_e32 v160, v160, v161
	v_add_f32_e32 v164, v164, v165
	v_add_f32_e32 v168, v168, v169
	v_add_f32_e32 v222, v222, v223
	ds_bpermute_b32 v145, v227, v144
	ds_bpermute_b32 v149, v227, v148
	ds_bpermute_b32 v153, v227, v152
	ds_bpermute_b32 v157, v227, v156
	ds_bpermute_b32 v161, v227, v160
	ds_bpermute_b32 v165, v227, v164
	ds_bpermute_b32 v169, v227, v168
	ds_bpermute_b32 v223, v227, v222
	s_waitcnt lgkmcnt(0)
	v_add_f32_e32 v144, v144, v145
	v_add_f32_e32 v148, v148, v149
	v_add_f32_e32 v152, v152, v153
	v_add_f32_e32 v156, v156, v157
	v_add_f32_e32 v160, v160, v161
	v_add_f32_e32 v164, v164, v165
	v_add_f32_e32 v168, v168, v169
	v_add_f32_e32 v222, v222, v223
	v_fmamk_f32 v144, v144, 0x3a800000, v212
	v_fmamk_f32 v148, v148, 0x3a800000, v212
	v_fmamk_f32 v152, v152, 0x3a800000, v212
	v_fmamk_f32 v156, v156, 0x3a800000, v212
	v_fmamk_f32 v160, v160, 0x3a800000, v212
	v_fmamk_f32 v164, v164, 0x3a800000, v212
	v_fmamk_f32 v168, v168, 0x3a800000, v212
	v_fmamk_f32 v222, v222, 0x3a800000, v212
	v_rsq_f32_e32 v246, v144
	v_rsq_f32_e32 v247, v148
	v_rsq_f32_e32 v248, v152
	v_rsq_f32_e32 v249, v156
	v_rsq_f32_e32 v250, v160
	v_rsq_f32_e32 v251, v164
	v_rsq_f32_e32 v252, v168
	v_rsq_f32_e32 v253, v222
	s_nop 0
	v_and_b32_e32 v144, 64, v215
	v_xor_b32_e32 v143, 16, v215
	v_add_u32_e32 v144, 64, v144
	v_cmp_lt_i32_e32 vcc, v143, v144
	v_lshl_add_u32 v142, s24, 8, v174
	s_mov_b32 s2, 0xff61b1e6
	v_cndmask_b32_e32 v143, v215, v143, vcc
	v_lshlrev_b32_e32 v209, 2, v143
	v_xor_b32_e32 v143, 32, v215
	v_cmp_lt_i32_e32 vcc, v143, v144
	v_max_f32_e32 v148, v114, v114
	v_add_u32_e32 v210, s74, v176
	v_cndmask_b32_e32 v143, v215, v143, vcc
	v_lshlrev_b32_e32 v208, 2, v143
	v_ashrrev_i32_e32 v143, 31, v142
	v_lshlrev_b64 v[144:145], 6, v[142:143]
	v_lshl_add_u64 v[158:159], v[136:137], 0, v[144:145]
	s_nop 0
	s_waitcnt lgkmcnt(0)
	s_nop 3
	v_max_f32_e32 v146, v126, v126
	v_max_f32_e32 v147, v122, v122
	s_waitcnt lgkmcnt(0)
	s_nop 1
	s_waitcnt lgkmcnt(0)
	s_nop 0
	v_max_f32_e32 v145, v127, v127
	v_max_f32_e32 v145, v146, v145
	v_max_f32_e32 v146, v123, v123
	v_max_f32_e32 v146, v147, v146
	v_max3_f32 v145, v124, v125, v145
	v_max3_f32 v146, v120, v121, v146
	s_nop 0
	v_max3_f32 v145, v145, s2, v146
	v_max_f32_e32 v146, v119, v119
	v_max_f32_e32 v147, v118, v118
	v_max_f32_e32 v146, v147, v146
	v_max_f32_e32 v147, v115, v115
	v_mov_b32_e32 v144, v246
	v_max_f32_e32 v147, v148, v147
	v_max3_f32 v146, v116, v117, v146
	v_max3_f32 v147, v112, v113, v147
	v_max3_f32 v145, v145, v146, v147
	v_mul_f32_e32 v144, v145, v144
	ds_bpermute_b32 v145, v209, v144
	s_waitcnt lgkmcnt(0)
	v_max_f32_e32 v145, v145, v145
	v_max_f32_e32 v144, v144, v145
	ds_bpermute_b32 v145, v208, v144
	s_and_saveexec_b64 s[24:25], s[4:5]
	s_cbranch_execz .LBB0_1000
	s_waitcnt lgkmcnt(0)
	v_max_f32_e32 v145, v145, v145
	v_max_f32_e32 v144, v144, v144
	v_max_f32_e32 v144, v144, v145
	ds_write_b32 v210, v144
;     __device__ __forceinline__ void operator()(const f32x4 (&acc_)[2][2][4][2], const pg8::Unit& u, int wr, int wc, int fr, int fq) const {
;     ...
;             for (int m = 0; m < 4; ++m) { const float rs = row_rstd(ssq, row0 + ai * 128 + m * 16, fq); float mx = -3.0e38f;
; #pragma unroll
;                 for (int bj = 0; bj < 2; ++bj)
; #pragma unroll
;                     for (int n = 0; n < 2; ++n) { const f32x4 a = acc[ai][bj][m][n]; mx = fmaxf(mx, fmaxf(fmaxf(a[0], a[1]), fmaxf(a[2], a[3]))); }
;                 mx *= rs; mx = fmaxf(mx, __shfl_xor(mx, 16)); mx = fmaxf(mx, __shfl_xor(mx, 32));
;                 if (fq == 0) xch[(lrow0 + ai * 128 + m * 16) * 4 + wc] = mx; }
.LBB0_1000:
	s_or_b64 exec, exec, s[24:25]
	v_or_b32_e32 v144, 16, v142
	s_waitcnt lgkmcnt(0)
	v_ashrrev_i32_e32 v145, 31, v144
	v_lshlrev_b64 v[146:147], 6, v[144:145]
	v_lshl_add_u64 v[160:161], v[136:137], 0, v[146:147]
	s_nop 0
	v_max_f32_e32 v150, v98, v98
	s_waitcnt lgkmcnt(0)
	s_nop 3
	v_max_f32_e32 v148, v110, v110
	v_max_f32_e32 v149, v106, v106
	s_waitcnt lgkmcnt(0)
	s_nop 1
	s_waitcnt lgkmcnt(0)
	s_nop 0
	v_max_f32_e32 v147, v111, v111
	v_max_f32_e32 v147, v148, v147
	v_max_f32_e32 v148, v107, v107
	v_max_f32_e32 v148, v149, v148
	v_max3_f32 v147, v108, v109, v147
	v_max3_f32 v148, v104, v105, v148
	s_nop 0
	v_max3_f32 v147, v147, s2, v148
	v_max_f32_e32 v148, v103, v103
	v_max_f32_e32 v149, v102, v102
	v_max_f32_e32 v148, v149, v148
	v_max_f32_e32 v149, v99, v99
	v_mov_b32_e32 v146, v247
	v_max_f32_e32 v149, v150, v149
	v_max3_f32 v148, v100, v101, v148
	v_max3_f32 v149, v96, v97, v149
	v_max3_f32 v147, v147, v148, v149
	v_mul_f32_e32 v146, v147, v146
	ds_bpermute_b32 v147, v209, v146
	s_waitcnt lgkmcnt(0)
	v_max_f32_e32 v147, v147, v147
	v_max_f32_e32 v146, v146, v147
	ds_bpermute_b32 v147, v208, v146
	s_and_saveexec_b64 s[24:25], s[4:5]
	s_cbranch_execz .LBB0_1002
	s_waitcnt lgkmcnt(0)
	v_max_f32_e32 v147, v147, v147
	v_max_f32_e32 v146, v146, v146
	v_max_f32_e32 v146, v146, v147
	ds_write_b32 v210, v146 offset:256
.LBB0_1002:
	s_or_b64 exec, exec, s[24:25]
	v_or_b32_e32 v146, 32, v142
	s_waitcnt lgkmcnt(0)
	v_ashrrev_i32_e32 v147, 31, v146
	v_lshlrev_b64 v[148:149], 6, v[146:147]
	v_lshl_add_u64 v[162:163], v[136:137], 0, v[148:149]
	s_nop 0
	v_max_f32_e32 v152, v82, v82
	s_waitcnt lgkmcnt(0)
	s_nop 3
	v_max_f32_e32 v150, v94, v94
	v_max_f32_e32 v151, v90, v90
	s_waitcnt lgkmcnt(0)
	s_nop 1
	s_waitcnt lgkmcnt(0)
	s_nop 0
	v_max_f32_e32 v149, v95, v95
	v_max_f32_e32 v149, v150, v149
	v_max_f32_e32 v150, v91, v91
	v_max_f32_e32 v150, v151, v150
	v_max3_f32 v149, v92, v93, v149
	v_max3_f32 v150, v88, v89, v150
	s_nop 0
	v_max3_f32 v149, v149, s2, v150
	v_max_f32_e32 v150, v87, v87
	v_max_f32_e32 v151, v86, v86
	v_max_f32_e32 v150, v151, v150
	v_max_f32_e32 v151, v83, v83
	v_mov_b32_e32 v148, v248
	v_max_f32_e32 v151, v152, v151
	v_max3_f32 v150, v84, v85, v150
	v_max3_f32 v151, v80, v81, v151
	v_max3_f32 v149, v149, v150, v151
	v_mul_f32_e32 v148, v149, v148
	ds_bpermute_b32 v149, v209, v148
	s_waitcnt lgkmcnt(0)
	v_max_f32_e32 v149, v149, v149
	v_max_f32_e32 v148, v148, v149
	ds_bpermute_b32 v149, v208, v148
	s_mov_b64 s[24:25], exec
	s_and_b64 s[26:27], s[24:25], s[4:5]
	v_mov_b64_e32 v[242:243], v[196:197]
	v_mov_b64_e32 v[196:197], v[198:199]
	v_mov_b64_e32 v[198:199], v[200:201]
	v_mov_b64_e32 v[200:201], v[178:179]
	s_mov_b64 exec, s[26:27]
	s_cbranch_execz .LBB0_1004
	s_waitcnt lgkmcnt(0)
	v_max_f32_e32 v149, v149, v149
	v_max_f32_e32 v148, v148, v148
	v_max_f32_e32 v148, v148, v149
	ds_write_b32 v210, v148 offset:512
.LBB0_1004:
	s_or_b64 exec, exec, s[24:25]
	v_or_b32_e32 v148, 48, v142
	s_waitcnt lgkmcnt(0)
	v_ashrrev_i32_e32 v149, 31, v148
	v_lshlrev_b64 v[150:151], 6, v[148:149]
	v_lshl_add_u64 v[164:165], v[136:137], 0, v[150:151]
	s_nop 0
	v_max_f32_e32 v154, v66, v66
	s_waitcnt lgkmcnt(0)
	s_nop 3
	v_max_f32_e32 v152, v78, v78
	v_max_f32_e32 v153, v74, v74
	s_waitcnt lgkmcnt(0)
	s_nop 1
	s_waitcnt lgkmcnt(0)
	s_nop 0
	v_max_f32_e32 v151, v79, v79
	v_max_f32_e32 v151, v152, v151
	v_max_f32_e32 v152, v75, v75
	v_max_f32_e32 v152, v153, v152
	v_max3_f32 v151, v76, v77, v151
	v_max3_f32 v152, v72, v73, v152
	s_nop 0
	v_max3_f32 v151, v151, s2, v152
	v_max_f32_e32 v152, v71, v71
	v_max_f32_e32 v153, v70, v70
	v_max_f32_e32 v152, v153, v152
	v_max_f32_e32 v153, v67, v67
	v_mov_b32_e32 v150, v249
	v_max_f32_e32 v153, v154, v153
	v_max3_f32 v152, v68, v69, v152
	v_max3_f32 v153, v64, v65, v153
	v_max3_f32 v151, v151, v152, v153
	v_mul_f32_e32 v150, v151, v150
	ds_bpermute_b32 v151, v209, v150
	s_waitcnt lgkmcnt(0)
	v_max_f32_e32 v151, v151, v151
	v_max_f32_e32 v150, v150, v151
	ds_bpermute_b32 v151, v208, v150
	s_and_saveexec_b64 s[24:25], s[4:5]
	s_cbranch_execz .LBB0_1006
	s_waitcnt lgkmcnt(0)
	v_max_f32_e32 v151, v151, v151
	v_max_f32_e32 v150, v150, v150
	v_max_f32_e32 v150, v150, v151
	ds_write_b32 v210, v150 offset:768
.LBB0_1006:
	s_or_b64 exec, exec, s[24:25]
	v_add_u32_e32 v150, 0x80, v142
	s_waitcnt lgkmcnt(0)
	v_ashrrev_i32_e32 v151, 31, v150
	v_lshlrev_b64 v[152:153], 6, v[150:151]
	v_lshl_add_u64 v[166:167], v[136:137], 0, v[152:153]
	s_nop 0
	v_max_f32_e32 v156, v50, v50
	s_waitcnt lgkmcnt(0)
	s_nop 3
	v_max_f32_e32 v154, v62, v62
	v_max_f32_e32 v155, v58, v58
	s_waitcnt lgkmcnt(0)
	s_nop 1
	s_waitcnt lgkmcnt(0)
	s_nop 0
	v_max_f32_e32 v153, v63, v63
	v_max_f32_e32 v153, v154, v153
	v_max_f32_e32 v154, v59, v59
	v_max_f32_e32 v154, v155, v154
	v_max3_f32 v153, v60, v61, v153
	v_max3_f32 v154, v56, v57, v154
	s_nop 0
	v_max3_f32 v153, v153, s2, v154
	v_max_f32_e32 v154, v55, v55
	v_max_f32_e32 v155, v54, v54
	v_max_f32_e32 v154, v155, v154
	v_max_f32_e32 v155, v51, v51
	v_mov_b32_e32 v152, v250
	v_max_f32_e32 v155, v156, v155
	v_max3_f32 v154, v52, v53, v154
	v_max3_f32 v155, v48, v49, v155
	v_max3_f32 v153, v153, v154, v155
	v_mul_f32_e32 v152, v153, v152
	ds_bpermute_b32 v153, v209, v152
	s_waitcnt lgkmcnt(0)
	v_max_f32_e32 v153, v153, v153
	v_max_f32_e32 v152, v152, v153
	ds_bpermute_b32 v153, v208, v152
	s_and_saveexec_b64 s[24:25], s[4:5]
	s_cbranch_execz .LBB0_1008
	s_waitcnt lgkmcnt(0)
	v_max_f32_e32 v153, v153, v153
	v_max_f32_e32 v152, v152, v152
	v_max_f32_e32 v152, v152, v153
	ds_write_b32 v210, v152 offset:2048
; #define LAS __attribute__((address_space(3)))
;     __device__ __forceinline__ void operator()(const f32x4 (&acc_)[2][2][4][2], const pg8::Unit& u, int wr, int wc, int fr, int fq) const {
;     ...
;             for (int m = 0; m < 4; ++m) { const float rs = row_rstd(ssq, row0 + ai * 128 + m * 16, fq); float mx = -3.0e38f;
; #pragma unroll
;                 for (int bj = 0; bj < 2; ++bj)
; #pragma unroll
;                     for (int n = 0; n < 2; ++n) { const f32x4 a = acc[ai][bj][m][n]; mx = fmaxf(mx, fmaxf(fmaxf(a[0], a[1]), fmaxf(a[2], a[3]))); }
;                 mx *= rs; mx = fmaxf(mx, __shfl_xor(mx, 16)); mx = fmaxf(mx, __shfl_xor(mx, 32));
;                 if (fq == 0) xch[(lrow0 + ai * 128 + m * 16) * 4 + wc] = mx; }
;         asm volatile("s_waitcnt lgkmcnt(0)" ::: "memory"); __builtin_amdgcn_s_barrier(); asm volatile("" ::: "memory");
; #pragma unroll
;         for (int ai = 0; ai < 2; ++ai)
; #pragma unroll
;             for (int m = 0; m < 4; ++m) { const f32x4 x4 = *(const LAS f32x4*)(xch + (lrow0 + ai * 128 + m * 16) * 4); const float mrow = fmaxf(fmaxf(x4[0], x4[1]), fmaxf(x4[2], x4[3])), rs = row_rstd(ssq, row0 + ai * 128 + m * 16, fq); float sm = 0.f;
; #pragma unroll
;                 for (int bj = 0; bj < 2; ++bj)
; #pragma unroll
;                     for (int n = 0; n < 2; ++n) { f32x4 a = acc[ai][bj][m][n];
; #pragma unroll
;                         for (int i = 0; i < 4; ++i) { a[i] = __expf(a[i] * rs - mrow); sm += a[i]; }
;                         asm volatile("" ::: "memory");
;                         acc[ai][bj][m][n] = a; }
;                 sm += __shfl_xor(sm, 16); sm += __shfl_xor(sm, 32);
;                 if (fq == 0) xch[1024 + (lrow0 + ai * 128 + m * 16) * 4 + wc] = sm; }
.LBB0_1008:
	s_or_b64 exec, exec, s[24:25]
	v_add_u32_e32 v152, 0x90, v142
	s_waitcnt lgkmcnt(0)
	v_ashrrev_i32_e32 v153, 31, v152
	v_lshlrev_b64 v[154:155], 6, v[152:153]
	v_lshl_add_u64 v[168:169], v[136:137], 0, v[154:155]
	s_nop 0
	v_max_f32_e32 v170, v34, v34
	s_waitcnt lgkmcnt(0)
	s_nop 3
	v_max_f32_e32 v156, v46, v46
	v_max_f32_e32 v157, v42, v42
	s_waitcnt lgkmcnt(0)
	s_nop 1
	s_waitcnt lgkmcnt(0)
	s_nop 0
	v_max_f32_e32 v155, v47, v47
	v_max_f32_e32 v155, v156, v155
	v_max_f32_e32 v156, v43, v43
	v_max_f32_e32 v156, v157, v156
	v_max3_f32 v155, v44, v45, v155
	v_max3_f32 v156, v40, v41, v156
	s_nop 0
	v_max3_f32 v155, v155, s2, v156
	v_max_f32_e32 v156, v39, v39
	v_max_f32_e32 v157, v38, v38
	v_max_f32_e32 v156, v157, v156
	v_max_f32_e32 v157, v35, v35
	v_mov_b32_e32 v154, v251
	v_max_f32_e32 v157, v170, v157
	v_max3_f32 v156, v36, v37, v156
	v_max3_f32 v157, v32, v33, v157
	v_max3_f32 v155, v155, v156, v157
	v_mul_f32_e32 v154, v155, v154
	ds_bpermute_b32 v155, v209, v154
	s_waitcnt lgkmcnt(0)
	v_max_f32_e32 v155, v155, v155
	v_max_f32_e32 v154, v154, v155
	ds_bpermute_b32 v155, v208, v154
	s_and_saveexec_b64 s[24:25], s[4:5]
	s_cbranch_execz .LBB0_1010
	s_waitcnt lgkmcnt(0)
	v_max_f32_e32 v155, v155, v155
	v_max_f32_e32 v154, v154, v154
	v_max_f32_e32 v154, v154, v155
	ds_write_b32 v210, v154 offset:2304
.LBB0_1010:
	s_or_b64 exec, exec, s[24:25]
	v_add_u32_e32 v154, 0xa0, v142
	s_waitcnt lgkmcnt(0)
	v_ashrrev_i32_e32 v155, 31, v154
	v_lshlrev_b64 v[156:157], 6, v[154:155]
	v_lshl_add_u64 v[170:171], v[136:137], 0, v[156:157]
	s_nop 0
	v_max_f32_e32 v172, v30, v30
	v_max_f32_e32 v173, v26, v26
	v_max_f32_e32 v194, v18, v18
	s_waitcnt lgkmcnt(0)
	s_nop 3
	s_waitcnt lgkmcnt(0)
	s_nop 1
	s_waitcnt lgkmcnt(0)
	s_nop 0
	v_max_f32_e32 v157, v31, v31
	v_max_f32_e32 v157, v172, v157
	v_max_f32_e32 v172, v27, v27
	v_max_f32_e32 v172, v173, v172
	v_max3_f32 v157, v28, v29, v157
	v_max3_f32 v172, v24, v25, v172
	s_nop 0
	v_max3_f32 v157, v157, s2, v172
	v_max_f32_e32 v172, v23, v23
	v_max_f32_e32 v173, v22, v22
	v_max_f32_e32 v172, v173, v172
	v_max_f32_e32 v173, v19, v19
	v_mov_b32_e32 v156, v252
	v_max_f32_e32 v173, v194, v173
	v_max3_f32 v172, v20, v21, v172
	v_max3_f32 v173, v16, v17, v173
	v_max3_f32 v157, v157, v172, v173
	v_mul_f32_e32 v156, v157, v156
	ds_bpermute_b32 v157, v209, v156
	s_waitcnt lgkmcnt(0)
	v_max_f32_e32 v157, v157, v157
	v_max_f32_e32 v156, v156, v157
	ds_bpermute_b32 v157, v208, v156
	s_and_saveexec_b64 s[24:25], s[4:5]
	s_cbranch_execz .LBB0_1012
	s_waitcnt lgkmcnt(0)
	v_max_f32_e32 v157, v157, v157
	v_max_f32_e32 v156, v156, v156
	v_max_f32_e32 v156, v156, v157
	ds_write_b32 v210, v156 offset:2560
.LBB0_1012:
	s_or_b64 exec, exec, s[24:25]
	v_add_u32_e32 v156, 0xb0, v142
	s_waitcnt lgkmcnt(0)
	v_ashrrev_i32_e32 v157, 31, v156
	v_lshlrev_b64 v[172:173], 6, v[156:157]
	v_lshl_add_u64 v[172:173], v[136:137], 0, v[172:173]
	s_nop 0
	v_max_f32_e32 v211, v14, v14
	s_waitcnt lgkmcnt(0)
	s_nop 3
	v_max_f32_e32 v218, v10, v10
	v_max_f32_e32 v219, v2, v2
	s_waitcnt lgkmcnt(0)
	s_nop 1
	s_waitcnt lgkmcnt(0)
	s_nop 0
	v_max_f32_e32 v195, v15, v15
	v_max_f32_e32 v195, v211, v195
	v_max_f32_e32 v211, v11, v11
	v_max_f32_e32 v211, v218, v211
	v_max3_f32 v195, v12, v13, v195
	v_max3_f32 v211, v8, v9, v211
	s_nop 0
	v_max3_f32 v195, v195, s2, v211
	v_max_f32_e32 v211, v7, v7
	v_max_f32_e32 v218, v6, v6
	v_max_f32_e32 v211, v218, v211
	v_max_f32_e32 v218, v3, v3
	v_mov_b32_e32 v194, v253
	v_max_f32_e32 v218, v219, v218
	v_max3_f32 v211, v4, v5, v211
	v_max3_f32 v218, v0, v1, v218
	v_max3_f32 v195, v195, v211, v218
	v_mul_f32_e32 v194, v195, v194
	ds_bpermute_b32 v195, v209, v194
	s_waitcnt lgkmcnt(0)
	v_max_f32_e32 v195, v195, v195
	v_max_f32_e32 v211, v194, v195
	ds_bpermute_b32 v218, v208, v211
	s_and_saveexec_b64 s[24:25], s[4:5]
	s_cbranch_execz .LBB0_1014
	s_waitcnt lgkmcnt(0)
	v_max_f32_e32 v194, v218, v218
	v_max_f32_e32 v195, v211, v211
	v_max_f32_e32 v194, v195, v194
	ds_write_b32 v210, v194 offset:2816
.LBB0_1014:
	s_or_b64 exec, exec, s[24:25]
	s_waitcnt lgkmcnt(0)
	s_barrier
	s_waitcnt lgkmcnt(0)
	s_nop 0
	s_waitcnt lgkmcnt(0)
	s_nop 3
	ds_read_b128 v[218:221], v180
	s_nop 1
	s_waitcnt lgkmcnt(0)
	v_max_f32_e32 v194, v221, v221
	s_waitcnt lgkmcnt(0)
	s_nop 1
	s_waitcnt lgkmcnt(0)
	s_nop 1
	v_mov_b32_e32 v158, v246
	v_max_f32_e32 v159, v220, v220
	v_max_f32_e32 v159, v159, v194
	v_max3_f32 v159, v218, v219, v159
	v_fma_f32 v124, v124, v158, -v159
	v_fma_f32 v125, v125, v158, -v159
	v_fma_f32 v122, v122, v158, -v159
	v_mul_f32_e32 v124, 0x3fb8aa3b, v124
	v_fma_f32 v126, v126, v158, -v159
	v_fma_f32 v127, v127, v158, -v159
	v_fma_f32 v120, v120, v158, -v159
	v_fma_f32 v121, v121, v158, -v159
	v_fma_f32 v123, v123, v158, -v159
	v_fma_f32 v116, v116, v158, -v159
	v_fma_f32 v117, v117, v158, -v159
	v_fma_f32 v118, v118, v158, -v159
	v_fma_f32 v119, v119, v158, -v159
	v_fma_f32 v112, v112, v158, -v159
	v_fma_f32 v113, v113, v158, -v159
	v_fma_f32 v114, v114, v158, -v159
	v_fma_f32 v115, v115, v158, -v159
	v_mul_f32_e32 v125, 0x3fb8aa3b, v125
	v_mul_f32_e32 v158, 0x3fb8aa3b, v122
	v_exp_f32_e32 v122, v124
	v_mul_f32_e32 v126, 0x3fb8aa3b, v126
	v_mul_f32_e32 v159, 0x3fb8aa3b, v123
	v_exp_f32_e32 v123, v125
	v_mul_f32_e32 v127, 0x3fb8aa3b, v127
	v_exp_f32_e32 v126, v126
	v_mul_f32_e32 v120, 0x3fb8aa3b, v120
	v_mul_f32_e32 v117, 0x3fb8aa3b, v117
	v_exp_f32_e32 v127, v127
	v_mul_f32_e32 v121, 0x3fb8aa3b, v121
	v_mul_f32_e32 v195, 0x3fb8aa3b, v115
	v_exp_f32_e32 v120, v120
	v_exp_f32_e32 v115, v117
	v_add_f32_e32 v117, 0, v122
	v_exp_f32_e32 v121, v121
	v_add_f32_e32 v117, v123, v117
	v_exp_f32_e32 v124, v158
	v_add_f32_e32 v117, v126, v117
	v_mul_f32_e32 v116, 0x3fb8aa3b, v116
	v_exp_f32_e32 v125, v159
	v_add_f32_e32 v117, v127, v117
	v_mul_f32_e32 v194, 0x3fb8aa3b, v114
	v_exp_f32_e32 v114, v116
	v_add_f32_e32 v117, v120, v117
	v_mul_f32_e32 v118, 0x3fb8aa3b, v118
	v_add_f32_e32 v117, v121, v117
	v_mul_f32_e32 v119, 0x3fb8aa3b, v119
	v_exp_f32_e32 v118, v118
	v_add_f32_e32 v117, v124, v117
	v_mul_f32_e32 v112, 0x3fb8aa3b, v112
	v_exp_f32_e32 v119, v119
	v_add_f32_e32 v117, v125, v117
	v_mul_f32_e32 v113, 0x3fb8aa3b, v113
	v_exp_f32_e32 v112, v112
	v_add_f32_e32 v117, v114, v117
	v_exp_f32_e32 v113, v113
	v_add_f32_e32 v117, v115, v117
	v_exp_f32_e32 v116, v194
	v_add_f32_e32 v117, v118, v117
	v_add_f32_e32 v158, v119, v117
	v_exp_f32_e32 v117, v195
	v_add_f32_e32 v158, v112, v158
	v_add_f32_e32 v158, v113, v158
	v_add_f32_e32 v158, v116, v158
	v_add_f32_e32 v158, v117, v158
	ds_bpermute_b32 v159, v209, v158
	s_waitcnt lgkmcnt(0)
	v_add_f32_e32 v158, v158, v159
	ds_bpermute_b32 v159, v208, v158
	s_and_saveexec_b64 s[24:25], s[4:5]
	s_cbranch_execz .LBB0_1016
	s_waitcnt lgkmcnt(0)
	v_add_f32_e32 v158, v158, v159
	ds_write_b32 v181, v158 offset:4096
; #define LAS __attribute__((address_space(3)))
;     __device__ __forceinline__ void operator()(const f32x4 (&acc_)[2][2][4][2], const pg8::Unit& u, int wr, int wc, int fr, int fq) const {
;     ...
;             for (int m = 0; m < 4; ++m) { const f32x4 x4 = *(const LAS f32x4*)(xch + (lrow0 + ai * 128 + m * 16) * 4); const float mrow = fmaxf(fmaxf(x4[0], x4[1]), fmaxf(x4[2], x4[3])), rs = row_rstd(ssq, row0 + ai * 128 + m * 16, fq); float sm = 0.f;
; #pragma unroll
;                 for (int bj = 0; bj < 2; ++bj)
; #pragma unroll
;                     for (int n = 0; n < 2; ++n) { f32x4 a = acc[ai][bj][m][n];
; #pragma unroll
;                         for (int i = 0; i < 4; ++i) { a[i] = __expf(a[i] * rs - mrow); sm += a[i]; }
;                         asm volatile("" ::: "memory");
;                         acc[ai][bj][m][n] = a; }
;                 sm += __shfl_xor(sm, 16); sm += __shfl_xor(sm, 32);
;                 if (fq == 0) xch[1024 + (lrow0 + ai * 128 + m * 16) * 4 + wc] = sm; }
.LBB0_1016:
	s_or_b64 exec, exec, s[24:25]
	s_waitcnt lgkmcnt(0)
	s_nop 0
	s_waitcnt lgkmcnt(0)
	s_nop 3
	s_nop 0
	s_nop 1
	ds_read_b128 v[158:161], v182
	s_waitcnt lgkmcnt(0)
	s_nop 1
	s_waitcnt lgkmcnt(0)
	v_max_f32_e32 v161, v161, v161
	v_max_f32_e32 v160, v160, v160
	v_max_f32_e32 v160, v160, v161
	v_max3_f32 v158, v158, v159, v160
	s_waitcnt lgkmcnt(0)
	s_nop 1
	v_mov_b32_e32 v194, v247
	s_nop 0
	v_fma_f32 v108, v108, v194, -v158
	v_fma_f32 v109, v109, v194, -v158
	v_fma_f32 v106, v106, v194, -v158
	v_mul_f32_e32 v108, 0x3fb8aa3b, v108
	v_fma_f32 v110, v110, v194, -v158
	v_fma_f32 v111, v111, v194, -v158
	v_fma_f32 v104, v104, v194, -v158
	v_fma_f32 v105, v105, v194, -v158
	v_fma_f32 v107, v107, v194, -v158
	v_fma_f32 v100, v100, v194, -v158
	v_fma_f32 v101, v101, v194, -v158
	v_fma_f32 v102, v102, v194, -v158
	v_fma_f32 v103, v103, v194, -v158
	v_fma_f32 v96, v96, v194, -v158
	v_fma_f32 v97, v97, v194, -v158
	v_fma_f32 v98, v98, v194, -v158
	v_fma_f32 v99, v99, v194, -v158
	v_mul_f32_e32 v109, 0x3fb8aa3b, v109
	v_mul_f32_e32 v158, 0x3fb8aa3b, v106
	v_exp_f32_e32 v106, v108
	v_mul_f32_e32 v110, 0x3fb8aa3b, v110
	v_mul_f32_e32 v159, 0x3fb8aa3b, v107
	v_exp_f32_e32 v107, v109
	v_mul_f32_e32 v111, 0x3fb8aa3b, v111
	v_exp_f32_e32 v110, v110
	v_mul_f32_e32 v104, 0x3fb8aa3b, v104
	v_mul_f32_e32 v101, 0x3fb8aa3b, v101
	v_exp_f32_e32 v111, v111
	v_mul_f32_e32 v105, 0x3fb8aa3b, v105
	v_mul_f32_e32 v161, 0x3fb8aa3b, v99
	v_exp_f32_e32 v104, v104
	v_exp_f32_e32 v99, v101
	v_add_f32_e32 v101, 0, v106
	v_exp_f32_e32 v105, v105
	v_add_f32_e32 v101, v107, v101
	v_exp_f32_e32 v108, v158
	v_add_f32_e32 v101, v110, v101
	v_mul_f32_e32 v100, 0x3fb8aa3b, v100
	v_exp_f32_e32 v109, v159
	v_add_f32_e32 v101, v111, v101
	v_mul_f32_e32 v160, 0x3fb8aa3b, v98
	v_exp_f32_e32 v98, v100
	v_add_f32_e32 v101, v104, v101
	v_mul_f32_e32 v102, 0x3fb8aa3b, v102
	v_add_f32_e32 v101, v105, v101
	v_mul_f32_e32 v103, 0x3fb8aa3b, v103
	v_exp_f32_e32 v102, v102
	v_add_f32_e32 v101, v108, v101
	v_mul_f32_e32 v96, 0x3fb8aa3b, v96
	v_exp_f32_e32 v103, v103
	v_add_f32_e32 v101, v109, v101
	v_mul_f32_e32 v97, 0x3fb8aa3b, v97
	v_exp_f32_e32 v96, v96
	v_add_f32_e32 v101, v98, v101
	v_exp_f32_e32 v97, v97
	v_add_f32_e32 v101, v99, v101
	v_exp_f32_e32 v100, v160
	v_add_f32_e32 v101, v102, v101
	v_add_f32_e32 v158, v103, v101
	v_exp_f32_e32 v101, v161
	v_add_f32_e32 v158, v96, v158
	v_add_f32_e32 v158, v97, v158
	v_add_f32_e32 v158, v100, v158
	v_add_f32_e32 v158, v101, v158
	ds_bpermute_b32 v159, v209, v158
	s_waitcnt lgkmcnt(0)
	v_add_f32_e32 v158, v158, v159
	ds_bpermute_b32 v159, v208, v158
	s_and_saveexec_b64 s[24:25], s[4:5]
	s_cbranch_execz .LBB0_1018
	s_waitcnt lgkmcnt(0)
	v_add_f32_e32 v158, v158, v159
	ds_write_b32 v183, v158 offset:4096
.LBB0_1018:
	s_or_b64 exec, exec, s[24:25]
	s_waitcnt lgkmcnt(0)
	s_nop 0
	s_waitcnt lgkmcnt(0)
	s_nop 3
	s_nop 0
	s_nop 1
	ds_read_b128 v[158:161], v184
	s_waitcnt lgkmcnt(0)
	s_nop 1
	s_waitcnt lgkmcnt(0)
	v_max_f32_e32 v161, v161, v161
	v_max_f32_e32 v160, v160, v160
	v_max_f32_e32 v160, v160, v161
	v_max3_f32 v158, v158, v159, v160
	s_waitcnt lgkmcnt(0)
	s_nop 1
	v_mov_b32_e32 v162, v248
	s_nop 0
	v_fma_f32 v92, v92, v162, -v158
	v_fma_f32 v93, v93, v162, -v158
	v_fma_f32 v90, v90, v162, -v158
	v_mul_f32_e32 v92, 0x3fb8aa3b, v92
	v_fma_f32 v94, v94, v162, -v158
	v_fma_f32 v95, v95, v162, -v158
	v_fma_f32 v88, v88, v162, -v158
	v_fma_f32 v89, v89, v162, -v158
	v_fma_f32 v91, v91, v162, -v158
	v_fma_f32 v84, v84, v162, -v158
	v_fma_f32 v85, v85, v162, -v158
	v_fma_f32 v86, v86, v162, -v158
	v_fma_f32 v87, v87, v162, -v158
	v_fma_f32 v80, v80, v162, -v158
	v_fma_f32 v81, v81, v162, -v158
	v_fma_f32 v82, v82, v162, -v158
	v_fma_f32 v83, v83, v162, -v158
	v_mul_f32_e32 v93, 0x3fb8aa3b, v93
	v_mul_f32_e32 v158, 0x3fb8aa3b, v90
	v_exp_f32_e32 v90, v92
	v_mul_f32_e32 v94, 0x3fb8aa3b, v94
	v_mul_f32_e32 v159, 0x3fb8aa3b, v91
	v_exp_f32_e32 v91, v93
	v_mul_f32_e32 v95, 0x3fb8aa3b, v95
	v_exp_f32_e32 v94, v94
	v_mul_f32_e32 v88, 0x3fb8aa3b, v88
	v_mul_f32_e32 v85, 0x3fb8aa3b, v85
	v_exp_f32_e32 v95, v95
	v_mul_f32_e32 v89, 0x3fb8aa3b, v89
	v_mul_f32_e32 v161, 0x3fb8aa3b, v83
	v_exp_f32_e32 v88, v88
	v_exp_f32_e32 v83, v85
	v_add_f32_e32 v85, 0, v90
	v_exp_f32_e32 v89, v89
	v_add_f32_e32 v85, v91, v85
	v_exp_f32_e32 v92, v158
	v_add_f32_e32 v85, v94, v85
	v_mul_f32_e32 v84, 0x3fb8aa3b, v84
	v_exp_f32_e32 v93, v159
	v_add_f32_e32 v85, v95, v85
	v_mul_f32_e32 v160, 0x3fb8aa3b, v82
	v_exp_f32_e32 v82, v84
	v_add_f32_e32 v85, v88, v85
	v_mul_f32_e32 v86, 0x3fb8aa3b, v86
	v_add_f32_e32 v85, v89, v85
	v_mul_f32_e32 v87, 0x3fb8aa3b, v87
	v_exp_f32_e32 v86, v86
	v_add_f32_e32 v85, v92, v85
	v_mul_f32_e32 v80, 0x3fb8aa3b, v80
	v_exp_f32_e32 v87, v87
	v_add_f32_e32 v85, v93, v85
	v_mul_f32_e32 v81, 0x3fb8aa3b, v81
	v_exp_f32_e32 v80, v80
	v_add_f32_e32 v85, v82, v85
	v_exp_f32_e32 v81, v81
	v_add_f32_e32 v85, v83, v85
	v_exp_f32_e32 v84, v160
	v_add_f32_e32 v85, v86, v85
	v_add_f32_e32 v158, v87, v85
	v_exp_f32_e32 v85, v161
	v_add_f32_e32 v158, v80, v158
	v_add_f32_e32 v158, v81, v158
	v_add_f32_e32 v158, v84, v158
	v_add_f32_e32 v158, v85, v158
	ds_bpermute_b32 v159, v209, v158
	s_waitcnt lgkmcnt(0)
	v_add_f32_e32 v158, v158, v159
	ds_bpermute_b32 v159, v208, v158
	s_and_saveexec_b64 s[24:25], s[4:5]
	s_cbranch_execz .LBB0_1020
	s_waitcnt lgkmcnt(0)
	v_add_f32_e32 v158, v158, v159
	ds_write_b32 v185, v158 offset:4096
; #define LAS __attribute__((address_space(3)))
;     __device__ __forceinline__ void operator()(const f32x4 (&acc_)[2][2][4][2], const pg8::Unit& u, int wr, int wc, int fr, int fq) const {
;     ...
;             for (int m = 0; m < 4; ++m) { const f32x4 x4 = *(const LAS f32x4*)(xch + (lrow0 + ai * 128 + m * 16) * 4); const float mrow = fmaxf(fmaxf(x4[0], x4[1]), fmaxf(x4[2], x4[3])), rs = row_rstd(ssq, row0 + ai * 128 + m * 16, fq); float sm = 0.f;
; #pragma unroll
;                 for (int bj = 0; bj < 2; ++bj)
; #pragma unroll
;                     for (int n = 0; n < 2; ++n) { f32x4 a = acc[ai][bj][m][n];
; #pragma unroll
;                         for (int i = 0; i < 4; ++i) { a[i] = __expf(a[i] * rs - mrow); sm += a[i]; }
;                         asm volatile("" ::: "memory");
;                         acc[ai][bj][m][n] = a; }
;                 sm += __shfl_xor(sm, 16); sm += __shfl_xor(sm, 32);
;                 if (fq == 0) xch[1024 + (lrow0 + ai * 128 + m * 16) * 4 + wc] = sm; }
.LBB0_1020:
	s_or_b64 exec, exec, s[24:25]
	s_waitcnt lgkmcnt(0)
	s_nop 0
	s_waitcnt lgkmcnt(0)
	s_nop 3
	s_nop 0
	s_nop 1
	ds_read_b128 v[158:161], v186
	s_waitcnt lgkmcnt(0)
	s_nop 1
	s_waitcnt lgkmcnt(0)
	v_max_f32_e32 v161, v161, v161
	v_max_f32_e32 v160, v160, v160
	v_max_f32_e32 v160, v160, v161
	v_max3_f32 v158, v158, v159, v160
	s_waitcnt lgkmcnt(0)
	s_nop 1
	v_mov_b32_e32 v162, v249
	s_nop 0
	v_fma_f32 v76, v76, v162, -v158
	v_fma_f32 v77, v77, v162, -v158
	v_fma_f32 v74, v74, v162, -v158
	v_mul_f32_e32 v76, 0x3fb8aa3b, v76
	v_fma_f32 v78, v78, v162, -v158
	v_fma_f32 v79, v79, v162, -v158
	v_fma_f32 v72, v72, v162, -v158
	v_fma_f32 v73, v73, v162, -v158
	v_fma_f32 v75, v75, v162, -v158
	v_fma_f32 v68, v68, v162, -v158
	v_fma_f32 v69, v69, v162, -v158
	v_fma_f32 v70, v70, v162, -v158
	v_fma_f32 v71, v71, v162, -v158
	v_fma_f32 v64, v64, v162, -v158
	v_fma_f32 v65, v65, v162, -v158
	v_fma_f32 v66, v66, v162, -v158
	v_fma_f32 v67, v67, v162, -v158
	v_mul_f32_e32 v77, 0x3fb8aa3b, v77
	v_mul_f32_e32 v158, 0x3fb8aa3b, v74
	v_exp_f32_e32 v74, v76
	v_mul_f32_e32 v78, 0x3fb8aa3b, v78
	v_mul_f32_e32 v159, 0x3fb8aa3b, v75
	v_exp_f32_e32 v75, v77
	v_mul_f32_e32 v79, 0x3fb8aa3b, v79
	v_exp_f32_e32 v78, v78
	v_mul_f32_e32 v72, 0x3fb8aa3b, v72
	v_mul_f32_e32 v69, 0x3fb8aa3b, v69
	v_exp_f32_e32 v79, v79
	v_mul_f32_e32 v73, 0x3fb8aa3b, v73
	v_mul_f32_e32 v161, 0x3fb8aa3b, v67
	v_exp_f32_e32 v72, v72
	v_exp_f32_e32 v67, v69
	v_add_f32_e32 v69, 0, v74
	v_exp_f32_e32 v73, v73
	v_add_f32_e32 v69, v75, v69
	v_exp_f32_e32 v76, v158
	v_add_f32_e32 v69, v78, v69
	v_mul_f32_e32 v68, 0x3fb8aa3b, v68
	v_exp_f32_e32 v77, v159
	v_add_f32_e32 v69, v79, v69
	v_mul_f32_e32 v160, 0x3fb8aa3b, v66
	v_exp_f32_e32 v66, v68
	v_add_f32_e32 v69, v72, v69
	v_mul_f32_e32 v70, 0x3fb8aa3b, v70
	v_add_f32_e32 v69, v73, v69
	v_mul_f32_e32 v71, 0x3fb8aa3b, v71
	v_exp_f32_e32 v70, v70
	v_add_f32_e32 v69, v76, v69
	v_mul_f32_e32 v64, 0x3fb8aa3b, v64
	v_exp_f32_e32 v71, v71
	v_add_f32_e32 v69, v77, v69
	v_mul_f32_e32 v65, 0x3fb8aa3b, v65
	v_exp_f32_e32 v64, v64
	v_add_f32_e32 v69, v66, v69
	v_exp_f32_e32 v65, v65
	v_add_f32_e32 v69, v67, v69
	v_exp_f32_e32 v68, v160
	v_add_f32_e32 v69, v70, v69
	v_add_f32_e32 v158, v71, v69
	v_exp_f32_e32 v69, v161
	v_add_f32_e32 v158, v64, v158
	v_add_f32_e32 v158, v65, v158
	v_add_f32_e32 v158, v68, v158
	v_add_f32_e32 v158, v69, v158
	ds_bpermute_b32 v159, v209, v158
	s_waitcnt lgkmcnt(0)
	v_add_f32_e32 v158, v158, v159
	ds_bpermute_b32 v159, v208, v158
	s_and_saveexec_b64 s[24:25], s[4:5]
	s_cbranch_execz .LBB0_1022
	s_waitcnt lgkmcnt(0)
	v_add_f32_e32 v158, v158, v159
	ds_write_b32 v187, v158 offset:4096
.LBB0_1022:
	s_or_b64 exec, exec, s[24:25]
	s_waitcnt lgkmcnt(0)
	s_nop 0
	s_waitcnt lgkmcnt(0)
	s_nop 3
	s_nop 0
	s_nop 1
	ds_read_b128 v[158:161], v188
	s_waitcnt lgkmcnt(0)
	s_nop 1
	s_waitcnt lgkmcnt(0)
	v_max_f32_e32 v161, v161, v161
	v_max_f32_e32 v160, v160, v160
	v_max_f32_e32 v160, v160, v161
	v_max3_f32 v158, v158, v159, v160
	s_waitcnt lgkmcnt(0)
	s_nop 1
	v_mov_b32_e32 v162, v250
	s_nop 0
	v_fma_f32 v60, v60, v162, -v158
	v_fma_f32 v61, v61, v162, -v158
	v_fma_f32 v58, v58, v162, -v158
	v_mul_f32_e32 v60, 0x3fb8aa3b, v60
	v_fma_f32 v62, v62, v162, -v158
	v_fma_f32 v63, v63, v162, -v158
	v_fma_f32 v56, v56, v162, -v158
	v_fma_f32 v57, v57, v162, -v158
	v_fma_f32 v59, v59, v162, -v158
	v_fma_f32 v52, v52, v162, -v158
	v_fma_f32 v53, v53, v162, -v158
	v_fma_f32 v54, v54, v162, -v158
	v_fma_f32 v55, v55, v162, -v158
	v_fma_f32 v48, v48, v162, -v158
	v_fma_f32 v49, v49, v162, -v158
	v_fma_f32 v50, v50, v162, -v158
	v_fma_f32 v51, v51, v162, -v158
	v_mul_f32_e32 v61, 0x3fb8aa3b, v61
	v_mul_f32_e32 v158, 0x3fb8aa3b, v58
	v_exp_f32_e32 v58, v60
	v_mul_f32_e32 v62, 0x3fb8aa3b, v62
	v_mul_f32_e32 v159, 0x3fb8aa3b, v59
	v_exp_f32_e32 v59, v61
	v_mul_f32_e32 v63, 0x3fb8aa3b, v63
	v_exp_f32_e32 v62, v62
	v_mul_f32_e32 v56, 0x3fb8aa3b, v56
	v_mul_f32_e32 v53, 0x3fb8aa3b, v53
	v_exp_f32_e32 v63, v63
	v_mul_f32_e32 v57, 0x3fb8aa3b, v57
	v_mul_f32_e32 v161, 0x3fb8aa3b, v51
	v_exp_f32_e32 v56, v56
	v_exp_f32_e32 v51, v53
	v_add_f32_e32 v53, 0, v58
	v_exp_f32_e32 v57, v57
	v_add_f32_e32 v53, v59, v53
	v_exp_f32_e32 v60, v158
	v_add_f32_e32 v53, v62, v53
	v_mul_f32_e32 v52, 0x3fb8aa3b, v52
	v_exp_f32_e32 v61, v159
	v_add_f32_e32 v53, v63, v53
	v_mul_f32_e32 v160, 0x3fb8aa3b, v50
	v_exp_f32_e32 v50, v52
	v_add_f32_e32 v53, v56, v53
	v_mul_f32_e32 v54, 0x3fb8aa3b, v54
	v_add_f32_e32 v53, v57, v53
	v_mul_f32_e32 v55, 0x3fb8aa3b, v55
	v_exp_f32_e32 v54, v54
	v_add_f32_e32 v53, v60, v53
	v_mul_f32_e32 v48, 0x3fb8aa3b, v48
	v_exp_f32_e32 v55, v55
	v_add_f32_e32 v53, v61, v53
	v_mul_f32_e32 v49, 0x3fb8aa3b, v49
	v_exp_f32_e32 v48, v48
	v_add_f32_e32 v53, v50, v53
	v_exp_f32_e32 v49, v49
	v_add_f32_e32 v53, v51, v53
	v_exp_f32_e32 v52, v160
	v_add_f32_e32 v53, v54, v53
	v_add_f32_e32 v158, v55, v53
	v_exp_f32_e32 v53, v161
	v_add_f32_e32 v158, v48, v158
	v_add_f32_e32 v158, v49, v158
	v_add_f32_e32 v158, v52, v158
	v_add_f32_e32 v158, v53, v158
	ds_bpermute_b32 v159, v209, v158
	s_waitcnt lgkmcnt(0)
	v_add_f32_e32 v158, v158, v159
	ds_bpermute_b32 v159, v208, v158
	s_and_saveexec_b64 s[24:25], s[4:5]
	s_cbranch_execz .LBB0_1024
	s_waitcnt lgkmcnt(0)
	v_add_f32_e32 v158, v158, v159
	ds_write_b32 v189, v158 offset:4096
; #define LAS __attribute__((address_space(3)))
;     __device__ __forceinline__ void operator()(const f32x4 (&acc_)[2][2][4][2], const pg8::Unit& u, int wr, int wc, int fr, int fq) const {
;     ...
;             for (int m = 0; m < 4; ++m) { const f32x4 x4 = *(const LAS f32x4*)(xch + (lrow0 + ai * 128 + m * 16) * 4); const float mrow = fmaxf(fmaxf(x4[0], x4[1]), fmaxf(x4[2], x4[3])), rs = row_rstd(ssq, row0 + ai * 128 + m * 16, fq); float sm = 0.f;
; #pragma unroll
;                 for (int bj = 0; bj < 2; ++bj)
; #pragma unroll
;                     for (int n = 0; n < 2; ++n) { f32x4 a = acc[ai][bj][m][n];
; #pragma unroll
;                         for (int i = 0; i < 4; ++i) { a[i] = __expf(a[i] * rs - mrow); sm += a[i]; }
;                         asm volatile("" ::: "memory");
;                         acc[ai][bj][m][n] = a; }
;                 sm += __shfl_xor(sm, 16); sm += __shfl_xor(sm, 32);
;                 if (fq == 0) xch[1024 + (lrow0 + ai * 128 + m * 16) * 4 + wc] = sm; }
.LBB0_1024:
	s_or_b64 exec, exec, s[24:25]
	s_waitcnt lgkmcnt(0)
	s_nop 0
	s_waitcnt lgkmcnt(0)
	s_nop 3
	s_nop 0
	s_nop 1
	ds_read_b128 v[158:161], v190
	s_waitcnt lgkmcnt(0)
	s_nop 1
	s_waitcnt lgkmcnt(0)
	v_max_f32_e32 v161, v161, v161
	v_max_f32_e32 v160, v160, v160
	v_max_f32_e32 v160, v160, v161
	v_max3_f32 v158, v158, v159, v160
	s_waitcnt lgkmcnt(0)
	s_nop 1
	v_mov_b32_e32 v162, v251
	s_nop 0
	v_fma_f32 v44, v44, v162, -v158
	v_fma_f32 v45, v45, v162, -v158
	v_fma_f32 v42, v42, v162, -v158
	v_mul_f32_e32 v44, 0x3fb8aa3b, v44
	v_fma_f32 v46, v46, v162, -v158
	v_fma_f32 v47, v47, v162, -v158
	v_fma_f32 v40, v40, v162, -v158
	v_fma_f32 v41, v41, v162, -v158
	v_fma_f32 v43, v43, v162, -v158
	v_fma_f32 v36, v36, v162, -v158
	v_fma_f32 v37, v37, v162, -v158
	v_fma_f32 v38, v38, v162, -v158
	v_fma_f32 v39, v39, v162, -v158
	v_fma_f32 v32, v32, v162, -v158
	v_fma_f32 v33, v33, v162, -v158
	v_fma_f32 v34, v34, v162, -v158
	v_fma_f32 v35, v35, v162, -v158
	v_mul_f32_e32 v45, 0x3fb8aa3b, v45
	v_mul_f32_e32 v158, 0x3fb8aa3b, v42
	v_exp_f32_e32 v42, v44
	v_mul_f32_e32 v46, 0x3fb8aa3b, v46
	v_mul_f32_e32 v159, 0x3fb8aa3b, v43
	v_exp_f32_e32 v43, v45
	v_mul_f32_e32 v47, 0x3fb8aa3b, v47
	v_exp_f32_e32 v46, v46
	v_mul_f32_e32 v40, 0x3fb8aa3b, v40
	v_mul_f32_e32 v37, 0x3fb8aa3b, v37
	v_exp_f32_e32 v47, v47
	v_mul_f32_e32 v41, 0x3fb8aa3b, v41
	v_mul_f32_e32 v161, 0x3fb8aa3b, v35
	v_exp_f32_e32 v40, v40
	v_exp_f32_e32 v35, v37
	v_add_f32_e32 v37, 0, v42
	v_exp_f32_e32 v41, v41
	v_add_f32_e32 v37, v43, v37
	v_exp_f32_e32 v44, v158
	v_add_f32_e32 v37, v46, v37
	v_mul_f32_e32 v36, 0x3fb8aa3b, v36
	v_exp_f32_e32 v45, v159
	v_add_f32_e32 v37, v47, v37
	v_mul_f32_e32 v160, 0x3fb8aa3b, v34
	v_exp_f32_e32 v34, v36
	v_add_f32_e32 v37, v40, v37
	v_mul_f32_e32 v38, 0x3fb8aa3b, v38
	v_add_f32_e32 v37, v41, v37
	v_mul_f32_e32 v39, 0x3fb8aa3b, v39
	v_exp_f32_e32 v38, v38
	v_add_f32_e32 v37, v44, v37
	v_mul_f32_e32 v32, 0x3fb8aa3b, v32
	v_exp_f32_e32 v39, v39
	v_add_f32_e32 v37, v45, v37
	v_mul_f32_e32 v33, 0x3fb8aa3b, v33
	v_exp_f32_e32 v32, v32
	v_add_f32_e32 v37, v34, v37
	v_exp_f32_e32 v33, v33
	v_add_f32_e32 v37, v35, v37
	v_exp_f32_e32 v36, v160
	v_add_f32_e32 v37, v38, v37
	v_add_f32_e32 v158, v39, v37
	v_exp_f32_e32 v37, v161
	v_add_f32_e32 v158, v32, v158
	v_add_f32_e32 v158, v33, v158
	v_add_f32_e32 v158, v36, v158
	v_add_f32_e32 v158, v37, v158
	ds_bpermute_b32 v159, v209, v158
	s_waitcnt lgkmcnt(0)
	v_add_f32_e32 v158, v158, v159
	ds_bpermute_b32 v159, v208, v158
	s_and_saveexec_b64 s[24:25], s[4:5]
	s_cbranch_execz .LBB0_1026
	s_waitcnt lgkmcnt(0)
	v_add_f32_e32 v158, v158, v159
	ds_write_b32 v191, v158 offset:4096
; #define LAS __attribute__((address_space(3)))
;     __device__ __forceinline__ void operator()(const f32x4 (&acc_)[2][2][4][2], const pg8::Unit& u, int wr, int wc, int fr, int fq) const {
;     ...
;             for (int m = 0; m < 4; ++m) { const f32x4 x4 = *(const LAS f32x4*)(xch + (lrow0 + ai * 128 + m * 16) * 4); const float mrow = fmaxf(fmaxf(x4[0], x4[1]), fmaxf(x4[2], x4[3])), rs = row_rstd(ssq, row0 + ai * 128 + m * 16, fq); float sm = 0.f;
; #pragma unroll
;                 for (int bj = 0; bj < 2; ++bj)
; #pragma unroll
;                     for (int n = 0; n < 2; ++n) { f32x4 a = acc[ai][bj][m][n];
; #pragma unroll
;                         for (int i = 0; i < 4; ++i) { a[i] = __expf(a[i] * rs - mrow); sm += a[i]; }
;                         asm volatile("" ::: "memory");
;                         acc[ai][bj][m][n] = a; }
;                 sm += __shfl_xor(sm, 16); sm += __shfl_xor(sm, 32);
;                 if (fq == 0) xch[1024 + (lrow0 + ai * 128 + m * 16) * 4 + wc] = sm; }
.LBB0_1026:
	s_or_b64 exec, exec, s[24:25]
	s_waitcnt lgkmcnt(0)
	s_nop 0
	s_waitcnt lgkmcnt(0)
	s_nop 3
	s_nop 0
	s_nop 1
	ds_read_b128 v[158:161], v202
	s_waitcnt lgkmcnt(0)
	s_nop 1
	s_waitcnt lgkmcnt(0)
	v_max_f32_e32 v161, v161, v161
	v_max_f32_e32 v160, v160, v160
	v_max_f32_e32 v160, v160, v161
	v_max3_f32 v158, v158, v159, v160
	s_waitcnt lgkmcnt(0)
	s_nop 1
	v_mov_b32_e32 v162, v252
	s_nop 0
	v_fma_f32 v28, v28, v162, -v158
	v_fma_f32 v29, v29, v162, -v158
	v_fma_f32 v26, v26, v162, -v158
	v_mul_f32_e32 v28, 0x3fb8aa3b, v28
	v_fma_f32 v30, v30, v162, -v158
	v_fma_f32 v31, v31, v162, -v158
	v_fma_f32 v24, v24, v162, -v158
	v_fma_f32 v25, v25, v162, -v158
	v_fma_f32 v27, v27, v162, -v158
	v_fma_f32 v20, v20, v162, -v158
	v_fma_f32 v21, v21, v162, -v158
	v_fma_f32 v22, v22, v162, -v158
	v_fma_f32 v23, v23, v162, -v158
	v_fma_f32 v16, v16, v162, -v158
	v_fma_f32 v17, v17, v162, -v158
	v_fma_f32 v18, v18, v162, -v158
	v_fma_f32 v19, v19, v162, -v158
	v_mul_f32_e32 v29, 0x3fb8aa3b, v29
	v_mul_f32_e32 v158, 0x3fb8aa3b, v26
	v_exp_f32_e32 v26, v28
	v_mul_f32_e32 v30, 0x3fb8aa3b, v30
	v_mul_f32_e32 v159, 0x3fb8aa3b, v27
	v_exp_f32_e32 v27, v29
	v_mul_f32_e32 v31, 0x3fb8aa3b, v31
	v_exp_f32_e32 v30, v30
	v_mul_f32_e32 v24, 0x3fb8aa3b, v24
	v_mul_f32_e32 v21, 0x3fb8aa3b, v21
	v_exp_f32_e32 v31, v31
	v_mul_f32_e32 v25, 0x3fb8aa3b, v25
	v_mul_f32_e32 v161, 0x3fb8aa3b, v19
	v_exp_f32_e32 v24, v24
	v_exp_f32_e32 v19, v21
	v_add_f32_e32 v21, 0, v26
	v_exp_f32_e32 v25, v25
	v_add_f32_e32 v21, v27, v21
	v_exp_f32_e32 v28, v158
	v_add_f32_e32 v21, v30, v21
	v_mul_f32_e32 v20, 0x3fb8aa3b, v20
	v_exp_f32_e32 v29, v159
	v_add_f32_e32 v21, v31, v21
	v_mul_f32_e32 v160, 0x3fb8aa3b, v18
	v_exp_f32_e32 v18, v20
	v_add_f32_e32 v21, v24, v21
	v_mul_f32_e32 v22, 0x3fb8aa3b, v22
	v_add_f32_e32 v21, v25, v21
	v_mul_f32_e32 v23, 0x3fb8aa3b, v23
	v_exp_f32_e32 v22, v22
	v_add_f32_e32 v21, v28, v21
	v_mul_f32_e32 v16, 0x3fb8aa3b, v16
	v_exp_f32_e32 v23, v23
	v_add_f32_e32 v21, v29, v21
	v_mul_f32_e32 v17, 0x3fb8aa3b, v17
	v_exp_f32_e32 v16, v16
	v_add_f32_e32 v21, v18, v21
	v_exp_f32_e32 v17, v17
	v_add_f32_e32 v21, v19, v21
	v_exp_f32_e32 v20, v160
	v_add_f32_e32 v21, v22, v21
	v_add_f32_e32 v158, v23, v21
	v_exp_f32_e32 v21, v161
	v_add_f32_e32 v158, v16, v158
	v_add_f32_e32 v158, v17, v158
	v_add_f32_e32 v158, v20, v158
	v_add_f32_e32 v158, v21, v158
	ds_bpermute_b32 v159, v209, v158
	s_waitcnt lgkmcnt(0)
	v_add_f32_e32 v158, v158, v159
	ds_bpermute_b32 v159, v208, v158
	s_and_saveexec_b64 s[24:25], s[4:5]
	s_cbranch_execz .LBB0_1028
	s_waitcnt lgkmcnt(0)
	v_add_f32_e32 v158, v158, v159
	ds_write_b32 v204, v158 offset:4096
.LBB0_1028:
	s_or_b64 exec, exec, s[24:25]
	s_waitcnt lgkmcnt(0)
	s_nop 0
	s_waitcnt lgkmcnt(0)
	s_nop 3
	s_nop 0
	s_nop 1
	ds_read_b128 v[158:161], v205
	s_waitcnt lgkmcnt(0)
	s_nop 1
	s_waitcnt lgkmcnt(0)
	v_max_f32_e32 v161, v161, v161
	v_max_f32_e32 v160, v160, v160
	v_max_f32_e32 v160, v160, v161
	v_max3_f32 v158, v158, v159, v160
	s_waitcnt lgkmcnt(0)
	s_nop 1
	v_mov_b32_e32 v162, v253
	s_nop 0
	v_fma_f32 v12, v12, v162, -v158
	v_fma_f32 v13, v13, v162, -v158
	v_fma_f32 v10, v10, v162, -v158
	v_mul_f32_e32 v12, 0x3fb8aa3b, v12
	v_fma_f32 v14, v14, v162, -v158
	v_fma_f32 v15, v15, v162, -v158
	v_fma_f32 v8, v8, v162, -v158
	v_fma_f32 v9, v9, v162, -v158
	v_fma_f32 v11, v11, v162, -v158
	v_fma_f32 v4, v4, v162, -v158
	v_fma_f32 v5, v5, v162, -v158
	v_fma_f32 v6, v6, v162, -v158
	v_fma_f32 v7, v7, v162, -v158
	v_fma_f32 v0, v0, v162, -v158
	v_fma_f32 v1, v1, v162, -v158
	v_fma_f32 v2, v2, v162, -v158
	v_fma_f32 v3, v3, v162, -v158
	v_mul_f32_e32 v13, 0x3fb8aa3b, v13
	v_mul_f32_e32 v158, 0x3fb8aa3b, v10
	v_exp_f32_e32 v10, v12
	v_mul_f32_e32 v14, 0x3fb8aa3b, v14
	v_mul_f32_e32 v159, 0x3fb8aa3b, v11
	v_exp_f32_e32 v11, v13
	v_mul_f32_e32 v15, 0x3fb8aa3b, v15
	v_exp_f32_e32 v14, v14
	v_mul_f32_e32 v8, 0x3fb8aa3b, v8
	v_mul_f32_e32 v5, 0x3fb8aa3b, v5
	v_exp_f32_e32 v15, v15
	v_mul_f32_e32 v9, 0x3fb8aa3b, v9
	v_mul_f32_e32 v161, 0x3fb8aa3b, v3
	v_exp_f32_e32 v8, v8
	v_exp_f32_e32 v3, v5
	v_add_f32_e32 v5, 0, v10
	v_exp_f32_e32 v9, v9
	v_add_f32_e32 v5, v11, v5
	v_exp_f32_e32 v12, v158
	v_add_f32_e32 v5, v14, v5
	v_mul_f32_e32 v4, 0x3fb8aa3b, v4
	v_exp_f32_e32 v13, v159
	v_add_f32_e32 v5, v15, v5
	v_mul_f32_e32 v160, 0x3fb8aa3b, v2
	v_exp_f32_e32 v2, v4
	v_add_f32_e32 v5, v8, v5
	v_mul_f32_e32 v6, 0x3fb8aa3b, v6
	v_add_f32_e32 v5, v9, v5
	v_mul_f32_e32 v7, 0x3fb8aa3b, v7
	v_exp_f32_e32 v6, v6
	v_add_f32_e32 v5, v12, v5
	v_mul_f32_e32 v0, 0x3fb8aa3b, v0
	v_exp_f32_e32 v7, v7
	v_add_f32_e32 v5, v13, v5
	v_mul_f32_e32 v1, 0x3fb8aa3b, v1
	v_exp_f32_e32 v0, v0
	v_add_f32_e32 v5, v2, v5
	v_exp_f32_e32 v1, v1
	v_add_f32_e32 v5, v3, v5
	v_exp_f32_e32 v4, v160
	v_add_f32_e32 v5, v6, v5
	v_add_f32_e32 v158, v7, v5
	v_exp_f32_e32 v5, v161
	v_add_f32_e32 v158, v0, v158
	v_add_f32_e32 v158, v1, v158
	v_add_f32_e32 v158, v4, v158
	v_add_f32_e32 v158, v5, v158
	ds_bpermute_b32 v159, v209, v158
	s_waitcnt lgkmcnt(0)
	v_add_f32_e32 v158, v158, v159
	ds_bpermute_b32 v159, v208, v158
	s_and_saveexec_b64 s[24:25], s[4:5]
	s_cbranch_execz .LBB0_1030
	s_waitcnt lgkmcnt(0)
	v_add_f32_e32 v158, v158, v159
	ds_write_b32 v206, v158 offset:4096

; __device__ __forceinline__ void row_rstd4(const float* ssq, int row0, int fq, float (&rs)[4]) {
;     f32x4 v[4];
; #pragma unroll
;     for (int m = 0; m < 4; ++m) v[m] = *(const f32x4*)(ssq + (size_t)(row0 + m * 16) * 16 + fq * 4);
; #pragma unroll
;     for (int m = 0; m < 4; ++m) { float t = (v[m][0] + v[m][1]) + (v[m][2] + v[m][3]); t += __shfl_xor(t, 16); t += __shfl_xor(t, 32); rs[m] = __builtin_amdgcn_rsqf(t * (1.f / DM) + EPS); }
; }
;     __device__ __forceinline__ void operator()(const f32x4 (&acc)[2][2][4][2], const pg8::Unit& u, int wr, int wc, int fr, int fq) const {
;         const int row0 = u.pm * 256 + wr * 64 + fr, col0 = u.pn * 128 + wc * 32 + 8 * fq;
; #pragma unroll
;         for (int ai = 0; ai < 2; ++ai) { float rsv[4]; row_rstd4(ssq, row0 + ai * 128, fq, rsv);
; #pragma unroll
;             for (int m = 0; m < 4; ++m) {
;                 const int row = row0 + ai * 128 + m * 16; const float rs = rsv[m], c = -rs * LOG2E, rs2 = rs * rs;
;                 f32x4 e0 = acc[ai][0][m][0] * c, e1 = acc[ai][0][m][1] * c;
; #pragma unroll
;                 for (int i = 0; i < 4; ++i) { e0[i] = __builtin_amdgcn_exp2f(e0[i]); e1[i] = __builtin_amdgcn_exp2f(e1[i]); }
;                 e0 = e0 + 1.0f; e1 = e1 + 1.0f;
; #pragma unroll
;                 for (int i = 0; i < 4; ++i) { e0[i] = __builtin_amdgcn_rcpf(e0[i]); e1[i] = __builtin_amdgcn_rcpf(e1[i]); }
;                 const f32x4 h0 = (acc[ai][0][m][0] * acc[ai][1][m][0]) * rs2 * e0, h1 = (acc[ai][0][m][1] * acc[ai][1][m][1]) * rs2 * e1;
.LBB0_1224:
	v_lshl_add_u32 v240, s20, 8, v148
	v_mov_b32_e32 v172, v240
	v_ashrrev_i32_e32 v173, 31, v172
	v_lshlrev_b64 v[172:173], 6, v[172:173]
	v_lshl_add_u64 v[172:173], v[134:135], 0, v[172:173]
	global_load_dwordx4 v[172:175], v[172:173], off
	v_add_u32_e32 v176, 16, v240
	v_ashrrev_i32_e32 v177, 31, v176
	v_lshlrev_b64 v[176:177], 6, v[176:177]
	v_lshl_add_u64 v[176:177], v[134:135], 0, v[176:177]
	global_load_dwordx4 v[176:179], v[176:177], off
	v_add_u32_e32 v180, 32, v240
	v_ashrrev_i32_e32 v181, 31, v180
	v_lshlrev_b64 v[180:181], 6, v[180:181]
	v_lshl_add_u64 v[180:181], v[134:135], 0, v[180:181]
	global_load_dwordx4 v[180:183], v[180:181], off
	v_add_u32_e32 v184, 48, v240
	v_ashrrev_i32_e32 v185, 31, v184
	v_lshlrev_b64 v[184:185], 6, v[184:185]
	v_lshl_add_u64 v[184:185], v[134:135], 0, v[184:185]
	global_load_dwordx4 v[184:187], v[184:185], off
	v_add_u32_e32 v188, 0x80, v240
	v_ashrrev_i32_e32 v189, 31, v188
	v_lshlrev_b64 v[188:189], 6, v[188:189]
	v_lshl_add_u64 v[188:189], v[134:135], 0, v[188:189]
	global_load_dwordx4 v[188:191], v[188:189], off
	v_add_u32_e32 v218, 0x90, v240
	v_ashrrev_i32_e32 v219, 31, v218
	v_lshlrev_b64 v[218:219], 6, v[218:219]
	v_lshl_add_u64 v[218:219], v[134:135], 0, v[218:219]
	global_load_dwordx4 v[218:221], v[218:219], off
	v_add_u32_e32 v222, 0xa0, v240
	v_ashrrev_i32_e32 v223, 31, v222
	v_lshlrev_b64 v[222:223], 6, v[222:223]
	v_lshl_add_u64 v[222:223], v[134:135], 0, v[222:223]
	global_load_dwordx4 v[222:225], v[222:223], off
	v_add_u32_e32 v226, 0xb0, v240
	v_ashrrev_i32_e32 v227, 31, v226
	v_lshlrev_b64 v[226:227], 6, v[226:227]
	v_lshl_add_u64 v[226:227], v[134:135], 0, v[226:227]
	global_load_dwordx4 v[226:229], v[226:227], off
	v_xor_b32_e32 v238, 16, v215
	v_xor_b32_e32 v239, 32, v215
	v_lshlrev_b32_e32 v238, 2, v238
	v_lshlrev_b32_e32 v239, 2, v239
	v_lshl_add_u32 v140, s20, 8, v148
	v_or_b32_e32 v146, 16, v140
	v_ashrrev_i32_e32 v141, 31, v140
	v_ashrrev_i32_e32 v147, 31, v146
	v_lshlrev_b64 v[142:143], 6, v[140:141]
	v_lshlrev_b64 v[144:145], 6, v[146:147]
	v_lshl_add_u64 v[142:143], v[134:135], 0, v[142:143]
	v_lshl_add_u64 v[144:145], v[134:135], 0, v[144:145]
	s_nop 1
	v_or_b32_e32 v144, 32, v140
	v_ashrrev_i32_e32 v145, 31, v144
	v_lshlrev_b64 v[142:143], 6, v[144:145]
	v_lshl_add_u64 v[142:143], v[134:135], 0, v[142:143]
	s_nop 0
	v_or_b32_e32 v142, 48, v140
	v_ashrrev_i32_e32 v143, 31, v142
	v_lshlrev_b64 v[164:165], 6, v[142:143]
	v_lshl_add_u64 v[164:165], v[134:135], 0, v[164:165]
	s_nop 0
	v_and_b32_e32 v143, 64, v215
	v_xor_b32_e32 v141, 16, v215
	v_add_u32_e32 v143, 64, v143
	v_xor_b32_e32 v145, 32, v215
	v_cmp_lt_i32_e32 vcc, v141, v143
	v_pk_mul_f32 v[126:127], v[118:119], v[126:127]
	v_pk_mul_f32 v[124:125], v[116:117], v[124:125]
	v_cndmask_b32_e32 v141, v215, v141, vcc
	v_cmp_lt_i32_e32 vcc, v145, v143
	v_lshlrev_b32_e32 v141, 2, v141
	v_pk_mul_f32 v[120:121], v[112:113], v[120:121]
	v_cndmask_b32_e32 v143, v215, v145, vcc
	v_lshlrev_b32_e32 v143, 2, v143
	v_pk_mul_f32 v[122:123], v[114:115], v[122:123]
	v_lshl_or_b32 v168, s66, 7, v150
	v_ashrrev_i32_e32 v169, 31, v168
	v_pk_mul_f32 v[100:101], v[108:109], v[100:101]
	v_pk_mul_f32 v[102:103], v[110:111], v[102:103]
	v_pk_mul_f32 v[98:99], v[106:107], v[98:99]
	v_pk_mul_f32 v[96:97], v[104:105], v[96:97]
	v_pk_mul_f32 v[84:85], v[92:93], v[84:85]
	v_pk_mul_f32 v[86:87], v[94:95], v[86:87]
	v_pk_mul_f32 v[82:83], v[90:91], v[82:83]
	v_pk_mul_f32 v[80:81], v[88:89], v[80:81]
	v_pk_mul_f32 v[68:69], v[76:77], v[68:69]
	v_pk_mul_f32 v[70:71], v[78:79], v[70:71]
	v_pk_mul_f32 v[66:67], v[74:75], v[66:67]
	v_pk_mul_f32 v[64:65], v[72:73], v[64:65]
	v_pk_mul_f32 v[52:53], v[60:61], v[52:53]
	v_pk_mul_f32 v[54:55], v[62:63], v[54:55]
	v_pk_mul_f32 v[50:51], v[58:59], v[50:51]
	v_pk_mul_f32 v[48:49], v[56:57], v[48:49]
	v_pk_mul_f32 v[36:37], v[44:45], v[36:37]
	v_pk_mul_f32 v[38:39], v[46:47], v[38:39]
	v_pk_mul_f32 v[34:35], v[42:43], v[34:35]
	v_pk_mul_f32 v[32:33], v[40:41], v[32:33]
	v_pk_mul_f32 v[20:21], v[28:29], v[20:21]
	v_pk_mul_f32 v[22:23], v[30:31], v[22:23]
	v_pk_mul_f32 v[18:19], v[26:27], v[18:19]
	v_pk_mul_f32 v[16:17], v[24:25], v[16:17]
	v_pk_mul_f32 v[4:5], v[12:13], v[4:5]
	v_pk_mul_f32 v[6:7], v[14:15], v[6:7]
	v_pk_mul_f32 v[2:3], v[10:11], v[2:3]
	v_pk_mul_f32 v[0:1], v[8:9], v[0:1]
	s_andn2_b64 vcc, exec, s[4:5]
	s_mov_b64 s[4:5], -1
	s_waitcnt vmcnt(0)
	v_add_f32_e32 v172, v172, v173
	v_add_f32_e32 v174, v174, v175
	v_add_f32_e32 v176, v176, v177
	v_add_f32_e32 v178, v178, v179
	v_add_f32_e32 v180, v180, v181
	v_add_f32_e32 v182, v182, v183
	v_add_f32_e32 v184, v184, v185
	v_add_f32_e32 v186, v186, v187
	v_add_f32_e32 v188, v188, v189
	v_add_f32_e32 v190, v190, v191
	v_add_f32_e32 v218, v218, v219
	v_add_f32_e32 v220, v220, v221
	v_add_f32_e32 v222, v222, v223
	v_add_f32_e32 v224, v224, v225
	v_add_f32_e32 v226, v226, v227
	v_add_f32_e32 v228, v228, v229
	v_add_f32_e32 v172, v172, v174
	v_add_f32_e32 v176, v176, v178
	v_add_f32_e32 v180, v180, v182
	v_add_f32_e32 v184, v184, v186
	v_add_f32_e32 v188, v188, v190
	v_add_f32_e32 v218, v218, v220
	v_add_f32_e32 v222, v222, v224
	v_add_f32_e32 v226, v226, v228
	ds_bpermute_b32 v173, v238, v172
	ds_bpermute_b32 v177, v238, v176
	ds_bpermute_b32 v181, v238, v180
	ds_bpermute_b32 v185, v238, v184
	ds_bpermute_b32 v189, v238, v188
	ds_bpermute_b32 v219, v238, v218
	ds_bpermute_b32 v223, v238, v222
	ds_bpermute_b32 v227, v238, v226
	s_waitcnt lgkmcnt(0)
; __device__ __forceinline__ unsigned cvt_pk_bf16(float lo, float hi) { const f32x2cv v = {lo, hi}; const bf16x2cv b = __builtin_convertvector(v, bf16x2cv); return __builtin_bit_cast(unsigned, b); }
; __device__ __forceinline__ void row_rstd4(const float* ssq, int row0, int fq, float (&rs)[4]) {
;     ...
;     for (int m = 0; m < 4; ++m) { float t = (v[m][0] + v[m][1]) + (v[m][2] + v[m][3]); t += __shfl_xor(t, 16); t += __shfl_xor(t, 32); rs[m] = __builtin_amdgcn_rsqf(t * (1.f / DM) + EPS); }
; }
; __device__ __forceinline__ v4u pack8(const f32x4 a, const f32x4 b) { v4u w; w.x = cvt_pk_bf16(a[0], a[1]); w.y = cvt_pk_bf16(a[2], a[3]); w.z = cvt_pk_bf16(b[0], b[1]); w.w = cvt_pk_bf16(b[2], b[3]); return w; }
;     __device__ __forceinline__ void operator()(const f32x4 (&acc)[2][2][4][2], const pg8::Unit& u, int wr, int wc, int fr, int fq) const {
;         const int row0 = u.pm * 256 + wr * 64 + fr, col0 = u.pn * 128 + wc * 32 + 8 * fq;
; #pragma unroll
;         for (int ai = 0; ai < 2; ++ai) { float rsv[4]; row_rstd4(ssq, row0 + ai * 128, fq, rsv);
; #pragma unroll
;             for (int m = 0; m < 4; ++m) {
;                 const int row = row0 + ai * 128 + m * 16; const float rs = rsv[m], c = -rs * LOG2E, rs2 = rs * rs;
;                 f32x4 e0 = acc[ai][0][m][0] * c, e1 = acc[ai][0][m][1] * c;
; #pragma unroll
;                 for (int i = 0; i < 4; ++i) { e0[i] = __builtin_amdgcn_exp2f(e0[i]); e1[i] = __builtin_amdgcn_exp2f(e1[i]); }
;                 e0 = e0 + 1.0f; e1 = e1 + 1.0f;
; #pragma unroll
;                 for (int i = 0; i < 4; ++i) { e0[i] = __builtin_amdgcn_rcpf(e0[i]); e1[i] = __builtin_amdgcn_rcpf(e1[i]); }
;                 const f32x4 h0 = (acc[ai][0][m][0] * acc[ai][1][m][0]) * rs2 * e0, h1 = (acc[ai][0][m][1] * acc[ai][1][m][1]) * rs2 * e1;
;                 *(v4u*)(O + (size_t)row * FFH + col0) = pack8(h0, h1);
	v_add_f32_e32 v172, v172, v173
	v_add_f32_e32 v176, v176, v177
	v_add_f32_e32 v180, v180, v181
	v_add_f32_e32 v184, v184, v185
	v_add_f32_e32 v188, v188, v189
	v_add_f32_e32 v218, v218, v219
	v_add_f32_e32 v222, v222, v223
	v_add_f32_e32 v226, v226, v227
	ds_bpermute_b32 v173, v239, v172
	ds_bpermute_b32 v177, v239, v176
	ds_bpermute_b32 v181, v239, v180
	ds_bpermute_b32 v185, v239, v184
	ds_bpermute_b32 v189, v239, v188
	ds_bpermute_b32 v219, v239, v218
	ds_bpermute_b32 v223, v239, v222
	ds_bpermute_b32 v227, v239, v226
	s_waitcnt lgkmcnt(0)
	v_add_f32_e32 v172, v172, v173
	v_add_f32_e32 v176, v176, v177
	v_add_f32_e32 v180, v180, v181
	v_add_f32_e32 v184, v184, v185
	v_add_f32_e32 v188, v188, v189
	v_add_f32_e32 v218, v218, v219
	v_add_f32_e32 v222, v222, v223
	v_add_f32_e32 v226, v226, v227
	v_fmamk_f32 v172, v172, 0x3a800000, v212
	v_fmamk_f32 v176, v176, 0x3a800000, v212
	v_fmamk_f32 v180, v180, 0x3a800000, v212
	v_fmamk_f32 v184, v184, 0x3a800000, v212
	v_fmamk_f32 v188, v188, 0x3a800000, v212
	v_fmamk_f32 v218, v218, 0x3a800000, v212
	v_fmamk_f32 v222, v222, 0x3a800000, v212
	v_fmamk_f32 v226, v226, 0x3a800000, v212
	v_rsq_f32_e32 v230, v172
	v_rsq_f32_e32 v231, v176
	v_rsq_f32_e32 v232, v180
	v_rsq_f32_e32 v233, v184
	v_rsq_f32_e32 v234, v188
	v_rsq_f32_e32 v235, v218
	v_rsq_f32_e32 v236, v222
	v_rsq_f32_e32 v237, v226
	s_nop 0
	s_waitcnt lgkmcnt(0)
	s_nop 4
	s_waitcnt lgkmcnt(0)
	s_nop 1
	s_waitcnt lgkmcnt(0)
	s_nop 0
	s_waitcnt lgkmcnt(0)
	s_nop 0
	s_waitcnt lgkmcnt(0)
	s_nop 3
	s_waitcnt lgkmcnt(0)
	s_nop 1
	s_waitcnt lgkmcnt(0)
	s_nop 0
	s_waitcnt lgkmcnt(0)
	s_nop 0
	s_waitcnt lgkmcnt(0)
	s_nop 0
	v_mov_b32_e32 v145, v230
	s_nop 0
	v_mov_b32_e32 v153, v233
	s_nop 0
	v_mov_b32_e32 v155, v232
	v_mul_f32_e32 v152, 0xbfb8aa3b, v145
	v_pk_mul_f32 v[118:119], v[118:119], v[152:153] op_sel_hi:[1,0]
	v_pk_mul_f32 v[116:117], v[116:117], v[152:153] op_sel_hi:[1,0]
	v_pk_mul_f32 v[112:113], v[112:113], v[152:153] op_sel_hi:[1,0]
	v_pk_mul_f32 v[114:115], v[114:115], v[152:153] op_sel_hi:[1,0]
	v_exp_f32_e32 v116, v116
	v_exp_f32_e32 v112, v112
	v_exp_f32_e32 v117, v117
	v_exp_f32_e32 v118, v118
	v_exp_f32_e32 v119, v119
	v_exp_f32_e32 v113, v113
	v_exp_f32_e32 v114, v114
	v_exp_f32_e32 v115, v115
	v_pk_add_f32 v[118:119], v[118:119], 1.0 op_sel_hi:[1,0]
	v_pk_add_f32 v[116:117], v[116:117], 1.0 op_sel_hi:[1,0]
	v_pk_add_f32 v[112:113], v[112:113], 1.0 op_sel_hi:[1,0]
	v_pk_add_f32 v[114:115], v[114:115], 1.0 op_sel_hi:[1,0]
	v_rcp_f32_e32 v116, v116
	v_rcp_f32_e32 v112, v112
	v_rcp_f32_e32 v117, v117
	v_rcp_f32_e32 v118, v118
	v_rcp_f32_e32 v119, v119
	v_rcp_f32_e32 v113, v113
	v_rcp_f32_e32 v114, v114
	v_rcp_f32_e32 v115, v115
	v_mul_f32_e32 v154, v145, v145
	s_nop 0
	v_pk_mul_f32 v[124:125], v[124:125], v[154:155] op_sel_hi:[1,0]
	v_pk_mul_f32 v[126:127], v[126:127], v[154:155] op_sel_hi:[1,0]
	v_pk_mul_f32 v[120:121], v[120:121], v[154:155] op_sel_hi:[1,0]
	v_mov_b32_e32 v147, v231
	v_pk_mul_f32 v[122:123], v[122:123], v[154:155] op_sel_hi:[1,0]
	v_pk_mul_f32 v[118:119], v[126:127], v[118:119]
	v_pk_mul_f32 v[116:117], v[124:125], v[116:117]
	v_pk_mul_f32 v[112:113], v[120:121], v[112:113]
	v_pk_mul_f32 v[114:115], v[122:123], v[114:115]
	v_cvt_pk_bf16_f32 v116, v116, v117
	v_cvt_pk_bf16_f32 v117, v118, v119
	v_cvt_pk_bf16_f32 v118, v112, v113
	v_mov_b64_e32 v[112:113], s[8:9]
	v_cvt_pk_bf16_f32 v119, v114, v115
	v_mad_i64_i32 v[120:121], s[22:23], v140, s3, v[112:113]
	v_lshlrev_b64 v[114:115], 1, v[168:169]
	v_lshl_add_u64 v[120:121], v[120:121], 0, v[114:115]
	global_store_dwordx4 v[120:121], v[116:119], off
	v_mul_f32_e32 v124, v147, v147
	v_pk_mul_f32 v[100:101], v[100:101], v[124:125] op_sel_hi:[1,0]
	v_mul_f32_e32 v116, 0xbfb8aa3b, v147
	v_pk_mul_f32 v[120:121], v[108:109], v[116:117] op_sel_hi:[1,0]
	v_pk_mul_f32 v[118:119], v[110:111], v[116:117] op_sel_hi:[1,0]
	v_pk_mul_f32 v[122:123], v[106:107], v[116:117] op_sel_hi:[1,0]
	v_pk_mul_f32 v[116:117], v[104:105], v[116:117] op_sel_hi:[1,0]
	v_exp_f32_e32 v120, v120
	v_exp_f32_e32 v121, v121
	v_exp_f32_e32 v116, v116
	v_exp_f32_e32 v118, v118
	v_exp_f32_e32 v119, v119
	v_exp_f32_e32 v122, v122
	v_exp_f32_e32 v123, v123
	v_exp_f32_e32 v117, v117
	v_pk_add_f32 v[120:121], v[120:121], 1.0 op_sel_hi:[1,0]
	v_pk_add_f32 v[118:119], v[118:119], 1.0 op_sel_hi:[1,0]
	v_pk_add_f32 v[122:123], v[122:123], 1.0 op_sel_hi:[1,0]
	v_pk_add_f32 v[116:117], v[116:117], 1.0 op_sel_hi:[1,0]
	v_rcp_f32_e32 v120, v120
	v_rcp_f32_e32 v121, v121
	v_rcp_f32_e32 v116, v116
	v_rcp_f32_e32 v117, v117
	v_rcp_f32_e32 v118, v118
	v_rcp_f32_e32 v122, v122
	v_rcp_f32_e32 v119, v119
	v_rcp_f32_e32 v123, v123
	v_pk_mul_f32 v[102:103], v[102:103], v[124:125] op_sel_hi:[1,0]
	v_pk_mul_f32 v[100:101], v[100:101], v[120:121]
	v_pk_mul_f32 v[96:97], v[96:97], v[124:125] op_sel_hi:[1,0]
	v_pk_mul_f32 v[98:99], v[98:99], v[124:125] op_sel_hi:[1,0]
	v_pk_mul_f32 v[102:103], v[102:103], v[118:119]
	v_pk_mul_f32 v[104:105], v[98:99], v[122:123]
	v_pk_mul_f32 v[98:99], v[96:97], v[116:117]
	v_cvt_pk_bf16_f32 v96, v100, v101
	v_mad_i64_i32 v[100:101], s[22:23], v146, s3, v[112:113]
	v_cvt_pk_bf16_f32 v97, v102, v103
	v_cvt_pk_bf16_f32 v98, v98, v99
	v_cvt_pk_bf16_f32 v99, v104, v105
	v_lshl_add_u64 v[100:101], v[100:101], 0, v[114:115]
	global_store_dwordx4 v[100:101], v[96:99], off
	v_mul_f32_e32 v104, v155, v155
	v_pk_mul_f32 v[84:85], v[84:85], v[104:105] op_sel_hi:[1,0]
	v_mul_f32_e32 v96, 0xbfb8aa3b, v155
	v_pk_mul_f32 v[100:101], v[92:93], v[96:97] op_sel_hi:[1,0]
	v_pk_mul_f32 v[98:99], v[94:95], v[96:97] op_sel_hi:[1,0]
	v_pk_mul_f32 v[102:103], v[90:91], v[96:97] op_sel_hi:[1,0]
; __device__ __forceinline__ v4u pack8(const f32x4 a, const f32x4 b) { v4u w; w.x = cvt_pk_bf16(a[0], a[1]); w.y = cvt_pk_bf16(a[2], a[3]); w.z = cvt_pk_bf16(b[0], b[1]); w.w = cvt_pk_bf16(b[2], b[3]); return w; }
;     __device__ __forceinline__ void operator()(const f32x4 (&acc)[2][2][4][2], const pg8::Unit& u, int wr, int wc, int fr, int fq) const {
;     ...
;                 const int row = row0 + ai * 128 + m * 16; const float rs = rsv[m], c = -rs * LOG2E, rs2 = rs * rs;
;                 f32x4 e0 = acc[ai][0][m][0] * c, e1 = acc[ai][0][m][1] * c;
; #pragma unroll
;                 for (int i = 0; i < 4; ++i) { e0[i] = __builtin_amdgcn_exp2f(e0[i]); e1[i] = __builtin_amdgcn_exp2f(e1[i]); }
;                 e0 = e0 + 1.0f; e1 = e1 + 1.0f;
; #pragma unroll
;                 for (int i = 0; i < 4; ++i) { e0[i] = __builtin_amdgcn_rcpf(e0[i]); e1[i] = __builtin_amdgcn_rcpf(e1[i]); }
;                 const f32x4 h0 = (acc[ai][0][m][0] * acc[ai][1][m][0]) * rs2 * e0, h1 = (acc[ai][0][m][1] * acc[ai][1][m][1]) * rs2 * e1;
;                 *(v4u*)(O + (size_t)row * FFH + col0) = pack8(h0, h1);
	v_pk_mul_f32 v[96:97], v[88:89], v[96:97] op_sel_hi:[1,0]
	v_exp_f32_e32 v100, v100
	v_exp_f32_e32 v101, v101
	v_exp_f32_e32 v96, v96
	v_exp_f32_e32 v98, v98
	v_exp_f32_e32 v99, v99
	v_exp_f32_e32 v102, v102
	v_exp_f32_e32 v103, v103
	v_exp_f32_e32 v97, v97
	v_pk_add_f32 v[100:101], v[100:101], 1.0 op_sel_hi:[1,0]
	v_pk_add_f32 v[98:99], v[98:99], 1.0 op_sel_hi:[1,0]
	v_pk_add_f32 v[102:103], v[102:103], 1.0 op_sel_hi:[1,0]
	v_pk_add_f32 v[96:97], v[96:97], 1.0 op_sel_hi:[1,0]
	v_rcp_f32_e32 v100, v100
	v_rcp_f32_e32 v101, v101
	v_rcp_f32_e32 v96, v96
	v_rcp_f32_e32 v97, v97
	v_rcp_f32_e32 v98, v98
	v_rcp_f32_e32 v102, v102
	v_rcp_f32_e32 v99, v99
	v_rcp_f32_e32 v103, v103
	v_pk_mul_f32 v[86:87], v[86:87], v[104:105] op_sel_hi:[1,0]
	v_pk_mul_f32 v[84:85], v[84:85], v[100:101]
	v_pk_mul_f32 v[80:81], v[80:81], v[104:105] op_sel_hi:[1,0]
	v_pk_mul_f32 v[82:83], v[82:83], v[104:105] op_sel_hi:[1,0]
	v_pk_mul_f32 v[86:87], v[86:87], v[98:99]
	v_pk_mul_f32 v[88:89], v[82:83], v[102:103]
	v_pk_mul_f32 v[82:83], v[80:81], v[96:97]
	v_cvt_pk_bf16_f32 v80, v84, v85
	v_mad_i64_i32 v[84:85], s[22:23], v144, s3, v[112:113]
	v_cvt_pk_bf16_f32 v81, v86, v87
	v_cvt_pk_bf16_f32 v82, v82, v83
	v_cvt_pk_bf16_f32 v83, v88, v89
	v_lshl_add_u64 v[84:85], v[84:85], 0, v[114:115]
	global_store_dwordx4 v[84:85], v[80:83], off
	v_mul_f32_e32 v88, v153, v153
	v_pk_mul_f32 v[68:69], v[68:69], v[88:89] op_sel_hi:[1,0]
	v_mul_f32_e32 v80, 0xbfb8aa3b, v153
	v_pk_mul_f32 v[84:85], v[76:77], v[80:81] op_sel_hi:[1,0]
	v_pk_mul_f32 v[82:83], v[78:79], v[80:81] op_sel_hi:[1,0]
	v_pk_mul_f32 v[86:87], v[74:75], v[80:81] op_sel_hi:[1,0]
	v_pk_mul_f32 v[80:81], v[72:73], v[80:81] op_sel_hi:[1,0]
	v_exp_f32_e32 v84, v84
	v_exp_f32_e32 v85, v85
	v_exp_f32_e32 v80, v80
	v_exp_f32_e32 v82, v82
	v_exp_f32_e32 v83, v83
	v_exp_f32_e32 v86, v86
	v_exp_f32_e32 v87, v87
	v_exp_f32_e32 v81, v81
	v_pk_add_f32 v[84:85], v[84:85], 1.0 op_sel_hi:[1,0]
	v_pk_add_f32 v[82:83], v[82:83], 1.0 op_sel_hi:[1,0]
	v_pk_add_f32 v[86:87], v[86:87], 1.0 op_sel_hi:[1,0]
	v_pk_add_f32 v[80:81], v[80:81], 1.0 op_sel_hi:[1,0]
	v_rcp_f32_e32 v84, v84
	v_rcp_f32_e32 v85, v85
	v_rcp_f32_e32 v80, v80
	v_rcp_f32_e32 v81, v81
	v_rcp_f32_e32 v82, v82
	v_rcp_f32_e32 v86, v86
	v_rcp_f32_e32 v83, v83
	v_rcp_f32_e32 v87, v87
	v_pk_mul_f32 v[70:71], v[70:71], v[88:89] op_sel_hi:[1,0]
	v_pk_mul_f32 v[68:69], v[68:69], v[84:85]
	v_pk_mul_f32 v[64:65], v[64:65], v[88:89] op_sel_hi:[1,0]
	v_pk_mul_f32 v[66:67], v[66:67], v[88:89] op_sel_hi:[1,0]
	v_pk_mul_f32 v[70:71], v[70:71], v[82:83]
	v_pk_mul_f32 v[72:73], v[66:67], v[86:87]
	v_pk_mul_f32 v[66:67], v[64:65], v[80:81]
	v_cvt_pk_bf16_f32 v64, v68, v69
	v_mad_i64_i32 v[68:69], s[22:23], v142, s3, v[112:113]
	v_add_u32_e32 v84, 0x80, v140
	v_cvt_pk_bf16_f32 v65, v70, v71
	v_cvt_pk_bf16_f32 v66, v66, v67
	v_cvt_pk_bf16_f32 v67, v72, v73
	v_lshl_add_u64 v[68:69], v[68:69], 0, v[114:115]
	v_ashrrev_i32_e32 v85, 31, v84
	global_store_dwordx4 v[68:69], v[64:67], off
	v_add_u32_e32 v86, 0x90, v140
	v_ashrrev_i32_e32 v87, 31, v86
	v_lshlrev_b64 v[64:65], 6, v[84:85]
	v_lshl_add_u64 v[64:65], v[134:135], 0, v[64:65]
	s_nop 0
	v_lshlrev_b64 v[64:65], 6, v[86:87]
	v_lshl_add_u64 v[64:65], v[134:135], 0, v[64:65]
	s_nop 0
	v_add_u32_e32 v66, 0xa0, v140
	v_ashrrev_i32_e32 v67, 31, v66
	v_lshlrev_b64 v[64:65], 6, v[66:67]
	v_lshl_add_u64 v[64:65], v[134:135], 0, v[64:65]
	s_nop 0
	v_add_u32_e32 v64, 0xb0, v140
	v_ashrrev_i32_e32 v65, 31, v64
	v_lshlrev_b64 v[80:81], 6, v[64:65]
	v_lshl_add_u64 v[80:81], v[134:135], 0, v[80:81]
	s_nop 0
	s_waitcnt lgkmcnt(0)
	s_nop 3
	s_nop 0
	s_nop 4
	s_waitcnt lgkmcnt(0)
	s_nop 3
	s_waitcnt lgkmcnt(0)
	s_nop 0
	s_waitcnt lgkmcnt(0)
	s_nop 4
	s_waitcnt lgkmcnt(0)
	s_nop 1
	s_waitcnt lgkmcnt(0)
	s_nop 1
	s_waitcnt lgkmcnt(0)
	s_nop 1
	v_mov_b32_e32 v65, v234
	s_nop 0
	s_waitcnt lgkmcnt(0)
	s_nop 1
	s_waitcnt lgkmcnt(0)
; #define PG8_BAR __builtin_amdgcn_s_barrier()
; __device__ __forceinline__ v4u pack8(const f32x4 a, const f32x4 b) { v4u w; w.x = cvt_pk_bf16(a[0], a[1]); w.y = cvt_pk_bf16(a[2], a[3]); w.z = cvt_pk_bf16(b[0], b[1]); w.w = cvt_pk_bf16(b[2], b[3]); return w; }
; template <class Epi, class Sched, bool ALIGN_EPI = false, bool SP2 = false>
; __device__ __forceinline__ void gemm_phase(PG8_LAS unsigned char* lds, const Gemm g, const Sched& S, const Epi& E) {
;     ...
;         if constexpr (!Epi::AFTER_DRAIN) { E(acc, cur, wr, wc, fr, fq); S.done(cur); }
;         if (!has_next) break;
; #pragma unroll
;         for (int a = 0; a < 2; ++a)
; #pragma unroll
;             for (int b = 0; b < 2; ++b)
; #pragma unroll
;                 for (int m = 0; m < 4; ++m)
; #pragma unroll
;                     for (int n = 0; n < 2; ++n) acc[a][b][m][n] = (f32x4){0.f, 0.f, 0.f, 0.f};
;         cur = nxt; cA = nA; cB = nB; ++ui;
;         if constexpr (ALIGN_EPI) { if (wr == 1) PG8_BAR; }
;     }
;     __device__ __forceinline__ void operator()(const f32x4 (&acc)[2][2][4][2], const pg8::Unit& u, int wr, int wc, int fr, int fq) const {
;     ...
;                 const int row = row0 + ai * 128 + m * 16; const float rs = rsv[m], c = -rs * LOG2E, rs2 = rs * rs;
;                 f32x4 e0 = acc[ai][0][m][0] * c, e1 = acc[ai][0][m][1] * c;
; #pragma unroll
;                 for (int i = 0; i < 4; ++i) { e0[i] = __builtin_amdgcn_exp2f(e0[i]); e1[i] = __builtin_amdgcn_exp2f(e1[i]); }
;                 e0 = e0 + 1.0f; e1 = e1 + 1.0f;
; #pragma unroll
;                 for (int i = 0; i < 4; ++i) { e0[i] = __builtin_amdgcn_rcpf(e0[i]); e1[i] = __builtin_amdgcn_rcpf(e1[i]); }
;                 const f32x4 h0 = (acc[ai][0][m][0] * acc[ai][1][m][0]) * rs2 * e0, h1 = (acc[ai][0][m][1] * acc[ai][1][m][1]) * rs2 * e1;
;                 *(v4u*)(O + (size_t)row * FFH + col0) = pack8(h0, h1);
	s_nop 1
	v_mov_b32_e32 v78, v237
	v_mul_f32_e32 v68, 0xbfb8aa3b, v65
	v_pk_mul_f32 v[72:73], v[60:61], v[68:69] op_sel_hi:[1,0]
	v_mov_b32_e32 v77, v236
	v_pk_mul_f32 v[70:71], v[62:63], v[68:69] op_sel_hi:[1,0]
	v_pk_mul_f32 v[74:75], v[58:59], v[68:69] op_sel_hi:[1,0]
	v_pk_mul_f32 v[68:69], v[56:57], v[68:69] op_sel_hi:[1,0]
	v_exp_f32_e32 v72, v72
	v_exp_f32_e32 v73, v73
	v_exp_f32_e32 v68, v68
	v_exp_f32_e32 v70, v70
	v_exp_f32_e32 v71, v71
	v_exp_f32_e32 v74, v74
	v_exp_f32_e32 v75, v75
	v_exp_f32_e32 v69, v69
	v_pk_add_f32 v[72:73], v[72:73], 1.0 op_sel_hi:[1,0]
	v_pk_add_f32 v[70:71], v[70:71], 1.0 op_sel_hi:[1,0]
	v_pk_add_f32 v[74:75], v[74:75], 1.0 op_sel_hi:[1,0]
	v_pk_add_f32 v[68:69], v[68:69], 1.0 op_sel_hi:[1,0]
	v_rcp_f32_e32 v72, v72
	v_rcp_f32_e32 v73, v73
	v_rcp_f32_e32 v68, v68
	v_rcp_f32_e32 v69, v69
	v_rcp_f32_e32 v70, v70
	v_rcp_f32_e32 v74, v74
	v_rcp_f32_e32 v71, v71
	v_rcp_f32_e32 v75, v75
	v_mul_f32_e32 v76, v65, v65
	v_mov_b32_e32 v67, v235
	v_pk_mul_f32 v[52:53], v[52:53], v[76:77] op_sel_hi:[1,0]
	v_pk_mul_f32 v[54:55], v[54:55], v[76:77] op_sel_hi:[1,0]
	v_pk_mul_f32 v[52:53], v[52:53], v[72:73]
	v_pk_mul_f32 v[48:49], v[48:49], v[76:77] op_sel_hi:[1,0]
	v_pk_mul_f32 v[50:51], v[50:51], v[76:77] op_sel_hi:[1,0]
	v_pk_mul_f32 v[54:55], v[54:55], v[70:71]
	v_pk_mul_f32 v[56:57], v[50:51], v[74:75]
	v_pk_mul_f32 v[50:51], v[48:49], v[68:69]
	v_cvt_pk_bf16_f32 v48, v52, v53
	v_mad_i64_i32 v[52:53], s[22:23], v84, s3, v[112:113]
	v_cvt_pk_bf16_f32 v49, v54, v55
	v_cvt_pk_bf16_f32 v50, v50, v51
	v_cvt_pk_bf16_f32 v51, v56, v57
	v_lshl_add_u64 v[52:53], v[52:53], 0, v[114:115]
	global_store_dwordx4 v[52:53], v[48:51], off
	v_mul_f32_e32 v56, v67, v67
	v_pk_mul_f32 v[36:37], v[36:37], v[56:57] op_sel_hi:[1,0]
	v_mul_f32_e32 v48, 0xbfb8aa3b, v67
	v_pk_mul_f32 v[52:53], v[44:45], v[48:49] op_sel_hi:[1,0]
	v_pk_mul_f32 v[50:51], v[46:47], v[48:49] op_sel_hi:[1,0]
	v_pk_mul_f32 v[54:55], v[42:43], v[48:49] op_sel_hi:[1,0]
	v_pk_mul_f32 v[48:49], v[40:41], v[48:49] op_sel_hi:[1,0]
	v_exp_f32_e32 v52, v52
	v_exp_f32_e32 v53, v53
	v_exp_f32_e32 v48, v48
	v_exp_f32_e32 v50, v50
	v_exp_f32_e32 v51, v51
	v_exp_f32_e32 v54, v54
	v_exp_f32_e32 v55, v55
	v_exp_f32_e32 v49, v49
	v_pk_add_f32 v[52:53], v[52:53], 1.0 op_sel_hi:[1,0]
	v_pk_add_f32 v[50:51], v[50:51], 1.0 op_sel_hi:[1,0]
	v_pk_add_f32 v[54:55], v[54:55], 1.0 op_sel_hi:[1,0]
	v_pk_add_f32 v[48:49], v[48:49], 1.0 op_sel_hi:[1,0]
	v_rcp_f32_e32 v52, v52
	v_rcp_f32_e32 v53, v53
	v_rcp_f32_e32 v48, v48
	v_rcp_f32_e32 v49, v49
	v_rcp_f32_e32 v50, v50
	v_rcp_f32_e32 v54, v54
	v_rcp_f32_e32 v51, v51
	v_rcp_f32_e32 v55, v55
	v_pk_mul_f32 v[38:39], v[38:39], v[56:57] op_sel_hi:[1,0]
	v_pk_mul_f32 v[36:37], v[36:37], v[52:53]
	v_pk_mul_f32 v[32:33], v[32:33], v[56:57] op_sel_hi:[1,0]
	v_pk_mul_f32 v[34:35], v[34:35], v[56:57] op_sel_hi:[1,0]
	v_pk_mul_f32 v[38:39], v[38:39], v[50:51]
	v_pk_mul_f32 v[40:41], v[34:35], v[54:55]
	v_pk_mul_f32 v[34:35], v[32:33], v[48:49]
	v_cvt_pk_bf16_f32 v32, v36, v37
	v_mad_i64_i32 v[36:37], s[22:23], v86, s3, v[112:113]
	v_cvt_pk_bf16_f32 v33, v38, v39
	v_cvt_pk_bf16_f32 v34, v34, v35
	v_cvt_pk_bf16_f32 v35, v40, v41
	v_lshl_add_u64 v[36:37], v[36:37], 0, v[114:115]
	global_store_dwordx4 v[36:37], v[32:35], off
	v_mul_f32_e32 v40, v77, v77
	v_pk_mul_f32 v[20:21], v[20:21], v[40:41] op_sel_hi:[1,0]
	v_mul_f32_e32 v32, 0xbfb8aa3b, v77
	v_pk_mul_f32 v[36:37], v[28:29], v[32:33] op_sel_hi:[1,0]
	v_pk_mul_f32 v[34:35], v[30:31], v[32:33] op_sel_hi:[1,0]
	v_pk_mul_f32 v[38:39], v[26:27], v[32:33] op_sel_hi:[1,0]
	v_pk_mul_f32 v[32:33], v[24:25], v[32:33] op_sel_hi:[1,0]
	v_exp_f32_e32 v36, v36
	v_exp_f32_e32 v37, v37
	v_exp_f32_e32 v32, v32
	v_exp_f32_e32 v34, v34
	v_exp_f32_e32 v35, v35
	v_exp_f32_e32 v38, v38
	v_exp_f32_e32 v39, v39
	v_exp_f32_e32 v33, v33
	v_pk_add_f32 v[36:37], v[36:37], 1.0 op_sel_hi:[1,0]
	v_pk_add_f32 v[34:35], v[34:35], 1.0 op_sel_hi:[1,0]
	v_pk_add_f32 v[38:39], v[38:39], 1.0 op_sel_hi:[1,0]
	v_pk_add_f32 v[32:33], v[32:33], 1.0 op_sel_hi:[1,0]
	v_rcp_f32_e32 v36, v36
	v_rcp_f32_e32 v37, v37
	v_rcp_f32_e32 v32, v32
	v_rcp_f32_e32 v33, v33
	v_rcp_f32_e32 v34, v34
	v_rcp_f32_e32 v38, v38
	v_rcp_f32_e32 v35, v35
	v_rcp_f32_e32 v39, v39
	v_pk_mul_f32 v[22:23], v[22:23], v[40:41] op_sel_hi:[1,0]
	v_pk_mul_f32 v[20:21], v[20:21], v[36:37]
	v_pk_mul_f32 v[16:17], v[16:17], v[40:41] op_sel_hi:[1,0]
	v_pk_mul_f32 v[18:19], v[18:19], v[40:41] op_sel_hi:[1,0]
	v_pk_mul_f32 v[22:23], v[22:23], v[34:35]
	v_pk_mul_f32 v[24:25], v[18:19], v[38:39]
	v_pk_mul_f32 v[18:19], v[16:17], v[32:33]
	v_cvt_pk_bf16_f32 v16, v20, v21
	v_mad_i64_i32 v[20:21], s[22:23], v66, s3, v[112:113]
	v_cvt_pk_bf16_f32 v17, v22, v23
	v_cvt_pk_bf16_f32 v18, v18, v19
	v_cvt_pk_bf16_f32 v19, v24, v25
	v_lshl_add_u64 v[20:21], v[20:21], 0, v[114:115]
	global_store_dwordx4 v[20:21], v[16:19], off
	v_mul_f32_e32 v24, v78, v78
	v_pk_mul_f32 v[4:5], v[4:5], v[24:25] op_sel_hi:[1,0]
	v_mul_f32_e32 v16, 0xbfb8aa3b, v78
	v_pk_mul_f32 v[20:21], v[12:13], v[16:17] op_sel_hi:[1,0]
	v_pk_mul_f32 v[18:19], v[14:15], v[16:17] op_sel_hi:[1,0]
	v_pk_mul_f32 v[22:23], v[10:11], v[16:17] op_sel_hi:[1,0]
	v_pk_mul_f32 v[16:17], v[8:9], v[16:17] op_sel_hi:[1,0]
	v_exp_f32_e32 v20, v20
	v_exp_f32_e32 v21, v21
	v_exp_f32_e32 v16, v16
	v_exp_f32_e32 v18, v18
	v_exp_f32_e32 v19, v19
	v_exp_f32_e32 v22, v22
	v_exp_f32_e32 v23, v23
	v_exp_f32_e32 v17, v17
	v_pk_add_f32 v[20:21], v[20:21], 1.0 op_sel_hi:[1,0]
	v_pk_add_f32 v[18:19], v[18:19], 1.0 op_sel_hi:[1,0]
	v_pk_add_f32 v[22:23], v[22:23], 1.0 op_sel_hi:[1,0]
	v_pk_add_f32 v[16:17], v[16:17], 1.0 op_sel_hi:[1,0]
	v_rcp_f32_e32 v20, v20
	v_rcp_f32_e32 v21, v21
	v_rcp_f32_e32 v16, v16
	v_rcp_f32_e32 v17, v17
	v_rcp_f32_e32 v18, v18
	v_rcp_f32_e32 v22, v22
	v_rcp_f32_e32 v19, v19
	v_rcp_f32_e32 v23, v23
	v_pk_mul_f32 v[6:7], v[6:7], v[24:25] op_sel_hi:[1,0]
	v_pk_mul_f32 v[4:5], v[4:5], v[20:21]
	v_pk_mul_f32 v[0:1], v[0:1], v[24:25] op_sel_hi:[1,0]
	v_pk_mul_f32 v[2:3], v[2:3], v[24:25] op_sel_hi:[1,0]
	v_pk_mul_f32 v[6:7], v[6:7], v[18:19]
	v_pk_mul_f32 v[8:9], v[2:3], v[22:23]
	v_pk_mul_f32 v[2:3], v[0:1], v[16:17]
	v_cvt_pk_bf16_f32 v0, v4, v5
	v_mad_i64_i32 v[4:5], s[22:23], v64, s3, v[112:113]
	v_cvt_pk_bf16_f32 v1, v6, v7
	v_cvt_pk_bf16_f32 v2, v2, v3
	v_cvt_pk_bf16_f32 v3, v8, v9
	v_lshl_add_u64 v[4:5], v[4:5], 0, v[114:115]
	global_store_dwordx4 v[4:5], v[0:3], off
	s_cbranch_vccnz .LBB0_1217
	s_andn2_b64 vcc, exec, s[6:7]
	s_cbranch_vccnz .LBB0_1216
	s_barrier
	s_branch .LBB0_1216
